# v49 plus removal of s_nop 2 before v_cvt_pk_bf16_f32 wherever both inputs come from non-transcendental VALU ops
# speedup vs baseline: 1.0004x; 1.0004x over previous
.LBB0_126:
	s_or_b64 exec, exec, s[52:53]
	v_mov_b32_dpp v214, v80 row_ror:1 row_mask:0xf bank_mask:0xf bound_ctrl:1
	v_mov_b32_dpp v215, v81 row_ror:1 row_mask:0xf bank_mask:0xf bound_ctrl:1
	v_mov_b32_dpp v216, v82 row_ror:1 row_mask:0xf bank_mask:0xf bound_ctrl:1
	v_mov_b32_dpp v217, v83 row_ror:1 row_mask:0xf bank_mask:0xf bound_ctrl:1
	v_mov_b32_dpp v204, v124 row_ror:15 row_mask:0xf bank_mask:0xf bound_ctrl:1
	v_mov_b32_dpp v205, v125 row_ror:15 row_mask:0xf bank_mask:0xf bound_ctrl:1
	v_mov_b32_dpp v212, v126 row_ror:15 row_mask:0xf bank_mask:0xf bound_ctrl:1
	v_mov_b32_dpp v213, v127 row_ror:15 row_mask:0xf bank_mask:0xf bound_ctrl:1
	v_mov_b32_dpp v200, v112 row_ror:15 row_mask:0xf bank_mask:0xf bound_ctrl:1
	v_mov_b32_dpp v201, v113 row_ror:15 row_mask:0xf bank_mask:0xf bound_ctrl:1
	v_mov_b32_dpp v208, v114 row_ror:15 row_mask:0xf bank_mask:0xf bound_ctrl:1
	v_mov_b32_dpp v209, v115 row_ror:15 row_mask:0xf bank_mask:0xf bound_ctrl:1
	v_mov_b32_dpp v190, v72 row_ror:1 row_mask:0xf bank_mask:0xf bound_ctrl:1
	v_mov_b32_dpp v191, v73 row_ror:1 row_mask:0xf bank_mask:0xf bound_ctrl:1
	v_mov_b32_dpp v198, v74 row_ror:1 row_mask:0xf bank_mask:0xf bound_ctrl:1
	v_mov_b32_dpp v199, v75 row_ror:1 row_mask:0xf bank_mask:0xf bound_ctrl:1
	v_mov_b32_dpp v202, v120 row_ror:15 row_mask:0xf bank_mask:0xf bound_ctrl:1
	v_mov_b32_dpp v203, v121 row_ror:15 row_mask:0xf bank_mask:0xf bound_ctrl:1
	v_mov_b32_dpp v210, v122 row_ror:15 row_mask:0xf bank_mask:0xf bound_ctrl:1
	v_mov_b32_dpp v211, v123 row_ror:15 row_mask:0xf bank_mask:0xf bound_ctrl:1
	v_mov_b32_dpp v192, v104 row_ror:15 row_mask:0xf bank_mask:0xf bound_ctrl:1
	v_mov_b32_dpp v193, v105 row_ror:15 row_mask:0xf bank_mask:0xf bound_ctrl:1
	v_mov_b32_dpp v206, v106 row_ror:15 row_mask:0xf bank_mask:0xf bound_ctrl:1
	v_mov_b32_dpp v207, v107 row_ror:15 row_mask:0xf bank_mask:0xf bound_ctrl:1
	s_and_saveexec_b64 s[52:53], s[2:3]
	s_cbranch_execz .LBB0_128
	s_waitcnt vmcnt(0)
	v_pk_fma_f32 v[216:217], v[138:139], v[216:217], v[166:167]
	v_pk_fma_f32 v[214:215], v[136:137], v[214:215], v[164:165]
	v_pk_fma_f32 v[190:191], v[128:129], v[190:191], v[160:161]
	v_pk_fma_f32 v[216:217], v[126:127], v[146:147], v[216:217]
	v_pk_fma_f32 v[214:215], v[124:125], v[144:145], v[214:215]
	v_pk_fma_f32 v[190:191], v[120:121], v[132:133], v[190:191]
	v_pk_fma_f32 v[216:217], v[114:115], v[154:155], v[216:217]
	v_pk_fma_f32 v[214:215], v[112:113], v[152:153], v[214:215]
	v_pk_fma_f32 v[190:191], v[104:105], v[140:141], v[190:191]
	v_pk_fma_f32 v[216:217], v[98:99], v[158:159], v[216:217]
	v_pk_fma_f32 v[214:215], v[96:97], v[156:157], v[214:215]
	v_pk_fma_f32 v[190:191], v[88:89], v[148:149], v[190:191]
	v_ashrrev_i32_e32 v187, 31, v186
	v_pk_fma_f32 v[198:199], v[130:131], v[198:199], v[162:163]
	v_cvt_pk_bf16_f32 v214, v214, v215
	v_cvt_pk_bf16_f32 v215, v216, v217
	v_cvt_pk_bf16_f32 v216, v190, v191
	v_lshlrev_b64 v[190:191], 13, v[186:187]
	v_pk_fma_f32 v[198:199], v[122:123], v[134:135], v[198:199]
	v_lshl_add_u64 v[190:191], s[24:25], 0, v[190:191]
	v_pk_fma_f32 v[198:199], v[106:107], v[142:143], v[198:199]
	v_lshl_add_u64 v[190:191], v[188:189], 1, v[190:191]
	v_pk_fma_f32 v[198:199], v[90:91], v[150:151], v[198:199]
	s_nop 0
	v_cvt_pk_bf16_f32 v217, v198, v199
	global_store_dwordx4 v[190:191], v[214:217], off
.LBB0_128:
	s_or_b64 exec, exec, s[52:53]
	s_waitcnt vmcnt(0)
	v_pk_fma_f32 v[190:191], v[126:127], v[138:139], v[166:167]
	v_pk_fma_f32 v[198:199], v[124:125], v[136:137], v[164:165]
	v_pk_fma_f32 v[190:191], v[114:115], v[146:147], v[190:191]
	v_pk_fma_f32 v[214:215], v[122:123], v[130:131], v[162:163]
	v_pk_fma_f32 v[198:199], v[112:113], v[144:145], v[198:199]
	v_pk_fma_f32 v[190:191], v[98:99], v[154:155], v[190:191]
	v_pk_fma_f32 v[214:215], v[106:107], v[134:135], v[214:215]
	v_pk_fma_f32 v[198:199], v[96:97], v[152:153], v[198:199]
	v_pk_fma_f32 v[190:191], v[82:83], v[158:159], v[190:191]
	v_pk_fma_f32 v[214:215], v[90:91], v[142:143], v[214:215]
	v_pk_fma_f32 v[198:199], v[80:81], v[156:157], v[198:199]
	v_pk_fma_f32 v[218:219], v[74:75], v[150:151], v[214:215]
	v_cvt_pk_bf16_f32 v214, v198, v199
	v_cvt_pk_bf16_f32 v215, v190, v191
	v_or_b32_e32 v190, 1, v186
	v_pk_fma_f32 v[216:217], v[120:121], v[128:129], v[160:161]
	v_ashrrev_i32_e32 v191, 31, v190
	v_pk_fma_f32 v[216:217], v[104:105], v[132:133], v[216:217]
	v_lshlrev_b64 v[190:191], 13, v[190:191]
	v_pk_fma_f32 v[216:217], v[88:89], v[140:141], v[216:217]
	v_lshl_add_u64 v[190:191], s[24:25], 0, v[190:191]
	v_pk_fma_f32 v[216:217], v[72:73], v[148:149], v[216:217]
	v_lshl_add_u64 v[198:199], v[188:189], 1, v[190:191]
	v_lshlrev_b64 v[190:191], 1, v[188:189]
	v_cvt_pk_bf16_f32 v216, v216, v217
	v_cvt_pk_bf16_f32 v217, v218, v219
	global_store_dwordx4 v[198:199], v[214:217], off
	s_and_saveexec_b64 s[52:53], s[6:7]
	s_cbranch_execz .LBB0_130
	v_pk_fma_f32 v[214:215], v[114:115], v[138:139], v[166:167]
	v_pk_fma_f32 v[216:217], v[112:113], v[136:137], v[164:165]
	v_pk_fma_f32 v[214:215], v[98:99], v[146:147], v[214:215]
	v_pk_fma_f32 v[216:217], v[96:97], v[144:145], v[216:217]
	v_pk_fma_f32 v[214:215], v[82:83], v[154:155], v[214:215]
	v_pk_fma_f32 v[216:217], v[80:81], v[152:153], v[216:217]
	v_pk_fma_f32 v[218:219], v[158:159], v[212:213], v[214:215]
	v_pk_fma_f32 v[214:215], v[156:157], v[204:205], v[216:217]
	v_pk_fma_f32 v[216:217], v[106:107], v[130:131], v[162:163]
	v_cvt_pk_bf16_f32 v214, v214, v215
	v_cvt_pk_bf16_f32 v215, v218, v219
	v_or_b32_e32 v218, 2, v186
	v_pk_fma_f32 v[220:221], v[104:105], v[128:129], v[160:161]
	v_ashrrev_i32_e32 v219, 31, v218
	v_pk_fma_f32 v[216:217], v[90:91], v[134:135], v[216:217]
	v_pk_fma_f32 v[220:221], v[88:89], v[132:133], v[220:221]
	v_lshlrev_b64 v[218:219], 13, v[218:219]
	v_pk_fma_f32 v[216:217], v[74:75], v[142:143], v[216:217]
	v_pk_fma_f32 v[220:221], v[72:73], v[140:141], v[220:221]
	v_lshl_add_u64 v[218:219], s[24:25], 0, v[218:219]
	v_pk_fma_f32 v[222:223], v[150:151], v[210:211], v[216:217]
	v_pk_fma_f32 v[216:217], v[148:149], v[202:203], v[220:221]
	v_lshl_add_u64 v[218:219], v[218:219], 0, v[190:191]
	v_cvt_pk_bf16_f32 v216, v216, v217
	v_cvt_pk_bf16_f32 v217, v222, v223
	global_store_dwordx4 v[218:219], v[214:217], off
	s_nop 1
	v_pk_fma_f32 v[214:215], v[98:99], v[138:139], v[166:167]
	v_pk_fma_f32 v[216:217], v[96:97], v[136:137], v[164:165]
	v_pk_fma_f32 v[214:215], v[82:83], v[146:147], v[214:215]
	v_pk_fma_f32 v[216:217], v[80:81], v[144:145], v[216:217]
	v_pk_fma_f32 v[212:213], v[154:155], v[212:213], v[214:215]
	v_pk_fma_f32 v[204:205], v[152:153], v[204:205], v[216:217]
	v_pk_fma_f32 v[208:209], v[158:159], v[208:209], v[212:213]
	v_pk_fma_f32 v[212:213], v[88:89], v[128:129], v[160:161]
	v_pk_fma_f32 v[200:201], v[156:157], v[200:201], v[204:205]
	v_pk_fma_f32 v[212:213], v[72:73], v[132:133], v[212:213]
	v_cvt_pk_bf16_f32 v200, v200, v201
	v_cvt_pk_bf16_f32 v201, v208, v209
	v_pk_fma_f32 v[204:205], v[90:91], v[130:131], v[162:163]
	v_pk_fma_f32 v[202:203], v[140:141], v[202:203], v[212:213]
	v_pk_fma_f32 v[204:205], v[74:75], v[134:135], v[204:205]
	v_pk_fma_f32 v[192:193], v[148:149], v[192:193], v[202:203]
	v_pk_fma_f32 v[204:205], v[142:143], v[210:211], v[204:205]
	v_cvt_pk_bf16_f32 v202, v192, v193
	v_or_b32_e32 v192, 3, v186
	v_ashrrev_i32_e32 v193, 31, v192
	v_lshlrev_b64 v[192:193], 13, v[192:193]
	v_lshl_add_u64 v[192:193], s[24:25], 0, v[192:193]
	v_lshl_add_u64 v[192:193], v[192:193], 0, v[190:191]
	v_pk_fma_f32 v[204:205], v[150:151], v[206:207], v[204:205]
	s_nop 0
	v_cvt_pk_bf16_f32 v203, v204, v205
	global_store_dwordx4 v[192:193], v[200:203], off

.LBB0_134:
	s_or_b64 exec, exec, s[52:53]
	v_add_u32_e32 v192, 0x80, v186
	v_mov_b32_dpp v220, v12 row_ror:1 row_mask:0xf bank_mask:0xf bound_ctrl:1
	v_mov_b32_dpp v221, v13 row_ror:1 row_mask:0xf bank_mask:0xf bound_ctrl:1
	v_mov_b32_dpp v222, v14 row_ror:1 row_mask:0xf bank_mask:0xf bound_ctrl:1
	v_mov_b32_dpp v223, v15 row_ror:1 row_mask:0xf bank_mask:0xf bound_ctrl:1
	v_mov_b32_dpp v208, v60 row_ror:15 row_mask:0xf bank_mask:0xf bound_ctrl:1
	v_mov_b32_dpp v209, v61 row_ror:15 row_mask:0xf bank_mask:0xf bound_ctrl:1
	v_mov_b32_dpp v216, v62 row_ror:15 row_mask:0xf bank_mask:0xf bound_ctrl:1
	v_mov_b32_dpp v217, v63 row_ror:15 row_mask:0xf bank_mask:0xf bound_ctrl:1
	v_mov_b32_dpp v204, v44 row_ror:15 row_mask:0xf bank_mask:0xf bound_ctrl:1
	v_mov_b32_dpp v205, v45 row_ror:15 row_mask:0xf bank_mask:0xf bound_ctrl:1
	v_mov_b32_dpp v212, v46 row_ror:15 row_mask:0xf bank_mask:0xf bound_ctrl:1
	v_mov_b32_dpp v213, v47 row_ror:15 row_mask:0xf bank_mask:0xf bound_ctrl:1
	v_mov_b32_dpp v200, v8 row_ror:1 row_mask:0xf bank_mask:0xf bound_ctrl:1
	v_mov_b32_dpp v201, v9 row_ror:1 row_mask:0xf bank_mask:0xf bound_ctrl:1
	v_mov_b32_dpp v218, v10 row_ror:1 row_mask:0xf bank_mask:0xf bound_ctrl:1
	v_mov_b32_dpp v219, v11 row_ror:1 row_mask:0xf bank_mask:0xf bound_ctrl:1
	v_mov_b32_dpp v206, v56 row_ror:15 row_mask:0xf bank_mask:0xf bound_ctrl:1
	v_mov_b32_dpp v207, v57 row_ror:15 row_mask:0xf bank_mask:0xf bound_ctrl:1
	v_mov_b32_dpp v214, v58 row_ror:15 row_mask:0xf bank_mask:0xf bound_ctrl:1
	v_mov_b32_dpp v215, v59 row_ror:15 row_mask:0xf bank_mask:0xf bound_ctrl:1
	v_mov_b32_dpp v202, v40 row_ror:15 row_mask:0xf bank_mask:0xf bound_ctrl:1
	v_mov_b32_dpp v203, v41 row_ror:15 row_mask:0xf bank_mask:0xf bound_ctrl:1
	v_mov_b32_dpp v210, v42 row_ror:15 row_mask:0xf bank_mask:0xf bound_ctrl:1
	v_mov_b32_dpp v211, v43 row_ror:15 row_mask:0xf bank_mask:0xf bound_ctrl:1
	v_ashrrev_i32_e32 v193, 31, v192
	s_and_saveexec_b64 s[52:53], s[2:3]
	s_cbranch_execz .LBB0_136
	v_pk_fma_f32 v[220:221], v[136:137], v[220:221], v[164:165]
	v_pk_fma_f32 v[200:201], v[128:129], v[200:201], v[160:161]
	v_pk_fma_f32 v[222:223], v[138:139], v[222:223], v[166:167]
	v_pk_fma_f32 v[220:221], v[60:61], v[144:145], v[220:221]
	v_pk_fma_f32 v[218:219], v[130:131], v[218:219], v[162:163]
	v_pk_fma_f32 v[200:201], v[56:57], v[132:133], v[200:201]
	v_pk_fma_f32 v[222:223], v[62:63], v[146:147], v[222:223]
	v_pk_fma_f32 v[220:221], v[44:45], v[152:153], v[220:221]
	v_pk_fma_f32 v[218:219], v[58:59], v[134:135], v[218:219]
	v_pk_fma_f32 v[200:201], v[40:41], v[140:141], v[200:201]
	v_pk_fma_f32 v[222:223], v[46:47], v[154:155], v[222:223]
	v_pk_fma_f32 v[220:221], v[28:29], v[156:157], v[220:221]
	v_pk_fma_f32 v[218:219], v[42:43], v[142:143], v[218:219]
	v_pk_fma_f32 v[200:201], v[24:25], v[148:149], v[200:201]
	v_pk_fma_f32 v[222:223], v[30:31], v[158:159], v[222:223]
	v_pk_fma_f32 v[232:233], v[26:27], v[150:151], v[218:219]
	v_cvt_pk_bf16_f32 v218, v220, v221
	v_cvt_pk_bf16_f32 v219, v222, v223
	v_cvt_pk_bf16_f32 v220, v200, v201
	v_lshlrev_b64 v[200:201], 13, v[192:193]
	v_lshl_add_u64 v[200:201], s[24:25], 0, v[200:201]
	v_lshl_add_u64 v[200:201], v[188:189], 1, v[200:201]
	v_cvt_pk_bf16_f32 v221, v232, v233
	global_store_dwordx4 v[200:201], v[218:221], off
.LBB0_136:
	s_or_b64 exec, exec, s[52:53]
	v_pk_fma_f32 v[200:201], v[62:63], v[138:139], v[166:167]
	v_pk_fma_f32 v[218:219], v[60:61], v[136:137], v[164:165]
	v_pk_fma_f32 v[200:201], v[46:47], v[146:147], v[200:201]
	v_pk_fma_f32 v[218:219], v[44:45], v[144:145], v[218:219]
	v_pk_fma_f32 v[200:201], v[30:31], v[154:155], v[200:201]
	v_pk_fma_f32 v[218:219], v[28:29], v[152:153], v[218:219]
	v_pk_fma_f32 v[200:201], v[14:15], v[158:159], v[200:201]
	v_pk_fma_f32 v[218:219], v[12:13], v[156:157], v[218:219]
	v_ashrrev_i32_e32 v187, 31, v186
	v_pk_fma_f32 v[220:221], v[58:59], v[130:131], v[162:163]
	v_pk_fma_f32 v[222:223], v[56:57], v[128:129], v[160:161]
	v_cvt_pk_bf16_f32 v218, v218, v219
	v_cvt_pk_bf16_f32 v219, v200, v201
	v_lshlrev_b64 v[200:201], 13, v[186:187]
	v_pk_fma_f32 v[220:221], v[42:43], v[134:135], v[220:221]
	v_pk_fma_f32 v[222:223], v[40:41], v[132:133], v[222:223]
	v_lshl_add_u64 v[200:201], s[24:25], 0, v[200:201]
	v_pk_fma_f32 v[220:221], v[26:27], v[142:143], v[220:221]
	v_pk_fma_f32 v[222:223], v[24:25], v[140:141], v[222:223]
	v_lshl_add_u64 v[200:201], v[188:189], 1, v[200:201]
	v_pk_fma_f32 v[232:233], v[10:11], v[150:151], v[220:221]
	v_pk_fma_f32 v[220:221], v[8:9], v[148:149], v[222:223]
	v_add_co_u32_e32 v222, vcc, 0x102000, v200
	v_cvt_pk_bf16_f32 v220, v220, v221
	v_cvt_pk_bf16_f32 v221, v232, v233
	s_nop 1
	v_addc_co_u32_e32 v223, vcc, 0, v201, vcc
	global_store_dwordx4 v[222:223], v[218:221], off
	s_and_saveexec_b64 s[52:53], s[6:7]
	s_cbranch_execz .LBB0_138
	v_pk_fma_f32 v[218:219], v[46:47], v[138:139], v[166:167]
	v_pk_fma_f32 v[220:221], v[44:45], v[136:137], v[164:165]
	v_pk_fma_f32 v[218:219], v[30:31], v[146:147], v[218:219]
	v_pk_fma_f32 v[220:221], v[28:29], v[144:145], v[220:221]
	v_pk_fma_f32 v[218:219], v[14:15], v[154:155], v[218:219]
	v_pk_fma_f32 v[220:221], v[12:13], v[152:153], v[220:221]
	v_pk_fma_f32 v[222:223], v[158:159], v[216:217], v[218:219]
	v_pk_fma_f32 v[218:219], v[156:157], v[208:209], v[220:221]
	v_pk_fma_f32 v[220:221], v[42:43], v[130:131], v[162:163]
	v_pk_fma_f32 v[232:233], v[40:41], v[128:129], v[160:161]
	v_pk_fma_f32 v[130:131], v[26:27], v[130:131], v[162:163]
	v_pk_fma_f32 v[128:129], v[24:25], v[128:129], v[160:161]
	v_pk_fma_f32 v[220:221], v[26:27], v[134:135], v[220:221]
	v_pk_fma_f32 v[232:233], v[24:25], v[132:133], v[232:233]
	s_mov_b32 s34, 0x104000
	v_pk_fma_f32 v[138:139], v[30:31], v[138:139], v[166:167]
	v_pk_fma_f32 v[136:137], v[28:29], v[136:137], v[164:165]
	v_pk_fma_f32 v[130:131], v[10:11], v[134:135], v[130:131]
	v_pk_fma_f32 v[128:129], v[8:9], v[132:133], v[128:129]
	v_pk_fma_f32 v[220:221], v[10:11], v[142:143], v[220:221]
	v_pk_fma_f32 v[232:233], v[8:9], v[140:141], v[232:233]
	v_cvt_pk_bf16_f32 v218, v218, v219
	v_cvt_pk_bf16_f32 v219, v222, v223
	v_add_co_u32_e32 v222, vcc, s34, v200
	v_pk_fma_f32 v[138:139], v[14:15], v[146:147], v[138:139]
	v_pk_fma_f32 v[136:137], v[12:13], v[144:145], v[136:137]
	v_pk_fma_f32 v[130:131], v[142:143], v[214:215], v[130:131]
	v_pk_fma_f32 v[128:129], v[140:141], v[206:207], v[128:129]
	v_pk_fma_f32 v[234:235], v[150:151], v[214:215], v[220:221]
	v_pk_fma_f32 v[220:221], v[148:149], v[206:207], v[232:233]
	v_addc_co_u32_e32 v223, vcc, 0, v201, vcc
	v_pk_fma_f32 v[138:139], v[154:155], v[216:217], v[138:139]
	v_pk_fma_f32 v[136:137], v[152:153], v[208:209], v[136:137]
	v_pk_fma_f32 v[132:133], v[150:151], v[210:211], v[130:131]
	v_pk_fma_f32 v[130:131], v[148:149], v[202:203], v[128:129]
	v_cvt_pk_bf16_f32 v220, v220, v221
	v_cvt_pk_bf16_f32 v221, v234, v235
	global_store_dwordx4 v[222:223], v[218:221], off
	v_pk_fma_f32 v[138:139], v[158:159], v[212:213], v[138:139]
	v_pk_fma_f32 v[136:137], v[156:157], v[204:205], v[136:137]
	s_nop 0
	v_cvt_pk_bf16_f32 v128, v136, v137
	v_cvt_pk_bf16_f32 v129, v138, v139
	v_cvt_pk_bf16_f32 v130, v130, v131
	v_cvt_pk_bf16_f32 v131, v132, v133
	v_add_co_u32_e32 v132, vcc, 0x106000, v200
	s_nop 1
	v_addc_co_u32_e32 v133, vcc, 0, v201, vcc
	global_store_dwordx4 v[132:133], v[128:131], off

.LBB0_142:
	s_or_b64 exec, exec, s[52:53]
	v_mov_b32_dpp v218, v68 row_ror:1 row_mask:0xf bank_mask:0xf bound_ctrl:1
	v_mov_b32_dpp v219, v69 row_ror:1 row_mask:0xf bank_mask:0xf bound_ctrl:1
	v_mov_b32_dpp v220, v70 row_ror:1 row_mask:0xf bank_mask:0xf bound_ctrl:1
	v_mov_b32_dpp v221, v71 row_ror:1 row_mask:0xf bank_mask:0xf bound_ctrl:1
	v_mov_b32_dpp v204, v116 row_ror:15 row_mask:0xf bank_mask:0xf bound_ctrl:1
	v_mov_b32_dpp v205, v117 row_ror:15 row_mask:0xf bank_mask:0xf bound_ctrl:1
	v_mov_b32_dpp v212, v118 row_ror:15 row_mask:0xf bank_mask:0xf bound_ctrl:1
	v_mov_b32_dpp v213, v119 row_ror:15 row_mask:0xf bank_mask:0xf bound_ctrl:1
	v_mov_b32_dpp v196, v100 row_ror:15 row_mask:0xf bank_mask:0xf bound_ctrl:1
	v_mov_b32_dpp v197, v101 row_ror:15 row_mask:0xf bank_mask:0xf bound_ctrl:1
	v_mov_b32_dpp v208, v102 row_ror:15 row_mask:0xf bank_mask:0xf bound_ctrl:1
	v_mov_b32_dpp v209, v103 row_ror:15 row_mask:0xf bank_mask:0xf bound_ctrl:1
	v_mov_b32_dpp v214, v64 row_ror:1 row_mask:0xf bank_mask:0xf bound_ctrl:1
	v_mov_b32_dpp v215, v65 row_ror:1 row_mask:0xf bank_mask:0xf bound_ctrl:1
	v_mov_b32_dpp v216, v66 row_ror:1 row_mask:0xf bank_mask:0xf bound_ctrl:1
	v_mov_b32_dpp v217, v67 row_ror:1 row_mask:0xf bank_mask:0xf bound_ctrl:1
	v_mov_b32_dpp v202, v108 row_ror:15 row_mask:0xf bank_mask:0xf bound_ctrl:1
	v_mov_b32_dpp v203, v109 row_ror:15 row_mask:0xf bank_mask:0xf bound_ctrl:1
	v_mov_b32_dpp v210, v110 row_ror:15 row_mask:0xf bank_mask:0xf bound_ctrl:1
	v_mov_b32_dpp v211, v111 row_ror:15 row_mask:0xf bank_mask:0xf bound_ctrl:1
	v_mov_b32_dpp v194, v92 row_ror:15 row_mask:0xf bank_mask:0xf bound_ctrl:1
	v_mov_b32_dpp v195, v93 row_ror:15 row_mask:0xf bank_mask:0xf bound_ctrl:1
	v_mov_b32_dpp v206, v94 row_ror:15 row_mask:0xf bank_mask:0xf bound_ctrl:1
	v_mov_b32_dpp v207, v95 row_ror:15 row_mask:0xf bank_mask:0xf bound_ctrl:1
	s_and_saveexec_b64 s[52:53], s[2:3]
	s_cbranch_execz .LBB0_144
	s_waitcnt vmcnt(0)
	v_pk_fma_f32 v[218:219], v[136:137], v[218:219], v[164:165]
	v_pk_fma_f32 v[216:217], v[130:131], v[216:217], v[158:159]
	v_pk_fma_f32 v[218:219], v[116:117], v[144:145], v[218:219]
	v_pk_fma_f32 v[214:215], v[128:129], v[214:215], v[156:157]
	v_pk_fma_f32 v[218:219], v[100:101], v[152:153], v[218:219]
	v_pk_fma_f32 v[216:217], v[110:111], v[134:135], v[216:217]
	v_pk_fma_f32 v[214:215], v[108:109], v[132:133], v[214:215]
	v_pk_fma_f32 v[218:219], v[84:85], v[160:161], v[218:219]
	v_pk_fma_f32 v[216:217], v[94:95], v[142:143], v[216:217]
	v_pk_fma_f32 v[214:215], v[92:93], v[140:141], v[214:215]
	v_pk_fma_f32 v[220:221], v[138:139], v[220:221], v[166:167]
	v_pk_fma_f32 v[222:223], v[78:79], v[150:151], v[216:217]
	v_pk_fma_f32 v[216:217], v[76:77], v[148:149], v[214:215]
	v_cvt_pk_bf16_f32 v214, v218, v219
	v_lshlrev_b64 v[218:219], 13, v[186:187]
	v_pk_fma_f32 v[220:221], v[118:119], v[146:147], v[220:221]
	v_lshl_add_u64 v[218:219], s[24:25], 0, v[218:219]
	v_pk_fma_f32 v[220:221], v[102:103], v[154:155], v[220:221]
	v_lshl_add_u64 v[218:219], v[188:189], 1, v[218:219]
	v_pk_fma_f32 v[220:221], v[86:87], v[162:163], v[220:221]
	s_nop 0
	v_cvt_pk_bf16_f32 v215, v220, v221
	v_cvt_pk_bf16_f32 v216, v216, v217
	v_cvt_pk_bf16_f32 v217, v222, v223
	global_store_dwordx4 v[218:219], v[214:217], off offset:256
.LBB0_144:
	s_or_b64 exec, exec, s[52:53]
	s_waitcnt vmcnt(0)
	v_pk_fma_f32 v[214:215], v[118:119], v[138:139], v[166:167]
	v_pk_fma_f32 v[216:217], v[116:117], v[136:137], v[164:165]
	v_pk_fma_f32 v[214:215], v[102:103], v[146:147], v[214:215]
	v_pk_fma_f32 v[216:217], v[100:101], v[144:145], v[216:217]
	v_pk_fma_f32 v[214:215], v[86:87], v[154:155], v[214:215]
	v_pk_fma_f32 v[216:217], v[84:85], v[152:153], v[216:217]
	v_pk_fma_f32 v[218:219], v[70:71], v[162:163], v[214:215]
	v_pk_fma_f32 v[214:215], v[68:69], v[160:161], v[216:217]
	v_pk_fma_f32 v[216:217], v[110:111], v[130:131], v[158:159]
	v_pk_fma_f32 v[220:221], v[108:109], v[128:129], v[156:157]
	v_pk_fma_f32 v[216:217], v[94:95], v[134:135], v[216:217]
	v_pk_fma_f32 v[220:221], v[92:93], v[132:133], v[220:221]
	v_pk_fma_f32 v[216:217], v[78:79], v[142:143], v[216:217]
	v_pk_fma_f32 v[220:221], v[76:77], v[140:141], v[220:221]
	v_pk_fma_f32 v[222:223], v[66:67], v[150:151], v[216:217]
	v_pk_fma_f32 v[216:217], v[64:65], v[148:149], v[220:221]
	v_cvt_pk_bf16_f32 v214, v214, v215
	v_cvt_pk_bf16_f32 v215, v218, v219
	s_nop 0
	v_cvt_pk_bf16_f32 v216, v216, v217
	v_cvt_pk_bf16_f32 v217, v222, v223
	global_store_dwordx4 v[198:199], v[214:217], off offset:256
	s_and_saveexec_b64 s[52:53], s[6:7]
	s_cbranch_execnz .LBB0_168
	s_or_b64 exec, exec, s[52:53]
	s_and_saveexec_b64 s[52:53], s[0:1]
	s_cbranch_execnz .LBB0_169

.LBB0_148:
	s_or_b64 exec, exec, s[52:53]
	v_mov_b32_dpp v214, v4 row_ror:1 row_mask:0xf bank_mask:0xf bound_ctrl:1
	v_mov_b32_dpp v215, v5 row_ror:1 row_mask:0xf bank_mask:0xf bound_ctrl:1
	v_mov_b32_dpp v216, v6 row_ror:1 row_mask:0xf bank_mask:0xf bound_ctrl:1
	v_mov_b32_dpp v217, v7 row_ror:1 row_mask:0xf bank_mask:0xf bound_ctrl:1
	v_mov_b32_dpp v198, v52 row_ror:15 row_mask:0xf bank_mask:0xf bound_ctrl:1
	v_mov_b32_dpp v199, v53 row_ror:15 row_mask:0xf bank_mask:0xf bound_ctrl:1
	v_mov_b32_dpp v208, v54 row_ror:15 row_mask:0xf bank_mask:0xf bound_ctrl:1
	v_mov_b32_dpp v209, v55 row_ror:15 row_mask:0xf bank_mask:0xf bound_ctrl:1
	v_mov_b32_dpp v194, v36 row_ror:15 row_mask:0xf bank_mask:0xf bound_ctrl:1
	v_mov_b32_dpp v195, v37 row_ror:15 row_mask:0xf bank_mask:0xf bound_ctrl:1
	v_mov_b32_dpp v204, v38 row_ror:15 row_mask:0xf bank_mask:0xf bound_ctrl:1
	v_mov_b32_dpp v205, v39 row_ror:15 row_mask:0xf bank_mask:0xf bound_ctrl:1
	v_mov_b32_dpp v210, v0 row_ror:1 row_mask:0xf bank_mask:0xf bound_ctrl:1
	v_mov_b32_dpp v211, v1 row_ror:1 row_mask:0xf bank_mask:0xf bound_ctrl:1
	v_mov_b32_dpp v212, v2 row_ror:1 row_mask:0xf bank_mask:0xf bound_ctrl:1
	v_mov_b32_dpp v213, v3 row_ror:1 row_mask:0xf bank_mask:0xf bound_ctrl:1
	v_mov_b32_dpp v196, v48 row_ror:15 row_mask:0xf bank_mask:0xf bound_ctrl:1
	v_mov_b32_dpp v197, v49 row_ror:15 row_mask:0xf bank_mask:0xf bound_ctrl:1
	v_mov_b32_dpp v206, v50 row_ror:15 row_mask:0xf bank_mask:0xf bound_ctrl:1
	v_mov_b32_dpp v207, v51 row_ror:15 row_mask:0xf bank_mask:0xf bound_ctrl:1
	v_mov_b32_dpp v190, v32 row_ror:15 row_mask:0xf bank_mask:0xf bound_ctrl:1
	v_mov_b32_dpp v191, v33 row_ror:15 row_mask:0xf bank_mask:0xf bound_ctrl:1
	v_mov_b32_dpp v202, v34 row_ror:15 row_mask:0xf bank_mask:0xf bound_ctrl:1
	v_mov_b32_dpp v203, v35 row_ror:15 row_mask:0xf bank_mask:0xf bound_ctrl:1
	s_and_saveexec_b64 s[52:53], s[2:3]
	s_cbranch_execz .LBB0_150
	v_pk_fma_f32 v[212:213], v[130:131], v[212:213], v[158:159]
	v_pk_fma_f32 v[210:211], v[128:129], v[210:211], v[156:157]
	v_pk_fma_f32 v[216:217], v[138:139], v[216:217], v[166:167]
	v_pk_fma_f32 v[214:215], v[136:137], v[214:215], v[164:165]
	v_pk_fma_f32 v[212:213], v[50:51], v[134:135], v[212:213]
	v_pk_fma_f32 v[210:211], v[48:49], v[132:133], v[210:211]
	v_lshlrev_b64 v[192:193], 13, v[192:193]
	v_pk_fma_f32 v[216:217], v[54:55], v[146:147], v[216:217]
	v_pk_fma_f32 v[214:215], v[52:53], v[144:145], v[214:215]
	v_pk_fma_f32 v[212:213], v[34:35], v[142:143], v[212:213]
	v_pk_fma_f32 v[210:211], v[32:33], v[140:141], v[210:211]
	v_lshl_add_u64 v[192:193], s[24:25], 0, v[192:193]
	v_pk_fma_f32 v[216:217], v[38:39], v[154:155], v[216:217]
	v_pk_fma_f32 v[214:215], v[36:37], v[152:153], v[214:215]
	v_pk_fma_f32 v[218:219], v[18:19], v[150:151], v[212:213]
	v_pk_fma_f32 v[212:213], v[16:17], v[148:149], v[210:211]
	v_lshl_add_u64 v[192:193], v[188:189], 1, v[192:193]
	v_pk_fma_f32 v[216:217], v[22:23], v[162:163], v[216:217]
	v_pk_fma_f32 v[214:215], v[20:21], v[160:161], v[214:215]
	s_nop 0
	v_cvt_pk_bf16_f32 v210, v214, v215
	v_cvt_pk_bf16_f32 v211, v216, v217
	v_cvt_pk_bf16_f32 v212, v212, v213
	v_cvt_pk_bf16_f32 v213, v218, v219
	global_store_dwordx4 v[192:193], v[210:213], off offset:256
.LBB0_150:
	s_or_b64 exec, exec, s[52:53]
	s_mov_b64 s[34:35], 0x102000
	v_pk_fma_f32 v[210:211], v[52:53], v[136:137], v[164:165]
	v_pk_fma_f32 v[212:213], v[50:51], v[130:131], v[158:159]
	v_pk_fma_f32 v[214:215], v[48:49], v[128:129], v[156:157]
	v_lshl_add_u64 v[192:193], v[200:201], 0, s[34:35]
	v_pk_fma_f32 v[200:201], v[54:55], v[138:139], v[166:167]
	v_pk_fma_f32 v[210:211], v[36:37], v[144:145], v[210:211]
	v_pk_fma_f32 v[212:213], v[34:35], v[134:135], v[212:213]
	v_pk_fma_f32 v[214:215], v[32:33], v[132:133], v[214:215]
	v_pk_fma_f32 v[200:201], v[38:39], v[146:147], v[200:201]
	v_pk_fma_f32 v[210:211], v[20:21], v[152:153], v[210:211]
	v_pk_fma_f32 v[212:213], v[18:19], v[142:143], v[212:213]
	v_pk_fma_f32 v[214:215], v[16:17], v[140:141], v[214:215]
	v_pk_fma_f32 v[200:201], v[22:23], v[154:155], v[200:201]
	v_pk_fma_f32 v[210:211], v[4:5], v[160:161], v[210:211]
	v_pk_fma_f32 v[216:217], v[2:3], v[150:151], v[212:213]
	v_pk_fma_f32 v[212:213], v[0:1], v[148:149], v[214:215]
	v_pk_fma_f32 v[200:201], v[6:7], v[162:163], v[200:201]
	v_cvt_pk_bf16_f32 v210, v210, v211
	s_nop 0
	v_cvt_pk_bf16_f32 v211, v200, v201
	v_cvt_pk_bf16_f32 v212, v212, v213
	v_cvt_pk_bf16_f32 v213, v216, v217
	global_store_dwordx4 v[192:193], v[210:213], off offset:256
	s_and_saveexec_b64 s[52:53], s[6:7]
	s_cbranch_execz .LBB0_152
	v_pk_fma_f32 v[192:193], v[38:39], v[138:139], v[166:167]
	v_pk_fma_f32 v[200:201], v[36:37], v[136:137], v[164:165]
	v_pk_fma_f32 v[192:193], v[22:23], v[146:147], v[192:193]
	v_pk_fma_f32 v[210:211], v[34:35], v[130:131], v[158:159]
	v_pk_fma_f32 v[200:201], v[20:21], v[144:145], v[200:201]
	v_pk_fma_f32 v[192:193], v[6:7], v[154:155], v[192:193]
	v_pk_fma_f32 v[210:211], v[18:19], v[134:135], v[210:211]
	v_pk_fma_f32 v[200:201], v[4:5], v[152:153], v[200:201]
	v_pk_fma_f32 v[192:193], v[162:163], v[208:209], v[192:193]
	v_pk_fma_f32 v[210:211], v[2:3], v[142:143], v[210:211]
	v_pk_fma_f32 v[200:201], v[160:161], v[198:199], v[200:201]
	v_pk_fma_f32 v[214:215], v[150:151], v[206:207], v[210:211]
	v_cvt_pk_bf16_f32 v210, v200, v201
	v_cvt_pk_bf16_f32 v211, v192, v193
	v_lshlrev_b64 v[192:193], 13, v[186:187]
	v_pk_fma_f32 v[212:213], v[32:33], v[128:129], v[156:157]
	v_lshl_add_u64 v[192:193], s[24:25], 0, v[192:193]
	v_pk_fma_f32 v[130:131], v[18:19], v[130:131], v[158:159]
	v_pk_fma_f32 v[128:129], v[16:17], v[128:129], v[156:157]
	v_pk_fma_f32 v[212:213], v[16:17], v[132:133], v[212:213]
	v_lshl_add_u64 v[188:189], v[188:189], 1, v[192:193]
	s_mov_b32 s34, 0x104000
	v_pk_fma_f32 v[138:139], v[22:23], v[138:139], v[166:167]
	v_pk_fma_f32 v[136:137], v[20:21], v[136:137], v[164:165]
	v_pk_fma_f32 v[130:131], v[2:3], v[134:135], v[130:131]
	v_pk_fma_f32 v[128:129], v[0:1], v[132:133], v[128:129]
	v_pk_fma_f32 v[212:213], v[0:1], v[140:141], v[212:213]
	v_add_co_u32_e32 v192, vcc, s34, v188
	v_pk_fma_f32 v[138:139], v[6:7], v[146:147], v[138:139]
	v_pk_fma_f32 v[136:137], v[4:5], v[144:145], v[136:137]
	v_pk_fma_f32 v[130:131], v[142:143], v[206:207], v[130:131]
	v_pk_fma_f32 v[128:129], v[140:141], v[196:197], v[128:129]
	v_pk_fma_f32 v[212:213], v[148:149], v[196:197], v[212:213]
	v_addc_co_u32_e32 v193, vcc, 0, v189, vcc
	v_pk_fma_f32 v[138:139], v[154:155], v[208:209], v[138:139]
	v_pk_fma_f32 v[136:137], v[152:153], v[198:199], v[136:137]
	v_pk_fma_f32 v[132:133], v[150:151], v[202:203], v[130:131]
	v_pk_fma_f32 v[130:131], v[148:149], v[190:191], v[128:129]
	v_cvt_pk_bf16_f32 v212, v212, v213
	v_cvt_pk_bf16_f32 v213, v214, v215
	global_store_dwordx4 v[192:193], v[210:213], off offset:256
	v_pk_fma_f32 v[138:139], v[162:163], v[204:205], v[138:139]
	v_pk_fma_f32 v[136:137], v[160:161], v[194:195], v[136:137]
	s_nop 0
	v_cvt_pk_bf16_f32 v128, v136, v137
	v_cvt_pk_bf16_f32 v129, v138, v139
	v_cvt_pk_bf16_f32 v130, v130, v131
	v_cvt_pk_bf16_f32 v131, v132, v133
	v_add_co_u32_e32 v132, vcc, 0x106000, v188
	s_nop 1
	v_addc_co_u32_e32 v133, vcc, 0, v189, vcc
	global_store_dwordx4 v[132:133], v[128:131], off offset:256

.LBB0_165:
	v_add_u32_e32 v128, s34, v226
	v_ashrrev_i32_e32 v130, 31, v186
	v_ashrrev_i32_e32 v129, 31, v128
	v_mul_lo_u32 v132, s89, v186
	v_mul_lo_u32 v134, s88, v130
	v_mad_u64_u32 v[130:131], s[34:35], s88, v186, 0
	v_lshl_add_u64 v[128:129], v[128:129], 1, s[52:53]
	v_add3_u32 v131, v131, v134, v132
	v_lshl_add_u64 v[130:131], v[130:131], 1, v[128:129]
	v_pk_mul_f32 v[126:127], v[126:127], s[94:95] op_sel_hi:[1,0]
	v_pk_mul_f32 v[124:125], v[124:125], s[94:95] op_sel_hi:[1,0]
	v_pk_mul_f32 v[132:133], v[122:123], s[94:95] op_sel_hi:[1,0]
	v_pk_mul_f32 v[122:123], v[120:121], s[94:95] op_sel_hi:[1,0]
	v_cvt_pk_bf16_f32 v120, v124, v125
	v_cvt_pk_bf16_f32 v121, v126, v127
	v_pk_mul_f32 v[116:117], v[116:117], s[94:95] op_sel_hi:[1,0]
	v_cvt_pk_bf16_f32 v122, v122, v123
	v_cvt_pk_bf16_f32 v123, v132, v133
	global_store_dwordx4 v[130:131], v[120:123], off
	v_pk_mul_f32 v[118:119], v[118:119], s[94:95] op_sel_hi:[1,0]
	v_pk_mul_f32 v[112:113], v[112:113], s[94:95] op_sel_hi:[1,0]
	v_pk_mul_f32 v[120:121], v[110:111], s[94:95] op_sel_hi:[1,0]
	v_pk_mul_f32 v[110:111], v[108:109], s[94:95] op_sel_hi:[1,0]
	v_cvt_pk_bf16_f32 v108, v116, v117
	v_cvt_pk_bf16_f32 v109, v118, v119
	v_pk_mul_f32 v[100:101], v[100:101], s[94:95] op_sel_hi:[1,0]
	v_cvt_pk_bf16_f32 v110, v110, v111
	v_cvt_pk_bf16_f32 v111, v120, v121
	global_store_dwordx4 v[130:131], v[108:111], off offset:256
	v_pk_mul_f32 v[102:103], v[102:103], s[94:95] op_sel_hi:[1,0]
	v_pk_mul_f32 v[96:97], v[96:97], s[94:95] op_sel_hi:[1,0]
	v_or_b32_e32 v108, 1, v186
	v_mul_lo_u32 v110, s89, v108
	v_mad_u64_u32 v[108:109], s[34:35], s88, v108, 0
	v_add3_u32 v109, v109, v134, v110
	v_lshl_add_u64 v[108:109], v[108:109], 1, v[128:129]
	v_pk_mul_f32 v[110:111], v[114:115], s[94:95] op_sel_hi:[1,0]
	v_pk_mul_f32 v[114:115], v[106:107], s[94:95] op_sel_hi:[1,0]
	v_pk_mul_f32 v[106:107], v[104:105], s[94:95] op_sel_hi:[1,0]
	v_cvt_pk_bf16_f32 v104, v112, v113
	v_cvt_pk_bf16_f32 v105, v110, v111
	v_pk_mul_f32 v[84:85], v[84:85], s[94:95] op_sel_hi:[1,0]
	v_cvt_pk_bf16_f32 v106, v106, v107
	v_cvt_pk_bf16_f32 v107, v114, v115
	global_store_dwordx4 v[108:109], v[104:107], off
	v_pk_mul_f32 v[86:87], v[86:87], s[94:95] op_sel_hi:[1,0]
	v_pk_mul_f32 v[80:81], v[80:81], s[94:95] op_sel_hi:[1,0]
	v_pk_mul_f32 v[104:105], v[94:95], s[94:95] op_sel_hi:[1,0]
	v_pk_mul_f32 v[94:95], v[92:93], s[94:95] op_sel_hi:[1,0]
	v_cvt_pk_bf16_f32 v92, v100, v101
	v_cvt_pk_bf16_f32 v93, v102, v103
	v_pk_mul_f32 v[68:69], v[68:69], s[94:95] op_sel_hi:[1,0]
	v_cvt_pk_bf16_f32 v94, v94, v95
	v_cvt_pk_bf16_f32 v95, v104, v105
	global_store_dwordx4 v[108:109], v[92:95], off offset:256
	v_pk_mul_f32 v[70:71], v[70:71], s[94:95] op_sel_hi:[1,0]
	v_pk_mul_f32 v[62:63], v[62:63], s[94:95] op_sel_hi:[1,0]
	v_or_b32_e32 v92, 2, v186
	v_mul_lo_u32 v94, s89, v92
	v_mad_u64_u32 v[92:93], s[34:35], s88, v92, 0
	v_add3_u32 v93, v93, v134, v94
	v_lshl_add_u64 v[92:93], v[92:93], 1, v[128:129]
	v_pk_mul_f32 v[94:95], v[98:99], s[94:95] op_sel_hi:[1,0]
	v_pk_mul_f32 v[98:99], v[90:91], s[94:95] op_sel_hi:[1,0]
	v_pk_mul_f32 v[90:91], v[88:89], s[94:95] op_sel_hi:[1,0]
	v_cvt_pk_bf16_f32 v88, v96, v97
	v_cvt_pk_bf16_f32 v89, v94, v95
	v_pk_mul_f32 v[60:61], v[60:61], s[94:95] op_sel_hi:[1,0]
	v_cvt_pk_bf16_f32 v90, v90, v91
	v_cvt_pk_bf16_f32 v91, v98, v99
	global_store_dwordx4 v[92:93], v[88:91], off
	v_pk_mul_f32 v[52:53], v[52:53], s[94:95] op_sel_hi:[1,0]
	v_pk_mul_f32 v[54:55], v[54:55], s[94:95] op_sel_hi:[1,0]
	v_pk_mul_f32 v[88:89], v[78:79], s[94:95] op_sel_hi:[1,0]
	v_pk_mul_f32 v[78:79], v[76:77], s[94:95] op_sel_hi:[1,0]
	v_cvt_pk_bf16_f32 v76, v84, v85
	v_cvt_pk_bf16_f32 v77, v86, v87
	v_pk_mul_f32 v[46:47], v[46:47], s[94:95] op_sel_hi:[1,0]
	v_cvt_pk_bf16_f32 v78, v78, v79
	v_cvt_pk_bf16_f32 v79, v88, v89
	global_store_dwordx4 v[92:93], v[76:79], off offset:256
	v_pk_mul_f32 v[44:45], v[44:45], s[94:95] op_sel_hi:[1,0]
	v_pk_mul_f32 v[36:37], v[36:37], s[94:95] op_sel_hi:[1,0]
	v_or_b32_e32 v76, 3, v186
	v_mul_lo_u32 v78, s89, v76
	v_mad_u64_u32 v[76:77], s[34:35], s88, v76, 0
	v_add3_u32 v77, v77, v134, v78
	v_lshl_add_u64 v[76:77], v[76:77], 1, v[128:129]
	v_pk_mul_f32 v[78:79], v[82:83], s[94:95] op_sel_hi:[1,0]
	v_pk_mul_f32 v[82:83], v[74:75], s[94:95] op_sel_hi:[1,0]
	v_pk_mul_f32 v[74:75], v[72:73], s[94:95] op_sel_hi:[1,0]
	v_cvt_pk_bf16_f32 v72, v80, v81
	v_cvt_pk_bf16_f32 v73, v78, v79
	v_pk_mul_f32 v[38:39], v[38:39], s[94:95] op_sel_hi:[1,0]
	v_cvt_pk_bf16_f32 v74, v74, v75
	v_cvt_pk_bf16_f32 v75, v82, v83
	global_store_dwordx4 v[76:77], v[72:75], off
	v_pk_mul_f32 v[30:31], v[30:31], s[94:95] op_sel_hi:[1,0]
	v_pk_mul_f32 v[28:29], v[28:29], s[94:95] op_sel_hi:[1,0]
	v_pk_mul_f32 v[72:73], v[66:67], s[94:95] op_sel_hi:[1,0]
	v_pk_mul_f32 v[66:67], v[64:65], s[94:95] op_sel_hi:[1,0]
	v_cvt_pk_bf16_f32 v64, v68, v69
	v_cvt_pk_bf16_f32 v65, v70, v71
	v_pk_mul_f32 v[20:21], v[20:21], s[94:95] op_sel_hi:[1,0]
	v_cvt_pk_bf16_f32 v66, v66, v67
	v_cvt_pk_bf16_f32 v67, v72, v73
	global_store_dwordx4 v[76:77], v[64:67], off offset:256
	v_pk_mul_f32 v[22:23], v[22:23], s[94:95] op_sel_hi:[1,0]
	v_pk_mul_f32 v[14:15], v[14:15], s[94:95] op_sel_hi:[1,0]
	v_add_u32_e32 v64, 0x80, v186
	v_ashrrev_i32_e32 v65, 31, v64
	v_mul_lo_u32 v66, s88, v65
	v_mul_lo_u32 v67, s89, v64
	v_mad_u64_u32 v[64:65], s[34:35], s88, v64, 0
	v_add3_u32 v65, v65, v66, v67
	v_lshl_add_u64 v[64:65], v[64:65], 1, v[128:129]
	v_pk_mul_f32 v[66:67], v[58:59], s[94:95] op_sel_hi:[1,0]
	v_pk_mul_f32 v[58:59], v[56:57], s[94:95] op_sel_hi:[1,0]
	v_cvt_pk_bf16_f32 v56, v60, v61
	v_cvt_pk_bf16_f32 v57, v62, v63
	v_pk_mul_f32 v[12:13], v[12:13], s[94:95] op_sel_hi:[1,0]
	v_cvt_pk_bf16_f32 v58, v58, v59
	v_cvt_pk_bf16_f32 v59, v66, v67
	global_store_dwordx4 v[64:65], v[56:59], off
	v_pk_mul_f32 v[6:7], v[6:7], s[94:95] op_sel_hi:[1,0]
	v_pk_mul_f32 v[4:5], v[4:5], s[94:95] op_sel_hi:[1,0]
	v_pk_mul_f32 v[56:57], v[50:51], s[94:95] op_sel_hi:[1,0]
	v_pk_mul_f32 v[50:51], v[48:49], s[94:95] op_sel_hi:[1,0]
	v_cvt_pk_bf16_f32 v48, v52, v53
	v_cvt_pk_bf16_f32 v49, v54, v55
	s_nop 0
	v_cvt_pk_bf16_f32 v50, v50, v51
	v_cvt_pk_bf16_f32 v51, v56, v57
	global_store_dwordx4 v[64:65], v[48:51], off offset:256
	s_nop 1
	v_add_u32_e32 v48, 0x81, v186
	v_ashrrev_i32_e32 v49, 31, v48
	v_mul_lo_u32 v50, s88, v49
	v_mul_lo_u32 v51, s89, v48
	v_mad_u64_u32 v[48:49], s[34:35], s88, v48, 0
	v_add3_u32 v49, v49, v50, v51
	v_lshl_add_u64 v[48:49], v[48:49], 1, v[128:129]
	v_pk_mul_f32 v[50:51], v[42:43], s[94:95] op_sel_hi:[1,0]
	v_pk_mul_f32 v[42:43], v[40:41], s[94:95] op_sel_hi:[1,0]
	v_cvt_pk_bf16_f32 v40, v44, v45
	v_cvt_pk_bf16_f32 v41, v46, v47
	s_nop 0
	v_cvt_pk_bf16_f32 v42, v42, v43
	v_cvt_pk_bf16_f32 v43, v50, v51
	global_store_dwordx4 v[48:49], v[40:43], off
	s_nop 1
	v_pk_mul_f32 v[40:41], v[34:35], s[94:95] op_sel_hi:[1,0]
	v_pk_mul_f32 v[34:35], v[32:33], s[94:95] op_sel_hi:[1,0]
	v_cvt_pk_bf16_f32 v32, v36, v37
	v_cvt_pk_bf16_f32 v33, v38, v39
	s_nop 0
	v_cvt_pk_bf16_f32 v34, v34, v35
	v_cvt_pk_bf16_f32 v35, v40, v41
	global_store_dwordx4 v[48:49], v[32:35], off offset:256
	s_nop 1
	v_add_u32_e32 v32, 0x82, v186
	v_ashrrev_i32_e32 v33, 31, v32
	v_mul_lo_u32 v34, s88, v33
	v_mul_lo_u32 v35, s89, v32
	v_mad_u64_u32 v[32:33], s[34:35], s88, v32, 0
	v_add3_u32 v33, v33, v34, v35
	v_lshl_add_u64 v[32:33], v[32:33], 1, v[128:129]
	v_pk_mul_f32 v[34:35], v[26:27], s[94:95] op_sel_hi:[1,0]
	v_pk_mul_f32 v[26:27], v[24:25], s[94:95] op_sel_hi:[1,0]
	v_cvt_pk_bf16_f32 v24, v28, v29
	v_cvt_pk_bf16_f32 v25, v30, v31
	s_nop 0
	v_cvt_pk_bf16_f32 v26, v26, v27
	v_cvt_pk_bf16_f32 v27, v34, v35
	global_store_dwordx4 v[32:33], v[24:27], off
	s_nop 1
	v_pk_mul_f32 v[24:25], v[18:19], s[94:95] op_sel_hi:[1,0]
	v_pk_mul_f32 v[18:19], v[16:17], s[94:95] op_sel_hi:[1,0]
	v_cvt_pk_bf16_f32 v16, v20, v21
	v_cvt_pk_bf16_f32 v17, v22, v23
	s_nop 0
	v_cvt_pk_bf16_f32 v18, v18, v19
	v_cvt_pk_bf16_f32 v19, v24, v25
	global_store_dwordx4 v[32:33], v[16:19], off offset:256
	s_nop 1
	v_add_u32_e32 v16, 0x83, v186
	v_ashrrev_i32_e32 v17, 31, v16
	v_mul_lo_u32 v18, s88, v17
	v_mul_lo_u32 v19, s89, v16
	v_mad_u64_u32 v[16:17], s[34:35], s88, v16, 0
	v_add3_u32 v17, v17, v18, v19
	v_lshl_add_u64 v[16:17], v[16:17], 1, v[128:129]
	v_pk_mul_f32 v[18:19], v[10:11], s[94:95] op_sel_hi:[1,0]
	v_pk_mul_f32 v[10:11], v[8:9], s[94:95] op_sel_hi:[1,0]
	v_cvt_pk_bf16_f32 v8, v12, v13
	v_cvt_pk_bf16_f32 v9, v14, v15
	s_nop 0
	v_cvt_pk_bf16_f32 v10, v10, v11
	v_cvt_pk_bf16_f32 v11, v18, v19
	global_store_dwordx4 v[16:17], v[8:11], off
	s_nop 1
	v_pk_mul_f32 v[8:9], v[2:3], s[94:95] op_sel_hi:[1,0]
	v_pk_mul_f32 v[2:3], v[0:1], s[94:95] op_sel_hi:[1,0]
	v_cvt_pk_bf16_f32 v0, v4, v5
	v_cvt_pk_bf16_f32 v1, v6, v7
	s_nop 0
	v_cvt_pk_bf16_f32 v2, v2, v3
	v_cvt_pk_bf16_f32 v3, v8, v9
	global_store_dwordx4 v[16:17], v[0:3], off offset:256
	s_andn2_b64 vcc, exec, s[8:9]
	s_mov_b64 s[8:9], -1
	s_cbranch_vccnz .LBB0_112

.LBB0_168:
	v_pk_fma_f32 v[198:199], v[102:103], v[138:139], v[166:167]
	v_pk_fma_f32 v[214:215], v[100:101], v[136:137], v[164:165]
	v_pk_fma_f32 v[198:199], v[86:87], v[146:147], v[198:199]
	v_pk_fma_f32 v[214:215], v[84:85], v[144:145], v[214:215]
	v_pk_fma_f32 v[198:199], v[70:71], v[154:155], v[198:199]
	v_pk_fma_f32 v[214:215], v[68:69], v[152:153], v[214:215]
	v_pk_fma_f32 v[198:199], v[162:163], v[212:213], v[198:199]
	v_pk_fma_f32 v[214:215], v[160:161], v[204:205], v[214:215]
	v_pk_fma_f32 v[216:217], v[94:95], v[130:131], v[158:159]
	v_cvt_pk_bf16_f32 v214, v214, v215
	v_cvt_pk_bf16_f32 v215, v198, v199
	v_or_b32_e32 v198, 2, v186
	v_pk_fma_f32 v[218:219], v[92:93], v[128:129], v[156:157]
	v_ashrrev_i32_e32 v199, 31, v198
	v_pk_fma_f32 v[216:217], v[78:79], v[134:135], v[216:217]
	v_pk_fma_f32 v[218:219], v[76:77], v[132:133], v[218:219]
	v_lshlrev_b64 v[198:199], 13, v[198:199]
	v_pk_fma_f32 v[216:217], v[66:67], v[142:143], v[216:217]
	v_pk_fma_f32 v[218:219], v[64:65], v[140:141], v[218:219]
	v_lshl_add_u64 v[198:199], s[24:25], 0, v[198:199]
	v_pk_fma_f32 v[220:221], v[150:151], v[210:211], v[216:217]
	v_pk_fma_f32 v[216:217], v[148:149], v[202:203], v[218:219]
	v_lshl_add_u64 v[198:199], v[198:199], 0, v[190:191]
	v_cvt_pk_bf16_f32 v216, v216, v217
	v_cvt_pk_bf16_f32 v217, v220, v221
	global_store_dwordx4 v[198:199], v[214:217], off offset:256
	v_pk_fma_f32 v[198:199], v[86:87], v[138:139], v[166:167]
	s_nop 0
	v_pk_fma_f32 v[198:199], v[70:71], v[146:147], v[198:199]
	v_pk_fma_f32 v[214:215], v[84:85], v[136:137], v[164:165]
	v_pk_fma_f32 v[198:199], v[154:155], v[212:213], v[198:199]
	v_pk_fma_f32 v[214:215], v[68:69], v[144:145], v[214:215]
	v_pk_fma_f32 v[198:199], v[162:163], v[208:209], v[198:199]
	v_pk_fma_f32 v[208:209], v[76:77], v[128:129], v[156:157]
	v_pk_fma_f32 v[204:205], v[152:153], v[204:205], v[214:215]
	v_pk_fma_f32 v[208:209], v[64:65], v[132:133], v[208:209]
	v_pk_fma_f32 v[196:197], v[160:161], v[196:197], v[204:205]
	v_pk_fma_f32 v[202:203], v[140:141], v[202:203], v[208:209]
	v_pk_fma_f32 v[204:205], v[78:79], v[130:131], v[158:159]
	v_pk_fma_f32 v[202:203], v[148:149], v[194:195], v[202:203]
	v_cvt_pk_bf16_f32 v194, v196, v197
	v_cvt_pk_bf16_f32 v195, v198, v199
	v_or_b32_e32 v198, 3, v186
	v_ashrrev_i32_e32 v199, 31, v198
	v_lshlrev_b64 v[198:199], 13, v[198:199]
	v_pk_fma_f32 v[204:205], v[66:67], v[134:135], v[204:205]
	v_lshl_add_u64 v[198:199], s[24:25], 0, v[198:199]
	v_pk_fma_f32 v[204:205], v[142:143], v[210:211], v[204:205]
	v_lshl_add_u64 v[190:191], v[198:199], 0, v[190:191]
	v_pk_fma_f32 v[204:205], v[150:151], v[206:207], v[204:205]
	v_cvt_pk_bf16_f32 v196, v202, v203
	s_nop 0
	v_cvt_pk_bf16_f32 v197, v204, v205
	global_store_dwordx4 v[190:191], v[194:197], off offset:256
	s_or_b64 exec, exec, s[52:53]
	s_and_saveexec_b64 s[52:53], s[0:1]
	s_cbranch_execz .LBB0_146

.LBB0_258:
	s_or_b32 s56, s14, s93
	s_lshl_b32 s44, s56, 8
	s_or_b32 s14, s56, 1
	v_lshl_add_u64 v[4:5], v[180:181], 0, s[44:45]
	s_lshl_b32 s52, s14, 8
	s_mov_b32 s53, s45
	global_load_dwordx4 v[0:3], v[4:5], off
	global_load_dwordx4 v[48:51], v[4:5], off offset:64
	global_load_dwordx4 v[144:147], v[4:5], off offset:128
	global_load_dwordx4 v[148:151], v[4:5], off offset:192
	v_lshl_add_u64 v[4:5], v[180:181], 0, s[52:53]
	global_load_dwordx4 v[152:155], v[4:5], off
	global_load_dwordx4 v[156:159], v[4:5], off offset:64
	global_load_dwordx4 v[160:163], v[4:5], off offset:128
	global_load_dwordx4 v[164:167], v[4:5], off offset:192
	v_med3_i32 v4, s92, 0, v209
	v_lshlrev_b32_e32 v168, 10, v4
	v_lshl_add_u64 v[16:17], v[184:185], 0, v[168:169]
	global_load_dwordx4 v[4:7], v[16:17], off
	global_load_dwordx4 v[8:11], v[16:17], off offset:64
	global_load_dwordx4 v[12:15], v[16:17], off offset:128
	s_nop 0
	global_load_dwordx4 v[16:19], v[16:17], off offset:192
	s_nop 0
	global_load_dwordx4 v[20:23], v[186:187], off
	global_load_dwordx4 v[24:27], v[186:187], off offset:64
	global_load_dwordx4 v[28:31], v[186:187], off offset:128
	global_load_dwordx4 v[32:35], v[186:187], off offset:192
	s_waitcnt vmcnt(7)
	v_mfma_f32_16x16x32_bf16 v[36:39], v[4:7], v[0:3], 0
	s_add_i32 s34, s92, 48
	v_mfma_f32_16x16x32_bf16 v[4:7], v[4:7], v[152:155], 0
	s_waitcnt vmcnt(6)
	v_mfma_f32_16x16x32_bf16 v[36:39], v[8:11], v[48:51], v[36:39]
	v_mfma_f32_16x16x32_bf16 v[4:7], v[8:11], v[156:159], v[4:7]
	s_waitcnt vmcnt(5)
	v_mfma_f32_16x16x32_bf16 v[36:39], v[12:15], v[144:147], v[36:39]
	v_mfma_f32_16x16x32_bf16 v[4:7], v[12:15], v[160:163], v[4:7]
	s_waitcnt vmcnt(4)
	v_mfma_f32_16x16x32_bf16 v[140:143], v[16:19], v[148:151], v[36:39]
	v_mfma_f32_16x16x32_bf16 v[84:87], v[16:19], v[164:167], v[4:7]
	s_max_i32 s16, s92, 0xffffffe0
	s_add_i32 s16, s16, 32
	s_min_u32 s16, s16, 0x7ff0
	s_lshl_b32 s16, s16, 10
	s_mov_b32 s17, s45
	v_lshl_add_u64 v[16:17], v[184:185], 0, s[16:17]
	global_load_dwordx4 v[4:7], v[16:17], off
	global_load_dwordx4 v[8:11], v[16:17], off offset:64
	global_load_dwordx4 v[12:15], v[16:17], off offset:128
	s_nop 0
	global_load_dwordx4 v[16:19], v[16:17], off offset:192
	s_waitcnt vmcnt(7)
	v_mfma_f32_16x16x32_bf16 v[36:39], v[20:23], v[0:3], 0
	v_mfma_f32_16x16x32_bf16 v[20:23], v[20:23], v[152:155], 0
	s_waitcnt vmcnt(6)
	v_mfma_f32_16x16x32_bf16 v[36:39], v[24:27], v[48:51], v[36:39]
	v_mfma_f32_16x16x32_bf16 v[20:23], v[24:27], v[156:159], v[20:23]
	s_waitcnt vmcnt(5)
	v_mfma_f32_16x16x32_bf16 v[36:39], v[28:31], v[144:147], v[36:39]
	v_mfma_f32_16x16x32_bf16 v[20:23], v[28:31], v[160:163], v[20:23]
	s_waitcnt vmcnt(4)
	v_mfma_f32_16x16x32_bf16 v[136:139], v[32:35], v[148:151], v[36:39]
	v_mfma_f32_16x16x32_bf16 v[80:83], v[32:35], v[164:167], v[20:23]
	s_nop 4
	v_med3_i32 v20, s34, 0, v209
	v_lshlrev_b32_e32 v168, 10, v20
	v_lshl_add_u64 v[32:33], v[184:185], 0, v[168:169]
	global_load_dwordx4 v[20:23], v[32:33], off
	global_load_dwordx4 v[24:27], v[32:33], off offset:64
	global_load_dwordx4 v[28:31], v[32:33], off offset:128
	s_nop 0
	global_load_dwordx4 v[32:35], v[32:33], off offset:192
	s_waitcnt vmcnt(7)
	v_mfma_f32_16x16x32_bf16 v[36:39], v[4:7], v[0:3], 0
	v_mfma_f32_16x16x32_bf16 v[4:7], v[4:7], v[152:155], 0
	s_waitcnt vmcnt(6)
	v_mfma_f32_16x16x32_bf16 v[36:39], v[8:11], v[48:51], v[36:39]
	v_mfma_f32_16x16x32_bf16 v[4:7], v[8:11], v[156:159], v[4:7]
	s_waitcnt vmcnt(5)
	v_mfma_f32_16x16x32_bf16 v[36:39], v[12:15], v[144:147], v[36:39]
	v_mfma_f32_16x16x32_bf16 v[4:7], v[12:15], v[160:163], v[4:7]
	s_waitcnt vmcnt(4)
	v_mfma_f32_16x16x32_bf16 v[132:135], v[16:19], v[148:151], v[36:39]
	v_mfma_f32_16x16x32_bf16 v[72:75], v[16:19], v[164:167], v[4:7]
	s_max_i32 s16, s92, 0xffffffc0
	s_add_i32 s16, s16, 64
	s_min_u32 s16, s16, 0x7ff0
	s_lshl_b32 s16, s16, 10
	v_lshl_add_u64 v[16:17], v[184:185], 0, s[16:17]
	global_load_dwordx4 v[4:7], v[16:17], off
	global_load_dwordx4 v[8:11], v[16:17], off offset:64
	global_load_dwordx4 v[12:15], v[16:17], off offset:128
	s_nop 0
	global_load_dwordx4 v[16:19], v[16:17], off offset:192
	s_waitcnt vmcnt(7)
	v_mfma_f32_16x16x32_bf16 v[36:39], v[20:23], v[0:3], 0
	v_mfma_f32_16x16x32_bf16 v[20:23], v[20:23], v[152:155], 0
	s_waitcnt vmcnt(6)
	v_mfma_f32_16x16x32_bf16 v[36:39], v[24:27], v[48:51], v[36:39]
	v_mfma_f32_16x16x32_bf16 v[20:23], v[24:27], v[156:159], v[20:23]
	s_waitcnt vmcnt(5)
	v_mfma_f32_16x16x32_bf16 v[36:39], v[28:31], v[144:147], v[36:39]
	v_mfma_f32_16x16x32_bf16 v[20:23], v[28:31], v[160:163], v[20:23]
	s_waitcnt vmcnt(4)
	v_mfma_f32_16x16x32_bf16 v[128:131], v[32:35], v[148:151], v[36:39]
	v_mfma_f32_16x16x32_bf16 v[64:67], v[32:35], v[164:167], v[20:23]
	s_add_i32 s16, s92, 0x50
	s_nop 3
	v_med3_i32 v20, s16, 0, v209
	v_lshlrev_b32_e32 v168, 10, v20
	v_lshl_add_u64 v[32:33], v[184:185], 0, v[168:169]
	global_load_dwordx4 v[20:23], v[32:33], off
	global_load_dwordx4 v[24:27], v[32:33], off offset:64
	global_load_dwordx4 v[28:31], v[32:33], off offset:128
	s_nop 0
	global_load_dwordx4 v[32:35], v[32:33], off offset:192
	s_waitcnt vmcnt(7)
	v_mfma_f32_16x16x32_bf16 v[36:39], v[4:7], v[0:3], 0
	v_mfma_f32_16x16x32_bf16 v[4:7], v[4:7], v[152:155], 0
	s_waitcnt vmcnt(6)
	v_mfma_f32_16x16x32_bf16 v[36:39], v[8:11], v[48:51], v[36:39]
	v_mfma_f32_16x16x32_bf16 v[4:7], v[8:11], v[156:159], v[4:7]
	s_waitcnt vmcnt(5)
	v_mfma_f32_16x16x32_bf16 v[36:39], v[12:15], v[144:147], v[36:39]
	v_mfma_f32_16x16x32_bf16 v[4:7], v[12:15], v[160:163], v[4:7]
	s_waitcnt vmcnt(4)
	v_mfma_f32_16x16x32_bf16 v[124:127], v[16:19], v[148:151], v[36:39]
	v_mfma_f32_16x16x32_bf16 v[60:63], v[16:19], v[164:167], v[4:7]
	s_max_i32 s16, s92, 0xffffffa0
	s_addk_i32 s16, 0x60
	s_min_u32 s16, s16, 0x7ff0
	s_lshl_b32 s16, s16, 10
	v_lshl_add_u64 v[16:17], v[184:185], 0, s[16:17]
	global_load_dwordx4 v[4:7], v[16:17], off
	global_load_dwordx4 v[8:11], v[16:17], off offset:64
	global_load_dwordx4 v[12:15], v[16:17], off offset:128
	s_nop 0
	global_load_dwordx4 v[16:19], v[16:17], off offset:192
	s_waitcnt vmcnt(7)
	v_mfma_f32_16x16x32_bf16 v[36:39], v[20:23], v[0:3], 0
	v_mfma_f32_16x16x32_bf16 v[20:23], v[20:23], v[152:155], 0
	s_waitcnt vmcnt(6)
	v_mfma_f32_16x16x32_bf16 v[36:39], v[24:27], v[48:51], v[36:39]
	v_mfma_f32_16x16x32_bf16 v[20:23], v[24:27], v[156:159], v[20:23]
	s_waitcnt vmcnt(5)
	v_mfma_f32_16x16x32_bf16 v[36:39], v[28:31], v[144:147], v[36:39]
	v_mfma_f32_16x16x32_bf16 v[20:23], v[28:31], v[160:163], v[20:23]
	s_waitcnt vmcnt(4)
	v_mfma_f32_16x16x32_bf16 v[120:123], v[32:35], v[148:151], v[36:39]
	v_mfma_f32_16x16x32_bf16 v[52:55], v[32:35], v[164:167], v[20:23]
	s_add_i32 s16, s92, 0x70
	s_nop 3
	v_med3_i32 v20, s16, 0, v209
	v_lshlrev_b32_e32 v168, 10, v20
	v_lshl_add_u64 v[32:33], v[184:185], 0, v[168:169]
	global_load_dwordx4 v[20:23], v[32:33], off
	global_load_dwordx4 v[24:27], v[32:33], off offset:64
	global_load_dwordx4 v[28:31], v[32:33], off offset:128
	s_nop 0
	global_load_dwordx4 v[32:35], v[32:33], off offset:192
	s_waitcnt vmcnt(7)
	v_mfma_f32_16x16x32_bf16 v[36:39], v[4:7], v[0:3], 0
	v_mfma_f32_16x16x32_bf16 v[4:7], v[4:7], v[152:155], 0
	s_waitcnt vmcnt(6)
	v_mfma_f32_16x16x32_bf16 v[36:39], v[8:11], v[48:51], v[36:39]
	v_mfma_f32_16x16x32_bf16 v[4:7], v[8:11], v[156:159], v[4:7]
	s_waitcnt vmcnt(5)
	v_mfma_f32_16x16x32_bf16 v[36:39], v[12:15], v[144:147], v[36:39]
	v_mfma_f32_16x16x32_bf16 v[4:7], v[12:15], v[160:163], v[4:7]
	s_waitcnt vmcnt(4)
	v_mfma_f32_16x16x32_bf16 v[116:119], v[16:19], v[148:151], v[36:39]
	v_mfma_f32_16x16x32_bf16 v[44:47], v[16:19], v[164:167], v[4:7]
	s_max_i32 s16, s92, 0xffffff80
	s_addk_i32 s16, 0x80
	s_min_u32 s16, s16, 0x7ff0
	s_lshl_b32 s16, s16, 10
	v_lshl_add_u64 v[16:17], v[184:185], 0, s[16:17]
	global_load_dwordx4 v[4:7], v[16:17], off
	global_load_dwordx4 v[8:11], v[16:17], off offset:64
	global_load_dwordx4 v[12:15], v[16:17], off offset:128
	s_nop 0
	global_load_dwordx4 v[16:19], v[16:17], off offset:192
	s_waitcnt vmcnt(7)
	v_mfma_f32_16x16x32_bf16 v[36:39], v[20:23], v[0:3], 0
	v_mfma_f32_16x16x32_bf16 v[20:23], v[20:23], v[152:155], 0
	s_waitcnt vmcnt(6)
	v_mfma_f32_16x16x32_bf16 v[36:39], v[24:27], v[48:51], v[36:39]
	v_mfma_f32_16x16x32_bf16 v[20:23], v[24:27], v[156:159], v[20:23]
	s_waitcnt vmcnt(5)
	v_mfma_f32_16x16x32_bf16 v[36:39], v[28:31], v[144:147], v[36:39]
	v_mfma_f32_16x16x32_bf16 v[20:23], v[28:31], v[160:163], v[20:23]
	s_waitcnt vmcnt(4)
	v_mfma_f32_16x16x32_bf16 v[112:115], v[32:35], v[148:151], v[36:39]
	v_mfma_f32_16x16x32_bf16 v[40:43], v[32:35], v[164:167], v[20:23]
	s_add_i32 s16, s92, 0x90
	s_nop 3
	v_med3_i32 v20, s16, 0, v209
	v_lshlrev_b32_e32 v168, 10, v20
	v_lshl_add_u64 v[32:33], v[184:185], 0, v[168:169]
	global_load_dwordx4 v[20:23], v[32:33], off
	global_load_dwordx4 v[24:27], v[32:33], off offset:64
	global_load_dwordx4 v[28:31], v[32:33], off offset:128
	s_nop 0
	global_load_dwordx4 v[32:35], v[32:33], off offset:192
	s_waitcnt vmcnt(7)
	v_mfma_f32_16x16x32_bf16 v[36:39], v[4:7], v[0:3], 0
	v_mfma_f32_16x16x32_bf16 v[4:7], v[4:7], v[152:155], 0
	s_waitcnt vmcnt(6)
	v_mfma_f32_16x16x32_bf16 v[36:39], v[8:11], v[48:51], v[36:39]
	v_mfma_f32_16x16x32_bf16 v[4:7], v[8:11], v[156:159], v[4:7]
	s_waitcnt vmcnt(5)
	v_mfma_f32_16x16x32_bf16 v[36:39], v[12:15], v[144:147], v[36:39]
	v_mfma_f32_16x16x32_bf16 v[4:7], v[12:15], v[160:163], v[4:7]
	s_waitcnt vmcnt(4)
	v_mfma_f32_16x16x32_bf16 v[108:111], v[16:19], v[148:151], v[36:39]
	v_mfma_f32_16x16x32_bf16 v[36:39], v[16:19], v[164:167], v[4:7]
	s_max_i32 s16, s92, 0xffffff60
	s_addk_i32 s16, 0xa0
	s_min_u32 s16, s16, 0x7ff0
	s_lshl_b32 s16, s16, 10
	v_lshl_add_u64 v[16:17], v[184:185], 0, s[16:17]
	global_load_dwordx4 v[4:7], v[16:17], off
	global_load_dwordx4 v[8:11], v[16:17], off offset:64
	global_load_dwordx4 v[12:15], v[16:17], off offset:128
	s_nop 0
	global_load_dwordx4 v[16:19], v[16:17], off offset:192
	s_waitcnt vmcnt(7)
	v_mfma_f32_16x16x32_bf16 v[56:59], v[20:23], v[0:3], 0
	v_mfma_f32_16x16x32_bf16 v[20:23], v[20:23], v[152:155], 0
	s_waitcnt vmcnt(6)
	v_mfma_f32_16x16x32_bf16 v[56:59], v[24:27], v[48:51], v[56:59]
	v_mfma_f32_16x16x32_bf16 v[20:23], v[24:27], v[156:159], v[20:23]
	s_waitcnt vmcnt(5)
	v_mfma_f32_16x16x32_bf16 v[56:59], v[28:31], v[144:147], v[56:59]
	v_mfma_f32_16x16x32_bf16 v[20:23], v[28:31], v[160:163], v[20:23]
	s_waitcnt vmcnt(4)
	v_mfma_f32_16x16x32_bf16 v[104:107], v[32:35], v[148:151], v[56:59]
	v_mfma_f32_16x16x32_bf16 v[32:35], v[32:35], v[164:167], v[20:23]
	s_add_i32 s16, s92, 0xb0
	s_nop 3
	v_med3_i32 v20, s16, 0, v209
	v_lshlrev_b32_e32 v168, 10, v20
	v_lshl_add_u64 v[28:29], v[184:185], 0, v[168:169]
	global_load_dwordx4 v[20:23], v[28:29], off
	global_load_dwordx4 v[24:27], v[28:29], off offset:64
	global_load_dwordx4 v[56:59], v[28:29], off offset:128
	global_load_dwordx4 v[68:71], v[28:29], off offset:192
	s_waitcnt vmcnt(7)
	v_mfma_f32_16x16x32_bf16 v[28:31], v[4:7], v[0:3], 0
	v_mfma_f32_16x16x32_bf16 v[4:7], v[4:7], v[152:155], 0
	s_waitcnt vmcnt(6)
	v_mfma_f32_16x16x32_bf16 v[28:31], v[8:11], v[48:51], v[28:31]
	v_mfma_f32_16x16x32_bf16 v[4:7], v[8:11], v[156:159], v[4:7]
	s_waitcnt vmcnt(5)
	v_mfma_f32_16x16x32_bf16 v[28:31], v[12:15], v[144:147], v[28:31]
	v_mfma_f32_16x16x32_bf16 v[4:7], v[12:15], v[160:163], v[4:7]
	s_waitcnt vmcnt(4)
	v_mfma_f32_16x16x32_bf16 v[100:103], v[16:19], v[148:151], v[28:31]
	v_mfma_f32_16x16x32_bf16 v[28:31], v[16:19], v[164:167], v[4:7]
	s_max_i32 s16, s92, 0xffffff40
	s_addk_i32 s16, 0xc0
	s_min_u32 s16, s16, 0x7ff0
	s_lshl_b32 s16, s16, 10
	v_lshl_add_u64 v[16:17], v[184:185], 0, s[16:17]
	global_load_dwordx4 v[4:7], v[16:17], off
	global_load_dwordx4 v[8:11], v[16:17], off offset:64
	global_load_dwordx4 v[12:15], v[16:17], off offset:128
	s_nop 0
	global_load_dwordx4 v[16:19], v[16:17], off offset:192
	s_waitcnt vmcnt(7)
	v_mfma_f32_16x16x32_bf16 v[76:79], v[20:23], v[0:3], 0
	v_mfma_f32_16x16x32_bf16 v[20:23], v[20:23], v[152:155], 0
	s_waitcnt vmcnt(6)
	v_mfma_f32_16x16x32_bf16 v[76:79], v[24:27], v[48:51], v[76:79]
	v_mfma_f32_16x16x32_bf16 v[20:23], v[24:27], v[156:159], v[20:23]
	s_waitcnt vmcnt(5)
	v_mfma_f32_16x16x32_bf16 v[76:79], v[56:59], v[144:147], v[76:79]
	v_mfma_f32_16x16x32_bf16 v[20:23], v[56:59], v[160:163], v[20:23]
	s_waitcnt vmcnt(4)
	v_mfma_f32_16x16x32_bf16 v[96:99], v[68:71], v[148:151], v[76:79]
	v_mfma_f32_16x16x32_bf16 v[24:27], v[68:71], v[164:167], v[20:23]
	s_add_i32 s16, s92, 0xd0
	s_nop 3
	v_med3_i32 v20, s16, 0, v209
	v_lshlrev_b32_e32 v168, 10, v20
	v_lshl_add_u64 v[20:21], v[184:185], 0, v[168:169]
	global_load_dwordx4 v[56:59], v[20:21], off
	global_load_dwordx4 v[68:71], v[20:21], off offset:64
	global_load_dwordx4 v[76:79], v[20:21], off offset:128
	global_load_dwordx4 v[214:217], v[20:21], off offset:192
	s_waitcnt vmcnt(7)
	v_mfma_f32_16x16x32_bf16 v[20:23], v[4:7], v[0:3], 0
	v_mfma_f32_16x16x32_bf16 v[4:7], v[4:7], v[152:155], 0
	s_waitcnt vmcnt(6)
	v_mfma_f32_16x16x32_bf16 v[20:23], v[8:11], v[48:51], v[20:23]
	v_mfma_f32_16x16x32_bf16 v[4:7], v[8:11], v[156:159], v[4:7]
	s_waitcnt vmcnt(5)
	v_mfma_f32_16x16x32_bf16 v[20:23], v[12:15], v[144:147], v[20:23]
	v_mfma_f32_16x16x32_bf16 v[4:7], v[12:15], v[160:163], v[4:7]
	s_waitcnt vmcnt(4)
	v_mfma_f32_16x16x32_bf16 v[92:95], v[16:19], v[148:151], v[20:23]
	v_mfma_f32_16x16x32_bf16 v[20:23], v[16:19], v[164:167], v[4:7]
	s_max_i32 s16, s92, 0xffffff20
	s_addk_i32 s16, 0xe0
	s_min_u32 s16, s16, 0x7ff0
	s_lshl_b32 s16, s16, 10
	v_lshl_add_u64 v[16:17], v[184:185], 0, s[16:17]
	global_load_dwordx4 v[4:7], v[16:17], off
	global_load_dwordx4 v[8:11], v[16:17], off offset:64
	global_load_dwordx4 v[12:15], v[16:17], off offset:128
	global_load_dwordx4 v[218:221], v[16:17], off offset:192
	s_waitcnt vmcnt(7)
	v_mfma_f32_16x16x32_bf16 v[16:19], v[56:59], v[0:3], 0
	s_waitcnt vmcnt(6)
	v_mfma_f32_16x16x32_bf16 v[16:19], v[68:71], v[48:51], v[16:19]
	s_waitcnt vmcnt(5)
	v_mfma_f32_16x16x32_bf16 v[16:19], v[76:79], v[144:147], v[16:19]
	s_waitcnt vmcnt(4)
	v_mfma_f32_16x16x32_bf16 v[88:91], v[214:217], v[148:151], v[16:19]
	v_mfma_f32_16x16x32_bf16 v[16:19], v[56:59], v[152:155], 0
	v_mfma_f32_16x16x32_bf16 v[16:19], v[68:71], v[156:159], v[16:19]
	v_mfma_f32_16x16x32_bf16 v[16:19], v[76:79], v[160:163], v[16:19]
	v_mfma_f32_16x16x32_bf16 v[16:19], v[214:217], v[164:167], v[16:19]
	s_add_i32 s16, s92, 0xf0
	v_med3_i32 v56, s16, 0, v209
	v_lshlrev_b32_e32 v168, 10, v56
	v_lshl_add_u64 v[68:69], v[184:185], 0, v[168:169]
	global_load_dwordx4 v[56:59], v[68:69], off
	global_load_dwordx4 v[214:217], v[68:69], off offset:64
	global_load_dwordx4 v[226:229], v[68:69], off offset:128
	global_load_dwordx4 v[230:233], v[68:69], off offset:192
	s_waitcnt vmcnt(7)
	v_mfma_f32_16x16x32_bf16 v[68:71], v[4:7], v[0:3], 0
	v_mfma_f32_16x16x32_bf16 v[4:7], v[4:7], v[152:155], 0
	s_waitcnt vmcnt(6)
	v_mfma_f32_16x16x32_bf16 v[68:71], v[8:11], v[48:51], v[68:71]
	v_mfma_f32_16x16x32_bf16 v[4:7], v[8:11], v[156:159], v[4:7]
	s_waitcnt vmcnt(5)
	v_mfma_f32_16x16x32_bf16 v[68:71], v[12:15], v[144:147], v[68:71]
	v_mfma_f32_16x16x32_bf16 v[4:7], v[12:15], v[160:163], v[4:7]
	s_waitcnt vmcnt(4)
	v_mfma_f32_16x16x32_bf16 v[76:79], v[218:221], v[148:151], v[68:71]
	v_mfma_f32_16x16x32_bf16 v[12:15], v[218:221], v[164:167], v[4:7]
	s_max_i32 s16, s92, 0xffffff00
	s_addk_i32 s16, 0x100
	s_min_u32 s16, s16, 0x7ff0
	s_lshl_b32 s16, s16, 10
	v_lshl_add_u64 v[8:9], v[184:185], 0, s[16:17]
	global_load_dwordx4 v[4:7], v[8:9], off
	global_load_dwordx4 v[218:221], v[8:9], off offset:64
	global_load_dwordx4 v[234:237], v[8:9], off offset:128
	global_load_dwordx4 v[238:241], v[8:9], off offset:192
	s_waitcnt vmcnt(7)
	v_mfma_f32_16x16x32_bf16 v[8:11], v[56:59], v[0:3], 0
	s_waitcnt vmcnt(6)
	v_mfma_f32_16x16x32_bf16 v[8:11], v[214:217], v[48:51], v[8:11]
	s_waitcnt vmcnt(5)
	v_mfma_f32_16x16x32_bf16 v[8:11], v[226:229], v[144:147], v[8:11]
	s_waitcnt vmcnt(4)
	v_mfma_f32_16x16x32_bf16 v[68:71], v[230:233], v[148:151], v[8:11]
	v_mfma_f32_16x16x32_bf16 v[8:11], v[56:59], v[152:155], 0
	v_mfma_f32_16x16x32_bf16 v[8:11], v[214:217], v[156:159], v[8:11]
	v_mfma_f32_16x16x32_bf16 v[8:11], v[226:229], v[160:163], v[8:11]
	v_mfma_f32_16x16x32_bf16 v[8:11], v[230:233], v[164:167], v[8:11]
	s_add_i32 s16, s92, 0x110
	v_med3_i32 v56, s16, 0, v209
	v_lshlrev_b32_e32 v168, 10, v56
	v_lshl_add_u64 v[56:57], v[184:185], 0, v[168:169]
	global_load_dwordx4 v[214:217], v[56:57], off
	global_load_dwordx4 v[226:229], v[56:57], off offset:64
	global_load_dwordx4 v[230:233], v[56:57], off offset:128
	global_load_dwordx4 v[242:245], v[56:57], off offset:192
	s_waitcnt vmcnt(7)
	v_mfma_f32_16x16x32_bf16 v[56:59], v[4:7], v[0:3], 0
	v_mfma_f32_16x16x32_bf16 v[4:7], v[4:7], v[152:155], 0
	s_waitcnt vmcnt(6)
	v_mfma_f32_16x16x32_bf16 v[56:59], v[218:221], v[48:51], v[56:59]
	v_mfma_f32_16x16x32_bf16 v[4:7], v[218:221], v[156:159], v[4:7]
	s_waitcnt vmcnt(5)
	v_mfma_f32_16x16x32_bf16 v[56:59], v[234:237], v[144:147], v[56:59]
	v_mfma_f32_16x16x32_bf16 v[4:7], v[234:237], v[160:163], v[4:7]
	s_waitcnt vmcnt(4)
	v_mfma_f32_16x16x32_bf16 v[56:59], v[238:241], v[148:151], v[56:59]
	v_mfma_f32_16x16x32_bf16 v[4:7], v[238:241], v[164:167], v[4:7]
	s_waitcnt vmcnt(3)
	v_mfma_f32_16x16x32_bf16 v[0:3], v[214:217], v[0:3], 0
	s_waitcnt vmcnt(2)
	v_mfma_f32_16x16x32_bf16 v[0:3], v[226:229], v[48:51], v[0:3]
	s_waitcnt vmcnt(1)
	v_mfma_f32_16x16x32_bf16 v[0:3], v[230:233], v[144:147], v[0:3]
	s_waitcnt vmcnt(0)
	v_mfma_f32_16x16x32_bf16 v[48:51], v[242:245], v[148:151], v[0:3]
	v_mfma_f32_16x16x32_bf16 v[0:3], v[214:217], v[152:155], 0
	v_mfma_f32_16x16x32_bf16 v[0:3], v[226:229], v[156:159], v[0:3]
	v_mfma_f32_16x16x32_bf16 v[0:3], v[230:233], v[160:163], v[0:3]
	v_mfma_f32_16x16x32_bf16 v[0:3], v[242:245], v[164:167], v[0:3]
	v_cvt_f32_u32_e32 v144, s14
	s_mov_b32 s57, s45
	s_lshl_b64 s[16:17], s[56:57], 2
	s_add_u32 s64, s62, s16
	v_mul_f32_e32 v145, -0.5, v144
	v_cmp_gt_f32_e32 vcc, s76, v145
	s_addc_u32 s65, s63, s17
	v_mov_b32_e32 v146, v179
	v_cndmask_b32_e32 v145, 0, v211, vcc
	v_fmac_f32_e32 v145, -0.5, v144
	global_load_dword v144, v169, s[64:65]
	v_exp_f32_e32 v145, v145
	v_add_u32_e32 v146, v146, v197
	v_sub_u32_e32 v147, v178, v146
	v_sub_u32_e32 v148, 0, v147
	v_max_i32_e32 v147, v147, v148
	s_and_b64 s[16:17], vcc, exec
	v_cmp_gt_u32_e32 vcc, s84, v147
	v_cvt_f32_u32_e32 v147, v147
	s_cselect_b32 s14, 0xffffffc0, 0
	v_ldexp_f32 v145, v145, s14
	v_mul_f32_e32 v145, 0x3fb8aa3b, v145
	v_fma_f32 v140, -v145, v147, v140
	v_add_u32_e32 v147, 1, v146
	v_cmp_le_i32_e64 s[16:17], s89, v146
	v_sub_u32_e32 v148, v178, v147
	s_and_b64 s[16:17], vcc, s[16:17]
	v_cmp_gt_i32_e32 vcc, s91, v146
	v_sub_u32_e32 v149, 0, v148
	s_and_b64 vcc, s[16:17], vcc
	v_max_i32_e32 v148, v148, v149
	v_cndmask_b32_e32 v140, v212, v140, vcc
	v_cmp_gt_u32_e32 vcc, s84, v148
	v_cvt_f32_u32_e32 v148, v148
	v_cmp_le_i32_e64 s[16:17], s89, v147
	s_and_b64 s[16:17], vcc, s[16:17]
	v_cmp_gt_i32_e32 vcc, s91, v147
	v_fma_f32 v141, -v145, v148, v141
	v_add_u32_e32 v148, 2, v146
	v_sub_u32_e32 v149, v178, v148
	v_sub_u32_e32 v150, 0, v149
	s_and_b64 vcc, s[16:17], vcc
	v_max_i32_e32 v149, v149, v150
	v_cndmask_b32_e32 v141, v212, v141, vcc
	v_cmp_gt_u32_e32 vcc, s84, v149
	v_cvt_f32_u32_e32 v149, v149
	v_cmp_le_i32_e64 s[16:17], s89, v148
	s_and_b64 s[16:17], vcc, s[16:17]
	v_cmp_gt_i32_e32 vcc, s91, v148
	v_add_u32_e32 v148, 3, v146
	v_fma_f32 v142, -v145, v149, v142
	v_sub_u32_e32 v149, v178, v148
	v_sub_u32_e32 v150, 0, v149
	s_and_b64 vcc, s[16:17], vcc
	v_max_i32_e32 v149, v149, v150
	v_cndmask_b32_e32 v142, v212, v142, vcc
	v_cmp_gt_u32_e32 vcc, s84, v149
	v_cvt_f32_u32_e32 v149, v149
	v_cmp_le_i32_e64 s[16:17], s89, v148
	s_and_b64 s[16:17], vcc, s[16:17]
	v_cmp_gt_i32_e32 vcc, s91, v148
	v_add_u32_e32 v148, 16, v146
	v_fma_f32 v143, -v145, v149, v143
	v_sub_u32_e32 v149, v178, v148
	v_sub_u32_e32 v150, 0, v149
	s_and_b64 vcc, s[16:17], vcc
	v_max_i32_e32 v149, v149, v150
	v_cndmask_b32_e32 v143, v212, v143, vcc
	v_cmp_gt_u32_e32 vcc, s84, v149
	v_cvt_f32_u32_e32 v149, v149
	v_cmp_le_i32_e64 s[16:17], s89, v148
	s_and_b64 s[16:17], vcc, s[16:17]
	v_cmp_gt_i32_e32 vcc, s91, v148
	v_add_u32_e32 v148, 17, v146
	v_fma_f32 v136, -v145, v149, v136
	v_sub_u32_e32 v149, v178, v148
	v_sub_u32_e32 v150, 0, v149
	s_and_b64 vcc, s[16:17], vcc
	v_max_i32_e32 v149, v149, v150
	v_cndmask_b32_e32 v136, v212, v136, vcc
	v_cmp_gt_u32_e32 vcc, s84, v149
	v_cvt_f32_u32_e32 v149, v149
	v_cmp_le_i32_e64 s[16:17], s89, v148
	s_and_b64 s[16:17], vcc, s[16:17]
	v_cmp_gt_i32_e32 vcc, s91, v148
	v_add_u32_e32 v148, 18, v146
	v_fma_f32 v137, -v145, v149, v137
	v_sub_u32_e32 v149, v178, v148
	v_sub_u32_e32 v150, 0, v149
	s_and_b64 vcc, s[16:17], vcc
	v_max_i32_e32 v149, v149, v150
	v_cndmask_b32_e32 v137, v212, v137, vcc
	v_cmp_gt_u32_e32 vcc, s84, v149
	v_cvt_f32_u32_e32 v149, v149
	v_cmp_le_i32_e64 s[16:17], s89, v148
	s_and_b64 s[16:17], vcc, s[16:17]
	v_cmp_gt_i32_e32 vcc, s91, v148
	v_add_u32_e32 v148, 19, v146
	v_fma_f32 v138, -v145, v149, v138
	v_sub_u32_e32 v149, v178, v148
	v_sub_u32_e32 v150, 0, v149
	s_and_b64 vcc, s[16:17], vcc
	v_max_i32_e32 v149, v149, v150
	v_cndmask_b32_e32 v138, v212, v138, vcc
	v_cmp_gt_u32_e32 vcc, s84, v149
	v_cvt_f32_u32_e32 v149, v149
	v_cmp_le_i32_e64 s[16:17], s89, v148
	s_and_b64 s[16:17], vcc, s[16:17]
	v_cmp_gt_i32_e32 vcc, s91, v148
	v_add_u32_e32 v148, 32, v146
	v_fma_f32 v139, -v145, v149, v139
	v_sub_u32_e32 v149, v178, v148
	v_sub_u32_e32 v150, 0, v149
	s_and_b64 vcc, s[16:17], vcc
	v_max_i32_e32 v149, v149, v150
	v_cndmask_b32_e32 v139, v212, v139, vcc
	v_cmp_gt_u32_e32 vcc, s84, v149
	v_cvt_f32_u32_e32 v149, v149
	v_cmp_le_i32_e64 s[16:17], s89, v148
	s_and_b64 s[16:17], vcc, s[16:17]
	v_cmp_gt_i32_e32 vcc, s91, v148
	v_add_u32_e32 v148, 33, v146
	v_fma_f32 v132, -v145, v149, v132
	v_sub_u32_e32 v149, v178, v148
	v_sub_u32_e32 v150, 0, v149
	s_and_b64 vcc, s[16:17], vcc
	v_max_i32_e32 v149, v149, v150
	v_cndmask_b32_e32 v132, v212, v132, vcc
	v_cmp_gt_u32_e32 vcc, s84, v149
	v_cvt_f32_u32_e32 v149, v149
	v_cmp_le_i32_e64 s[16:17], s89, v148
	s_and_b64 s[16:17], vcc, s[16:17]
	v_cmp_gt_i32_e32 vcc, s91, v148
	v_add_u32_e32 v148, 34, v146
	v_fma_f32 v133, -v145, v149, v133
	v_sub_u32_e32 v149, v178, v148
	v_sub_u32_e32 v150, 0, v149
	s_and_b64 vcc, s[16:17], vcc
	v_max_i32_e32 v149, v149, v150
	v_cndmask_b32_e32 v133, v212, v133, vcc
	v_cmp_gt_u32_e32 vcc, s84, v149
	v_cvt_f32_u32_e32 v149, v149
	v_cmp_le_i32_e64 s[16:17], s89, v148
	s_and_b64 s[16:17], vcc, s[16:17]
	v_cmp_gt_i32_e32 vcc, s91, v148
	v_add_u32_e32 v148, 35, v146
	v_fma_f32 v134, -v145, v149, v134
	v_sub_u32_e32 v149, v178, v148
	v_sub_u32_e32 v150, 0, v149
	s_and_b64 vcc, s[16:17], vcc
	v_max_i32_e32 v149, v149, v150
	v_cndmask_b32_e32 v134, v212, v134, vcc
	v_cmp_gt_u32_e32 vcc, s84, v149
	v_cvt_f32_u32_e32 v149, v149
	v_cmp_le_i32_e64 s[16:17], s89, v148
	s_and_b64 s[16:17], vcc, s[16:17]
	v_cmp_gt_i32_e32 vcc, s91, v148
	v_add_u32_e32 v148, 48, v146
	v_fma_f32 v135, -v145, v149, v135
	v_sub_u32_e32 v149, v178, v148
	v_sub_u32_e32 v150, 0, v149
	s_and_b64 vcc, s[16:17], vcc
	v_max_i32_e32 v149, v149, v150
	v_cndmask_b32_e32 v135, v212, v135, vcc
	v_cmp_gt_u32_e32 vcc, s84, v149
	v_cvt_f32_u32_e32 v149, v149
	v_cmp_le_i32_e64 s[16:17], s89, v148
	s_and_b64 s[16:17], vcc, s[16:17]
	v_cmp_gt_i32_e32 vcc, s91, v148
	v_add_u32_e32 v148, 49, v146
	v_fma_f32 v128, -v145, v149, v128
	v_sub_u32_e32 v149, v178, v148
	v_sub_u32_e32 v150, 0, v149
	s_and_b64 vcc, s[16:17], vcc
	v_max_i32_e32 v149, v149, v150
	v_cndmask_b32_e32 v128, v212, v128, vcc
	v_cmp_gt_u32_e32 vcc, s84, v149
	v_cvt_f32_u32_e32 v149, v149
	v_cmp_le_i32_e64 s[16:17], s89, v148
	s_and_b64 s[16:17], vcc, s[16:17]
	v_cmp_gt_i32_e32 vcc, s91, v148
	v_add_u32_e32 v148, 50, v146
	v_fma_f32 v129, -v145, v149, v129
	v_sub_u32_e32 v149, v178, v148
	v_sub_u32_e32 v150, 0, v149
	s_and_b64 vcc, s[16:17], vcc
	v_max_i32_e32 v149, v149, v150
	v_cndmask_b32_e32 v129, v212, v129, vcc
	v_cmp_gt_u32_e32 vcc, s84, v149
	v_cvt_f32_u32_e32 v149, v149
	v_cmp_le_i32_e64 s[16:17], s89, v148
	s_and_b64 s[16:17], vcc, s[16:17]
	v_cmp_gt_i32_e32 vcc, s91, v148
	v_add_u32_e32 v148, 51, v146
	v_fma_f32 v130, -v145, v149, v130
	v_sub_u32_e32 v149, v178, v148
	v_sub_u32_e32 v150, 0, v149
	s_and_b64 vcc, s[16:17], vcc
	v_max_i32_e32 v149, v149, v150
	v_cndmask_b32_e32 v130, v212, v130, vcc
	v_cmp_gt_u32_e32 vcc, s84, v149
	v_cvt_f32_u32_e32 v149, v149
	v_cmp_le_i32_e64 s[16:17], s89, v148
	s_and_b64 s[16:17], vcc, s[16:17]
	v_cmp_gt_i32_e32 vcc, s91, v148
	v_add_u32_e32 v148, 64, v146
	v_fma_f32 v131, -v145, v149, v131
	v_sub_u32_e32 v149, v178, v148
	v_sub_u32_e32 v150, 0, v149
	s_and_b64 vcc, s[16:17], vcc
	v_max_i32_e32 v149, v149, v150
	v_cndmask_b32_e32 v131, v212, v131, vcc
	v_cmp_gt_u32_e32 vcc, s84, v149
	v_cvt_f32_u32_e32 v149, v149
	v_cmp_le_i32_e64 s[16:17], s89, v148
	s_and_b64 s[16:17], vcc, s[16:17]
	v_cmp_gt_i32_e32 vcc, s91, v148
	v_add_u32_e32 v148, 0x41, v146
	v_fma_f32 v124, -v145, v149, v124
	v_sub_u32_e32 v149, v178, v148
	v_sub_u32_e32 v150, 0, v149
	s_and_b64 vcc, s[16:17], vcc
	v_max_i32_e32 v149, v149, v150
	v_cndmask_b32_e32 v124, v212, v124, vcc
	v_cmp_gt_u32_e32 vcc, s84, v149
	v_cvt_f32_u32_e32 v149, v149
	v_cmp_le_i32_e64 s[16:17], s89, v148
	s_and_b64 s[16:17], vcc, s[16:17]
	v_cmp_gt_i32_e32 vcc, s91, v148
	v_add_u32_e32 v148, 0x42, v146
	v_fma_f32 v125, -v145, v149, v125
	v_sub_u32_e32 v149, v178, v148
	v_sub_u32_e32 v150, 0, v149
	s_and_b64 vcc, s[16:17], vcc
	v_max_i32_e32 v149, v149, v150
	v_cndmask_b32_e32 v125, v212, v125, vcc
	v_cmp_gt_u32_e32 vcc, s84, v149
	v_cvt_f32_u32_e32 v149, v149
	v_cmp_le_i32_e64 s[16:17], s89, v148
	s_and_b64 s[16:17], vcc, s[16:17]
	v_cmp_gt_i32_e32 vcc, s91, v148
	v_add_u32_e32 v148, 0x43, v146
	v_fma_f32 v126, -v145, v149, v126
	v_sub_u32_e32 v149, v178, v148
	v_sub_u32_e32 v150, 0, v149
	s_and_b64 vcc, s[16:17], vcc
	v_max_i32_e32 v149, v149, v150
	v_cndmask_b32_e32 v126, v212, v126, vcc
	v_cmp_gt_u32_e32 vcc, s84, v149
	v_cvt_f32_u32_e32 v149, v149
	v_cmp_le_i32_e64 s[16:17], s89, v148
	s_and_b64 s[16:17], vcc, s[16:17]
	v_cmp_gt_i32_e32 vcc, s91, v148
	v_add_u32_e32 v148, 0x50, v146
	v_fma_f32 v127, -v145, v149, v127
	v_sub_u32_e32 v149, v178, v148
	v_sub_u32_e32 v150, 0, v149
	s_and_b64 vcc, s[16:17], vcc
	v_max_i32_e32 v149, v149, v150
	v_cndmask_b32_e32 v127, v212, v127, vcc
	v_cmp_gt_u32_e32 vcc, s84, v149
	v_cvt_f32_u32_e32 v149, v149
	v_cmp_le_i32_e64 s[16:17], s89, v148
	s_and_b64 s[16:17], vcc, s[16:17]
	v_cmp_gt_i32_e32 vcc, s91, v148
	v_add_u32_e32 v148, 0x51, v146
	v_fma_f32 v120, -v145, v149, v120
	v_sub_u32_e32 v149, v178, v148
	v_sub_u32_e32 v150, 0, v149
	s_and_b64 vcc, s[16:17], vcc
	v_max_i32_e32 v149, v149, v150
	v_cndmask_b32_e32 v120, v212, v120, vcc
	v_cmp_gt_u32_e32 vcc, s84, v149
	v_cvt_f32_u32_e32 v149, v149
	v_cmp_le_i32_e64 s[16:17], s89, v148
	s_and_b64 s[16:17], vcc, s[16:17]
	v_cmp_gt_i32_e32 vcc, s91, v148
	v_add_u32_e32 v148, 0x52, v146
	v_fma_f32 v121, -v145, v149, v121
	v_sub_u32_e32 v149, v178, v148
	v_sub_u32_e32 v150, 0, v149
	s_and_b64 vcc, s[16:17], vcc
	v_max_i32_e32 v149, v149, v150
	v_cndmask_b32_e32 v121, v212, v121, vcc
	v_cmp_gt_u32_e32 vcc, s84, v149
	v_cvt_f32_u32_e32 v149, v149
	v_cmp_le_i32_e64 s[16:17], s89, v148
	s_and_b64 s[16:17], vcc, s[16:17]
	v_cmp_gt_i32_e32 vcc, s91, v148
	v_add_u32_e32 v148, 0x53, v146
	v_fma_f32 v122, -v145, v149, v122
	v_sub_u32_e32 v149, v178, v148
	v_sub_u32_e32 v150, 0, v149
	s_and_b64 vcc, s[16:17], vcc
	v_max_i32_e32 v149, v149, v150
	v_cndmask_b32_e32 v122, v212, v122, vcc
	v_cmp_gt_u32_e32 vcc, s84, v149
	v_cvt_f32_u32_e32 v149, v149
	v_cmp_le_i32_e64 s[16:17], s89, v148
	s_and_b64 s[16:17], vcc, s[16:17]
	v_cmp_gt_i32_e32 vcc, s91, v148
	v_add_u32_e32 v148, 0x60, v146
	v_fma_f32 v123, -v145, v149, v123
	v_sub_u32_e32 v149, v178, v148
	v_sub_u32_e32 v150, 0, v149
	s_and_b64 vcc, s[16:17], vcc
	v_max_i32_e32 v149, v149, v150
	v_cndmask_b32_e32 v123, v212, v123, vcc
	v_cmp_gt_u32_e32 vcc, s84, v149
	v_cvt_f32_u32_e32 v149, v149
	v_cmp_le_i32_e64 s[16:17], s89, v148
	s_and_b64 s[16:17], vcc, s[16:17]
	v_cmp_gt_i32_e32 vcc, s91, v148
	v_add_u32_e32 v148, 0x61, v146
	v_fma_f32 v116, -v145, v149, v116
	v_sub_u32_e32 v149, v178, v148
	v_sub_u32_e32 v150, 0, v149
	s_and_b64 vcc, s[16:17], vcc
	v_max_i32_e32 v149, v149, v150
	v_cndmask_b32_e32 v116, v212, v116, vcc
	v_cmp_gt_u32_e32 vcc, s84, v149
	v_cvt_f32_u32_e32 v149, v149
	v_cmp_le_i32_e64 s[16:17], s89, v148
	s_and_b64 s[16:17], vcc, s[16:17]
	v_cmp_gt_i32_e32 vcc, s91, v148
	v_add_u32_e32 v148, 0x62, v146
	v_fma_f32 v117, -v145, v149, v117
	v_sub_u32_e32 v149, v178, v148
	v_sub_u32_e32 v150, 0, v149
	s_and_b64 vcc, s[16:17], vcc
	v_max_i32_e32 v149, v149, v150
	v_cndmask_b32_e32 v117, v212, v117, vcc
	v_cmp_gt_u32_e32 vcc, s84, v149
	v_cvt_f32_u32_e32 v149, v149
	v_cmp_le_i32_e64 s[16:17], s89, v148
	s_and_b64 s[16:17], vcc, s[16:17]
	v_cmp_gt_i32_e32 vcc, s91, v148
	v_add_u32_e32 v148, 0x63, v146
	v_fma_f32 v118, -v145, v149, v118
	v_sub_u32_e32 v149, v178, v148
	v_sub_u32_e32 v150, 0, v149
	s_and_b64 vcc, s[16:17], vcc
	v_max_i32_e32 v149, v149, v150
	v_cndmask_b32_e32 v118, v212, v118, vcc
	v_cmp_gt_u32_e32 vcc, s84, v149
	v_cvt_f32_u32_e32 v149, v149
	v_cmp_le_i32_e64 s[16:17], s89, v148
	s_and_b64 s[16:17], vcc, s[16:17]
	v_cmp_gt_i32_e32 vcc, s91, v148
	v_add_u32_e32 v148, 0x70, v146
	v_fma_f32 v119, -v145, v149, v119
	v_sub_u32_e32 v149, v178, v148
	v_sub_u32_e32 v150, 0, v149
	s_and_b64 vcc, s[16:17], vcc
	v_max_i32_e32 v149, v149, v150
	v_cndmask_b32_e32 v119, v212, v119, vcc
	v_cmp_gt_u32_e32 vcc, s84, v149
	v_cvt_f32_u32_e32 v149, v149
	v_cmp_le_i32_e64 s[16:17], s89, v148
	s_and_b64 s[16:17], vcc, s[16:17]
	v_cmp_gt_i32_e32 vcc, s91, v148
	v_add_u32_e32 v148, 0x71, v146
	v_fma_f32 v112, -v145, v149, v112
	v_sub_u32_e32 v149, v178, v148
	v_sub_u32_e32 v150, 0, v149
	s_and_b64 vcc, s[16:17], vcc
	v_max_i32_e32 v149, v149, v150
	v_cndmask_b32_e32 v112, v212, v112, vcc
	v_cmp_gt_u32_e32 vcc, s84, v149
	v_cvt_f32_u32_e32 v149, v149
	v_cmp_le_i32_e64 s[16:17], s89, v148
	s_and_b64 s[16:17], vcc, s[16:17]
	v_cmp_gt_i32_e32 vcc, s91, v148
	v_add_u32_e32 v148, 0x72, v146
	v_fma_f32 v113, -v145, v149, v113
	v_sub_u32_e32 v149, v178, v148
	v_max3_f32 v147, v140, s85, v141
	v_sub_u32_e32 v150, 0, v149
	v_max3_f32 v147, v147, v142, v143
	s_and_b64 vcc, s[16:17], vcc
	v_max_i32_e32 v149, v149, v150
	v_max3_f32 v147, v147, v136, v137
	v_cndmask_b32_e32 v113, v212, v113, vcc
	v_cmp_gt_u32_e32 vcc, s84, v149
	v_cvt_f32_u32_e32 v149, v149
	v_max3_f32 v147, v147, v138, v139
	v_max3_f32 v147, v147, v132, v133
	v_cmp_le_i32_e64 s[16:17], s89, v148
	v_max3_f32 v147, v147, v134, v135
	s_and_b64 s[16:17], vcc, s[16:17]
	v_cmp_gt_i32_e32 vcc, s91, v148
	v_add_u32_e32 v148, 0x73, v146
	v_max3_f32 v147, v147, v128, v129
	v_fma_f32 v114, -v145, v149, v114
	v_sub_u32_e32 v149, v178, v148
	v_max3_f32 v147, v147, v130, v131
	v_sub_u32_e32 v150, 0, v149
	v_max3_f32 v147, v147, v124, v125
	s_and_b64 vcc, s[16:17], vcc
	v_max_i32_e32 v149, v149, v150
	v_max3_f32 v147, v147, v126, v127
	v_cndmask_b32_e32 v114, v212, v114, vcc
	v_cmp_gt_u32_e32 vcc, s84, v149
	v_cvt_f32_u32_e32 v149, v149
	v_max3_f32 v147, v147, v120, v121
	v_max3_f32 v147, v147, v122, v123
	v_cmp_le_i32_e64 s[16:17], s89, v148
	v_max3_f32 v147, v147, v116, v117
	s_and_b64 s[16:17], vcc, s[16:17]
	v_cmp_gt_i32_e32 vcc, s91, v148
	v_max3_f32 v147, v147, v118, v119
	v_fma_f32 v115, -v145, v149, v115
	s_and_b64 vcc, s[16:17], vcc
	v_max3_f32 v147, v147, v112, v113
	v_cndmask_b32_e32 v115, v212, v115, vcc
	v_max3_f32 v149, v147, v114, v115
	v_add_u32_e32 v147, 0x80, v146
	v_sub_u32_e32 v148, v178, v147
	v_sub_u32_e32 v150, 0, v148
	v_max_i32_e32 v148, v148, v150
	v_cmp_gt_u32_e32 vcc, s84, v148
	v_cvt_f32_u32_e32 v148, v148
	v_cmp_le_i32_e64 s[16:17], s89, v147
	s_and_b64 s[16:17], vcc, s[16:17]
	v_cmp_gt_i32_e32 vcc, s91, v147
	v_fma_f32 v108, -v145, v148, v108
	s_and_b64 vcc, s[16:17], vcc
	v_cndmask_b32_e32 v147, v212, v108, vcc
	v_add_u32_e32 v108, 0x81, v146
	v_sub_u32_e32 v148, v178, v108
	v_sub_u32_e32 v150, 0, v148
	v_max_i32_e32 v148, v148, v150
	v_cmp_gt_u32_e32 vcc, s84, v148
	v_cvt_f32_u32_e32 v148, v148
	v_cmp_le_i32_e64 s[16:17], s89, v108
	s_and_b64 s[16:17], vcc, s[16:17]
	v_cmp_gt_i32_e32 vcc, s91, v108
	v_fma_f32 v108, -v145, v148, v109
	s_and_b64 vcc, s[16:17], vcc
	v_cndmask_b32_e32 v148, v212, v108, vcc
	v_add_u32_e32 v109, 0x82, v146
	v_max3_f32 v108, v149, v147, v148
	v_sub_u32_e32 v149, v178, v109
	v_sub_u32_e32 v150, 0, v149
	v_max_i32_e32 v149, v149, v150
	v_cmp_gt_u32_e32 vcc, s84, v149
	v_cvt_f32_u32_e32 v149, v149
	v_cmp_le_i32_e64 s[16:17], s89, v109
	s_and_b64 s[16:17], vcc, s[16:17]
	v_cmp_gt_i32_e32 vcc, s91, v109
	v_fma_f32 v109, -v145, v149, v110
	s_and_b64 vcc, s[16:17], vcc
	v_cndmask_b32_e32 v110, v212, v109, vcc
	v_add_u32_e32 v109, 0x83, v146
	v_sub_u32_e32 v149, v178, v109
	v_sub_u32_e32 v150, 0, v149
	v_max_i32_e32 v149, v149, v150
	v_cmp_gt_u32_e32 vcc, s84, v149
	v_cvt_f32_u32_e32 v149, v149
	v_cmp_le_i32_e64 s[16:17], s89, v109
	s_and_b64 s[16:17], vcc, s[16:17]
	v_cmp_gt_i32_e32 vcc, s91, v109
	v_fma_f32 v109, -v145, v149, v111
	s_and_b64 vcc, s[16:17], vcc
	v_cndmask_b32_e32 v111, v212, v109, vcc
	v_add_u32_e32 v109, 0x90, v146
	v_sub_u32_e32 v149, v178, v109
	v_sub_u32_e32 v150, 0, v149
	v_max_i32_e32 v149, v149, v150
	v_cmp_gt_u32_e32 vcc, s84, v149
	v_cvt_f32_u32_e32 v149, v149
	v_cmp_le_i32_e64 s[16:17], s89, v109
	s_and_b64 s[16:17], vcc, s[16:17]
	v_cmp_gt_i32_e32 vcc, s91, v109
	v_add_u32_e32 v109, 0x91, v146
	v_fma_f32 v104, -v145, v149, v104
	v_sub_u32_e32 v149, v178, v109
	v_sub_u32_e32 v150, 0, v149
	s_and_b64 vcc, s[16:17], vcc
	v_max_i32_e32 v149, v149, v150
	v_cndmask_b32_e32 v104, v212, v104, vcc
	v_cmp_gt_u32_e32 vcc, s84, v149
	v_cvt_f32_u32_e32 v149, v149
	v_cmp_le_i32_e64 s[16:17], s89, v109
	s_and_b64 s[16:17], vcc, s[16:17]
	v_cmp_gt_i32_e32 vcc, s91, v109
	v_add_u32_e32 v109, 0x92, v146
	v_fma_f32 v105, -v145, v149, v105
	v_sub_u32_e32 v149, v178, v109
	v_sub_u32_e32 v150, 0, v149
	s_and_b64 vcc, s[16:17], vcc
	v_max_i32_e32 v149, v149, v150
	v_cndmask_b32_e32 v105, v212, v105, vcc
	v_cmp_gt_u32_e32 vcc, s84, v149
	v_cvt_f32_u32_e32 v149, v149
	v_cmp_le_i32_e64 s[16:17], s89, v109
	s_and_b64 s[16:17], vcc, s[16:17]
	v_cmp_gt_i32_e32 vcc, s91, v109
	v_add_u32_e32 v109, 0x93, v146
	v_fma_f32 v106, -v145, v149, v106
	v_sub_u32_e32 v149, v178, v109
	v_sub_u32_e32 v150, 0, v149
	s_and_b64 vcc, s[16:17], vcc
	v_max_i32_e32 v149, v149, v150
	v_cndmask_b32_e32 v106, v212, v106, vcc
	v_cmp_gt_u32_e32 vcc, s84, v149
	v_cvt_f32_u32_e32 v149, v149
	v_cmp_le_i32_e64 s[16:17], s89, v109
	s_and_b64 s[16:17], vcc, s[16:17]
	v_cmp_gt_i32_e32 vcc, s91, v109
	v_add_u32_e32 v109, 0xa0, v146
	v_fma_f32 v107, -v145, v149, v107
	v_sub_u32_e32 v149, v178, v109
	v_sub_u32_e32 v150, 0, v149
	s_and_b64 vcc, s[16:17], vcc
	v_max_i32_e32 v149, v149, v150
	v_cndmask_b32_e32 v107, v212, v107, vcc
	v_cmp_gt_u32_e32 vcc, s84, v149
	v_cvt_f32_u32_e32 v149, v149
	v_cmp_le_i32_e64 s[16:17], s89, v109
	s_and_b64 s[16:17], vcc, s[16:17]
	v_cmp_gt_i32_e32 vcc, s91, v109
	v_add_u32_e32 v109, 0xa1, v146
	v_fma_f32 v100, -v145, v149, v100
	v_sub_u32_e32 v149, v178, v109
	v_sub_u32_e32 v150, 0, v149
	s_and_b64 vcc, s[16:17], vcc
	v_max_i32_e32 v149, v149, v150
	v_cndmask_b32_e32 v100, v212, v100, vcc
	v_cmp_gt_u32_e32 vcc, s84, v149
	v_cvt_f32_u32_e32 v149, v149
	v_cmp_le_i32_e64 s[16:17], s89, v109
	s_and_b64 s[16:17], vcc, s[16:17]
	v_cmp_gt_i32_e32 vcc, s91, v109
	v_add_u32_e32 v109, 0xa2, v146
	v_fma_f32 v101, -v145, v149, v101
	v_sub_u32_e32 v149, v178, v109
	v_sub_u32_e32 v150, 0, v149
	s_and_b64 vcc, s[16:17], vcc
	v_max_i32_e32 v149, v149, v150
	v_cndmask_b32_e32 v101, v212, v101, vcc
	v_cmp_gt_u32_e32 vcc, s84, v149
	v_cvt_f32_u32_e32 v149, v149
	v_cmp_le_i32_e64 s[16:17], s89, v109
	s_and_b64 s[16:17], vcc, s[16:17]
	v_cmp_gt_i32_e32 vcc, s91, v109
	v_add_u32_e32 v109, 0xa3, v146
	v_fma_f32 v102, -v145, v149, v102
	v_sub_u32_e32 v149, v178, v109
	v_sub_u32_e32 v150, 0, v149
	s_and_b64 vcc, s[16:17], vcc
	v_max_i32_e32 v149, v149, v150
	v_cndmask_b32_e32 v102, v212, v102, vcc
	v_cmp_gt_u32_e32 vcc, s84, v149
	v_cvt_f32_u32_e32 v149, v149
	v_cmp_le_i32_e64 s[16:17], s89, v109
	s_and_b64 s[16:17], vcc, s[16:17]
	v_cmp_gt_i32_e32 vcc, s91, v109
	v_add_u32_e32 v109, 0xb0, v146
	v_fma_f32 v103, -v145, v149, v103
	v_sub_u32_e32 v149, v178, v109
	v_sub_u32_e32 v150, 0, v149
	s_and_b64 vcc, s[16:17], vcc
	v_max_i32_e32 v149, v149, v150
	v_cndmask_b32_e32 v103, v212, v103, vcc
	v_cmp_gt_u32_e32 vcc, s84, v149
	v_cvt_f32_u32_e32 v149, v149
	v_cmp_le_i32_e64 s[16:17], s89, v109
	s_and_b64 s[16:17], vcc, s[16:17]
	v_cmp_gt_i32_e32 vcc, s91, v109
	v_add_u32_e32 v109, 0xb1, v146
	v_fma_f32 v96, -v145, v149, v96
	v_sub_u32_e32 v149, v178, v109
	v_sub_u32_e32 v150, 0, v149
	s_and_b64 vcc, s[16:17], vcc
	v_max_i32_e32 v149, v149, v150
	v_cndmask_b32_e32 v96, v212, v96, vcc
	v_cmp_gt_u32_e32 vcc, s84, v149
	v_cvt_f32_u32_e32 v149, v149
	v_cmp_le_i32_e64 s[16:17], s89, v109
	s_and_b64 s[16:17], vcc, s[16:17]
	v_cmp_gt_i32_e32 vcc, s91, v109
	v_add_u32_e32 v109, 0xb2, v146
	v_fma_f32 v97, -v145, v149, v97
	v_sub_u32_e32 v149, v178, v109
	v_sub_u32_e32 v150, 0, v149
	s_and_b64 vcc, s[16:17], vcc
	v_max_i32_e32 v149, v149, v150
	v_cndmask_b32_e32 v97, v212, v97, vcc
	v_cmp_gt_u32_e32 vcc, s84, v149
	v_cvt_f32_u32_e32 v149, v149
	v_cmp_le_i32_e64 s[16:17], s89, v109
	s_and_b64 s[16:17], vcc, s[16:17]
	v_cmp_gt_i32_e32 vcc, s91, v109
	v_add_u32_e32 v109, 0xb3, v146
	v_fma_f32 v98, -v145, v149, v98
	v_sub_u32_e32 v149, v178, v109
	v_sub_u32_e32 v150, 0, v149
	s_and_b64 vcc, s[16:17], vcc
	v_max_i32_e32 v149, v149, v150
	v_cndmask_b32_e32 v98, v212, v98, vcc
	v_cmp_gt_u32_e32 vcc, s84, v149
	v_cvt_f32_u32_e32 v149, v149
	v_cmp_le_i32_e64 s[16:17], s89, v109
	s_and_b64 s[16:17], vcc, s[16:17]
	v_cmp_gt_i32_e32 vcc, s91, v109
	v_add_u32_e32 v109, 0xc0, v146
	v_fma_f32 v99, -v145, v149, v99
	v_sub_u32_e32 v149, v178, v109
	v_sub_u32_e32 v150, 0, v149
	s_and_b64 vcc, s[16:17], vcc
	v_max_i32_e32 v149, v149, v150
	v_cndmask_b32_e32 v99, v212, v99, vcc
	v_cmp_gt_u32_e32 vcc, s84, v149
	v_cvt_f32_u32_e32 v149, v149
	v_cmp_le_i32_e64 s[16:17], s89, v109
	s_and_b64 s[16:17], vcc, s[16:17]
	v_cmp_gt_i32_e32 vcc, s91, v109
	v_add_u32_e32 v109, 0xc1, v146
	v_fma_f32 v92, -v145, v149, v92
	v_sub_u32_e32 v149, v178, v109
	v_sub_u32_e32 v150, 0, v149
	s_and_b64 vcc, s[16:17], vcc
	v_max_i32_e32 v149, v149, v150
	v_cndmask_b32_e32 v92, v212, v92, vcc
	v_cmp_gt_u32_e32 vcc, s84, v149
	v_cvt_f32_u32_e32 v149, v149
	v_cmp_le_i32_e64 s[16:17], s89, v109
	s_and_b64 s[16:17], vcc, s[16:17]
	v_cmp_gt_i32_e32 vcc, s91, v109
	v_add_u32_e32 v109, 0xc2, v146
	v_fma_f32 v93, -v145, v149, v93
	v_sub_u32_e32 v149, v178, v109
	v_sub_u32_e32 v150, 0, v149
	s_and_b64 vcc, s[16:17], vcc
	v_max_i32_e32 v149, v149, v150
	v_cndmask_b32_e32 v93, v212, v93, vcc
	v_cmp_gt_u32_e32 vcc, s84, v149
	v_cvt_f32_u32_e32 v149, v149
	v_cmp_le_i32_e64 s[16:17], s89, v109
	s_and_b64 s[16:17], vcc, s[16:17]
	v_cmp_gt_i32_e32 vcc, s91, v109
	v_add_u32_e32 v109, 0xc3, v146
	v_fma_f32 v94, -v145, v149, v94
	v_sub_u32_e32 v149, v178, v109
	v_sub_u32_e32 v150, 0, v149
	s_and_b64 vcc, s[16:17], vcc
	v_max_i32_e32 v149, v149, v150
	v_cndmask_b32_e32 v94, v212, v94, vcc
	v_cmp_gt_u32_e32 vcc, s84, v149
	v_cvt_f32_u32_e32 v149, v149
	v_cmp_le_i32_e64 s[16:17], s89, v109
	s_and_b64 s[16:17], vcc, s[16:17]
	v_cmp_gt_i32_e32 vcc, s91, v109
	v_add_u32_e32 v109, 0xd0, v146
	v_fma_f32 v95, -v145, v149, v95
	v_sub_u32_e32 v149, v178, v109
	v_sub_u32_e32 v150, 0, v149
	s_and_b64 vcc, s[16:17], vcc
	v_max_i32_e32 v149, v149, v150
	v_cndmask_b32_e32 v95, v212, v95, vcc
	v_cmp_gt_u32_e32 vcc, s84, v149
	v_cvt_f32_u32_e32 v149, v149
	v_cmp_le_i32_e64 s[16:17], s89, v109
	s_and_b64 s[16:17], vcc, s[16:17]
	v_cmp_gt_i32_e32 vcc, s91, v109
	v_add_u32_e32 v109, 0xd1, v146
	v_fma_f32 v88, -v145, v149, v88
	v_sub_u32_e32 v149, v178, v109
	v_sub_u32_e32 v150, 0, v149
	s_and_b64 vcc, s[16:17], vcc
	v_max_i32_e32 v149, v149, v150
	v_cndmask_b32_e32 v88, v212, v88, vcc
	v_cmp_gt_u32_e32 vcc, s84, v149
	v_cvt_f32_u32_e32 v149, v149
	v_cmp_le_i32_e64 s[16:17], s89, v109
	s_and_b64 s[16:17], vcc, s[16:17]
	v_cmp_gt_i32_e32 vcc, s91, v109
	v_add_u32_e32 v109, 0xd2, v146
	v_fma_f32 v89, -v145, v149, v89
	v_sub_u32_e32 v149, v178, v109
	v_sub_u32_e32 v150, 0, v149
	s_and_b64 vcc, s[16:17], vcc
	v_max_i32_e32 v149, v149, v150
	v_cndmask_b32_e32 v89, v212, v89, vcc
	v_cmp_gt_u32_e32 vcc, s84, v149
	v_cvt_f32_u32_e32 v149, v149
	v_cmp_le_i32_e64 s[16:17], s89, v109
	s_and_b64 s[16:17], vcc, s[16:17]
	v_cmp_gt_i32_e32 vcc, s91, v109
	v_add_u32_e32 v109, 0xd3, v146
	v_fma_f32 v90, -v145, v149, v90
	v_sub_u32_e32 v149, v178, v109
	v_sub_u32_e32 v150, 0, v149
	s_and_b64 vcc, s[16:17], vcc
	v_max_i32_e32 v149, v149, v150
	v_cndmask_b32_e32 v90, v212, v90, vcc
	v_cmp_gt_u32_e32 vcc, s84, v149
	v_cvt_f32_u32_e32 v149, v149
	v_cmp_le_i32_e64 s[16:17], s89, v109
	s_and_b64 s[16:17], vcc, s[16:17]
	v_cmp_gt_i32_e32 vcc, s91, v109
	v_add_u32_e32 v109, 0xe0, v146
	v_fma_f32 v91, -v145, v149, v91
	v_sub_u32_e32 v149, v178, v109
	v_sub_u32_e32 v150, 0, v149
	s_and_b64 vcc, s[16:17], vcc
	v_max_i32_e32 v149, v149, v150
	v_cndmask_b32_e32 v91, v212, v91, vcc
	v_cmp_gt_u32_e32 vcc, s84, v149
	v_cvt_f32_u32_e32 v149, v149
	v_cmp_le_i32_e64 s[16:17], s89, v109
	s_and_b64 s[16:17], vcc, s[16:17]
	v_cmp_gt_i32_e32 vcc, s91, v109
	v_add_u32_e32 v109, 0xe1, v146
	v_fma_f32 v76, -v145, v149, v76
	v_sub_u32_e32 v149, v178, v109
	v_sub_u32_e32 v150, 0, v149
	s_and_b64 vcc, s[16:17], vcc
	v_max_i32_e32 v149, v149, v150
	v_cndmask_b32_e32 v76, v212, v76, vcc
	v_cmp_gt_u32_e32 vcc, s84, v149
	v_cvt_f32_u32_e32 v149, v149
	v_cmp_le_i32_e64 s[16:17], s89, v109
	s_and_b64 s[16:17], vcc, s[16:17]
	v_cmp_gt_i32_e32 vcc, s91, v109
	v_add_u32_e32 v109, 0xe2, v146
	v_fma_f32 v77, -v145, v149, v77
	v_sub_u32_e32 v149, v178, v109
	v_sub_u32_e32 v150, 0, v149
	s_and_b64 vcc, s[16:17], vcc
	v_max_i32_e32 v149, v149, v150
	v_cndmask_b32_e32 v77, v212, v77, vcc
	v_cmp_gt_u32_e32 vcc, s84, v149
	v_cvt_f32_u32_e32 v149, v149
	v_cmp_le_i32_e64 s[16:17], s89, v109
	s_and_b64 s[16:17], vcc, s[16:17]
	v_cmp_gt_i32_e32 vcc, s91, v109
	v_add_u32_e32 v109, 0xe3, v146
	v_fma_f32 v78, -v145, v149, v78
	v_sub_u32_e32 v149, v178, v109
	v_sub_u32_e32 v150, 0, v149
	s_and_b64 vcc, s[16:17], vcc
	v_max_i32_e32 v149, v149, v150
	v_cndmask_b32_e32 v78, v212, v78, vcc
	v_cmp_gt_u32_e32 vcc, s84, v149
	v_cvt_f32_u32_e32 v149, v149
	v_cmp_le_i32_e64 s[16:17], s89, v109
	s_and_b64 s[16:17], vcc, s[16:17]
	v_cmp_gt_i32_e32 vcc, s91, v109
	v_add_u32_e32 v109, 0xf0, v146
	v_fma_f32 v79, -v145, v149, v79
	v_sub_u32_e32 v149, v178, v109
	v_sub_u32_e32 v150, 0, v149
	s_and_b64 vcc, s[16:17], vcc
	v_max_i32_e32 v149, v149, v150
	v_cndmask_b32_e32 v79, v212, v79, vcc
	v_cmp_gt_u32_e32 vcc, s84, v149
	v_cvt_f32_u32_e32 v149, v149
	v_cmp_le_i32_e64 s[16:17], s89, v109
	s_and_b64 s[16:17], vcc, s[16:17]
	v_cmp_gt_i32_e32 vcc, s91, v109
	v_add_u32_e32 v109, 0xf1, v146
	v_fma_f32 v68, -v145, v149, v68
	v_sub_u32_e32 v149, v178, v109
	v_sub_u32_e32 v150, 0, v149
	s_and_b64 vcc, s[16:17], vcc
	v_max_i32_e32 v149, v149, v150
	v_cndmask_b32_e32 v68, v212, v68, vcc
	v_cmp_gt_u32_e32 vcc, s84, v149
	v_cvt_f32_u32_e32 v149, v149
	v_cmp_le_i32_e64 s[16:17], s89, v109
	s_and_b64 s[16:17], vcc, s[16:17]
	v_cmp_gt_i32_e32 vcc, s91, v109
	v_add_u32_e32 v109, 0xf2, v146
	v_fma_f32 v69, -v145, v149, v69
	v_sub_u32_e32 v149, v178, v109
	v_sub_u32_e32 v150, 0, v149
	s_and_b64 vcc, s[16:17], vcc
	v_max_i32_e32 v149, v149, v150
	v_cndmask_b32_e32 v69, v212, v69, vcc
	v_cmp_gt_u32_e32 vcc, s84, v149
	v_cvt_f32_u32_e32 v149, v149
	v_cmp_le_i32_e64 s[16:17], s89, v109
	s_and_b64 s[16:17], vcc, s[16:17]
	v_cmp_gt_i32_e32 vcc, s91, v109
	v_add_u32_e32 v109, 0xf3, v146
	v_fma_f32 v70, -v145, v149, v70
	v_sub_u32_e32 v149, v178, v109
	v_sub_u32_e32 v150, 0, v149
	s_and_b64 vcc, s[16:17], vcc
	v_max_i32_e32 v149, v149, v150
	v_cndmask_b32_e32 v70, v212, v70, vcc
	v_cmp_gt_u32_e32 vcc, s84, v149
	v_cvt_f32_u32_e32 v149, v149
	v_cmp_le_i32_e64 s[16:17], s89, v109
	s_and_b64 s[16:17], vcc, s[16:17]
	v_cmp_gt_i32_e32 vcc, s91, v109
	v_add_u32_e32 v109, 0x100, v146
	v_fma_f32 v71, -v145, v149, v71
	v_sub_u32_e32 v149, v178, v109
	v_sub_u32_e32 v150, 0, v149
	s_and_b64 vcc, s[16:17], vcc
	v_max_i32_e32 v149, v149, v150
	v_cndmask_b32_e32 v71, v212, v71, vcc
	v_cmp_gt_u32_e32 vcc, s84, v149
	v_cvt_f32_u32_e32 v149, v149
	v_cmp_le_i32_e64 s[16:17], s89, v109
	s_and_b64 s[16:17], vcc, s[16:17]
	v_cmp_gt_i32_e32 vcc, s91, v109
	v_add_u32_e32 v109, 0x101, v146
	v_fma_f32 v56, -v145, v149, v56
	v_sub_u32_e32 v149, v178, v109
	v_sub_u32_e32 v150, 0, v149
	s_and_b64 vcc, s[16:17], vcc
	v_max_i32_e32 v149, v149, v150
	v_cndmask_b32_e32 v56, v212, v56, vcc
	v_cmp_gt_u32_e32 vcc, s84, v149
	v_cvt_f32_u32_e32 v149, v149
	v_cmp_le_i32_e64 s[16:17], s89, v109
	s_and_b64 s[16:17], vcc, s[16:17]
	v_cmp_gt_i32_e32 vcc, s91, v109
	v_add_u32_e32 v109, 0x102, v146
	v_fma_f32 v57, -v145, v149, v57
	v_sub_u32_e32 v149, v178, v109
	v_sub_u32_e32 v150, 0, v149
	s_and_b64 vcc, s[16:17], vcc
	v_max_i32_e32 v149, v149, v150
	v_cndmask_b32_e32 v57, v212, v57, vcc
	v_cmp_gt_u32_e32 vcc, s84, v149
	v_cvt_f32_u32_e32 v149, v149
	v_cmp_le_i32_e64 s[16:17], s89, v109
	s_and_b64 s[16:17], vcc, s[16:17]
	v_cmp_gt_i32_e32 vcc, s91, v109
	v_add_u32_e32 v109, 0x103, v146
	v_fma_f32 v58, -v145, v149, v58
	v_sub_u32_e32 v149, v178, v109
	v_sub_u32_e32 v150, 0, v149
	s_and_b64 vcc, s[16:17], vcc
	v_max_i32_e32 v149, v149, v150
	v_cndmask_b32_e32 v58, v212, v58, vcc
	v_cmp_gt_u32_e32 vcc, s84, v149
	v_cvt_f32_u32_e32 v149, v149
	v_cmp_le_i32_e64 s[16:17], s89, v109
	s_and_b64 s[16:17], vcc, s[16:17]
	v_cmp_gt_i32_e32 vcc, s91, v109
	v_add_u32_e32 v109, 0x110, v146
	v_fma_f32 v59, -v145, v149, v59
	v_sub_u32_e32 v149, v178, v109
	v_sub_u32_e32 v150, 0, v149
	s_and_b64 vcc, s[16:17], vcc
	v_max_i32_e32 v149, v149, v150
	v_cndmask_b32_e32 v59, v212, v59, vcc
	v_cmp_gt_u32_e32 vcc, s84, v149
	v_cvt_f32_u32_e32 v149, v149
	v_cmp_le_i32_e64 s[16:17], s89, v109
	s_and_b64 s[16:17], vcc, s[16:17]
	v_cmp_gt_i32_e32 vcc, s91, v109
	v_add_u32_e32 v109, 0x111, v146
	v_fma_f32 v48, -v145, v149, v48
	v_sub_u32_e32 v149, v178, v109
	v_sub_u32_e32 v150, 0, v149
	s_and_b64 vcc, s[16:17], vcc
	v_max_i32_e32 v149, v149, v150
	v_cndmask_b32_e32 v48, v212, v48, vcc
	v_cmp_gt_u32_e32 vcc, s84, v149
	v_cvt_f32_u32_e32 v149, v149
	v_max3_f32 v108, v108, v110, v111
	v_max3_f32 v108, v108, v104, v105
	v_cmp_le_i32_e64 s[16:17], s89, v109
	v_max3_f32 v108, v108, v106, v107
	s_and_b64 s[16:17], vcc, s[16:17]
	v_cmp_gt_i32_e32 vcc, s91, v109
	v_add_u32_e32 v109, 0x112, v146
	v_max3_f32 v108, v108, v100, v101
	v_fma_f32 v49, -v145, v149, v49
	v_sub_u32_e32 v149, v178, v109
	v_max3_f32 v108, v108, v102, v103
	v_sub_u32_e32 v150, 0, v149
	v_max3_f32 v108, v108, v96, v97
	s_and_b64 vcc, s[16:17], vcc
	v_max_i32_e32 v149, v149, v150
	v_max3_f32 v108, v108, v98, v99
	v_cndmask_b32_e32 v49, v212, v49, vcc
	v_cmp_gt_u32_e32 vcc, s84, v149
	v_cvt_f32_u32_e32 v149, v149
	v_max3_f32 v108, v108, v92, v93
	v_cmp_le_i32_e64 s[16:17], s89, v109
	v_max3_f32 v108, v108, v94, v95
	s_and_b64 s[16:17], vcc, s[16:17]
	v_cmp_gt_i32_e32 vcc, s91, v109
	v_add_u32_e32 v109, 0x113, v146
	v_max3_f32 v108, v108, v88, v89
	v_sub_u32_e32 v146, v178, v109
	v_max3_f32 v108, v108, v90, v91
	v_fma_f32 v50, -v145, v149, v50
	v_sub_u32_e32 v149, 0, v146
	v_max3_f32 v108, v108, v76, v77
	s_and_b64 vcc, s[16:17], vcc
	v_max_i32_e32 v146, v146, v149
	v_max3_f32 v108, v108, v78, v79
	v_cndmask_b32_e32 v50, v212, v50, vcc
	v_cmp_gt_u32_e32 vcc, s84, v146
	v_cvt_f32_u32_e32 v146, v146
	v_max3_f32 v108, v108, v68, v69
	v_max3_f32 v108, v108, v70, v71
	v_cmp_le_i32_e64 s[16:17], s89, v109
	v_max3_f32 v108, v108, v56, v57
	s_and_b64 s[16:17], vcc, s[16:17]
	v_cmp_gt_i32_e32 vcc, s91, v109
	v_max3_f32 v108, v108, v58, v59
	v_fma_f32 v51, -v145, v146, v51
	s_and_b64 vcc, s[16:17], vcc
	v_max3_f32 v108, v108, v48, v49
	v_cndmask_b32_e32 v51, v212, v51, vcc
	v_and_b32_e32 v145, 64, v213
	v_max3_f32 v109, v108, v50, v51
	v_xor_b32_e32 v108, 16, v213
	v_add_u32_e32 v145, 64, v145
	v_cmp_lt_i32_e32 vcc, v108, v145
	s_waitcnt vmcnt(0)
	v_mul_f32_e32 v149, 0x3fb8aa3b, v144
	s_add_i32 s14, s56, 2
	v_cndmask_b32_e32 v108, v213, v108, vcc
	v_lshlrev_b32_e32 v108, 2, v108
	ds_bpermute_b32 v146, v108, v109
	s_waitcnt lgkmcnt(0)
	v_max_f32_e32 v146, v146, v146
	v_max_f32_e32 v146, v109, v146
	v_xor_b32_e32 v109, 32, v213
	v_cmp_lt_i32_e32 vcc, v109, v145
	s_nop 1
	v_cndmask_b32_e32 v109, v213, v109, vcc
	v_lshlrev_b32_e32 v109, 2, v109
	ds_bpermute_b32 v145, v109, v146
	s_waitcnt lgkmcnt(0)
	v_max3_f32 v145, v146, v145, v149
	v_sub_f32_e32 v140, v140, v145
	v_exp_f32_e32 v140, v140
	v_sub_f32_e32 v141, v141, v145
	v_exp_f32_e32 v141, v141
	v_sub_f32_e32 v142, v142, v145
	v_exp_f32_e32 v142, v142
	v_sub_f32_e32 v143, v143, v145
	v_exp_f32_e32 v143, v143
	v_sub_f32_e32 v136, v136, v145
	v_add_f32_e32 v146, 0, v140
	v_exp_f32_e32 v136, v136
	v_sub_f32_e32 v137, v137, v145
	v_add_f32_e32 v146, v141, v146
	v_exp_f32_e32 v137, v137
	v_sub_f32_e32 v138, v138, v145
	v_add_f32_e32 v146, v142, v146
	v_exp_f32_e32 v138, v138
	v_sub_f32_e32 v139, v139, v145
	v_add_f32_e32 v146, v143, v146
	v_exp_f32_e32 v139, v139
	v_sub_f32_e32 v132, v132, v145
	v_add_f32_e32 v146, v136, v146
	v_exp_f32_e32 v132, v132
	v_sub_f32_e32 v133, v133, v145
	v_add_f32_e32 v146, v137, v146
	v_exp_f32_e32 v133, v133
	v_sub_f32_e32 v134, v134, v145
	v_add_f32_e32 v146, v138, v146
	v_exp_f32_e32 v134, v134
	v_sub_f32_e32 v135, v135, v145
	v_add_f32_e32 v146, v139, v146
	v_exp_f32_e32 v135, v135
	v_sub_f32_e32 v128, v128, v145
	v_add_f32_e32 v146, v132, v146
	v_exp_f32_e32 v128, v128
	v_sub_f32_e32 v129, v129, v145
	v_add_f32_e32 v146, v133, v146
	v_exp_f32_e32 v129, v129
	v_sub_f32_e32 v130, v130, v145
	v_add_f32_e32 v146, v134, v146
	v_exp_f32_e32 v130, v130
	v_sub_f32_e32 v131, v131, v145
	v_add_f32_e32 v146, v135, v146
	v_exp_f32_e32 v131, v131
	v_sub_f32_e32 v124, v124, v145
	v_add_f32_e32 v146, v128, v146
	v_exp_f32_e32 v124, v124
	v_sub_f32_e32 v125, v125, v145
	v_add_f32_e32 v146, v129, v146
	v_exp_f32_e32 v125, v125
	v_sub_f32_e32 v126, v126, v145
	v_add_f32_e32 v146, v130, v146
	v_exp_f32_e32 v126, v126
	v_sub_f32_e32 v127, v127, v145
	v_add_f32_e32 v146, v131, v146
	v_exp_f32_e32 v127, v127
	v_sub_f32_e32 v120, v120, v145
	v_add_f32_e32 v146, v124, v146
	v_exp_f32_e32 v120, v120
	v_sub_f32_e32 v121, v121, v145
	v_add_f32_e32 v146, v125, v146
	v_exp_f32_e32 v121, v121
	v_sub_f32_e32 v122, v122, v145
	v_add_f32_e32 v146, v126, v146
	v_exp_f32_e32 v122, v122
	v_sub_f32_e32 v123, v123, v145
	v_add_f32_e32 v146, v127, v146
	v_exp_f32_e32 v123, v123
	v_sub_f32_e32 v116, v116, v145
	v_add_f32_e32 v146, v120, v146
	v_exp_f32_e32 v116, v116
	v_sub_f32_e32 v117, v117, v145
	v_add_f32_e32 v146, v121, v146
	v_exp_f32_e32 v117, v117
	v_sub_f32_e32 v118, v118, v145
	v_add_f32_e32 v146, v122, v146
	v_exp_f32_e32 v118, v118
	v_sub_f32_e32 v119, v119, v145
	v_add_f32_e32 v146, v123, v146
	v_exp_f32_e32 v119, v119
	v_sub_f32_e32 v112, v112, v145
	v_add_f32_e32 v146, v116, v146
	v_exp_f32_e32 v149, v112
	v_add_f32_e32 v146, v117, v146
	v_sub_f32_e32 v112, v113, v145
	v_add_f32_e32 v146, v118, v146
	v_exp_f32_e32 v113, v112
	v_sub_f32_e32 v112, v114, v145
	v_add_f32_e32 v146, v119, v146
	v_exp_f32_e32 v114, v112
	v_sub_f32_e32 v112, v115, v145
	v_exp_f32_e32 v115, v112
	v_add_f32_e32 v112, v149, v146
	v_sub_f32_e32 v146, v147, v145
	v_exp_f32_e32 v146, v146
	v_sub_f32_e32 v147, v148, v145
	v_add_f32_e32 v112, v113, v112
	v_exp_f32_e32 v147, v147
	v_sub_f32_e32 v110, v110, v145
	v_add_f32_e32 v112, v114, v112
	v_exp_f32_e32 v110, v110
	v_sub_f32_e32 v111, v111, v145
	v_add_f32_e32 v112, v115, v112
	v_exp_f32_e32 v148, v111
	v_sub_f32_e32 v104, v104, v145
	v_add_f32_e32 v111, v146, v112
	v_exp_f32_e32 v150, v104
	v_sub_f32_e32 v104, v105, v145
	v_add_f32_e32 v111, v147, v111
	v_exp_f32_e32 v151, v104
	v_sub_f32_e32 v104, v106, v145
	v_add_f32_e32 v111, v110, v111
	v_exp_f32_e32 v152, v104
	v_sub_f32_e32 v104, v107, v145
	v_add_f32_e32 v111, v148, v111
	v_exp_f32_e32 v153, v104
	v_sub_f32_e32 v100, v100, v145
	v_add_f32_e32 v104, v150, v111
	v_exp_f32_e32 v154, v100
	v_sub_f32_e32 v100, v101, v145
	v_add_f32_e32 v104, v151, v104
	v_exp_f32_e32 v155, v100
	v_sub_f32_e32 v100, v102, v145
	v_add_f32_e32 v104, v152, v104
	v_exp_f32_e32 v156, v100
	v_sub_f32_e32 v100, v103, v145
	v_add_f32_e32 v104, v153, v104
	v_exp_f32_e32 v157, v100
	v_sub_f32_e32 v96, v96, v145
	v_add_f32_e32 v100, v154, v104
	v_exp_f32_e32 v158, v96
	v_sub_f32_e32 v96, v97, v145
	v_add_f32_e32 v100, v155, v100
	v_exp_f32_e32 v159, v96
	v_sub_f32_e32 v96, v98, v145
	v_add_f32_e32 v100, v156, v100
	v_exp_f32_e32 v160, v96
	v_sub_f32_e32 v96, v99, v145
	v_add_f32_e32 v100, v157, v100
	v_exp_f32_e32 v161, v96
	v_sub_f32_e32 v92, v92, v145
	v_add_f32_e32 v96, v158, v100
	v_exp_f32_e32 v162, v92
	v_sub_f32_e32 v92, v93, v145
	v_add_f32_e32 v96, v159, v96
	v_exp_f32_e32 v163, v92
	v_sub_f32_e32 v92, v94, v145
	v_add_f32_e32 v96, v160, v96
	v_exp_f32_e32 v164, v92
	v_sub_f32_e32 v92, v95, v145
	v_add_f32_e32 v96, v161, v96
	v_exp_f32_e32 v165, v92
	v_sub_f32_e32 v88, v88, v145
	v_add_f32_e32 v92, v162, v96
	v_exp_f32_e32 v166, v88
	v_sub_f32_e32 v88, v89, v145
	v_add_f32_e32 v92, v163, v92
	v_exp_f32_e32 v167, v88
	v_sub_f32_e32 v88, v90, v145
	v_add_f32_e32 v92, v164, v92
	v_exp_f32_e32 v168, v88
	v_sub_f32_e32 v88, v91, v145
	v_add_f32_e32 v92, v165, v92
	v_exp_f32_e32 v214, v88
	v_sub_f32_e32 v76, v76, v145
	v_add_f32_e32 v88, v166, v92
	v_exp_f32_e32 v215, v76
	v_sub_f32_e32 v76, v77, v145
	v_add_f32_e32 v88, v167, v88
	v_exp_f32_e32 v216, v76
	v_sub_f32_e32 v76, v78, v145
	v_add_f32_e32 v88, v168, v88
	v_exp_f32_e32 v217, v76
	v_sub_f32_e32 v76, v79, v145
	v_add_f32_e32 v88, v214, v88
	v_exp_f32_e32 v218, v76
	v_sub_f32_e32 v68, v68, v145
	v_add_f32_e32 v76, v215, v88
	v_exp_f32_e32 v219, v68
	v_sub_f32_e32 v68, v69, v145
	v_add_f32_e32 v76, v216, v76
	v_exp_f32_e32 v220, v68
	v_sub_f32_e32 v68, v70, v145
	v_add_f32_e32 v76, v217, v76
	v_exp_f32_e32 v221, v68
	v_sub_f32_e32 v68, v71, v145
	v_add_f32_e32 v76, v218, v76
	v_exp_f32_e32 v222, v68
	v_sub_f32_e32 v56, v56, v145
	v_add_f32_e32 v68, v219, v76
	v_exp_f32_e32 v223, v56
	v_sub_f32_e32 v56, v57, v145
	v_add_f32_e32 v68, v220, v68
	v_exp_f32_e32 v225, v56
	v_sub_f32_e32 v56, v58, v145
	v_add_f32_e32 v68, v221, v68
	v_exp_f32_e32 v226, v56
	v_sub_f32_e32 v56, v59, v145
	v_add_f32_e32 v68, v222, v68
	v_exp_f32_e32 v227, v56
	v_sub_f32_e32 v48, v48, v145
	v_add_f32_e32 v56, v223, v68
	v_exp_f32_e32 v228, v48
	v_sub_f32_e32 v48, v49, v145
	v_add_f32_e32 v56, v225, v56
	v_exp_f32_e32 v229, v48
	v_sub_f32_e32 v48, v50, v145
	v_add_f32_e32 v56, v226, v56
	v_exp_f32_e32 v230, v48
	v_sub_f32_e32 v48, v51, v145
	v_add_f32_e32 v56, v227, v56
	v_exp_f32_e32 v51, v48
	v_add_f32_e32 v48, v228, v56
	v_add_f32_e32 v48, v229, v48
	v_add_f32_e32 v48, v230, v48
	v_add_f32_e32 v48, v51, v48
	s_nop 2
	v_cvt_pk_bf16_f32 v104, v140, v141
	s_nop 2
	v_cvt_pk_bf16_f32 v105, v142, v143
	s_nop 2
	v_cvt_pk_bf16_f32 v106, v136, v137
	s_nop 2
	v_cvt_pk_bf16_f32 v107, v138, v139
	s_nop 2
	v_cvt_pk_bf16_f32 v100, v132, v133
	s_nop 2
	v_cvt_pk_bf16_f32 v101, v134, v135
	s_nop 2
	v_cvt_pk_bf16_f32 v102, v128, v129
	s_nop 2
	v_cvt_pk_bf16_f32 v103, v130, v131
	s_nop 2
	v_cvt_pk_bf16_f32 v96, v124, v125
	s_nop 2
	v_cvt_pk_bf16_f32 v97, v126, v127
	s_nop 2
	v_cvt_pk_bf16_f32 v98, v120, v121
	s_nop 2
	v_cvt_pk_bf16_f32 v99, v122, v123
	s_nop 2
	v_cvt_pk_bf16_f32 v92, v116, v117
	s_nop 2
	v_cvt_pk_bf16_f32 v93, v118, v119
	s_nop 2
	v_cvt_pk_bf16_f32 v94, v149, v113
	s_nop 2
	v_cvt_pk_bf16_f32 v95, v114, v115
	s_nop 2
	v_cvt_pk_bf16_f32 v88, v146, v147
	s_nop 2
	v_cvt_pk_bf16_f32 v89, v110, v148
	v_cvt_f32_u32_e32 v110, s14
	ds_bpermute_b32 v49, v108, v48
	v_mov_b32_e32 v114, v179
	s_nop 2
	v_cvt_pk_bf16_f32 v90, v150, v151
	v_mul_f32_e32 v113, -0.5, v110
	v_cmp_gt_f32_e32 vcc, s76, v113
	s_waitcnt lgkmcnt(0)
	v_add_f32_e32 v48, v48, v49
	ds_bpermute_b32 v49, v109, v48
	v_cndmask_b32_e32 v113, 0, v211, vcc
	v_fmac_f32_e32 v113, -0.5, v110
	v_exp_f32_e32 v110, v113
	s_and_b64 s[16:17], vcc, exec
	s_cselect_b32 s14, 0xffffffc0, 0
	s_waitcnt lgkmcnt(0)
	v_add_f32_e32 v111, v48, v49
	v_fma_f32 v48, v144, s81, -v145
	v_ldexp_f32 v110, v110, s14
	v_exp_f32_e32 v112, v48
	s_nop 2
	v_cvt_pk_bf16_f32 v91, v152, v153
	s_nop 2
	v_cvt_pk_bf16_f32 v76, v154, v155
	s_nop 2
	v_cvt_pk_bf16_f32 v77, v156, v157
	s_nop 2
	v_cvt_pk_bf16_f32 v78, v158, v159
	s_nop 2
	v_cvt_pk_bf16_f32 v79, v160, v161
	s_nop 2
	v_cvt_pk_bf16_f32 v68, v162, v163
	s_nop 2
	v_cvt_pk_bf16_f32 v69, v164, v165
	s_nop 2
	v_cvt_pk_bf16_f32 v70, v166, v167
	s_nop 2
	v_cvt_pk_bf16_f32 v71, v168, v214
	s_nop 2
	v_cvt_pk_bf16_f32 v56, v215, v216
	s_nop 2
	v_cvt_pk_bf16_f32 v57, v217, v218
	s_nop 2
	v_cvt_pk_bf16_f32 v58, v219, v220
	s_nop 2
	v_cvt_pk_bf16_f32 v59, v221, v222
	s_nop 2
	v_cvt_pk_bf16_f32 v48, v223, v225
	s_nop 2
	v_cvt_pk_bf16_f32 v49, v226, v227
	s_nop 2
	v_cvt_pk_bf16_f32 v50, v228, v229
	s_nop 2
	v_cvt_pk_bf16_f32 v51, v230, v51
	v_mul_f32_e32 v113, 0x3fb8aa3b, v110
	global_load_dword v110, v169, s[64:65] offset:4
	v_add_f32_e32 v111, v112, v111
	v_add_u32_e32 v114, v114, v197
	v_sub_u32_e32 v115, v178, v114
	v_sub_u32_e32 v116, 0, v115
	v_max_i32_e32 v115, v115, v116
	v_cmp_gt_u32_e32 vcc, s84, v115
	v_cvt_f32_u32_e32 v115, v115
	v_cmp_le_i32_e64 s[16:17], s89, v114
	s_and_b64 s[16:17], vcc, s[16:17]
	v_cmp_gt_i32_e32 vcc, s91, v114
	v_fma_f32 v84, -v113, v115, v84
	v_add_u32_e32 v115, 1, v114
	v_sub_u32_e32 v116, v178, v115
	v_sub_u32_e32 v117, 0, v116
	s_and_b64 vcc, s[16:17], vcc
	v_max_i32_e32 v116, v116, v117
	v_cndmask_b32_e32 v84, v212, v84, vcc
	v_cmp_gt_u32_e32 vcc, s84, v116
	v_cvt_f32_u32_e32 v116, v116
	v_cmp_le_i32_e64 s[16:17], s89, v115
	s_and_b64 s[16:17], vcc, s[16:17]
	v_cmp_gt_i32_e32 vcc, s91, v115
	v_fma_f32 v85, -v113, v116, v85
	v_add_u32_e32 v116, 2, v114
	v_sub_u32_e32 v117, v178, v116
	v_sub_u32_e32 v118, 0, v117
	s_and_b64 vcc, s[16:17], vcc
	v_max_i32_e32 v117, v117, v118
	v_cndmask_b32_e32 v85, v212, v85, vcc
	v_cmp_gt_u32_e32 vcc, s84, v117
	v_cvt_f32_u32_e32 v117, v117
	v_cmp_le_i32_e64 s[16:17], s89, v116
	s_and_b64 s[16:17], vcc, s[16:17]
	v_cmp_gt_i32_e32 vcc, s91, v116
	v_add_u32_e32 v116, 3, v114
	v_fma_f32 v86, -v113, v117, v86
	v_sub_u32_e32 v117, v178, v116
	v_sub_u32_e32 v118, 0, v117
	s_and_b64 vcc, s[16:17], vcc
	v_max_i32_e32 v117, v117, v118
	v_cndmask_b32_e32 v86, v212, v86, vcc
	v_cmp_gt_u32_e32 vcc, s84, v117
	v_cvt_f32_u32_e32 v117, v117
	v_cmp_le_i32_e64 s[16:17], s89, v116
	s_and_b64 s[16:17], vcc, s[16:17]
	v_cmp_gt_i32_e32 vcc, s91, v116
	v_add_u32_e32 v116, 16, v114
	v_fma_f32 v87, -v113, v117, v87
	v_sub_u32_e32 v117, v178, v116
	v_sub_u32_e32 v118, 0, v117
	s_and_b64 vcc, s[16:17], vcc
	v_max_i32_e32 v117, v117, v118
	v_cndmask_b32_e32 v87, v212, v87, vcc
	v_cmp_gt_u32_e32 vcc, s84, v117
	v_cvt_f32_u32_e32 v117, v117
	v_cmp_le_i32_e64 s[16:17], s89, v116
	s_and_b64 s[16:17], vcc, s[16:17]
	v_cmp_gt_i32_e32 vcc, s91, v116
	v_add_u32_e32 v116, 17, v114
	v_fma_f32 v80, -v113, v117, v80
	v_sub_u32_e32 v117, v178, v116
	v_sub_u32_e32 v118, 0, v117
	s_and_b64 vcc, s[16:17], vcc
	v_max_i32_e32 v117, v117, v118
	v_cndmask_b32_e32 v80, v212, v80, vcc
	v_cmp_gt_u32_e32 vcc, s84, v117
	v_cvt_f32_u32_e32 v117, v117
	v_cmp_le_i32_e64 s[16:17], s89, v116
	s_and_b64 s[16:17], vcc, s[16:17]
	v_cmp_gt_i32_e32 vcc, s91, v116
	v_add_u32_e32 v116, 18, v114
	v_fma_f32 v81, -v113, v117, v81
	v_sub_u32_e32 v117, v178, v116
	v_sub_u32_e32 v118, 0, v117
	s_and_b64 vcc, s[16:17], vcc
	v_max_i32_e32 v117, v117, v118
	v_cndmask_b32_e32 v81, v212, v81, vcc
	v_cmp_gt_u32_e32 vcc, s84, v117
	v_cvt_f32_u32_e32 v117, v117
	v_cmp_le_i32_e64 s[16:17], s89, v116
	s_and_b64 s[16:17], vcc, s[16:17]
	v_cmp_gt_i32_e32 vcc, s91, v116
	v_add_u32_e32 v116, 19, v114
	v_fma_f32 v82, -v113, v117, v82
	v_sub_u32_e32 v117, v178, v116
	v_sub_u32_e32 v118, 0, v117
	s_and_b64 vcc, s[16:17], vcc
	v_max_i32_e32 v117, v117, v118
	v_cndmask_b32_e32 v82, v212, v82, vcc
	v_cmp_gt_u32_e32 vcc, s84, v117
	v_cvt_f32_u32_e32 v117, v117
	v_cmp_le_i32_e64 s[16:17], s89, v116
	s_and_b64 s[16:17], vcc, s[16:17]
	v_cmp_gt_i32_e32 vcc, s91, v116
	v_add_u32_e32 v116, 32, v114
	v_fma_f32 v83, -v113, v117, v83
	v_sub_u32_e32 v117, v178, v116
	v_sub_u32_e32 v118, 0, v117
	s_and_b64 vcc, s[16:17], vcc
	v_max_i32_e32 v117, v117, v118
	v_cndmask_b32_e32 v83, v212, v83, vcc
	v_cmp_gt_u32_e32 vcc, s84, v117
	v_cvt_f32_u32_e32 v117, v117
	v_cmp_le_i32_e64 s[16:17], s89, v116
	s_and_b64 s[16:17], vcc, s[16:17]
	v_cmp_gt_i32_e32 vcc, s91, v116
	v_add_u32_e32 v116, 33, v114
	v_fma_f32 v72, -v113, v117, v72
	v_sub_u32_e32 v117, v178, v116
	v_sub_u32_e32 v118, 0, v117
	s_and_b64 vcc, s[16:17], vcc
	v_max_i32_e32 v117, v117, v118
	v_cndmask_b32_e32 v72, v212, v72, vcc
	v_cmp_gt_u32_e32 vcc, s84, v117
	v_cvt_f32_u32_e32 v117, v117
	v_cmp_le_i32_e64 s[16:17], s89, v116
	s_and_b64 s[16:17], vcc, s[16:17]
	v_cmp_gt_i32_e32 vcc, s91, v116
	v_add_u32_e32 v116, 34, v114
	v_fma_f32 v73, -v113, v117, v73
	v_sub_u32_e32 v117, v178, v116
	v_sub_u32_e32 v118, 0, v117
	s_and_b64 vcc, s[16:17], vcc
	v_max_i32_e32 v117, v117, v118
	v_cndmask_b32_e32 v73, v212, v73, vcc
	v_cmp_gt_u32_e32 vcc, s84, v117
	v_cvt_f32_u32_e32 v117, v117
	v_cmp_le_i32_e64 s[16:17], s89, v116
	s_and_b64 s[16:17], vcc, s[16:17]
	v_cmp_gt_i32_e32 vcc, s91, v116
	v_add_u32_e32 v116, 35, v114
	v_fma_f32 v74, -v113, v117, v74
	v_sub_u32_e32 v117, v178, v116
	v_sub_u32_e32 v118, 0, v117
	s_and_b64 vcc, s[16:17], vcc
	v_max_i32_e32 v117, v117, v118
	v_cndmask_b32_e32 v74, v212, v74, vcc
	v_cmp_gt_u32_e32 vcc, s84, v117
	v_cvt_f32_u32_e32 v117, v117
	v_cmp_le_i32_e64 s[16:17], s89, v116
	s_and_b64 s[16:17], vcc, s[16:17]
	v_cmp_gt_i32_e32 vcc, s91, v116
	v_add_u32_e32 v116, 48, v114
	v_fma_f32 v75, -v113, v117, v75
	v_sub_u32_e32 v117, v178, v116
	v_sub_u32_e32 v118, 0, v117
	s_and_b64 vcc, s[16:17], vcc
	v_max_i32_e32 v117, v117, v118
	v_cndmask_b32_e32 v75, v212, v75, vcc
	v_cmp_gt_u32_e32 vcc, s84, v117
	v_cvt_f32_u32_e32 v117, v117
	v_cmp_le_i32_e64 s[16:17], s89, v116
	s_and_b64 s[16:17], vcc, s[16:17]
	v_cmp_gt_i32_e32 vcc, s91, v116
	v_add_u32_e32 v116, 49, v114
	v_fma_f32 v64, -v113, v117, v64
	v_sub_u32_e32 v117, v178, v116
	v_sub_u32_e32 v118, 0, v117
	s_and_b64 vcc, s[16:17], vcc
	v_max_i32_e32 v117, v117, v118
	v_cndmask_b32_e32 v64, v212, v64, vcc
	v_cmp_gt_u32_e32 vcc, s84, v117
	v_cvt_f32_u32_e32 v117, v117
	v_cmp_le_i32_e64 s[16:17], s89, v116
	s_and_b64 s[16:17], vcc, s[16:17]
	v_cmp_gt_i32_e32 vcc, s91, v116
	v_add_u32_e32 v116, 50, v114
	v_fma_f32 v65, -v113, v117, v65
	v_sub_u32_e32 v117, v178, v116
	v_sub_u32_e32 v118, 0, v117
	s_and_b64 vcc, s[16:17], vcc
	v_max_i32_e32 v117, v117, v118
	v_cndmask_b32_e32 v65, v212, v65, vcc
	v_cmp_gt_u32_e32 vcc, s84, v117
	v_cvt_f32_u32_e32 v117, v117
	v_cmp_le_i32_e64 s[16:17], s89, v116
	s_and_b64 s[16:17], vcc, s[16:17]
	v_cmp_gt_i32_e32 vcc, s91, v116
	v_add_u32_e32 v116, 51, v114
	v_fma_f32 v66, -v113, v117, v66
	v_sub_u32_e32 v117, v178, v116
	v_sub_u32_e32 v118, 0, v117
	s_and_b64 vcc, s[16:17], vcc
	v_max_i32_e32 v117, v117, v118
	v_cndmask_b32_e32 v66, v212, v66, vcc
	v_cmp_gt_u32_e32 vcc, s84, v117
	v_cvt_f32_u32_e32 v117, v117
	v_cmp_le_i32_e64 s[16:17], s89, v116
	s_and_b64 s[16:17], vcc, s[16:17]
	v_cmp_gt_i32_e32 vcc, s91, v116
	v_add_u32_e32 v116, 64, v114
	v_fma_f32 v67, -v113, v117, v67
	v_sub_u32_e32 v117, v178, v116
	v_sub_u32_e32 v118, 0, v117
	s_and_b64 vcc, s[16:17], vcc
	v_max_i32_e32 v117, v117, v118
	v_cndmask_b32_e32 v67, v212, v67, vcc
	v_cmp_gt_u32_e32 vcc, s84, v117
	v_cvt_f32_u32_e32 v117, v117
	v_cmp_le_i32_e64 s[16:17], s89, v116
	s_and_b64 s[16:17], vcc, s[16:17]
	v_cmp_gt_i32_e32 vcc, s91, v116
	v_add_u32_e32 v116, 0x41, v114
	v_fma_f32 v60, -v113, v117, v60
	v_sub_u32_e32 v117, v178, v116
	v_sub_u32_e32 v118, 0, v117
	s_and_b64 vcc, s[16:17], vcc
	v_max_i32_e32 v117, v117, v118
	v_cndmask_b32_e32 v60, v212, v60, vcc
	v_cmp_gt_u32_e32 vcc, s84, v117
	v_cvt_f32_u32_e32 v117, v117
	v_cmp_le_i32_e64 s[16:17], s89, v116
	s_and_b64 s[16:17], vcc, s[16:17]
	v_cmp_gt_i32_e32 vcc, s91, v116
	v_add_u32_e32 v116, 0x42, v114
	v_fma_f32 v61, -v113, v117, v61
	v_sub_u32_e32 v117, v178, v116
	v_sub_u32_e32 v118, 0, v117
	s_and_b64 vcc, s[16:17], vcc
	v_max_i32_e32 v117, v117, v118
	v_cndmask_b32_e32 v61, v212, v61, vcc
	v_cmp_gt_u32_e32 vcc, s84, v117
	v_cvt_f32_u32_e32 v117, v117
	v_cmp_le_i32_e64 s[16:17], s89, v116
	s_and_b64 s[16:17], vcc, s[16:17]
	v_cmp_gt_i32_e32 vcc, s91, v116
	v_add_u32_e32 v116, 0x43, v114
	v_fma_f32 v62, -v113, v117, v62
	v_sub_u32_e32 v117, v178, v116
	v_sub_u32_e32 v118, 0, v117
	s_and_b64 vcc, s[16:17], vcc
	v_max_i32_e32 v117, v117, v118
	v_cndmask_b32_e32 v62, v212, v62, vcc
	v_cmp_gt_u32_e32 vcc, s84, v117
	v_cvt_f32_u32_e32 v117, v117
	v_cmp_le_i32_e64 s[16:17], s89, v116
	s_and_b64 s[16:17], vcc, s[16:17]
	v_cmp_gt_i32_e32 vcc, s91, v116
	v_add_u32_e32 v116, 0x50, v114
	v_fma_f32 v63, -v113, v117, v63
	v_sub_u32_e32 v117, v178, v116
	v_sub_u32_e32 v118, 0, v117
	s_and_b64 vcc, s[16:17], vcc
	v_max_i32_e32 v117, v117, v118
	v_cndmask_b32_e32 v63, v212, v63, vcc
	v_cmp_gt_u32_e32 vcc, s84, v117
	v_cvt_f32_u32_e32 v117, v117
	v_cmp_le_i32_e64 s[16:17], s89, v116
	s_and_b64 s[16:17], vcc, s[16:17]
	v_cmp_gt_i32_e32 vcc, s91, v116
	v_add_u32_e32 v116, 0x51, v114
	v_fma_f32 v52, -v113, v117, v52
	v_sub_u32_e32 v117, v178, v116
	v_sub_u32_e32 v118, 0, v117
	s_and_b64 vcc, s[16:17], vcc
	v_max_i32_e32 v117, v117, v118
	v_cndmask_b32_e32 v52, v212, v52, vcc
	v_cmp_gt_u32_e32 vcc, s84, v117
	v_cvt_f32_u32_e32 v117, v117
	v_cmp_le_i32_e64 s[16:17], s89, v116
	s_and_b64 s[16:17], vcc, s[16:17]
	v_cmp_gt_i32_e32 vcc, s91, v116
	v_add_u32_e32 v116, 0x52, v114
	v_fma_f32 v53, -v113, v117, v53
	v_sub_u32_e32 v117, v178, v116
	v_sub_u32_e32 v118, 0, v117
	s_and_b64 vcc, s[16:17], vcc
	v_max_i32_e32 v117, v117, v118
	v_cndmask_b32_e32 v53, v212, v53, vcc
	v_cmp_gt_u32_e32 vcc, s84, v117
	v_cvt_f32_u32_e32 v117, v117
	v_cmp_le_i32_e64 s[16:17], s89, v116
	s_and_b64 s[16:17], vcc, s[16:17]
	v_cmp_gt_i32_e32 vcc, s91, v116
	v_add_u32_e32 v116, 0x53, v114
	v_fma_f32 v54, -v113, v117, v54
	v_sub_u32_e32 v117, v178, v116
	v_sub_u32_e32 v118, 0, v117
	s_and_b64 vcc, s[16:17], vcc
	v_max_i32_e32 v117, v117, v118
	v_cndmask_b32_e32 v54, v212, v54, vcc
	v_cmp_gt_u32_e32 vcc, s84, v117
	v_cvt_f32_u32_e32 v117, v117
	v_cmp_le_i32_e64 s[16:17], s89, v116
	s_and_b64 s[16:17], vcc, s[16:17]
	v_cmp_gt_i32_e32 vcc, s91, v116
	v_add_u32_e32 v116, 0x60, v114
	v_fma_f32 v55, -v113, v117, v55
	v_sub_u32_e32 v117, v178, v116
	v_sub_u32_e32 v118, 0, v117
	s_and_b64 vcc, s[16:17], vcc
	v_max_i32_e32 v117, v117, v118
	v_cndmask_b32_e32 v55, v212, v55, vcc
	v_cmp_gt_u32_e32 vcc, s84, v117
	v_cvt_f32_u32_e32 v117, v117
	v_cmp_le_i32_e64 s[16:17], s89, v116
	s_and_b64 s[16:17], vcc, s[16:17]
	v_cmp_gt_i32_e32 vcc, s91, v116
	v_add_u32_e32 v116, 0x61, v114
	v_fma_f32 v44, -v113, v117, v44
	v_sub_u32_e32 v117, v178, v116
	v_sub_u32_e32 v118, 0, v117
	s_and_b64 vcc, s[16:17], vcc
	v_max_i32_e32 v117, v117, v118
	v_cndmask_b32_e32 v44, v212, v44, vcc
	v_cmp_gt_u32_e32 vcc, s84, v117
	v_cvt_f32_u32_e32 v117, v117
	v_cmp_le_i32_e64 s[16:17], s89, v116
	s_and_b64 s[16:17], vcc, s[16:17]
	v_cmp_gt_i32_e32 vcc, s91, v116
	v_add_u32_e32 v116, 0x62, v114
	v_fma_f32 v45, -v113, v117, v45
	v_sub_u32_e32 v117, v178, v116
	v_sub_u32_e32 v118, 0, v117
	s_and_b64 vcc, s[16:17], vcc
	v_max_i32_e32 v117, v117, v118
	v_cndmask_b32_e32 v45, v212, v45, vcc
	v_cmp_gt_u32_e32 vcc, s84, v117
	v_cvt_f32_u32_e32 v117, v117
	v_cmp_le_i32_e64 s[16:17], s89, v116
	s_and_b64 s[16:17], vcc, s[16:17]
	v_cmp_gt_i32_e32 vcc, s91, v116
	v_add_u32_e32 v116, 0x63, v114
	v_fma_f32 v46, -v113, v117, v46
	v_sub_u32_e32 v117, v178, v116
	v_sub_u32_e32 v118, 0, v117
	s_and_b64 vcc, s[16:17], vcc
	v_max_i32_e32 v117, v117, v118
	v_cndmask_b32_e32 v46, v212, v46, vcc
	v_cmp_gt_u32_e32 vcc, s84, v117
	v_cvt_f32_u32_e32 v117, v117
	v_cmp_le_i32_e64 s[16:17], s89, v116
	s_and_b64 s[16:17], vcc, s[16:17]
	v_cmp_gt_i32_e32 vcc, s91, v116
	v_add_u32_e32 v116, 0x70, v114
	v_fma_f32 v47, -v113, v117, v47
	v_sub_u32_e32 v117, v178, v116
	v_sub_u32_e32 v118, 0, v117
	s_and_b64 vcc, s[16:17], vcc
	v_max_i32_e32 v117, v117, v118
	v_cndmask_b32_e32 v47, v212, v47, vcc
	v_cmp_gt_u32_e32 vcc, s84, v117
	v_cvt_f32_u32_e32 v117, v117
	v_cmp_le_i32_e64 s[16:17], s89, v116
	s_and_b64 s[16:17], vcc, s[16:17]
	v_cmp_gt_i32_e32 vcc, s91, v116
	v_add_u32_e32 v116, 0x71, v114
	v_fma_f32 v40, -v113, v117, v40
	v_sub_u32_e32 v117, v178, v116
	v_sub_u32_e32 v118, 0, v117
	s_and_b64 vcc, s[16:17], vcc
	v_max_i32_e32 v117, v117, v118
	v_cndmask_b32_e32 v40, v212, v40, vcc
	v_cmp_gt_u32_e32 vcc, s84, v117
	v_cvt_f32_u32_e32 v117, v117
	v_cmp_le_i32_e64 s[16:17], s89, v116
	s_and_b64 s[16:17], vcc, s[16:17]
	v_cmp_gt_i32_e32 vcc, s91, v116
	v_add_u32_e32 v116, 0x72, v114
	v_fma_f32 v41, -v113, v117, v41
	v_sub_u32_e32 v117, v178, v116
	v_sub_u32_e32 v118, 0, v117
	s_and_b64 vcc, s[16:17], vcc
	v_max_i32_e32 v117, v117, v118
	v_cndmask_b32_e32 v41, v212, v41, vcc
	v_cmp_gt_u32_e32 vcc, s84, v117
	v_cvt_f32_u32_e32 v117, v117
	v_cmp_le_i32_e64 s[16:17], s89, v116
	s_and_b64 s[16:17], vcc, s[16:17]
	v_cmp_gt_i32_e32 vcc, s91, v116
	v_add_u32_e32 v116, 0x73, v114
	v_fma_f32 v42, -v113, v117, v42
	v_sub_u32_e32 v117, v178, v116
	v_sub_u32_e32 v118, 0, v117
	s_and_b64 vcc, s[16:17], vcc
	v_max_i32_e32 v117, v117, v118
	v_cndmask_b32_e32 v42, v212, v42, vcc
	v_cmp_gt_u32_e32 vcc, s84, v117
	v_cvt_f32_u32_e32 v117, v117
	v_cmp_le_i32_e64 s[16:17], s89, v116
	s_and_b64 s[16:17], vcc, s[16:17]
	v_cmp_gt_i32_e32 vcc, s91, v116
	v_add_u32_e32 v116, 0x80, v114
	v_fma_f32 v43, -v113, v117, v43
	v_sub_u32_e32 v117, v178, v116
	v_sub_u32_e32 v118, 0, v117
	s_and_b64 vcc, s[16:17], vcc
	v_max_i32_e32 v117, v117, v118
	v_cndmask_b32_e32 v43, v212, v43, vcc
	v_cmp_gt_u32_e32 vcc, s84, v117
	v_cvt_f32_u32_e32 v117, v117
	v_cmp_le_i32_e64 s[16:17], s89, v116
	s_and_b64 s[16:17], vcc, s[16:17]
	v_cmp_gt_i32_e32 vcc, s91, v116
	v_add_u32_e32 v116, 0x81, v114
	v_fma_f32 v36, -v113, v117, v36
	v_sub_u32_e32 v117, v178, v116
	v_sub_u32_e32 v118, 0, v117
	s_and_b64 vcc, s[16:17], vcc
	v_max_i32_e32 v117, v117, v118
	v_cndmask_b32_e32 v36, v212, v36, vcc
	v_cmp_gt_u32_e32 vcc, s84, v117
	v_cvt_f32_u32_e32 v117, v117
	v_cmp_le_i32_e64 s[16:17], s89, v116
	s_and_b64 s[16:17], vcc, s[16:17]
	v_cmp_gt_i32_e32 vcc, s91, v116
	v_add_u32_e32 v116, 0x82, v114
	v_fma_f32 v37, -v113, v117, v37
	v_sub_u32_e32 v117, v178, v116
	v_sub_u32_e32 v118, 0, v117
	s_and_b64 vcc, s[16:17], vcc
	v_max_i32_e32 v117, v117, v118
	v_cndmask_b32_e32 v37, v212, v37, vcc
	v_cmp_gt_u32_e32 vcc, s84, v117
	v_cvt_f32_u32_e32 v117, v117
	v_cmp_le_i32_e64 s[16:17], s89, v116
	s_and_b64 s[16:17], vcc, s[16:17]
	v_cmp_gt_i32_e32 vcc, s91, v116
	v_add_u32_e32 v116, 0x83, v114
	v_fma_f32 v38, -v113, v117, v38
	v_sub_u32_e32 v117, v178, v116
	v_sub_u32_e32 v118, 0, v117
	s_and_b64 vcc, s[16:17], vcc
	v_max_i32_e32 v117, v117, v118
	v_cndmask_b32_e32 v38, v212, v38, vcc
	v_cmp_gt_u32_e32 vcc, s84, v117
	v_cvt_f32_u32_e32 v117, v117
	v_cmp_le_i32_e64 s[16:17], s89, v116
	s_and_b64 s[16:17], vcc, s[16:17]
	v_cmp_gt_i32_e32 vcc, s91, v116
	v_add_u32_e32 v116, 0x90, v114
	v_fma_f32 v39, -v113, v117, v39
	v_sub_u32_e32 v117, v178, v116
	v_sub_u32_e32 v118, 0, v117
	s_and_b64 vcc, s[16:17], vcc
	v_max_i32_e32 v117, v117, v118
	v_cndmask_b32_e32 v39, v212, v39, vcc
	v_cmp_gt_u32_e32 vcc, s84, v117
	v_cvt_f32_u32_e32 v117, v117
	v_cmp_le_i32_e64 s[16:17], s89, v116
	s_and_b64 s[16:17], vcc, s[16:17]
	v_cmp_gt_i32_e32 vcc, s91, v116
	v_add_u32_e32 v116, 0x91, v114
	v_fma_f32 v32, -v113, v117, v32
	v_sub_u32_e32 v117, v178, v116
	v_sub_u32_e32 v118, 0, v117
	s_and_b64 vcc, s[16:17], vcc
	v_max_i32_e32 v117, v117, v118
	v_cndmask_b32_e32 v32, v212, v32, vcc
	v_cmp_gt_u32_e32 vcc, s84, v117
	v_cvt_f32_u32_e32 v117, v117
	v_cmp_le_i32_e64 s[16:17], s89, v116
	s_and_b64 s[16:17], vcc, s[16:17]
	v_cmp_gt_i32_e32 vcc, s91, v116
	v_add_u32_e32 v116, 0x92, v114
	v_fma_f32 v33, -v113, v117, v33
	v_sub_u32_e32 v117, v178, v116
	v_sub_u32_e32 v118, 0, v117
	s_and_b64 vcc, s[16:17], vcc
	v_max_i32_e32 v117, v117, v118
	v_cndmask_b32_e32 v33, v212, v33, vcc
	v_cmp_gt_u32_e32 vcc, s84, v117
	v_cvt_f32_u32_e32 v117, v117
	v_cmp_le_i32_e64 s[16:17], s89, v116
	s_and_b64 s[16:17], vcc, s[16:17]
	v_cmp_gt_i32_e32 vcc, s91, v116
	v_add_u32_e32 v116, 0x93, v114
	v_fma_f32 v34, -v113, v117, v34
	v_sub_u32_e32 v117, v178, v116
	v_sub_u32_e32 v118, 0, v117
	s_and_b64 vcc, s[16:17], vcc
	v_max_i32_e32 v117, v117, v118
	v_cndmask_b32_e32 v34, v212, v34, vcc
	v_cmp_gt_u32_e32 vcc, s84, v117
	v_cvt_f32_u32_e32 v117, v117
	v_cmp_le_i32_e64 s[16:17], s89, v116
	s_and_b64 s[16:17], vcc, s[16:17]
	v_cmp_gt_i32_e32 vcc, s91, v116
	v_add_u32_e32 v116, 0xa0, v114
	v_fma_f32 v35, -v113, v117, v35
	v_sub_u32_e32 v117, v178, v116
	v_sub_u32_e32 v118, 0, v117
	s_and_b64 vcc, s[16:17], vcc
	v_max_i32_e32 v117, v117, v118
	v_cndmask_b32_e32 v35, v212, v35, vcc
	v_cmp_gt_u32_e32 vcc, s84, v117
	v_cvt_f32_u32_e32 v117, v117
	v_cmp_le_i32_e64 s[16:17], s89, v116
	s_and_b64 s[16:17], vcc, s[16:17]
	v_cmp_gt_i32_e32 vcc, s91, v116
	v_add_u32_e32 v116, 0xa1, v114
	v_fma_f32 v28, -v113, v117, v28
	v_sub_u32_e32 v117, v178, v116
	v_sub_u32_e32 v118, 0, v117
	s_and_b64 vcc, s[16:17], vcc
	v_max_i32_e32 v117, v117, v118
	v_cndmask_b32_e32 v28, v212, v28, vcc
	v_cmp_gt_u32_e32 vcc, s84, v117
	v_cvt_f32_u32_e32 v117, v117
	v_cmp_le_i32_e64 s[16:17], s89, v116
	s_and_b64 s[16:17], vcc, s[16:17]
	v_cmp_gt_i32_e32 vcc, s91, v116
	v_add_u32_e32 v116, 0xa2, v114
	v_fma_f32 v29, -v113, v117, v29
	v_sub_u32_e32 v117, v178, v116
	v_sub_u32_e32 v118, 0, v117
	s_and_b64 vcc, s[16:17], vcc
	v_max_i32_e32 v117, v117, v118
	v_cndmask_b32_e32 v29, v212, v29, vcc
	v_cmp_gt_u32_e32 vcc, s84, v117
	v_cvt_f32_u32_e32 v117, v117
	v_cmp_le_i32_e64 s[16:17], s89, v116
	s_and_b64 s[16:17], vcc, s[16:17]
	v_cmp_gt_i32_e32 vcc, s91, v116
	v_add_u32_e32 v116, 0xa3, v114
	v_fma_f32 v30, -v113, v117, v30
	v_sub_u32_e32 v117, v178, v116
	v_sub_u32_e32 v118, 0, v117
	s_and_b64 vcc, s[16:17], vcc
	v_max_i32_e32 v117, v117, v118
	v_cndmask_b32_e32 v30, v212, v30, vcc
	v_cmp_gt_u32_e32 vcc, s84, v117
	v_cvt_f32_u32_e32 v117, v117
	v_cmp_le_i32_e64 s[16:17], s89, v116
	s_and_b64 s[16:17], vcc, s[16:17]
	v_cmp_gt_i32_e32 vcc, s91, v116
	v_add_u32_e32 v116, 0xb0, v114
	v_fma_f32 v31, -v113, v117, v31
	v_sub_u32_e32 v117, v178, v116
	v_sub_u32_e32 v118, 0, v117
	s_and_b64 vcc, s[16:17], vcc
	v_max_i32_e32 v117, v117, v118
	v_cndmask_b32_e32 v31, v212, v31, vcc
	v_cmp_gt_u32_e32 vcc, s84, v117
	v_cvt_f32_u32_e32 v117, v117
	v_cmp_le_i32_e64 s[16:17], s89, v116
	s_and_b64 s[16:17], vcc, s[16:17]
	v_cmp_gt_i32_e32 vcc, s91, v116
	v_add_u32_e32 v116, 0xb1, v114
	v_fma_f32 v24, -v113, v117, v24
	v_sub_u32_e32 v117, v178, v116
	v_sub_u32_e32 v118, 0, v117
	s_and_b64 vcc, s[16:17], vcc
	v_max_i32_e32 v117, v117, v118
	v_cndmask_b32_e32 v24, v212, v24, vcc
	v_cmp_gt_u32_e32 vcc, s84, v117
	v_cvt_f32_u32_e32 v117, v117
	v_cmp_le_i32_e64 s[16:17], s89, v116
	s_and_b64 s[16:17], vcc, s[16:17]
	v_cmp_gt_i32_e32 vcc, s91, v116
	v_add_u32_e32 v116, 0xb2, v114
	v_fma_f32 v25, -v113, v117, v25
	v_sub_u32_e32 v117, v178, v116
	v_sub_u32_e32 v118, 0, v117
	s_and_b64 vcc, s[16:17], vcc
	v_max_i32_e32 v117, v117, v118
	v_cndmask_b32_e32 v25, v212, v25, vcc
	v_cmp_gt_u32_e32 vcc, s84, v117
	v_cvt_f32_u32_e32 v117, v117
	v_cmp_le_i32_e64 s[16:17], s89, v116
	s_and_b64 s[16:17], vcc, s[16:17]
	v_cmp_gt_i32_e32 vcc, s91, v116
	v_add_u32_e32 v116, 0xb3, v114
	v_fma_f32 v26, -v113, v117, v26
	v_sub_u32_e32 v117, v178, v116
	v_sub_u32_e32 v118, 0, v117
	s_and_b64 vcc, s[16:17], vcc
	v_max_i32_e32 v117, v117, v118
	v_cndmask_b32_e32 v26, v212, v26, vcc
	v_cmp_gt_u32_e32 vcc, s84, v117
	v_cvt_f32_u32_e32 v117, v117
	v_cmp_le_i32_e64 s[16:17], s89, v116
	s_and_b64 s[16:17], vcc, s[16:17]
	v_cmp_gt_i32_e32 vcc, s91, v116
	v_add_u32_e32 v116, 0xc0, v114
	v_fma_f32 v27, -v113, v117, v27
	v_sub_u32_e32 v117, v178, v116
	v_sub_u32_e32 v118, 0, v117
	s_and_b64 vcc, s[16:17], vcc
	v_max_i32_e32 v117, v117, v118
	v_cndmask_b32_e32 v27, v212, v27, vcc
	v_cmp_gt_u32_e32 vcc, s84, v117
	v_cvt_f32_u32_e32 v117, v117
	v_cmp_le_i32_e64 s[16:17], s89, v116
	s_and_b64 s[16:17], vcc, s[16:17]
	v_cmp_gt_i32_e32 vcc, s91, v116
	v_add_u32_e32 v116, 0xc1, v114
	v_fma_f32 v20, -v113, v117, v20
	v_sub_u32_e32 v117, v178, v116
	v_sub_u32_e32 v118, 0, v117
	s_and_b64 vcc, s[16:17], vcc
	v_max_i32_e32 v117, v117, v118
	v_cndmask_b32_e32 v20, v212, v20, vcc
	v_cmp_gt_u32_e32 vcc, s84, v117
	v_cvt_f32_u32_e32 v117, v117
	v_cmp_le_i32_e64 s[16:17], s89, v116
	s_and_b64 s[16:17], vcc, s[16:17]
	v_cmp_gt_i32_e32 vcc, s91, v116
	v_add_u32_e32 v116, 0xc2, v114
	v_fma_f32 v21, -v113, v117, v21
	v_sub_u32_e32 v117, v178, v116
	v_sub_u32_e32 v118, 0, v117
	s_and_b64 vcc, s[16:17], vcc
	v_max_i32_e32 v117, v117, v118
	v_cndmask_b32_e32 v21, v212, v21, vcc
	v_cmp_gt_u32_e32 vcc, s84, v117
	v_cvt_f32_u32_e32 v117, v117
	v_cmp_le_i32_e64 s[16:17], s89, v116
	s_and_b64 s[16:17], vcc, s[16:17]
	v_cmp_gt_i32_e32 vcc, s91, v116
	v_add_u32_e32 v116, 0xc3, v114
	v_fma_f32 v22, -v113, v117, v22
	v_sub_u32_e32 v117, v178, v116
	v_sub_u32_e32 v118, 0, v117
	s_and_b64 vcc, s[16:17], vcc
	v_max_i32_e32 v117, v117, v118
	v_cndmask_b32_e32 v22, v212, v22, vcc
	v_cmp_gt_u32_e32 vcc, s84, v117
	v_cvt_f32_u32_e32 v117, v117
	v_cmp_le_i32_e64 s[16:17], s89, v116
	s_and_b64 s[16:17], vcc, s[16:17]
	v_cmp_gt_i32_e32 vcc, s91, v116
	v_add_u32_e32 v116, 0xd0, v114
	v_fma_f32 v23, -v113, v117, v23
	v_sub_u32_e32 v117, v178, v116
	v_sub_u32_e32 v118, 0, v117
	s_and_b64 vcc, s[16:17], vcc
	v_max_i32_e32 v117, v117, v118
	v_cndmask_b32_e32 v23, v212, v23, vcc
	v_cmp_gt_u32_e32 vcc, s84, v117
	v_cvt_f32_u32_e32 v117, v117
	v_cmp_le_i32_e64 s[16:17], s89, v116
	s_and_b64 s[16:17], vcc, s[16:17]
	v_cmp_gt_i32_e32 vcc, s91, v116
	v_add_u32_e32 v116, 0xd1, v114
	v_fma_f32 v16, -v113, v117, v16
	v_sub_u32_e32 v117, v178, v116
	v_sub_u32_e32 v118, 0, v117
	s_and_b64 vcc, s[16:17], vcc
	v_max_i32_e32 v117, v117, v118
	v_cndmask_b32_e32 v16, v212, v16, vcc
	v_cmp_gt_u32_e32 vcc, s84, v117
	v_cvt_f32_u32_e32 v117, v117
	v_cmp_le_i32_e64 s[16:17], s89, v116
	s_and_b64 s[16:17], vcc, s[16:17]
	v_cmp_gt_i32_e32 vcc, s91, v116
	v_add_u32_e32 v116, 0xd2, v114
	v_fma_f32 v17, -v113, v117, v17
	v_sub_u32_e32 v117, v178, v116
	v_sub_u32_e32 v118, 0, v117
	s_and_b64 vcc, s[16:17], vcc
	v_max_i32_e32 v117, v117, v118
	v_cndmask_b32_e32 v17, v212, v17, vcc
	v_cmp_gt_u32_e32 vcc, s84, v117
	v_cvt_f32_u32_e32 v117, v117
	v_cmp_le_i32_e64 s[16:17], s89, v116
	s_and_b64 s[16:17], vcc, s[16:17]
	v_cmp_gt_i32_e32 vcc, s91, v116
	v_add_u32_e32 v116, 0xd3, v114
	v_fma_f32 v18, -v113, v117, v18
	v_sub_u32_e32 v117, v178, v116
	v_sub_u32_e32 v118, 0, v117
	s_and_b64 vcc, s[16:17], vcc
	v_max_i32_e32 v117, v117, v118
	v_cndmask_b32_e32 v18, v212, v18, vcc
	v_cmp_gt_u32_e32 vcc, s84, v117
	v_cvt_f32_u32_e32 v117, v117
	v_cmp_le_i32_e64 s[16:17], s89, v116
	s_and_b64 s[16:17], vcc, s[16:17]
	v_cmp_gt_i32_e32 vcc, s91, v116
	v_add_u32_e32 v116, 0xe0, v114
	v_fma_f32 v19, -v113, v117, v19
	v_sub_u32_e32 v117, v178, v116
	v_sub_u32_e32 v118, 0, v117
	s_and_b64 vcc, s[16:17], vcc
	v_max_i32_e32 v117, v117, v118
	v_cndmask_b32_e32 v19, v212, v19, vcc
	v_cmp_gt_u32_e32 vcc, s84, v117
	v_cvt_f32_u32_e32 v117, v117
	v_cmp_le_i32_e64 s[16:17], s89, v116
	s_and_b64 s[16:17], vcc, s[16:17]
	v_cmp_gt_i32_e32 vcc, s91, v116
	v_add_u32_e32 v116, 0xe1, v114
	v_fma_f32 v12, -v113, v117, v12
	v_sub_u32_e32 v117, v178, v116
	v_sub_u32_e32 v118, 0, v117
	s_and_b64 vcc, s[16:17], vcc
	v_max_i32_e32 v117, v117, v118
	v_cndmask_b32_e32 v12, v212, v12, vcc
	v_cmp_gt_u32_e32 vcc, s84, v117
	v_cvt_f32_u32_e32 v117, v117
	v_cmp_le_i32_e64 s[16:17], s89, v116
	s_and_b64 s[16:17], vcc, s[16:17]
	v_cmp_gt_i32_e32 vcc, s91, v116
	v_add_u32_e32 v116, 0xe2, v114
	v_fma_f32 v13, -v113, v117, v13
	v_sub_u32_e32 v117, v178, v116
	v_sub_u32_e32 v118, 0, v117
	s_and_b64 vcc, s[16:17], vcc
	v_max_i32_e32 v117, v117, v118
	v_cndmask_b32_e32 v13, v212, v13, vcc
	v_cmp_gt_u32_e32 vcc, s84, v117
	v_cvt_f32_u32_e32 v117, v117
	v_cmp_le_i32_e64 s[16:17], s89, v116
	s_and_b64 s[16:17], vcc, s[16:17]
	v_cmp_gt_i32_e32 vcc, s91, v116
	v_add_u32_e32 v116, 0xe3, v114
	v_fma_f32 v14, -v113, v117, v14
	v_sub_u32_e32 v117, v178, v116
	v_sub_u32_e32 v118, 0, v117
	s_and_b64 vcc, s[16:17], vcc
	v_max_i32_e32 v117, v117, v118
	v_cndmask_b32_e32 v14, v212, v14, vcc
	v_cmp_gt_u32_e32 vcc, s84, v117
	v_cvt_f32_u32_e32 v117, v117
	v_cmp_le_i32_e64 s[16:17], s89, v116
	s_and_b64 s[16:17], vcc, s[16:17]
	v_cmp_gt_i32_e32 vcc, s91, v116
	v_add_u32_e32 v116, 0xf0, v114
	v_fma_f32 v15, -v113, v117, v15
	v_sub_u32_e32 v117, v178, v116
	v_sub_u32_e32 v118, 0, v117
	s_and_b64 vcc, s[16:17], vcc
	v_max_i32_e32 v117, v117, v118
	v_cndmask_b32_e32 v15, v212, v15, vcc
	v_cmp_gt_u32_e32 vcc, s84, v117
	v_cvt_f32_u32_e32 v117, v117
	v_cmp_le_i32_e64 s[16:17], s89, v116
	s_and_b64 s[16:17], vcc, s[16:17]
	v_cmp_gt_i32_e32 vcc, s91, v116
	v_add_u32_e32 v116, 0xf1, v114
	v_fma_f32 v8, -v113, v117, v8
	v_sub_u32_e32 v117, v178, v116
	v_sub_u32_e32 v118, 0, v117
	s_and_b64 vcc, s[16:17], vcc
	v_max_i32_e32 v117, v117, v118
	v_cndmask_b32_e32 v8, v212, v8, vcc
	v_cmp_gt_u32_e32 vcc, s84, v117
	v_cvt_f32_u32_e32 v117, v117
	v_cmp_le_i32_e64 s[16:17], s89, v116
	s_and_b64 s[16:17], vcc, s[16:17]
	v_cmp_gt_i32_e32 vcc, s91, v116
	v_add_u32_e32 v116, 0xf2, v114
	v_fma_f32 v9, -v113, v117, v9
	v_sub_u32_e32 v117, v178, v116
	v_sub_u32_e32 v118, 0, v117
	s_and_b64 vcc, s[16:17], vcc
	v_max_i32_e32 v117, v117, v118
	v_cndmask_b32_e32 v9, v212, v9, vcc
	v_cmp_gt_u32_e32 vcc, s84, v117
	v_cvt_f32_u32_e32 v117, v117
	v_cmp_le_i32_e64 s[16:17], s89, v116
	s_and_b64 s[16:17], vcc, s[16:17]
	v_cmp_gt_i32_e32 vcc, s91, v116
	v_add_u32_e32 v116, 0xf3, v114
	v_fma_f32 v10, -v113, v117, v10
	v_sub_u32_e32 v117, v178, v116
	v_sub_u32_e32 v118, 0, v117
	s_and_b64 vcc, s[16:17], vcc
	v_max_i32_e32 v117, v117, v118
	v_cndmask_b32_e32 v10, v212, v10, vcc
	v_cmp_gt_u32_e32 vcc, s84, v117
	v_cvt_f32_u32_e32 v117, v117
	v_cmp_le_i32_e64 s[16:17], s89, v116
	s_and_b64 s[16:17], vcc, s[16:17]
	v_cmp_gt_i32_e32 vcc, s91, v116
	v_add_u32_e32 v116, 0x100, v114
	v_fma_f32 v11, -v113, v117, v11
	v_sub_u32_e32 v117, v178, v116
	v_sub_u32_e32 v118, 0, v117
	s_and_b64 vcc, s[16:17], vcc
	v_max_i32_e32 v117, v117, v118
	v_cndmask_b32_e32 v11, v212, v11, vcc
	v_cmp_gt_u32_e32 vcc, s84, v117
	v_cvt_f32_u32_e32 v117, v117
	v_cmp_le_i32_e64 s[16:17], s89, v116
	s_and_b64 s[16:17], vcc, s[16:17]
	v_cmp_gt_i32_e32 vcc, s91, v116
	v_add_u32_e32 v116, 0x101, v114
	v_fma_f32 v4, -v113, v117, v4
	v_sub_u32_e32 v117, v178, v116
	v_sub_u32_e32 v118, 0, v117
	s_and_b64 vcc, s[16:17], vcc
	v_max_i32_e32 v117, v117, v118
	v_cndmask_b32_e32 v4, v212, v4, vcc
	v_cmp_gt_u32_e32 vcc, s84, v117
	v_cvt_f32_u32_e32 v117, v117
	v_cmp_le_i32_e64 s[16:17], s89, v116
	s_and_b64 s[16:17], vcc, s[16:17]
	v_cmp_gt_i32_e32 vcc, s91, v116
	v_add_u32_e32 v116, 0x102, v114
	v_fma_f32 v5, -v113, v117, v5
	v_sub_u32_e32 v117, v178, v116
	v_sub_u32_e32 v118, 0, v117
	s_and_b64 vcc, s[16:17], vcc
	v_max_i32_e32 v117, v117, v118
	v_cndmask_b32_e32 v5, v212, v5, vcc
	v_cmp_gt_u32_e32 vcc, s84, v117
	v_cvt_f32_u32_e32 v117, v117
	v_cmp_le_i32_e64 s[16:17], s89, v116
	s_and_b64 s[16:17], vcc, s[16:17]
	v_cmp_gt_i32_e32 vcc, s91, v116
	v_add_u32_e32 v116, 0x103, v114
	v_fma_f32 v6, -v113, v117, v6
	v_sub_u32_e32 v117, v178, v116
	v_max3_f32 v115, v84, s85, v85
	v_sub_u32_e32 v118, 0, v117
	v_max3_f32 v115, v115, v86, v87
	s_and_b64 vcc, s[16:17], vcc
	v_max_i32_e32 v117, v117, v118
	v_max3_f32 v115, v115, v80, v81
	v_cndmask_b32_e32 v6, v212, v6, vcc
	v_cmp_gt_u32_e32 vcc, s84, v117
	v_cvt_f32_u32_e32 v117, v117
	v_max3_f32 v115, v115, v82, v83
	v_max3_f32 v115, v115, v72, v73
	v_cmp_le_i32_e64 s[16:17], s89, v116
	v_max3_f32 v115, v115, v74, v75
	s_and_b64 s[16:17], vcc, s[16:17]
	v_cmp_gt_i32_e32 vcc, s91, v116
	v_add_u32_e32 v116, 0x110, v114
	v_max3_f32 v115, v115, v64, v65
	v_fma_f32 v7, -v113, v117, v7
	v_sub_u32_e32 v117, v178, v116
	v_max3_f32 v115, v115, v66, v67
	v_sub_u32_e32 v118, 0, v117
	v_max3_f32 v115, v115, v60, v61
	s_and_b64 vcc, s[16:17], vcc
	v_max_i32_e32 v117, v117, v118
	v_max3_f32 v115, v115, v62, v63
	v_cndmask_b32_e32 v7, v212, v7, vcc
	v_cmp_gt_u32_e32 vcc, s84, v117
	v_cvt_f32_u32_e32 v117, v117
	v_max3_f32 v115, v115, v52, v53
	v_max3_f32 v115, v115, v54, v55
	v_cmp_le_i32_e64 s[16:17], s89, v116
	v_max3_f32 v115, v115, v44, v45
	s_and_b64 s[16:17], vcc, s[16:17]
	v_cmp_gt_i32_e32 vcc, s91, v116
	v_add_u32_e32 v116, 0x111, v114
	v_max3_f32 v115, v115, v46, v47
	v_fma_f32 v0, -v113, v117, v0
	v_sub_u32_e32 v117, v178, v116
	v_max3_f32 v115, v115, v40, v41
	v_sub_u32_e32 v118, 0, v117
	v_max3_f32 v115, v115, v42, v43
	s_and_b64 vcc, s[16:17], vcc
	v_max_i32_e32 v117, v117, v118
	v_max3_f32 v115, v115, v36, v37
	v_cndmask_b32_e32 v0, v212, v0, vcc
	v_cmp_gt_u32_e32 vcc, s84, v117
	v_cvt_f32_u32_e32 v117, v117
	v_max3_f32 v115, v115, v38, v39
	v_max3_f32 v115, v115, v32, v33
	v_cmp_le_i32_e64 s[16:17], s89, v116
	v_max3_f32 v115, v115, v34, v35
	s_and_b64 s[16:17], vcc, s[16:17]
	v_cmp_gt_i32_e32 vcc, s91, v116
	v_add_u32_e32 v116, 0x112, v114
	v_max3_f32 v115, v115, v28, v29
	v_fma_f32 v1, -v113, v117, v1
	v_sub_u32_e32 v117, v178, v116
	v_max3_f32 v115, v115, v30, v31
	v_sub_u32_e32 v118, 0, v117
	v_max3_f32 v115, v115, v24, v25
	s_and_b64 vcc, s[16:17], vcc
	v_max_i32_e32 v117, v117, v118
	v_max3_f32 v115, v115, v26, v27
	v_cndmask_b32_e32 v1, v212, v1, vcc
	v_cmp_gt_u32_e32 vcc, s84, v117
	v_cvt_f32_u32_e32 v117, v117
	v_max3_f32 v115, v115, v20, v21
	v_max3_f32 v115, v115, v22, v23
	v_cmp_le_i32_e64 s[16:17], s89, v116
	v_add_u32_e32 v114, 0x113, v114
	v_max3_f32 v115, v115, v16, v17
	s_and_b64 s[16:17], vcc, s[16:17]
	v_cmp_gt_i32_e32 vcc, s91, v116
	v_sub_u32_e32 v116, v178, v114
	v_max3_f32 v115, v115, v18, v19
	v_fma_f32 v2, -v113, v117, v2
	v_sub_u32_e32 v117, 0, v116
	v_max3_f32 v115, v115, v12, v13
	s_and_b64 vcc, s[16:17], vcc
	v_max_i32_e32 v116, v116, v117
	v_max3_f32 v115, v115, v14, v15
	v_cndmask_b32_e32 v2, v212, v2, vcc
	v_cmp_gt_u32_e32 vcc, s84, v116
	v_cvt_f32_u32_e32 v116, v116
	v_max3_f32 v115, v115, v8, v9
	v_max3_f32 v115, v115, v10, v11
	v_cmp_le_i32_e64 s[16:17], s89, v114
	v_max3_f32 v115, v115, v4, v5
	s_and_b64 s[16:17], vcc, s[16:17]
	v_cmp_gt_i32_e32 vcc, s91, v114
	v_max3_f32 v115, v115, v6, v7
	v_fma_f32 v3, -v113, v116, v3
	s_and_b64 vcc, s[16:17], vcc
	v_max3_f32 v115, v115, v0, v1
	v_cndmask_b32_e32 v3, v212, v3, vcc
	v_max3_f32 v113, v115, v2, v3
	ds_bpermute_b32 v114, v108, v113
	v_div_scale_f32 v112, s[16:17], v111, v111, 1.0
	v_rcp_f32_e32 v115, v112
	s_mov_b32 s14, 2
	s_waitcnt lgkmcnt(0)
	v_max_f32_e32 v114, v114, v114
	v_max_f32_e32 v113, v113, v114
	ds_bpermute_b32 v114, v109, v113
	v_fma_f32 v116, -v112, v115, 1.0
	v_fmac_f32_e32 v115, v116, v115
	s_waitcnt vmcnt(0)
	v_mul_f32_e32 v116, 0x3fb8aa3b, v110
	s_waitcnt lgkmcnt(0)
	v_max3_f32 v113, v113, v114, v116
	v_sub_f32_e32 v84, v84, v113
	v_exp_f32_e32 v84, v84
	v_sub_f32_e32 v85, v85, v113
	v_exp_f32_e32 v85, v85
	v_sub_f32_e32 v86, v86, v113
	v_exp_f32_e32 v86, v86
	v_sub_f32_e32 v87, v87, v113
	v_exp_f32_e32 v87, v87
	v_sub_f32_e32 v80, v80, v113
	v_add_f32_e32 v114, 0, v84
	v_exp_f32_e32 v80, v80
	v_sub_f32_e32 v81, v81, v113
	v_add_f32_e32 v114, v85, v114
	v_exp_f32_e32 v81, v81
	v_sub_f32_e32 v82, v82, v113
	v_add_f32_e32 v114, v86, v114
	v_exp_f32_e32 v82, v82
	v_sub_f32_e32 v83, v83, v113
	v_add_f32_e32 v114, v87, v114
	v_exp_f32_e32 v83, v83
	v_sub_f32_e32 v72, v72, v113
	v_add_f32_e32 v114, v80, v114
	v_exp_f32_e32 v72, v72
	v_sub_f32_e32 v73, v73, v113
	v_add_f32_e32 v114, v81, v114
	v_exp_f32_e32 v73, v73
	v_sub_f32_e32 v74, v74, v113
	v_add_f32_e32 v114, v82, v114
	v_exp_f32_e32 v74, v74
	v_sub_f32_e32 v75, v75, v113
	v_add_f32_e32 v114, v83, v114
	v_exp_f32_e32 v75, v75
	v_sub_f32_e32 v64, v64, v113
	v_add_f32_e32 v114, v72, v114
	v_exp_f32_e32 v64, v64
	v_sub_f32_e32 v65, v65, v113
	v_add_f32_e32 v114, v73, v114
	v_exp_f32_e32 v65, v65
	v_sub_f32_e32 v66, v66, v113
	v_add_f32_e32 v114, v74, v114
	v_exp_f32_e32 v66, v66
	v_sub_f32_e32 v67, v67, v113
	v_add_f32_e32 v114, v75, v114
	v_exp_f32_e32 v67, v67
	v_sub_f32_e32 v60, v60, v113
	v_add_f32_e32 v114, v64, v114
	v_exp_f32_e32 v60, v60
	v_sub_f32_e32 v61, v61, v113
	v_add_f32_e32 v114, v65, v114
	v_exp_f32_e32 v61, v61
	v_sub_f32_e32 v62, v62, v113
	v_add_f32_e32 v114, v66, v114
	v_exp_f32_e32 v62, v62
	v_sub_f32_e32 v63, v63, v113
	v_add_f32_e32 v114, v67, v114
	v_exp_f32_e32 v63, v63
	v_sub_f32_e32 v52, v52, v113
	v_add_f32_e32 v114, v60, v114
	v_exp_f32_e32 v52, v52
	v_sub_f32_e32 v53, v53, v113
	v_add_f32_e32 v114, v61, v114
	v_exp_f32_e32 v53, v53
	v_sub_f32_e32 v54, v54, v113
	v_add_f32_e32 v114, v62, v114
	v_exp_f32_e32 v54, v54
	v_sub_f32_e32 v55, v55, v113
	v_add_f32_e32 v114, v63, v114
	v_exp_f32_e32 v55, v55
	v_sub_f32_e32 v44, v44, v113
	v_add_f32_e32 v114, v52, v114
	v_exp_f32_e32 v44, v44
	v_sub_f32_e32 v45, v45, v113
	v_add_f32_e32 v114, v53, v114
	v_exp_f32_e32 v45, v45
	v_sub_f32_e32 v46, v46, v113
	v_add_f32_e32 v114, v54, v114
	v_exp_f32_e32 v46, v46
	v_sub_f32_e32 v47, v47, v113
	v_add_f32_e32 v114, v55, v114
	v_exp_f32_e32 v47, v47
	v_sub_f32_e32 v40, v40, v113
	v_add_f32_e32 v114, v44, v114
	v_exp_f32_e32 v116, v40
	v_sub_f32_e32 v40, v41, v113
	v_add_f32_e32 v114, v45, v114
	v_exp_f32_e32 v117, v40
	v_sub_f32_e32 v40, v42, v113
	v_add_f32_e32 v114, v46, v114
	v_exp_f32_e32 v42, v40
	v_sub_f32_e32 v40, v43, v113
	v_add_f32_e32 v114, v47, v114
	v_exp_f32_e32 v43, v40
	v_sub_f32_e32 v36, v36, v113
	v_add_f32_e32 v40, v116, v114
	v_exp_f32_e32 v114, v36
	v_sub_f32_e32 v36, v37, v113
	v_add_f32_e32 v40, v117, v40
	v_exp_f32_e32 v118, v36
	v_sub_f32_e32 v36, v38, v113
	v_add_f32_e32 v40, v42, v40
	v_exp_f32_e32 v119, v36
	v_sub_f32_e32 v36, v39, v113
	v_add_f32_e32 v40, v43, v40
	v_exp_f32_e32 v120, v36
	v_sub_f32_e32 v32, v32, v113
	v_add_f32_e32 v36, v114, v40
	v_exp_f32_e32 v32, v32
	v_sub_f32_e32 v33, v33, v113
	v_add_f32_e32 v36, v118, v36
	v_exp_f32_e32 v33, v33
	v_sub_f32_e32 v34, v34, v113
	v_add_f32_e32 v36, v119, v36
	v_exp_f32_e32 v121, v34
	v_sub_f32_e32 v34, v35, v113
	v_add_f32_e32 v36, v120, v36
	v_exp_f32_e32 v122, v34
	v_sub_f32_e32 v28, v28, v113
	v_add_f32_e32 v34, v32, v36
	v_exp_f32_e32 v123, v28
	v_sub_f32_e32 v28, v29, v113
	v_add_f32_e32 v34, v33, v34
	v_exp_f32_e32 v29, v28
	v_sub_f32_e32 v28, v30, v113
	v_add_f32_e32 v34, v121, v34
	v_exp_f32_e32 v30, v28
	v_sub_f32_e32 v28, v31, v113
	v_add_f32_e32 v34, v122, v34
	v_exp_f32_e32 v31, v28
	v_sub_f32_e32 v24, v24, v113
	v_add_f32_e32 v28, v123, v34
	v_exp_f32_e32 v124, v24
	v_sub_f32_e32 v24, v25, v113
	v_add_f32_e32 v28, v29, v28
	v_exp_f32_e32 v125, v24
	v_sub_f32_e32 v24, v26, v113
	v_add_f32_e32 v28, v30, v28
	v_exp_f32_e32 v126, v24
	v_sub_f32_e32 v24, v27, v113
	v_add_f32_e32 v28, v31, v28
	v_exp_f32_e32 v127, v24
	v_sub_f32_e32 v20, v20, v113
	v_add_f32_e32 v24, v124, v28
	v_exp_f32_e32 v128, v20
	v_sub_f32_e32 v20, v21, v113
	v_add_f32_e32 v24, v125, v24
	v_exp_f32_e32 v129, v20
	v_sub_f32_e32 v20, v22, v113
	v_add_f32_e32 v24, v126, v24
	v_exp_f32_e32 v130, v20
	v_sub_f32_e32 v20, v23, v113
	v_add_f32_e32 v24, v127, v24
	v_exp_f32_e32 v131, v20
	v_sub_f32_e32 v16, v16, v113
	v_add_f32_e32 v20, v128, v24
	v_exp_f32_e32 v132, v16
	v_sub_f32_e32 v16, v17, v113
	v_add_f32_e32 v20, v129, v20
	v_exp_f32_e32 v133, v16
	v_sub_f32_e32 v16, v18, v113
	v_add_f32_e32 v20, v130, v20
	v_exp_f32_e32 v134, v16
	v_sub_f32_e32 v16, v19, v113
	v_add_f32_e32 v20, v131, v20
	v_exp_f32_e32 v135, v16
	v_sub_f32_e32 v12, v12, v113
	v_add_f32_e32 v16, v132, v20
	v_exp_f32_e32 v136, v12
	v_sub_f32_e32 v12, v13, v113
	v_add_f32_e32 v16, v133, v16
	v_exp_f32_e32 v137, v12
	v_sub_f32_e32 v12, v14, v113
	v_add_f32_e32 v16, v134, v16
	v_exp_f32_e32 v138, v12
	v_sub_f32_e32 v12, v15, v113
	v_add_f32_e32 v16, v135, v16
	v_exp_f32_e32 v139, v12
	v_sub_f32_e32 v8, v8, v113
	v_add_f32_e32 v12, v136, v16
	v_exp_f32_e32 v140, v8
	v_sub_f32_e32 v8, v9, v113
	v_add_f32_e32 v12, v137, v12
	v_exp_f32_e32 v141, v8
	v_sub_f32_e32 v8, v10, v113
	v_add_f32_e32 v12, v138, v12
	v_exp_f32_e32 v142, v8
	v_sub_f32_e32 v8, v11, v113
	v_add_f32_e32 v12, v139, v12
	v_exp_f32_e32 v143, v8
	v_sub_f32_e32 v4, v4, v113
	v_add_f32_e32 v8, v140, v12
	v_exp_f32_e32 v144, v4
	v_sub_f32_e32 v4, v5, v113
	v_add_f32_e32 v8, v141, v8
	v_exp_f32_e32 v145, v4
	v_sub_f32_e32 v4, v6, v113
	v_add_f32_e32 v8, v142, v8
	v_exp_f32_e32 v146, v4
	v_sub_f32_e32 v4, v7, v113
	v_add_f32_e32 v8, v143, v8
	v_exp_f32_e32 v147, v4
	v_sub_f32_e32 v0, v0, v113
	v_add_f32_e32 v4, v144, v8
	v_exp_f32_e32 v148, v0
	v_sub_f32_e32 v0, v1, v113
	v_add_f32_e32 v4, v145, v4
	v_exp_f32_e32 v149, v0
	v_sub_f32_e32 v0, v2, v113
	v_add_f32_e32 v4, v146, v4
	v_exp_f32_e32 v150, v0
	v_sub_f32_e32 v0, v3, v113
	v_add_f32_e32 v4, v147, v4
	v_exp_f32_e32 v3, v0
	v_add_f32_e32 v0, v148, v4
	v_add_f32_e32 v0, v149, v0
	v_add_f32_e32 v0, v150, v0
	v_add_f32_e32 v0, v3, v0
	ds_bpermute_b32 v1, v108, v0
	v_fma_f32 v6, v110, s81, -v113
	v_div_scale_f32 v2, vcc, 1.0, v111, 1.0
	v_exp_f32_e32 v6, v6
	s_waitcnt lgkmcnt(0)
	v_add_f32_e32 v0, v0, v1
	ds_bpermute_b32 v1, v109, v0
	v_mul_f32_e32 v4, v2, v115
	v_fma_f32 v5, -v112, v4, v2
	v_fmac_f32_e32 v4, v5, v115
	v_fma_f32 v2, -v112, v4, v2
	s_waitcnt lgkmcnt(0)
	v_add_f32_e32 v0, v0, v1
	v_add_f32_e32 v112, v6, v0
	v_div_scale_f32 v113, s[16:17], v112, v112, 1.0
	v_rcp_f32_e32 v151, v113
	v_div_fmas_f32 v0, v2, v115, v4
	v_div_fixup_f32 v28, v0, v111, 1.0
	v_div_scale_f32 v115, vcc, 1.0, v112, 1.0
	v_fma_f32 v0, -v113, v151, 1.0
	v_fmac_f32_e32 v151, v0, v151
	v_mul_f32_e32 v152, v115, v151
	v_fma_f32 v0, -v113, v152, v115
	s_nop 2
	v_cvt_pk_bf16_f32 v34, v84, v85
	s_nop 2
	v_cvt_pk_bf16_f32 v35, v86, v87
	s_nop 2
	v_cvt_pk_bf16_f32 v36, v80, v81
	s_nop 2
	v_cvt_pk_bf16_f32 v37, v82, v83
	s_nop 2
	v_cvt_pk_bf16_f32 v38, v72, v73
	s_nop 2
	v_cvt_pk_bf16_f32 v39, v74, v75
	s_nop 2
	v_cvt_pk_bf16_f32 v40, v64, v65
	s_nop 2
	v_cvt_pk_bf16_f32 v41, v66, v67
	s_nop 2
	v_cvt_pk_bf16_f32 v24, v60, v61
	s_nop 2
	v_cvt_pk_bf16_f32 v25, v62, v63
	s_nop 2
	v_cvt_pk_bf16_f32 v26, v52, v53
	s_nop 2
	v_cvt_pk_bf16_f32 v27, v54, v55
	s_nop 2
	v_cvt_pk_bf16_f32 v20, v44, v45
	s_nop 2
	v_cvt_pk_bf16_f32 v21, v46, v47
	s_nop 2
	v_cvt_pk_bf16_f32 v22, v116, v117
	s_nop 2
	v_cvt_pk_bf16_f32 v23, v42, v43
	s_nop 2
	v_cvt_pk_bf16_f32 v16, v114, v118
	s_nop 2
	v_cvt_pk_bf16_f32 v17, v119, v120
	s_nop 2
	v_cvt_pk_bf16_f32 v18, v32, v33
	s_nop 2
	v_cvt_pk_bf16_f32 v19, v121, v122
	s_nop 2
	v_cvt_pk_bf16_f32 v12, v123, v29
	s_nop 2
	v_cvt_pk_bf16_f32 v13, v30, v31
	v_add_u32_e32 v30, 0x3000, v198
	v_add_u32_e32 v33, 0x6000, v198
	v_add_u32_e32 v31, 0x9800, v198
	v_add_u32_e32 v32, 0xc800, v198
	v_add_u32_e32 v46, 0xf800, v198
	v_fmac_f32_e32 v152, v0, v151
	s_nop 2
	v_cvt_pk_bf16_f32 v14, v124, v125
	s_nop 2
	v_cvt_pk_bf16_f32 v15, v126, v127
	s_nop 2
	v_cvt_pk_bf16_f32 v8, v128, v129
	s_nop 2
	v_cvt_pk_bf16_f32 v9, v130, v131
	s_nop 2
	v_cvt_pk_bf16_f32 v10, v132, v133
	s_nop 2
	v_cvt_pk_bf16_f32 v11, v134, v135
	s_nop 2
	v_cvt_pk_bf16_f32 v4, v136, v137
	s_nop 2
	v_cvt_pk_bf16_f32 v5, v138, v139
	s_nop 2
	v_cvt_pk_bf16_f32 v6, v140, v141
	s_nop 2
	v_cvt_pk_bf16_f32 v7, v142, v143
	s_nop 2
	v_cvt_pk_bf16_f32 v0, v144, v145
	s_nop 2
	v_cvt_pk_bf16_f32 v1, v146, v147
	s_nop 2
	v_cvt_pk_bf16_f32 v2, v148, v149
	s_nop 2
	v_cvt_pk_bf16_f32 v3, v150, v3
	ds_read2_b64 v[42:45], v198 offset1:4
	ds_read2_b64 v[52:55], v30 offset0:96 offset1:100
	ds_read2_b64 v[60:63], v33 offset0:192 offset1:196
	ds_read2_b64 v[64:67], v31 offset0:32 offset1:36
	ds_read2_b64 v[72:75], v32 offset0:128 offset1:132
	ds_read2_b64 v[80:83], v46 offset0:224 offset1:228
	ds_read2_b64 v[84:87], v206 offset1:4
	ds_read2_b64 v[108:111], v207 offset1:4
	v_fma_f32 v29, -v113, v152, v115
	v_div_fmas_f32 v29, v29, v151, v152
	v_div_fixup_f32 v29, v29, v112, 1.0
	s_waitcnt lgkmcnt(7)
	v_mfma_f32_16x16x32_bf16 v[112:115], v[42:45], v[104:107], 0
	v_mfma_f32_16x16x32_bf16 v[42:45], v[42:45], v[34:37], 0
	s_waitcnt lgkmcnt(6)
	v_mfma_f32_16x16x32_bf16 v[116:119], v[52:55], v[104:107], 0
	v_mfma_f32_16x16x32_bf16 v[52:55], v[52:55], v[34:37], 0
	s_waitcnt lgkmcnt(5)
	v_mfma_f32_16x16x32_bf16 v[120:123], v[60:63], v[104:107], 0
	v_mfma_f32_16x16x32_bf16 v[60:63], v[60:63], v[34:37], 0
	s_waitcnt lgkmcnt(4)
	v_mfma_f32_16x16x32_bf16 v[124:127], v[64:67], v[104:107], 0
	v_mfma_f32_16x16x32_bf16 v[64:67], v[64:67], v[34:37], 0
	s_waitcnt lgkmcnt(3)
	v_mfma_f32_16x16x32_bf16 v[128:131], v[72:75], v[104:107], 0
	v_mfma_f32_16x16x32_bf16 v[72:75], v[72:75], v[34:37], 0
	s_waitcnt lgkmcnt(2)
	v_mfma_f32_16x16x32_bf16 v[132:135], v[80:83], v[104:107], 0
	v_mfma_f32_16x16x32_bf16 v[80:83], v[80:83], v[34:37], 0
	s_waitcnt lgkmcnt(1)
	v_mfma_f32_16x16x32_bf16 v[136:139], v[84:87], v[104:107], 0
	v_mfma_f32_16x16x32_bf16 v[84:87], v[84:87], v[34:37], 0
	s_waitcnt lgkmcnt(0)
	v_mfma_f32_16x16x32_bf16 v[104:107], v[108:111], v[104:107], 0
	v_mfma_f32_16x16x32_bf16 v[34:37], v[108:111], v[34:37], 0
	ds_read2_b64 v[108:111], v198 offset0:8 offset1:12
	ds_read2_b64 v[140:143], v30 offset0:104 offset1:108
	ds_read2_b64 v[144:147], v33 offset0:200 offset1:204
	ds_read2_b64 v[148:151], v31 offset0:40 offset1:44
	ds_read2_b64 v[152:155], v32 offset0:136 offset1:140
	ds_read2_b64 v[156:159], v46 offset0:232 offset1:236
	ds_read2_b64 v[160:163], v206 offset0:8 offset1:12
	ds_read2_b64 v[164:167], v207 offset0:8 offset1:12
	s_waitcnt lgkmcnt(7)
	v_mfma_f32_16x16x32_bf16 v[112:115], v[108:111], v[100:103], v[112:115]
	v_mfma_f32_16x16x32_bf16 v[42:45], v[108:111], v[38:41], v[42:45]
	s_waitcnt lgkmcnt(6)
	v_mfma_f32_16x16x32_bf16 v[108:111], v[140:143], v[100:103], v[116:119]
	v_mfma_f32_16x16x32_bf16 v[52:55], v[140:143], v[38:41], v[52:55]
	s_waitcnt lgkmcnt(5)
	v_mfma_f32_16x16x32_bf16 v[116:119], v[144:147], v[100:103], v[120:123]
	v_mfma_f32_16x16x32_bf16 v[60:63], v[144:147], v[38:41], v[60:63]
	s_waitcnt lgkmcnt(4)
	v_mfma_f32_16x16x32_bf16 v[120:123], v[148:151], v[100:103], v[124:127]
	v_mfma_f32_16x16x32_bf16 v[64:67], v[148:151], v[38:41], v[64:67]
	s_waitcnt lgkmcnt(3)
	v_mfma_f32_16x16x32_bf16 v[124:127], v[152:155], v[100:103], v[128:131]
	v_mfma_f32_16x16x32_bf16 v[72:75], v[152:155], v[38:41], v[72:75]
	s_waitcnt lgkmcnt(2)
	v_mfma_f32_16x16x32_bf16 v[128:131], v[156:159], v[100:103], v[132:135]
	v_mfma_f32_16x16x32_bf16 v[80:83], v[156:159], v[38:41], v[80:83]
	s_waitcnt lgkmcnt(1)
	v_mfma_f32_16x16x32_bf16 v[132:135], v[160:163], v[100:103], v[136:139]
	v_mfma_f32_16x16x32_bf16 v[84:87], v[160:163], v[38:41], v[84:87]
	s_waitcnt lgkmcnt(0)
	v_mfma_f32_16x16x32_bf16 v[100:103], v[164:167], v[100:103], v[104:107]
	v_mfma_f32_16x16x32_bf16 v[34:37], v[164:167], v[38:41], v[34:37]
	ds_read2_b64 v[38:41], v198 offset0:16 offset1:20
	s_nop 0
	ds_read2_b64 v[104:107], v30 offset0:112 offset1:116
	ds_read2_b64 v[136:139], v33 offset0:208 offset1:212
	ds_read2_b64 v[140:143], v31 offset0:48 offset1:52
	ds_read2_b64 v[144:147], v32 offset0:144 offset1:148
	ds_read2_b64 v[148:151], v46 offset0:240 offset1:244
	ds_read2_b64 v[152:155], v206 offset0:16 offset1:20
	ds_read2_b64 v[156:159], v207 offset0:16 offset1:20
	s_waitcnt lgkmcnt(7)
	v_mfma_f32_16x16x32_bf16 v[112:115], v[38:41], v[96:99], v[112:115]
	v_mfma_f32_16x16x32_bf16 v[38:41], v[38:41], v[24:27], v[42:45]
	s_waitcnt lgkmcnt(6)
	v_mfma_f32_16x16x32_bf16 v[42:45], v[104:107], v[96:99], v[108:111]
	v_mfma_f32_16x16x32_bf16 v[52:55], v[104:107], v[24:27], v[52:55]
	s_waitcnt lgkmcnt(5)
	v_mfma_f32_16x16x32_bf16 v[104:107], v[136:139], v[96:99], v[116:119]
	v_mfma_f32_16x16x32_bf16 v[60:63], v[136:139], v[24:27], v[60:63]
	s_waitcnt lgkmcnt(4)
	v_mfma_f32_16x16x32_bf16 v[108:111], v[140:143], v[96:99], v[120:123]
	v_mfma_f32_16x16x32_bf16 v[64:67], v[140:143], v[24:27], v[64:67]
	s_waitcnt lgkmcnt(3)
	v_mfma_f32_16x16x32_bf16 v[116:119], v[144:147], v[96:99], v[124:127]
	v_mfma_f32_16x16x32_bf16 v[72:75], v[144:147], v[24:27], v[72:75]
	s_waitcnt lgkmcnt(2)
	v_mfma_f32_16x16x32_bf16 v[120:123], v[148:151], v[96:99], v[128:131]
	v_mfma_f32_16x16x32_bf16 v[80:83], v[148:151], v[24:27], v[80:83]
	s_waitcnt lgkmcnt(1)
	v_mfma_f32_16x16x32_bf16 v[124:127], v[152:155], v[96:99], v[132:135]
	v_mfma_f32_16x16x32_bf16 v[84:87], v[152:155], v[24:27], v[84:87]
	s_waitcnt lgkmcnt(0)
	v_mfma_f32_16x16x32_bf16 v[96:99], v[156:159], v[96:99], v[100:103]
	v_mfma_f32_16x16x32_bf16 v[24:27], v[156:159], v[24:27], v[34:37]
	s_nop 2
	ds_read2_b64 v[34:37], v198 offset0:24 offset1:28
	ds_read2_b64 v[100:103], v30 offset0:120 offset1:124
	ds_read2_b64 v[128:131], v33 offset0:216 offset1:220
	ds_read2_b64 v[132:135], v31 offset0:56 offset1:60
	ds_read2_b64 v[136:139], v32 offset0:152 offset1:156
	ds_read2_b64 v[140:143], v46 offset0:248 offset1:252
	ds_read2_b64 v[144:147], v206 offset0:24 offset1:28
	ds_read2_b64 v[148:151], v207 offset0:24 offset1:28
	s_waitcnt lgkmcnt(7)
	v_mfma_f32_16x16x32_bf16 v[112:115], v[34:37], v[92:95], v[112:115]
	v_mfma_f32_16x16x32_bf16 v[34:37], v[34:37], v[20:23], v[38:41]
	s_waitcnt lgkmcnt(6)
	v_mfma_f32_16x16x32_bf16 v[38:41], v[100:103], v[92:95], v[42:45]
	v_mfma_f32_16x16x32_bf16 v[42:45], v[100:103], v[20:23], v[52:55]
	s_waitcnt lgkmcnt(5)
	v_mfma_f32_16x16x32_bf16 v[52:55], v[128:131], v[92:95], v[104:107]
	v_mfma_f32_16x16x32_bf16 v[60:63], v[128:131], v[20:23], v[60:63]
	s_waitcnt lgkmcnt(4)
	v_mfma_f32_16x16x32_bf16 v[100:103], v[132:135], v[92:95], v[108:111]
	v_mfma_f32_16x16x32_bf16 v[64:67], v[132:135], v[20:23], v[64:67]
	s_waitcnt lgkmcnt(3)
	v_mfma_f32_16x16x32_bf16 v[104:107], v[136:139], v[92:95], v[116:119]
	v_mfma_f32_16x16x32_bf16 v[72:75], v[136:139], v[20:23], v[72:75]
	s_waitcnt lgkmcnt(2)
	v_mfma_f32_16x16x32_bf16 v[108:111], v[140:143], v[92:95], v[120:123]
	v_mfma_f32_16x16x32_bf16 v[80:83], v[140:143], v[20:23], v[80:83]
	s_waitcnt lgkmcnt(1)
	v_mfma_f32_16x16x32_bf16 v[116:119], v[144:147], v[92:95], v[124:127]
	v_mfma_f32_16x16x32_bf16 v[84:87], v[144:147], v[20:23], v[84:87]
	s_waitcnt lgkmcnt(0)
	v_mfma_f32_16x16x32_bf16 v[92:95], v[148:151], v[92:95], v[96:99]
	v_mfma_f32_16x16x32_bf16 v[20:23], v[148:151], v[20:23], v[24:27]
	s_nop 2
	ds_read2_b64 v[24:27], v198 offset0:32 offset1:36
	ds_read2_b64 v[96:99], v30 offset0:128 offset1:132
	ds_read2_b64 v[120:123], v33 offset0:224 offset1:228
	ds_read2_b64 v[124:127], v31 offset0:64 offset1:68
	ds_read2_b64 v[128:131], v32 offset0:160 offset1:164
	ds_read2_b64 v[132:135], v208 offset0:32 offset1:36
	ds_read2_b64 v[136:139], v206 offset0:32 offset1:36
	ds_read2_b64 v[140:143], v207 offset0:32 offset1:36
	s_waitcnt lgkmcnt(7)
	v_mfma_f32_16x16x32_bf16 v[112:115], v[24:27], v[88:91], v[112:115]
	v_mfma_f32_16x16x32_bf16 v[24:27], v[24:27], v[16:19], v[34:37]
	s_waitcnt lgkmcnt(6)
	v_mfma_f32_16x16x32_bf16 v[34:37], v[96:99], v[88:91], v[38:41]
	v_mfma_f32_16x16x32_bf16 v[38:41], v[96:99], v[16:19], v[42:45]
	s_waitcnt lgkmcnt(5)
	v_mfma_f32_16x16x32_bf16 v[42:45], v[120:123], v[88:91], v[52:55]
	v_mfma_f32_16x16x32_bf16 v[52:55], v[120:123], v[16:19], v[60:63]
	s_waitcnt lgkmcnt(4)
	v_mfma_f32_16x16x32_bf16 v[60:63], v[124:127], v[88:91], v[100:103]
	v_mfma_f32_16x16x32_bf16 v[64:67], v[124:127], v[16:19], v[64:67]
	s_waitcnt lgkmcnt(3)
	v_mfma_f32_16x16x32_bf16 v[96:99], v[128:131], v[88:91], v[104:107]
	v_mfma_f32_16x16x32_bf16 v[72:75], v[128:131], v[16:19], v[72:75]
	s_waitcnt lgkmcnt(2)
	v_mfma_f32_16x16x32_bf16 v[100:103], v[132:135], v[88:91], v[108:111]
	v_mfma_f32_16x16x32_bf16 v[80:83], v[132:135], v[16:19], v[80:83]
	s_waitcnt lgkmcnt(1)
	v_mfma_f32_16x16x32_bf16 v[104:107], v[136:139], v[88:91], v[116:119]
	v_mfma_f32_16x16x32_bf16 v[84:87], v[136:139], v[16:19], v[84:87]
	s_waitcnt lgkmcnt(0)
	v_mfma_f32_16x16x32_bf16 v[88:91], v[140:143], v[88:91], v[92:95]
	v_mfma_f32_16x16x32_bf16 v[16:19], v[140:143], v[16:19], v[20:23]
	s_nop 2
	ds_read2_b64 v[20:23], v198 offset0:40 offset1:44
	ds_read2_b64 v[92:95], v30 offset0:136 offset1:140
	ds_read2_b64 v[108:111], v33 offset0:232 offset1:236
	ds_read2_b64 v[116:119], v31 offset0:72 offset1:76
	ds_read2_b64 v[120:123], v32 offset0:168 offset1:172
	ds_read2_b64 v[124:127], v208 offset0:40 offset1:44
	ds_read2_b64 v[128:131], v206 offset0:40 offset1:44
	ds_read2_b64 v[132:135], v207 offset0:40 offset1:44
	s_waitcnt lgkmcnt(7)
	v_mfma_f32_16x16x32_bf16 v[112:115], v[20:23], v[76:79], v[112:115]
	v_mfma_f32_16x16x32_bf16 v[20:23], v[20:23], v[12:15], v[24:27]
	s_waitcnt lgkmcnt(6)
	v_mfma_f32_16x16x32_bf16 v[24:27], v[92:95], v[76:79], v[34:37]
	v_mfma_f32_16x16x32_bf16 v[34:37], v[92:95], v[12:15], v[38:41]
	s_waitcnt lgkmcnt(5)
	v_mfma_f32_16x16x32_bf16 v[38:41], v[108:111], v[76:79], v[42:45]
	v_mfma_f32_16x16x32_bf16 v[42:45], v[108:111], v[12:15], v[52:55]
	s_waitcnt lgkmcnt(4)
	v_mfma_f32_16x16x32_bf16 v[52:55], v[116:119], v[76:79], v[60:63]
	v_mfma_f32_16x16x32_bf16 v[60:63], v[116:119], v[12:15], v[64:67]
	s_waitcnt lgkmcnt(3)
	v_mfma_f32_16x16x32_bf16 v[64:67], v[120:123], v[76:79], v[96:99]
	v_mfma_f32_16x16x32_bf16 v[72:75], v[120:123], v[12:15], v[72:75]
	s_waitcnt lgkmcnt(2)
	v_mfma_f32_16x16x32_bf16 v[92:95], v[124:127], v[76:79], v[100:103]
	v_mfma_f32_16x16x32_bf16 v[80:83], v[124:127], v[12:15], v[80:83]
	s_waitcnt lgkmcnt(1)
	v_mfma_f32_16x16x32_bf16 v[96:99], v[128:131], v[76:79], v[104:107]
	v_mfma_f32_16x16x32_bf16 v[84:87], v[128:131], v[12:15], v[84:87]
	s_waitcnt lgkmcnt(0)
	v_mfma_f32_16x16x32_bf16 v[76:79], v[132:135], v[76:79], v[88:91]
	v_mfma_f32_16x16x32_bf16 v[12:15], v[132:135], v[12:15], v[16:19]
	s_nop 2
	ds_read2_b64 v[16:19], v198 offset0:48 offset1:52
	ds_read2_b64 v[88:91], v30 offset0:144 offset1:148
	ds_read2_b64 v[100:103], v33 offset0:240 offset1:244
	ds_read2_b64 v[104:107], v31 offset0:80 offset1:84
	ds_read2_b64 v[108:111], v32 offset0:176 offset1:180
	ds_read2_b64 v[116:119], v208 offset0:48 offset1:52
	ds_read2_b64 v[120:123], v206 offset0:48 offset1:52
	ds_read2_b64 v[124:127], v207 offset0:48 offset1:52
	s_waitcnt lgkmcnt(7)
	v_mfma_f32_16x16x32_bf16 v[112:115], v[16:19], v[68:71], v[112:115]
	v_mfma_f32_16x16x32_bf16 v[16:19], v[16:19], v[8:11], v[20:23]
	s_waitcnt lgkmcnt(6)
	v_mfma_f32_16x16x32_bf16 v[20:23], v[88:91], v[68:71], v[24:27]
	v_mfma_f32_16x16x32_bf16 v[24:27], v[88:91], v[8:11], v[34:37]
	s_waitcnt lgkmcnt(5)
	v_mfma_f32_16x16x32_bf16 v[34:37], v[100:103], v[68:71], v[38:41]
	v_mfma_f32_16x16x32_bf16 v[38:41], v[100:103], v[8:11], v[42:45]
	s_waitcnt lgkmcnt(4)
	v_mfma_f32_16x16x32_bf16 v[42:45], v[104:107], v[68:71], v[52:55]
	v_mfma_f32_16x16x32_bf16 v[52:55], v[104:107], v[8:11], v[60:63]
	s_waitcnt lgkmcnt(3)
	v_mfma_f32_16x16x32_bf16 v[60:63], v[108:111], v[68:71], v[64:67]
	v_mfma_f32_16x16x32_bf16 v[64:67], v[108:111], v[8:11], v[72:75]
	s_waitcnt lgkmcnt(2)
	v_mfma_f32_16x16x32_bf16 v[72:75], v[116:119], v[68:71], v[92:95]
	v_mfma_f32_16x16x32_bf16 v[80:83], v[116:119], v[8:11], v[80:83]
	s_waitcnt lgkmcnt(1)
	v_mfma_f32_16x16x32_bf16 v[88:91], v[120:123], v[68:71], v[96:99]
	v_mfma_f32_16x16x32_bf16 v[84:87], v[120:123], v[8:11], v[84:87]
	s_waitcnt lgkmcnt(0)
	v_mfma_f32_16x16x32_bf16 v[68:71], v[124:127], v[68:71], v[76:79]
	v_mfma_f32_16x16x32_bf16 v[8:11], v[124:127], v[8:11], v[12:15]
	s_nop 2
	ds_read2_b64 v[12:15], v198 offset0:56 offset1:60
	ds_read2_b64 v[76:79], v30 offset0:152 offset1:156
	ds_read2_b64 v[92:95], v33 offset0:248 offset1:252
	ds_read2_b64 v[96:99], v31 offset0:88 offset1:92
	ds_read2_b64 v[100:103], v32 offset0:184 offset1:188
	ds_read2_b64 v[104:107], v208 offset0:56 offset1:60
	ds_read2_b64 v[108:111], v206 offset0:56 offset1:60
	ds_read2_b64 v[116:119], v207 offset0:56 offset1:60
	s_waitcnt lgkmcnt(7)
	v_mfma_f32_16x16x32_bf16 v[112:115], v[12:15], v[56:59], v[112:115]
	v_mfma_f32_16x16x32_bf16 v[12:15], v[12:15], v[4:7], v[16:19]
	s_waitcnt lgkmcnt(6)
	v_mfma_f32_16x16x32_bf16 v[16:19], v[76:79], v[56:59], v[20:23]
	v_mfma_f32_16x16x32_bf16 v[20:23], v[76:79], v[4:7], v[24:27]
	s_waitcnt lgkmcnt(5)
	v_mfma_f32_16x16x32_bf16 v[24:27], v[92:95], v[56:59], v[34:37]
	v_mfma_f32_16x16x32_bf16 v[34:37], v[92:95], v[4:7], v[38:41]
	s_waitcnt lgkmcnt(4)
	v_mfma_f32_16x16x32_bf16 v[38:41], v[96:99], v[56:59], v[42:45]
	v_mfma_f32_16x16x32_bf16 v[42:45], v[96:99], v[4:7], v[52:55]
	s_waitcnt lgkmcnt(3)
	v_mfma_f32_16x16x32_bf16 v[52:55], v[100:103], v[56:59], v[60:63]
	v_mfma_f32_16x16x32_bf16 v[60:63], v[100:103], v[4:7], v[64:67]
	s_waitcnt lgkmcnt(2)
	v_mfma_f32_16x16x32_bf16 v[64:67], v[104:107], v[56:59], v[72:75]
	v_mfma_f32_16x16x32_bf16 v[72:75], v[104:107], v[4:7], v[80:83]
	s_waitcnt lgkmcnt(1)
	v_mfma_f32_16x16x32_bf16 v[76:79], v[108:111], v[56:59], v[88:91]
	v_mfma_f32_16x16x32_bf16 v[80:83], v[108:111], v[4:7], v[84:87]
	s_waitcnt lgkmcnt(0)
	v_mfma_f32_16x16x32_bf16 v[56:59], v[116:119], v[56:59], v[68:71]
	v_mfma_f32_16x16x32_bf16 v[4:7], v[116:119], v[4:7], v[8:11]
	s_nop 2
	ds_read2_b64 v[8:11], v198 offset0:64 offset1:68
	ds_read2_b64 v[68:71], v30 offset0:160 offset1:164
	v_add_u32_e32 v30, 0x6800, v198
	ds_read2_b64 v[84:87], v30 offset1:4
	ds_read2_b64 v[88:91], v31 offset0:96 offset1:100
	ds_read2_b64 v[30:33], v32 offset0:192 offset1:196
	ds_read2_b64 v[92:95], v208 offset0:64 offset1:68
	ds_read2_b64 v[96:99], v206 offset0:64 offset1:68
	ds_read2_b64 v[100:103], v207 offset0:64 offset1:68
	s_waitcnt lgkmcnt(7)
	v_mfma_f32_16x16x32_bf16 v[104:107], v[8:11], v[48:51], v[112:115]
	v_mfma_f32_16x16x32_bf16 v[8:11], v[8:11], v[0:3], v[12:15]
	s_waitcnt lgkmcnt(6)
	v_mfma_f32_16x16x32_bf16 v[12:15], v[68:71], v[48:51], v[16:19]
	v_mfma_f32_16x16x32_bf16 v[16:19], v[68:71], v[0:3], v[20:23]
	s_waitcnt lgkmcnt(5)
	v_mfma_f32_16x16x32_bf16 v[20:23], v[84:87], v[48:51], v[24:27]
	v_mfma_f32_16x16x32_bf16 v[24:27], v[84:87], v[0:3], v[34:37]
	s_waitcnt lgkmcnt(4)
	v_mfma_f32_16x16x32_bf16 v[34:37], v[88:91], v[48:51], v[38:41]
	v_mfma_f32_16x16x32_bf16 v[38:41], v[88:91], v[0:3], v[42:45]
	s_waitcnt lgkmcnt(3)
	v_mfma_f32_16x16x32_bf16 v[42:45], v[30:33], v[48:51], v[52:55]
	v_mfma_f32_16x16x32_bf16 v[30:33], v[30:33], v[0:3], v[60:63]
	s_waitcnt lgkmcnt(2)
	v_mfma_f32_16x16x32_bf16 v[52:55], v[92:95], v[48:51], v[64:67]
	v_mfma_f32_16x16x32_bf16 v[60:63], v[92:95], v[0:3], v[72:75]
	s_waitcnt lgkmcnt(1)
	v_mfma_f32_16x16x32_bf16 v[64:67], v[96:99], v[48:51], v[76:79]
	v_mfma_f32_16x16x32_bf16 v[68:71], v[96:99], v[0:3], v[80:83]
	s_waitcnt lgkmcnt(0)
	v_mfma_f32_16x16x32_bf16 v[46:49], v[100:103], v[48:51], v[56:59]
	v_mfma_f32_16x16x32_bf16 v[0:3], v[100:103], v[0:3], v[4:7]
	s_nop 2
	v_lshl_add_u64 v[4:5], v[182:183], 0, s[44:45]
	v_mul_f32_e32 v50, v28, v104
	v_mul_f32_e32 v51, v28, v105
	v_mul_f32_e32 v56, v28, v106
	v_mul_f32_e32 v57, v28, v107
	v_mul_f32_e32 v58, v28, v64
	v_mul_f32_e32 v59, v28, v65
	v_mul_f32_e32 v64, v28, v66
	v_mul_f32_e32 v65, v28, v67
	v_mul_f32_e32 v66, v29, v69
	v_mul_f32_e32 v67, v29, v70
	v_mul_f32_e32 v69, v29, v0
	v_mul_f32_e32 v70, v29, v1
	v_cvt_pk_bf16_f32 v0, v50, v51
	v_cvt_pk_bf16_f32 v1, v56, v57
	v_mul_f32_e32 v12, v28, v12
	v_mul_f32_e32 v13, v28, v13
	v_mul_f32_e32 v14, v28, v14
	v_mul_f32_e32 v15, v28, v15
	global_store_dwordx2 v[4:5], v[0:1], off
	v_cvt_pk_bf16_f32 v0, v12, v13
	v_cvt_pk_bf16_f32 v1, v14, v15
	v_mul_f32_e32 v20, v28, v20
	v_mul_f32_e32 v21, v28, v21
	v_mul_f32_e32 v22, v28, v22
	v_mul_f32_e32 v23, v28, v23
	global_store_dwordx2 v[4:5], v[0:1], off offset:32
	v_cvt_pk_bf16_f32 v0, v20, v21
	v_cvt_pk_bf16_f32 v1, v22, v23
	v_mul_f32_e32 v34, v28, v34
	v_mul_f32_e32 v35, v28, v35
	v_mul_f32_e32 v36, v28, v36
	v_mul_f32_e32 v37, v28, v37
	global_store_dwordx2 v[4:5], v[0:1], off offset:64
	v_cvt_pk_bf16_f32 v0, v34, v35
	v_cvt_pk_bf16_f32 v1, v36, v37
	v_mul_f32_e32 v42, v28, v42
	v_mul_f32_e32 v43, v28, v43
	v_mul_f32_e32 v44, v28, v44
	v_mul_f32_e32 v45, v28, v45
	global_store_dwordx2 v[4:5], v[0:1], off offset:96
	v_cvt_pk_bf16_f32 v0, v42, v43
	v_cvt_pk_bf16_f32 v1, v44, v45
	v_mul_f32_e32 v52, v28, v52
	v_mul_f32_e32 v53, v28, v53
	v_mul_f32_e32 v54, v28, v54
	v_mul_f32_e32 v55, v28, v55
	global_store_dwordx2 v[4:5], v[0:1], off offset:128
	v_cvt_pk_bf16_f32 v0, v52, v53
	v_cvt_pk_bf16_f32 v1, v54, v55
	global_store_dwordx2 v[4:5], v[0:1], off offset:160
	v_cvt_pk_bf16_f32 v0, v58, v59
	v_cvt_pk_bf16_f32 v1, v64, v65
	v_mul_f32_e32 v46, v28, v46
	v_mul_f32_e32 v47, v28, v47
	v_mul_f32_e32 v48, v28, v48
	v_mul_f32_e32 v28, v28, v49
	global_store_dwordx2 v[4:5], v[0:1], off offset:192
	v_cvt_pk_bf16_f32 v0, v46, v47
	v_cvt_pk_bf16_f32 v1, v48, v28
	v_lshl_add_u64 v[6:7], v[182:183], 0, s[52:53]
	v_mul_f32_e32 v8, v29, v8
	v_mul_f32_e32 v9, v29, v9
	v_mul_f32_e32 v10, v29, v10
	v_mul_f32_e32 v11, v29, v11
	global_store_dwordx2 v[4:5], v[0:1], off offset:224
	v_cvt_pk_bf16_f32 v0, v8, v9
	v_cvt_pk_bf16_f32 v1, v10, v11
	v_mul_f32_e32 v16, v29, v16
	v_mul_f32_e32 v17, v29, v17
	v_mul_f32_e32 v18, v29, v18
	v_mul_f32_e32 v19, v29, v19
	global_store_dwordx2 v[6:7], v[0:1], off
	v_cvt_pk_bf16_f32 v0, v16, v17
	v_cvt_pk_bf16_f32 v1, v18, v19
	v_mul_f32_e32 v24, v29, v24
	v_mul_f32_e32 v25, v29, v25
	v_mul_f32_e32 v26, v29, v26
	v_mul_f32_e32 v27, v29, v27
	global_store_dwordx2 v[6:7], v[0:1], off offset:32
	v_cvt_pk_bf16_f32 v0, v24, v25
	v_cvt_pk_bf16_f32 v1, v26, v27
	v_mul_f32_e32 v38, v29, v38
	v_mul_f32_e32 v39, v29, v39
	v_mul_f32_e32 v40, v29, v40
	v_mul_f32_e32 v41, v29, v41
	global_store_dwordx2 v[6:7], v[0:1], off offset:64
	v_cvt_pk_bf16_f32 v0, v38, v39
	v_cvt_pk_bf16_f32 v1, v40, v41
	v_mul_f32_e32 v30, v29, v30
	v_mul_f32_e32 v31, v29, v31
	v_mul_f32_e32 v32, v29, v32
	v_mul_f32_e32 v33, v29, v33
	global_store_dwordx2 v[6:7], v[0:1], off offset:96
	v_cvt_pk_bf16_f32 v0, v30, v31
	v_cvt_pk_bf16_f32 v1, v32, v33
	v_mul_f32_e32 v49, v29, v60
	v_mul_f32_e32 v60, v29, v61
	v_mul_f32_e32 v61, v29, v62
	v_mul_f32_e32 v62, v29, v63
	global_store_dwordx2 v[6:7], v[0:1], off offset:128
	v_cvt_pk_bf16_f32 v0, v49, v60
	v_cvt_pk_bf16_f32 v1, v61, v62
	v_mul_f32_e32 v63, v29, v68
	v_mul_f32_e32 v68, v29, v71
	s_and_b64 vcc, exec, s[46:47]
	s_mov_b64 s[46:47], 0
	global_store_dwordx2 v[6:7], v[0:1], off offset:160
	v_cvt_pk_bf16_f32 v0, v63, v66
	v_cvt_pk_bf16_f32 v1, v67, v68
	v_mul_f32_e32 v2, v29, v2
	v_mul_f32_e32 v3, v29, v3
	global_store_dwordx2 v[6:7], v[0:1], off offset:192
	v_cvt_pk_bf16_f32 v0, v69, v70
	v_cvt_pk_bf16_f32 v1, v2, v3
	global_store_dwordx2 v[6:7], v[0:1], off offset:224
	s_cbranch_vccnz .LBB0_258
	s_add_i32 s88, s88, s15
	s_cmpk_gt_i32 s88, 0x3ff
	s_mov_b32 s92, s28
	s_cbranch_scc0 .LBB0_229

.LBB0_433:
	s_nop 6
	v_sub_f32_e32 v16, v16, v195
	v_exp_f32_e32 v16, v16
	v_sub_f32_e32 v17, v17, v195
	v_exp_f32_e32 v17, v17
	v_sub_f32_e32 v0, v0, v196
	v_add_f32_e32 v16, 1.0, v16
	v_rcp_f32_e32 v16, v16
	v_exp_f32_e32 v177, v0
	v_add_f32_e32 v17, 1.0, v17
	v_rcp_f32_e32 v17, v17
	v_mul_f32_e32 v0, v197, v16
	v_exp_f32_e32 v0, v0
	v_add_f32_e32 v16, 1.0, v177
	v_sub_f32_e32 v1, v1, v196
	v_rcp_f32_e32 v16, v16
	v_fma_f32 v177, -v0, v0, 1.0
	v_sqrt_f32_e32 v184, v177
	v_exp_f32_e32 v185, v1
	v_mul_f32_e32 v17, v197, v17
	v_exp_f32_e32 v17, v17
	v_sub_f32_e32 v18, v18, v195
	v_add3_u32 v187, s35, v214, v215
	v_exp_f32_e32 v18, v18
	ds_read_u16 v1, v187
	ds_read_u16 v186, v187 offset:528
	ds_read_u16 v188, v187 offset:1056
	ds_read_u16 v189, v187 offset:1584
	ds_read_u16 v191, v187 offset:4224
	ds_read_u16 v192, v187 offset:4752
	ds_read_u16 v193, v187 offset:5280
	ds_read_u16 v199, v187 offset:5808
	s_waitcnt lgkmcnt(7)
	v_lshlrev_b32_e32 v177, 16, v1
	v_mul_f32_e32 v1, v16, v184
	v_add_f32_e32 v16, 1.0, v185
	v_rcp_f32_e32 v184, v16
	v_fma_f32 v16, -v17, v17, 1.0
	v_sqrt_f32_e32 v185, v16
	v_add_f32_e32 v16, 1.0, v18
	v_rcp_f32_e32 v18, v16
	v_sub_f32_e32 v2, v2, v196
	s_waitcnt lgkmcnt(6)
	v_lshlrev_b32_e32 v16, 16, v186
	v_mul_f32_e32 v186, v184, v185
	v_mul_f32_e32 v18, v197, v18
	v_exp_f32_e32 v185, v18
	v_sub_f32_e32 v18, v19, v195
	v_exp_f32_e32 v2, v2
	v_exp_f32_e32 v18, v18
	v_fma_f32 v19, -v185, v185, 1.0
	v_sub_f32_e32 v3, v3, v196
	v_add_f32_e32 v2, 1.0, v2
	v_add_f32_e32 v18, 1.0, v18
	v_rcp_f32_e32 v2, v2
	v_sqrt_f32_e32 v19, v19
	v_exp_f32_e32 v3, v3
	v_rcp_f32_e32 v18, v18
	s_waitcnt lgkmcnt(5)
	v_lshlrev_b32_e32 v184, 16, v188
	v_mul_f32_e32 v188, v2, v19
	v_add_f32_e32 v2, 1.0, v3
	v_mul_f32_e32 v3, v197, v18
	v_exp_f32_e32 v3, v3
	v_sub_f32_e32 v18, v20, v195
	v_exp_f32_e32 v18, v18
	v_rcp_f32_e32 v19, v2
	v_fma_f32 v2, -v3, v3, 1.0
	v_sqrt_f32_e32 v20, v2
	v_add_f32_e32 v2, 1.0, v18
	v_sub_f32_e32 v4, v4, v196
	v_exp_f32_e32 v4, v4
	v_rcp_f32_e32 v18, v2
	v_mul_f32_e32 v190, v19, v20
	v_sub_f32_e32 v5, v5, v196
	v_add_f32_e32 v19, 1.0, v4
	v_mul_f32_e32 v4, v197, v18
	v_sub_f32_e32 v18, v21, v195
	v_exp_f32_e32 v18, v18
	v_exp_f32_e32 v4, v4
	v_rcp_f32_e32 v19, v19
	v_exp_f32_e32 v21, v5
	v_add_f32_e32 v18, 1.0, v18
	v_fma_f32 v20, -v4, v4, 1.0
	v_rcp_f32_e32 v18, v18
	v_sqrt_f32_e32 v20, v20
	s_waitcnt lgkmcnt(4)
	v_lshlrev_b32_e32 v2, 16, v189
	v_sub_f32_e32 v6, v6, v196
	v_mul_f32_e32 v18, v197, v18
	v_mul_f32_e32 v5, v19, v20
	v_exp_f32_e32 v19, v18
	v_sub_f32_e32 v18, v22, v195
	v_exp_f32_e32 v18, v18
	v_add_f32_e32 v20, 1.0, v21
	v_fma_f32 v21, -v19, v19, 1.0
	v_rcp_f32_e32 v20, v20
	v_add_f32_e32 v18, 1.0, v18
	v_sqrt_f32_e32 v21, v21
	v_rcp_f32_e32 v189, v18
	v_exp_f32_e32 v6, v6
	v_sub_f32_e32 v7, v7, v196
	v_mul_f32_e32 v22, v20, v21
	v_mul_f32_e32 v20, v197, v189
	v_exp_f32_e32 v21, v20
	v_sub_f32_e32 v20, v23, v195
	v_exp_f32_e32 v20, v20
	v_add_f32_e32 v6, 1.0, v6
	v_fma_f32 v23, -v21, v21, 1.0
	v_rcp_f32_e32 v6, v6
	v_add_f32_e32 v20, 1.0, v20
	v_sqrt_f32_e32 v23, v23
	v_exp_f32_e32 v7, v7
	v_rcp_f32_e32 v189, v20
	s_waitcnt lgkmcnt(2)
	v_lshlrev_b32_e32 v18, 16, v192
	v_mul_f32_e32 v192, v6, v23
	v_add_f32_e32 v6, 1.0, v7
	v_mul_f32_e32 v7, v197, v189
	v_exp_f32_e32 v7, v7
	v_sub_f32_e32 v23, v24, v195
	v_exp_f32_e32 v23, v23
	v_rcp_f32_e32 v24, v6
	v_fma_f32 v6, -v7, v7, 1.0
	v_sqrt_f32_e32 v189, v6
	v_add_f32_e32 v6, 1.0, v23
	v_sub_f32_e32 v8, v8, v196
	v_exp_f32_e32 v8, v8
	v_rcp_f32_e32 v23, v6
	v_mul_f32_e32 v200, v24, v189
	v_sub_f32_e32 v9, v9, v196
	v_add_f32_e32 v24, 1.0, v8
	v_mul_f32_e32 v8, v197, v23
	v_sub_f32_e32 v23, v25, v195
	v_exp_f32_e32 v23, v23
	v_exp_f32_e32 v8, v8
	v_rcp_f32_e32 v24, v24
	v_lshlrev_b32_e32 v201, 16, v191
	v_add_f32_e32 v23, 1.0, v23
	v_fma_f32 v25, -v8, v8, 1.0
	v_rcp_f32_e32 v23, v23
	v_sqrt_f32_e32 v25, v25
	s_waitcnt lgkmcnt(1)
	v_lshlrev_b32_e32 v20, 16, v193
	s_waitcnt lgkmcnt(0)
	v_lshlrev_b32_e32 v6, 16, v199
	v_exp_f32_e32 v189, v9
	ds_read_u16 v9, v187 offset:8448
	ds_read_u16 v191, v187 offset:8976
	ds_read_u16 v193, v187 offset:9504
	ds_read_u16 v199, v187 offset:10032
	ds_read_u16 v206, v187 offset:12672
	ds_read_u16 v228, v187 offset:13200
	ds_read_u16 v230, v187 offset:13728
	ds_read_u16 v187, v187 offset:14256
	v_mul_f32_e32 v23, v197, v23
	s_waitcnt lgkmcnt(7)
	v_lshlrev_b32_e32 v231, 16, v9
	v_mul_f32_e32 v9, v24, v25
	v_exp_f32_e32 v25, v23
	v_sub_f32_e32 v23, v26, v195
	v_exp_f32_e32 v23, v23
	v_add_f32_e32 v24, 1.0, v189
	v_rcp_f32_e32 v26, v24
	v_fma_f32 v24, -v25, v25, 1.0
	v_add_f32_e32 v23, 1.0, v23
	v_rcp_f32_e32 v23, v23
	v_sub_f32_e32 v10, v10, v196
	v_sqrt_f32_e32 v189, v24
	v_exp_f32_e32 v202, v10
	v_mul_f32_e32 v23, v197, v23
	v_exp_f32_e32 v203, v23
	v_sub_f32_e32 v23, v27, v195
	v_exp_f32_e32 v23, v23
	v_mul_f32_e32 v10, v26, v189
	v_add_f32_e32 v26, 1.0, v202
	v_fma_f32 v27, -v203, v203, 1.0
	v_add_f32_e32 v23, 1.0, v23
	v_rcp_f32_e32 v23, v23
	v_sub_f32_e32 v11, v11, v196
	v_rcp_f32_e32 v26, v26
	v_sqrt_f32_e32 v27, v27
	v_mul_f32_e32 v23, v197, v23
	v_exp_f32_e32 v205, v23
	v_sub_f32_e32 v23, v28, v195
	v_exp_f32_e32 v23, v23
	v_exp_f32_e32 v11, v11
	v_mul_f32_e32 v26, v26, v27
	v_fma_f32 v27, -v205, v205, 1.0
	v_add_f32_e32 v23, 1.0, v23
	v_add_f32_e32 v11, 1.0, v11
	v_sub_f32_e32 v12, v12, v196
	v_rcp_f32_e32 v23, v23
	v_rcp_f32_e32 v11, v11
	v_sqrt_f32_e32 v27, v27
	v_exp_f32_e32 v28, v12
	v_mul_f32_e32 v23, v197, v23
	v_sub_f32_e32 v14, v14, v196
	v_mul_f32_e32 v12, v11, v27
	v_add_f32_e32 v11, 1.0, v28
	v_exp_f32_e32 v28, v23
	v_sub_f32_e32 v23, v29, v195
	v_exp_f32_e32 v23, v23
	v_rcp_f32_e32 v11, v11
	v_fma_f32 v27, -v28, v28, 1.0
	v_sqrt_f32_e32 v27, v27
	v_add_f32_e32 v23, 1.0, v23
	v_rcp_f32_e32 v23, v23
	v_pk_mul_f32 v[234:235], v[0:1], v[176:177]
	v_mul_f32_e32 v29, v11, v27
	v_sub_f32_e32 v11, v13, v196
	v_mul_f32_e32 v13, v197, v23
	v_exp_f32_e32 v11, v11
	v_exp_f32_e32 v207, v13
	v_sub_f32_e32 v23, v30, v195
	v_exp_f32_e32 v23, v23
	v_add_f32_e32 v11, 1.0, v11
	v_fma_f32 v13, -v207, v207, 1.0
	v_rcp_f32_e32 v11, v11
	v_sqrt_f32_e32 v13, v13
	v_exp_f32_e32 v27, v14
	v_sub_f32_e32 v15, v15, v196
	v_pk_fma_f32 v[236:237], v[0:1], v[176:177], v[234:235] op_sel_hi:[1,1,0]
	v_mul_f32_e32 v14, v11, v13
	v_add_f32_e32 v11, 1.0, v23
	v_rcp_f32_e32 v11, v11
	v_sub_f32_e32 v23, v31, v195
	v_exp_f32_e32 v23, v23
	v_add_f32_e32 v13, 1.0, v27
	v_mul_f32_e32 v11, v197, v11
	v_exp_f32_e32 v31, v11
	v_rcp_f32_e32 v11, v13
	v_add_f32_e32 v13, 1.0, v23
	v_rcp_f32_e32 v13, v13
	s_waitcnt lgkmcnt(4)
	v_lshlrev_b32_e32 v204, 16, v199
	s_waitcnt lgkmcnt(3)
	v_lshlrev_b32_e32 v199, 16, v206
	s_waitcnt lgkmcnt(2)
	v_lshlrev_b32_e32 v206, 16, v228
	v_mul_f32_e32 v13, v197, v13
	v_exp_f32_e32 v15, v15
	v_exp_f32_e32 v229, v13
	s_waitcnt lgkmcnt(0)
	v_lshlrev_b32_e32 v228, 16, v187
	v_mov_b32_e32 v187, v237
	v_pk_mul_f32 v[236:237], v[186:187], v[16:17]
	v_fma_f32 v23, -v31, v31, 1.0
	v_pk_fma_f32 v[186:187], v[186:187], v[16:17], v[236:237] op_sel_hi:[1,1,0]
	v_sqrt_f32_e32 v13, v23
	v_mov_b32_e32 v189, v187
	v_add_f32_e32 v15, 1.0, v15
	v_fma_f32 v23, -v229, v229, 1.0
	v_pk_mul_f32 v[186:187], v[188:189], v[184:185]
	v_rcp_f32_e32 v15, v15
	v_sqrt_f32_e32 v23, v23
	v_pk_fma_f32 v[188:189], v[188:189], v[184:185], v[186:187] op_sel_hi:[1,1,0]
	v_lshlrev_b32_e32 v24, 16, v191
	v_mov_b32_e32 v191, v189
	v_mov_b32_e32 v177, v201
	v_pk_mul_f32 v[188:189], v[190:191], v[2:3]
	v_pk_mul_f32 v[190:191], v[4:5], v[176:177]
	v_mul_f32_e32 v232, v15, v23
	v_pk_fma_f32 v[238:239], v[4:5], v[176:177], v[190:191] op_sel_hi:[1,1,0]
	v_lshlrev_b32_e32 v202, 16, v193
	v_mov_b32_e32 v23, v239
	v_pk_mul_f32 v[238:239], v[22:23], v[18:19]
	v_mov_b32_e32 v177, v231
	v_pk_fma_f32 v[22:23], v[22:23], v[18:19], v[238:239] op_sel_hi:[1,1,0]
	v_lshlrev_b32_e32 v30, 16, v230
	v_mov_b32_e32 v193, v23
	v_pk_mul_f32 v[22:23], v[192:193], v[20:21]
	v_mul_f32_e32 v230, v11, v13
	v_pk_fma_f32 v[192:193], v[192:193], v[20:21], v[22:23] op_sel_hi:[1,1,0]
	v_mul_f32_e32 v1, v0, v17
	v_mov_b32_e32 v201, v193
	v_pk_mul_f32 v[192:193], v[200:201], v[6:7]
	v_pk_mul_f32 v[200:201], v[8:9], v[176:177]
	v_mul_f32_e32 v1, v185, v1
	v_pk_fma_f32 v[240:241], v[8:9], v[176:177], v[200:201] op_sel_hi:[1,1,0]
	v_mov_b32_e32 v177, v199
	v_mov_b32_e32 v11, v241
	v_pk_mul_f32 v[240:241], v[10:11], v[24:25]
	v_pk_mul_f32 v[244:245], v[28:29], v[176:177]
	v_pk_fma_f32 v[10:11], v[10:11], v[24:25], v[240:241] op_sel_hi:[1,1,0]
	v_add_f32_e32 v16, v188, v189
	v_mov_b32_e32 v27, v11
	v_pk_mul_f32 v[242:243], v[26:27], v[202:203]
	v_mul_f32_e32 v184, v3, v1
	v_pk_fma_f32 v[10:11], v[26:27], v[202:203], v[242:243] op_sel_hi:[1,1,0]
	v_mul_f32_e32 v1, v4, v19
	v_mov_b32_e32 v13, v11
	v_pk_fma_f32 v[10:11], v[28:29], v[176:177], v[244:245] op_sel_hi:[1,1,0]
	v_mul_f32_e32 v1, v21, v1
	v_mov_b32_e32 v15, v11
	v_pk_mul_f32 v[246:247], v[14:15], v[206:207]
	v_add_f32_e32 v18, v192, v193
	v_pk_fma_f32 v[10:11], v[14:15], v[206:207], v[246:247] op_sel_hi:[1,1,0]
	v_mul_f32_e32 v20, v7, v1
	v_mov_b32_e32 v231, v11
	v_pk_mul_f32 v[248:249], v[230:231], v[30:31]
	v_mul_f32_e32 v1, v8, v25
	v_pk_fma_f32 v[10:11], v[230:231], v[30:31], v[248:249] op_sel_hi:[1,1,0]
	ds_bpermute_b32 v10, v209, v184
	v_mov_b32_e32 v233, v11
	ds_bpermute_b32 v11, v209, v16
	v_mul_f32_e32 v1, v203, v1
	v_pk_mul_f32 v[26:27], v[12:13], v[204:205]
	ds_bpermute_b32 v13, v209, v20
	ds_bpermute_b32 v14, v209, v18
	v_add_f32_e32 v9, v26, v27
	v_mul_f32_e32 v12, v205, v1
	v_mul_f32_e32 v1, v28, v207
	v_mul_f32_e32 v2, v31, v1
	v_pk_mul_f32 v[230:231], v[232:233], v[228:229]
	ds_bpermute_b32 v15, v209, v12
	ds_bpermute_b32 v23, v209, v9
	v_add_f32_e32 v1, v230, v231
	v_mul_f32_e32 v2, v229, v2
	s_waitcnt lgkmcnt(5)
	v_cndmask_b32_e64 v24, v10, v184, s[0:1]
	s_waitcnt lgkmcnt(4)
	v_cndmask_b32_e64 v27, v11, v16, s[0:1]
	ds_bpermute_b32 v5, v209, v2
	ds_bpermute_b32 v6, v209, v1
	v_cndmask_b32_e64 v10, v184, v10, s[0:1]
	v_cndmask_b32_e64 v11, v16, v11, s[0:1]
	v_fmac_f32_e32 v27, v194, v24
	v_fmac_f32_e32 v11, v10, v27
	s_waitcnt lgkmcnt(5)
	v_cndmask_b32_e64 v16, v13, v20, s[0:1]
	s_waitcnt lgkmcnt(4)
	v_cndmask_b32_e64 v24, v14, v18, s[0:1]
	v_cndmask_b32_e64 v13, v20, v13, s[0:1]
	v_cndmask_b32_e64 v14, v18, v14, s[0:1]
	v_fmac_f32_e32 v24, v16, v11
	v_fmac_f32_e32 v14, v13, v24
	s_waitcnt lgkmcnt(3)
	v_cndmask_b32_e64 v13, v15, v12, s[0:1]
	s_waitcnt lgkmcnt(2)
	v_cndmask_b32_e64 v16, v23, v9, s[0:1]
	v_cndmask_b32_e64 v12, v12, v15, s[0:1]
	v_cndmask_b32_e64 v15, v9, v23, s[0:1]
	v_fmac_f32_e32 v16, v13, v14
	v_fmac_f32_e32 v15, v12, v16
	s_waitcnt lgkmcnt(1)
	v_cndmask_b32_e64 v13, v5, v2, s[0:1]
	s_waitcnt lgkmcnt(0)
	v_cndmask_b32_e64 v9, v6, v1, s[0:1]
	v_fmac_f32_e32 v9, v13, v15
	v_cndmask_b32_e64 v10, v27, v194, s[0:1]
	v_cndmask_b32_e64 v11, v24, v11, s[0:1]
	v_cndmask_b32_e64 v12, v16, v14, s[0:1]
	v_cndmask_b32_e64 v13, v9, v15, s[0:1]
	s_ashr_i32 s47, s46, 31
	v_fmac_f32_e32 v235, v0, v10
	v_fmac_f32_e32 v191, v4, v11
	v_fmac_f32_e32 v201, v8, v12
	v_fmac_f32_e32 v245, v28, v13
	v_fmac_f32_e32 v236, v17, v235
	v_fmac_f32_e32 v238, v19, v191
	v_fmac_f32_e32 v240, v25, v201
	v_fmac_f32_e32 v246, v207, v245
	s_lshl_b64 s[36:37], s[46:47], 11
	v_fmac_f32_e32 v186, v185, v236
	v_fmac_f32_e32 v22, v21, v238
	v_fmac_f32_e32 v242, v203, v240
	v_fmac_f32_e32 v248, v31, v246
	v_lshl_add_u64 v[18:19], v[174:175], 0, s[36:37]
	s_and_b64 vcc, exec, s[2:3]
	v_fmac_f32_e32 v188, v3, v186
	v_fmac_f32_e32 v192, v7, v22
	v_fmac_f32_e32 v26, v205, v242
	v_fmac_f32_e32 v230, v229, v248
	v_cvt_pk_bf16_f32 v10, v235, v236
	v_cvt_pk_bf16_f32 v11, v186, v188
	v_cvt_pk_bf16_f32 v12, v191, v238
	v_cvt_pk_bf16_f32 v13, v22, v192
	v_cvt_pk_bf16_f32 v14, v201, v240
	v_cvt_pk_bf16_f32 v15, v242, v26
	v_cvt_pk_bf16_f32 v16, v245, v246
	v_cvt_pk_bf16_f32 v17, v248, v230
	global_store_dwordx4 v[18:19], v[10:13], off
	global_store_dwordx4 v[18:19], v[14:17], off offset:1024
	s_cbranch_vccnz .LBB0_427
	s_waitcnt vmcnt(2)
	ds_write_b128 v198, v[160:163] offset:16
	s_branch .LBB0_427

.LBB0_446:
	s_nop 2
	v_sub_f32_e32 v16, v16, v177
	v_exp_f32_e32 v16, v16
	v_sub_f32_e32 v17, v17, v177
	v_exp_f32_e32 v17, v17
	v_sub_f32_e32 v0, v0, v228
	v_add_f32_e32 v16, 1.0, v16
	v_rcp_f32_e32 v16, v16
	v_exp_f32_e32 v0, v0
	v_sub_f32_e32 v1, v1, v228
	v_exp_f32_e32 v1, v1
	v_mul_f32_e32 v16, v229, v16
	v_exp_f32_e32 v241, v16
	v_add_f32_e32 v16, 1.0, v17
	v_rcp_f32_e32 v16, v16
	v_add_f32_e32 v0, 1.0, v0
	v_fma_f32 v17, -v241, v241, 1.0
	v_rcp_f32_e32 v0, v0
	v_mul_f32_e32 v16, v229, v16
	v_exp_f32_e32 v242, v16
	v_sqrt_f32_e32 v16, v17
	v_add_f32_e32 v1, 1.0, v1
	v_rcp_f32_e32 v1, v1
	v_fma_f32 v17, -v242, v242, 1.0
	v_sqrt_f32_e32 v17, v17
	v_add3_u32 v233, s34, v214, v215
	ds_read_u16 v231, v233
	ds_read_u16 v234, v233 offset:528
	ds_read_u16 v235, v233 offset:1056
	ds_read_u16 v236, v233 offset:1584
	ds_read_u16 v237, v233 offset:4224
	ds_read_u16 v238, v233 offset:4752
	ds_read_u16 v239, v233 offset:5280
	ds_read_u16 v240, v233 offset:5808
	s_waitcnt lgkmcnt(7)
	v_lshlrev_b32_e32 v231, 16, v231
	v_mul_f32_e32 v0, v0, v16
	v_mul_f32_e32 v232, v0, v231
	s_waitcnt lgkmcnt(6)
	v_lshlrev_b32_e32 v0, 16, v234
	v_mul_f32_e32 v1, v1, v17
	v_mul_f32_e32 v231, v1, v0
	v_sub_f32_e32 v0, v18, v177
	v_exp_f32_e32 v0, v0
	v_sub_f32_e32 v1, v2, v228
	v_exp_f32_e32 v1, v1
	v_sub_f32_e32 v16, v19, v177
	v_add_f32_e32 v0, 1.0, v0
	v_rcp_f32_e32 v0, v0
	v_exp_f32_e32 v16, v16
	v_add_f32_e32 v1, 1.0, v1
	v_sub_f32_e32 v3, v3, v228
	v_mul_f32_e32 v0, v229, v0
	v_exp_f32_e32 v234, v0
	v_rcp_f32_e32 v0, v1
	v_add_f32_e32 v1, 1.0, v16
	v_rcp_f32_e32 v1, v1
	s_waitcnt lgkmcnt(5)
	v_lshlrev_b32_e32 v2, 16, v235
	v_exp_f32_e32 v3, v3
	v_fma_f32 v16, -v234, v234, 1.0
	v_mul_f32_e32 v1, v229, v1
	v_exp_f32_e32 v235, v1
	v_sqrt_f32_e32 v1, v16
	v_add_f32_e32 v3, 1.0, v3
	v_rcp_f32_e32 v3, v3
	v_fma_f32 v16, -v235, v235, 1.0
	v_sqrt_f32_e32 v16, v16
	v_mul_f32_e32 v0, v0, v1
	v_mul_f32_e32 v17, v0, v2
	s_waitcnt lgkmcnt(4)
	v_lshlrev_b32_e32 v0, 16, v236
	v_mul_f32_e32 v1, v3, v16
	v_mul_f32_e32 v16, v1, v0
	v_sub_f32_e32 v0, v20, v177
	v_exp_f32_e32 v0, v0
	v_sub_f32_e32 v1, v4, v228
	v_exp_f32_e32 v1, v1
	v_sub_f32_e32 v3, v21, v177
	v_add_f32_e32 v0, 1.0, v0
	v_rcp_f32_e32 v0, v0
	v_exp_f32_e32 v3, v3
	v_add_f32_e32 v1, 1.0, v1
	v_sub_f32_e32 v4, v5, v228
	v_mul_f32_e32 v0, v229, v0
	v_exp_f32_e32 v236, v0
	v_rcp_f32_e32 v0, v1
	v_add_f32_e32 v1, 1.0, v3
	v_rcp_f32_e32 v1, v1
	v_exp_f32_e32 v4, v4
	s_waitcnt lgkmcnt(3)
	v_lshlrev_b32_e32 v2, 16, v237
	v_fma_f32 v3, -v236, v236, 1.0
	v_mul_f32_e32 v1, v229, v1
	v_exp_f32_e32 v237, v1
	v_sqrt_f32_e32 v1, v3
	v_add_f32_e32 v3, 1.0, v4
	v_rcp_f32_e32 v4, v3
	v_fma_f32 v3, -v237, v237, 1.0
	v_sqrt_f32_e32 v5, v3
	v_mul_f32_e32 v0, v0, v1
	v_mul_f32_e32 v3, v0, v2
	s_waitcnt lgkmcnt(2)
	v_lshlrev_b32_e32 v0, 16, v238
	v_mul_f32_e32 v1, v4, v5
	v_mul_f32_e32 v2, v1, v0
	v_sub_f32_e32 v0, v22, v177
	v_exp_f32_e32 v0, v0
	v_sub_f32_e32 v1, v6, v228
	v_exp_f32_e32 v1, v1
	v_sub_f32_e32 v5, v23, v177
	v_add_f32_e32 v0, 1.0, v0
	v_rcp_f32_e32 v0, v0
	v_exp_f32_e32 v5, v5
	v_add_f32_e32 v1, 1.0, v1
	v_sub_f32_e32 v6, v7, v228
	v_mul_f32_e32 v0, v229, v0
	v_exp_f32_e32 v22, v0
	v_rcp_f32_e32 v0, v1
	v_add_f32_e32 v1, 1.0, v5
	v_rcp_f32_e32 v1, v1
	v_exp_f32_e32 v6, v6
	v_fma_f32 v5, -v22, v22, 1.0
	s_waitcnt lgkmcnt(1)
	v_lshlrev_b32_e32 v4, 16, v239
	v_mul_f32_e32 v1, v229, v1
	v_exp_f32_e32 v23, v1
	v_sqrt_f32_e32 v1, v5
	v_add_f32_e32 v5, 1.0, v6
	v_rcp_f32_e32 v5, v5
	v_fma_f32 v6, -v23, v23, 1.0
	v_sqrt_f32_e32 v6, v6
	v_mul_f32_e32 v0, v0, v1
	v_mul_f32_e32 v1, v0, v4
	s_waitcnt lgkmcnt(0)
	v_lshlrev_b32_e32 v0, 16, v240
	v_mul_f32_e32 v4, v5, v6
	v_mul_f32_e32 v0, v4, v0
	v_sub_f32_e32 v4, v24, v177
	v_exp_f32_e32 v4, v4
	v_sub_f32_e32 v5, v8, v228
	v_exp_f32_e32 v5, v5
	v_sub_f32_e32 v19, v25, v177
	v_add_f32_e32 v4, 1.0, v4
	v_rcp_f32_e32 v4, v4
	v_exp_f32_e32 v19, v19
	v_add_f32_e32 v5, 1.0, v5
	v_sub_f32_e32 v9, v9, v228
	v_mul_f32_e32 v4, v229, v4
	v_exp_f32_e32 v25, v4
	v_rcp_f32_e32 v4, v5
	v_add_f32_e32 v5, 1.0, v19
	v_rcp_f32_e32 v5, v5
	v_exp_f32_e32 v9, v9
	v_fma_f32 v19, -v25, v25, 1.0
	ds_read_u16 v6, v233 offset:8448
	ds_read_u16 v7, v233 offset:8976
	ds_read_u16 v8, v233 offset:9504
	ds_read_u16 v18, v233 offset:10032
	ds_read_u16 v24, v233 offset:12672
	ds_read_u16 v238, v233 offset:13200
	ds_read_u16 v239, v233 offset:13728
	ds_read_u16 v233, v233 offset:14256
	v_mul_f32_e32 v5, v229, v5
	v_exp_f32_e32 v240, v5
	v_sqrt_f32_e32 v5, v19
	v_add_f32_e32 v9, 1.0, v9
	v_rcp_f32_e32 v9, v9
	v_fma_f32 v19, -v240, v240, 1.0
	v_sqrt_f32_e32 v19, v19
	s_waitcnt lgkmcnt(7)
	v_lshlrev_b32_e32 v6, 16, v6
	v_mul_f32_e32 v4, v4, v5
	v_mul_f32_e32 v21, v4, v6
	s_waitcnt lgkmcnt(6)
	v_lshlrev_b32_e32 v4, 16, v7
	v_mul_f32_e32 v5, v9, v19
	v_mul_f32_e32 v20, v5, v4
	v_sub_f32_e32 v4, v26, v177
	v_exp_f32_e32 v4, v4
	v_sub_f32_e32 v5, v10, v228
	v_exp_f32_e32 v5, v5
	v_sub_f32_e32 v7, v27, v177
	v_add_f32_e32 v4, 1.0, v4
	v_rcp_f32_e32 v4, v4
	v_exp_f32_e32 v7, v7
	v_add_f32_e32 v5, 1.0, v5
	s_waitcnt lgkmcnt(5)
	v_lshlrev_b32_e32 v6, 16, v8
	v_mul_f32_e32 v4, v229, v4
	v_exp_f32_e32 v26, v4
	v_rcp_f32_e32 v4, v5
	v_add_f32_e32 v5, 1.0, v7
	v_rcp_f32_e32 v5, v5
	v_sub_f32_e32 v8, v11, v228
	v_exp_f32_e32 v8, v8
	v_fma_f32 v7, -v26, v26, 1.0
	v_mul_f32_e32 v5, v229, v5
	v_exp_f32_e32 v27, v5
	v_sqrt_f32_e32 v5, v7
	v_add_f32_e32 v7, 1.0, v8
	v_rcp_f32_e32 v7, v7
	v_fma_f32 v8, -v27, v27, 1.0
	v_sqrt_f32_e32 v8, v8
	v_mul_f32_e32 v4, v4, v5
	v_mul_f32_e32 v19, v4, v6
	s_waitcnt lgkmcnt(4)
	v_lshlrev_b32_e32 v4, 16, v18
	v_mul_f32_e32 v5, v7, v8
	v_mul_f32_e32 v18, v5, v4
	v_sub_f32_e32 v4, v28, v177
	v_exp_f32_e32 v4, v4
	v_sub_f32_e32 v5, v12, v228
	v_exp_f32_e32 v5, v5
	v_sub_f32_e32 v7, v29, v177
	v_add_f32_e32 v4, 1.0, v4
	v_rcp_f32_e32 v4, v4
	v_exp_f32_e32 v7, v7
	v_add_f32_e32 v5, 1.0, v5
	s_waitcnt lgkmcnt(3)
	v_lshlrev_b32_e32 v6, 16, v24
	v_mul_f32_e32 v4, v229, v4
	v_exp_f32_e32 v24, v4
	v_rcp_f32_e32 v4, v5
	v_add_f32_e32 v5, 1.0, v7
	v_rcp_f32_e32 v5, v5
	v_sub_f32_e32 v8, v13, v228
	v_exp_f32_e32 v8, v8
	v_fma_f32 v7, -v24, v24, 1.0
	v_mul_f32_e32 v5, v229, v5
	v_exp_f32_e32 v28, v5
	v_sqrt_f32_e32 v5, v7
	v_add_f32_e32 v7, 1.0, v8
	v_rcp_f32_e32 v7, v7
	v_fma_f32 v8, -v28, v28, 1.0
	v_sqrt_f32_e32 v8, v8
	v_mul_f32_e32 v4, v4, v5
	v_mul_f32_e32 v11, v4, v6
	s_waitcnt lgkmcnt(2)
	v_lshlrev_b32_e32 v4, 16, v238
	v_mul_f32_e32 v5, v7, v8
	v_mul_f32_e32 v10, v5, v4
	v_sub_f32_e32 v4, v30, v177
	v_exp_f32_e32 v4, v4
	v_sub_f32_e32 v5, v14, v228
	v_exp_f32_e32 v5, v5
	v_sub_f32_e32 v7, v31, v177
	v_add_f32_e32 v4, 1.0, v4
	v_rcp_f32_e32 v4, v4
	v_exp_f32_e32 v7, v7
	v_add_f32_e32 v5, 1.0, v5
	v_sub_f32_e32 v8, v15, v228
	v_mul_f32_e32 v4, v229, v4
	v_exp_f32_e32 v14, v4
	v_rcp_f32_e32 v4, v5
	v_add_f32_e32 v5, 1.0, v7
	v_rcp_f32_e32 v5, v5
	v_exp_f32_e32 v8, v8
	v_fma_f32 v7, -v14, v14, 1.0
	s_waitcnt lgkmcnt(1)
	v_lshlrev_b32_e32 v6, 16, v239
	v_mul_f32_e32 v5, v229, v5
	v_exp_f32_e32 v15, v5
	v_sqrt_f32_e32 v5, v7
	v_add_f32_e32 v7, 1.0, v8
	v_rcp_f32_e32 v8, v7
	v_fma_f32 v7, -v15, v15, 1.0
	v_sqrt_f32_e32 v9, v7
	v_mul_f32_e32 v4, v4, v5
	v_mul_f32_e32 v7, v4, v6
	s_waitcnt lgkmcnt(0)
	v_lshlrev_b32_e32 v4, 16, v233
	v_mul_f32_e32 v5, v8, v9
	v_fma_f32 v8, 0, v23, v0
	v_fma_f32 v8, v22, v8, v1
	v_fma_f32 v8, v237, v8, v2
	v_mul_f32_e32 v9, v23, v22
	v_fma_f32 v29, v236, v8, v3
	v_fma_f32 v8, 0, v27, v18
	v_mul_f32_e32 v9, v237, v9
	v_fma_f32 v8, v26, v8, v19
	v_mul_f32_e32 v6, v5, v4
	v_mul_f32_e32 v30, v236, v9
	v_mul_f32_e32 v9, v27, v26
	v_fma_f32 v8, v240, v8, v20
	v_mul_f32_e32 v9, v240, v9
	v_fma_f32 v12, v25, v8, v21
	v_fma_f32 v8, 0, v15, v6
	v_mul_f32_e32 v13, v25, v9
	v_fma_f32 v8, v14, v8, v7
	v_mul_f32_e32 v9, v15, v14
	v_fma_f32 v8, v28, v8, v10
	v_mul_f32_e32 v9, v28, v9
	v_fma_f32 v31, v24, v8, v11
	v_mul_f32_e32 v233, v24, v9
	ds_bpermute_b32 v239, v209, v233
	ds_bpermute_b32 v243, v209, v31
	ds_bpermute_b32 v245, v209, v13
	ds_bpermute_b32 v246, v209, v12
	v_lshl_add_u64 v[206:207], v[196:197], 0, s[44:45]
	s_waitcnt lgkmcnt(3)
	v_cndmask_b32_e64 v247, v239, v233, s[0:1]
	s_waitcnt lgkmcnt(2)
	v_cndmask_b32_e64 v248, v243, v31, s[0:1]
	v_cndmask_b32_e64 v233, v233, v239, s[0:1]
	v_cndmask_b32_e64 v31, v31, v243, s[0:1]
	v_fmac_f32_e32 v31, v227, v233
	v_fmac_f32_e32 v248, v247, v31
	v_cndmask_b32_e64 v31, v227, v31, s[0:1]
	s_waitcnt lgkmcnt(1)
	v_cndmask_b32_e64 v227, v245, v13, s[0:1]
	s_waitcnt lgkmcnt(0)
	v_cndmask_b32_e64 v233, v246, v12, s[0:1]
	v_cndmask_b32_e64 v13, v13, v245, s[0:1]
	v_cndmask_b32_e64 v239, v12, v246, s[0:1]
	v_add_co_u32_e32 v12, vcc, s66, v206
	v_fmac_f32_e32 v239, v13, v248
	s_nop 0
	v_addc_co_u32_e32 v13, vcc, 0, v207, vcc
	v_fmac_f32_e32 v233, v227, v239
	global_load_ushort v227, v[12:13], off
	v_add_co_u32_e32 v12, vcc, s67, v206
	v_fma_f32 v4, 0, v235, v16
	s_nop 0
	v_addc_co_u32_e32 v13, vcc, 0, v207, vcc
	global_load_ushort v13, v[12:13], off
	v_fma_f32 v4, v234, v4, v17
	v_mul_f32_e32 v5, v235, v234
	v_fma_f32 v4, v242, v4, v231
	v_mul_f32_e32 v5, v242, v5
	ds_bpermute_b32 v238, v209, v30
	ds_bpermute_b32 v244, v209, v29
	v_fma_f32 v4, v241, v4, v232
	v_mul_f32_e32 v5, v241, v5
	ds_bpermute_b32 v8, v209, v5
	ds_bpermute_b32 v9, v209, v4
	s_waitcnt lgkmcnt(3)
	v_cndmask_b32_e64 v12, v238, v30, s[0:1]
	s_waitcnt lgkmcnt(2)
	v_cndmask_b32_e64 v243, v244, v29, s[0:1]
	v_cndmask_b32_e64 v30, v30, v238, s[0:1]
	v_cndmask_b32_e64 v29, v29, v244, s[0:1]
	v_fmac_f32_e32 v29, v30, v233
	v_fmac_f32_e32 v6, v15, v31
	v_fmac_f32_e32 v243, v12, v29
	s_waitcnt lgkmcnt(1)
	v_cndmask_b32_e64 v30, v5, v8, s[0:1]
	s_waitcnt lgkmcnt(0)
	v_cndmask_b32_e64 v12, v4, v9, s[0:1]
	v_fmac_f32_e32 v7, v14, v6
	v_add_co_u32_e32 v14, vcc, s76, v206
	v_fmac_f32_e32 v12, v30, v243
	s_nop 0
	v_addc_co_u32_e32 v15, vcc, 0, v207, vcc
	v_cndmask_b32_e64 v29, v233, v29, s[0:1]
	v_cndmask_b32_e64 v30, v243, v12, s[0:1]
	global_load_ushort v243, v[14:15], off
	v_add_co_u32_e32 v14, vcc, s77, v206
	v_lshl_add_u64 v[204:205], v[192:193], 0, s[44:45]
	v_cndmask_b32_e64 v239, v248, v239, s[0:1]
	v_fmac_f32_e32 v0, v23, v29
	v_addc_co_u32_e32 v15, vcc, 0, v207, vcc
	v_fmac_f32_e32 v1, v22, v0
	v_fmac_f32_e32 v18, v27, v239
	v_add_co_u32_e32 v22, vcc, s66, v204
	v_fmac_f32_e32 v19, v26, v18
	v_fmac_f32_e32 v10, v28, v7
	v_addc_co_u32_e32 v23, vcc, 0, v205, vcc
	v_fmac_f32_e32 v20, v240, v19
	v_fmac_f32_e32 v11, v24, v10
	v_add_co_u32_e32 v24, vcc, s67, v204
	v_fmac_f32_e32 v21, v25, v20
	s_nop 0
	v_addc_co_u32_e32 v25, vcc, 0, v205, vcc
	v_add_co_u32_e32 v26, vcc, s76, v204
	v_fmac_f32_e32 v16, v235, v30
	s_nop 0
	v_addc_co_u32_e32 v27, vcc, 0, v205, vcc
	v_add_co_u32_e32 v28, vcc, s77, v204
	v_fmac_f32_e32 v17, v234, v16
	s_nop 0
	v_addc_co_u32_e32 v29, vcc, 0, v205, vcc
	global_load_ushort v204, v[14:15], off
	global_load_ushort v205, v[22:23], off
	global_load_ushort v206, v[24:25], off
	global_load_ushort v207, v[26:27], off
	global_load_ushort v244, v[28:29], off
	v_fmac_f32_e32 v231, v242, v17
	v_fmac_f32_e32 v232, v241, v231
	s_waitcnt vmcnt(9)
	v_lshlrev_b32_e32 v30, 16, v168
	v_and_b32_e32 v31, 0xffff0000, v168
	v_add_f32_e32 v23, v232, v30
	v_lshl_add_u64 v[202:203], v[188:189], 0, s[44:45]
	v_lshl_add_u64 v[200:201], v[184:185], 0, s[44:45]
	v_fmac_f32_e32 v2, v237, v1
	v_fmac_f32_e32 v3, v236, v2
	s_waitcnt vmcnt(8)
	v_lshlrev_b32_e32 v235, 16, v164
	v_and_b32_e32 v236, 0xffff0000, v164
	v_lshlrev_b32_e32 v237, 16, v165
	s_waitcnt vmcnt(7)
	v_lshlrev_b32_e32 v14, 16, v227
	v_mul_f32_e32 v15, v14, v14
	v_fmamk_f32 v15, v15, 0xbdd2d3e7, v225
	v_mul_f32_e32 v15, v15, v14
	v_exp_f32_e32 v15, v15
	v_and_b32_e32 v238, 0xffff0000, v165
	s_waitcnt vmcnt(6)
	v_lshlrev_b32_e32 v13, 16, v13
	v_mul_f32_e32 v22, v13, v13
	v_fmamk_f32 v22, v22, 0xbdd2d3e7, v225
	v_mul_f32_e32 v22, v22, v13
	v_exp_f32_e32 v22, v22
	v_add_f32_e32 v15, 1.0, v15
	v_rcp_f32_e32 v15, v15
	v_lshlrev_b32_e32 v239, 16, v166
	v_add_f32_e32 v22, 1.0, v22
	v_rcp_f32_e32 v22, v22
	v_mul_f32_e32 v14, v15, v14
	v_mul_f32_e32 v227, v14, v23
	v_add_f32_e32 v14, v231, v31
	v_mul_f32_e32 v13, v22, v13
	v_mul_f32_e32 v13, v13, v14
	v_add_co_u32_e32 v14, vcc, s66, v202
	v_and_b32_e32 v240, 0xffff0000, v166
	s_nop 0
	v_addc_co_u32_e32 v15, vcc, 0, v203, vcc
	v_add_co_u32_e32 v22, vcc, s67, v202
	v_lshlrev_b32_e32 v241, 16, v167
	s_nop 0
	v_addc_co_u32_e32 v23, vcc, 0, v203, vcc
	v_add_co_u32_e32 v24, vcc, s76, v202
	v_and_b32_e32 v242, 0xffff0000, v167
	s_nop 0
	v_addc_co_u32_e32 v25, vcc, 0, v203, vcc
	v_add_co_u32_e32 v26, vcc, s77, v202
	v_lshlrev_b32_e32 v168, 16, v169
	s_nop 0
	v_addc_co_u32_e32 v27, vcc, 0, v203, vcc
	v_add_co_u32_e32 v28, vcc, s66, v200
	v_and_b32_e32 v169, 0xffff0000, v169
	s_nop 0
	v_addc_co_u32_e32 v29, vcc, 0, v201, vcc
	v_add_co_u32_e32 v30, vcc, s67, v200
	v_add_f32_e32 v17, v17, v168
	s_nop 0
	v_addc_co_u32_e32 v31, vcc, 0, v201, vcc
	v_add_co_u32_e32 v164, vcc, s76, v200
	v_add_f32_e32 v16, v16, v169
	s_nop 0
	v_addc_co_u32_e32 v165, vcc, 0, v201, vcc
	v_add_co_u32_e32 v166, vcc, s77, v200
	v_lshlrev_b32_e32 v233, 16, v170
	s_nop 0
	v_addc_co_u32_e32 v167, vcc, 0, v201, vcc
	global_load_ushort v200, v[14:15], off
	global_load_ushort v201, v[22:23], off
	s_nop 0
	global_load_ushort v24, v[24:25], off
	s_nop 0
	global_load_ushort v25, v[26:27], off
	s_nop 0
	global_load_ushort v26, v[28:29], off
	global_load_ushort v27, v[30:31], off
	s_nop 0
	global_load_ushort v28, v[164:165], off
	global_load_ushort v29, v[166:167], off
	v_lshl_add_u64 v[14:15], v[198:199], 0, s[44:45]
	v_add_co_u32_e32 v22, vcc, s78, v14
	v_cvt_pk_bf16_f32 v13, v227, v13
	v_and_b32_e32 v170, 0xffff0000, v170
	s_nop 0
	v_addc_co_u32_e32 v23, vcc, 0, v15, vcc
	global_store_short v[22:23], v13, off
	v_add_co_u32_e32 v22, vcc, s79, v14
	v_add_f32_e32 v3, v3, v233
	s_nop 0
	v_addc_co_u32_e32 v23, vcc, 0, v15, vcc
	global_store_short_d16_hi v[22:23], v13, off
	s_waitcnt vmcnt(15)
	v_lshlrev_b32_e32 v13, 16, v243
	v_mul_f32_e32 v22, v13, v13
	s_waitcnt vmcnt(14)
	v_lshlrev_b32_e32 v23, 16, v204
	v_fmamk_f32 v22, v22, 0xbdd2d3e7, v225
	v_mul_f32_e32 v30, v23, v23
	v_mul_f32_e32 v22, v22, v13
	v_fmamk_f32 v30, v30, 0xbdd2d3e7, v225
	v_exp_f32_e32 v22, v22
	v_mul_f32_e32 v30, v30, v23
	v_exp_f32_e32 v30, v30
	v_add_f32_e32 v2, v2, v170
	v_add_f32_e32 v22, 1.0, v22
	v_rcp_f32_e32 v22, v22
	v_add_f32_e32 v30, 1.0, v30
	v_rcp_f32_e32 v30, v30
	v_lshlrev_b32_e32 v234, 16, v171
	v_mul_f32_e32 v13, v22, v13
	v_mul_f32_e32 v13, v13, v17
	v_mul_f32_e32 v17, v30, v23
	v_mul_f32_e32 v16, v17, v16
	v_cvt_pk_bf16_f32 v13, v13, v16
	v_add_co_u32_e32 v16, vcc, s81, v14
	v_and_b32_e32 v171, 0xffff0000, v171
	s_nop 0
	v_addc_co_u32_e32 v17, vcc, 0, v15, vcc
	v_add_co_u32_e32 v14, vcc, s84, v14
	global_store_short v[16:17], v13, off
	s_nop 0
	v_addc_co_u32_e32 v15, vcc, 0, v15, vcc
	global_store_short_d16_hi v[14:15], v13, off
	s_waitcnt vmcnt(15)
	v_lshlrev_b32_e32 v13, 16, v205
	v_mul_f32_e32 v14, v13, v13
	s_waitcnt vmcnt(14)
	v_lshlrev_b32_e32 v15, 16, v206
	v_fmamk_f32 v14, v14, 0xbdd2d3e7, v225
	v_mul_f32_e32 v16, v15, v15
	v_mul_f32_e32 v14, v14, v13
	v_fmamk_f32 v16, v16, 0xbdd2d3e7, v225
	v_exp_f32_e32 v14, v14
	v_mul_f32_e32 v16, v16, v15
	v_exp_f32_e32 v16, v16
	v_add_f32_e32 v1, v1, v234
	v_add_f32_e32 v14, 1.0, v14
	v_rcp_f32_e32 v14, v14
	v_add_f32_e32 v16, 1.0, v16
	v_rcp_f32_e32 v16, v16
	v_add_f32_e32 v0, v0, v171
	v_mul_f32_e32 v13, v14, v13
	v_mul_f32_e32 v3, v13, v3
	v_mul_f32_e32 v13, v16, v15
	v_mul_f32_e32 v2, v13, v2
	v_cvt_pk_bf16_f32 v13, v3, v2
	v_lshl_add_u64 v[2:3], v[194:195], 0, s[44:45]
	v_add_co_u32_e32 v14, vcc, s78, v2
	v_add_f32_e32 v11, v11, v239
	s_nop 0
	v_addc_co_u32_e32 v15, vcc, 0, v3, vcc
	global_store_short v[14:15], v13, off
	v_add_co_u32_e32 v14, vcc, s79, v2
	v_add_f32_e32 v7, v7, v241
	s_nop 0
	v_addc_co_u32_e32 v15, vcc, 0, v3, vcc
	global_store_short_d16_hi v[14:15], v13, off
	s_waitcnt vmcnt(15)
	v_lshlrev_b32_e32 v13, 16, v207
	v_mul_f32_e32 v14, v13, v13
	s_waitcnt vmcnt(14)
	v_lshlrev_b32_e32 v15, 16, v244
	v_fmamk_f32 v14, v14, 0xbdd2d3e7, v225
	v_mul_f32_e32 v16, v15, v15
	v_mul_f32_e32 v14, v14, v13
	v_fmamk_f32 v16, v16, 0xbdd2d3e7, v225
	v_exp_f32_e32 v14, v14
	v_mul_f32_e32 v16, v16, v15
	v_exp_f32_e32 v16, v16
	v_add_f32_e32 v14, 1.0, v14
	v_rcp_f32_e32 v14, v14
	v_add_f32_e32 v16, 1.0, v16
	v_rcp_f32_e32 v16, v16
	v_mul_f32_e32 v13, v14, v13
	v_mul_f32_e32 v1, v13, v1
	v_mul_f32_e32 v13, v16, v15
	v_mul_f32_e32 v0, v13, v0
	v_cvt_pk_bf16_f32 v13, v1, v0
	v_add_co_u32_e32 v0, vcc, s81, v2
	v_add_f32_e32 v15, v19, v237
	s_nop 0
	v_addc_co_u32_e32 v1, vcc, 0, v3, vcc
	global_store_short v[0:1], v13, off
	v_add_co_u32_e32 v0, vcc, s84, v2
	s_waitcnt vmcnt(13)
	v_lshlrev_b32_e32 v2, 16, v201
	v_addc_co_u32_e32 v1, vcc, 0, v3, vcc
	global_store_short_d16_hi v[0:1], v13, off
	v_lshlrev_b32_e32 v0, 16, v200
	v_mul_f32_e32 v1, v0, v0
	v_mul_f32_e32 v3, v2, v2
	v_fmamk_f32 v1, v1, 0xbdd2d3e7, v225
	v_fmamk_f32 v3, v3, 0xbdd2d3e7, v225
	v_mul_f32_e32 v1, v1, v0
	v_mul_f32_e32 v3, v3, v2
	v_exp_f32_e32 v1, v1
	v_exp_f32_e32 v3, v3
	v_add_f32_e32 v13, v21, v235
	v_add_f32_e32 v1, 1.0, v1
	v_add_f32_e32 v3, 1.0, v3
	v_rcp_f32_e32 v1, v1
	v_rcp_f32_e32 v3, v3
	v_mul_f32_e32 v0, v1, v0
	v_add_f32_e32 v1, v20, v236
	v_mul_f32_e32 v2, v3, v2
	v_mul_f32_e32 v0, v0, v13
	v_mul_f32_e32 v1, v2, v1
	v_cvt_pk_bf16_f32 v13, v0, v1
	v_lshl_add_u64 v[0:1], v[190:191], 0, s[44:45]
	v_add_co_u32_e32 v2, vcc, s78, v0
	s_nop 1
	v_addc_co_u32_e32 v3, vcc, 0, v1, vcc
	global_store_short v[2:3], v13, off
	v_add_co_u32_e32 v2, vcc, s79, v0
	s_nop 1
	v_addc_co_u32_e32 v3, vcc, 0, v1, vcc
	global_store_short_d16_hi v[2:3], v13, off
	s_waitcnt vmcnt(15)
	v_lshlrev_b32_e32 v2, 16, v24
	v_mul_f32_e32 v3, v2, v2
	s_waitcnt vmcnt(14)
	v_lshlrev_b32_e32 v13, 16, v25
	v_fmamk_f32 v3, v3, 0xbdd2d3e7, v225
	v_mul_f32_e32 v14, v13, v13
	v_mul_f32_e32 v3, v3, v2
	v_fmamk_f32 v14, v14, 0xbdd2d3e7, v225
	v_exp_f32_e32 v3, v3
	v_mul_f32_e32 v14, v14, v13
	v_exp_f32_e32 v14, v14
	v_add_f32_e32 v3, 1.0, v3
	v_rcp_f32_e32 v3, v3
	v_add_f32_e32 v14, 1.0, v14
	v_rcp_f32_e32 v14, v14
	v_mul_f32_e32 v2, v3, v2
	v_mul_f32_e32 v2, v2, v15
	v_add_f32_e32 v3, v18, v238
	v_mul_f32_e32 v13, v14, v13
	v_mul_f32_e32 v3, v13, v3
	v_cvt_pk_bf16_f32 v13, v2, v3
	v_add_co_u32_e32 v2, vcc, s81, v0
	s_nop 1
	v_addc_co_u32_e32 v3, vcc, 0, v1, vcc
	v_add_co_u32_e32 v0, vcc, s84, v0
	global_store_short v[2:3], v13, off
	s_nop 0
	v_addc_co_u32_e32 v1, vcc, 0, v1, vcc
	global_store_short_d16_hi v[0:1], v13, off
	s_waitcnt vmcnt(15)
	v_lshlrev_b32_e32 v0, 16, v26
	s_waitcnt vmcnt(14)
	v_lshlrev_b32_e32 v2, 16, v27
	v_mul_f32_e32 v1, v0, v0
	v_mul_f32_e32 v3, v2, v2
	v_fmamk_f32 v1, v1, 0xbdd2d3e7, v225
	v_fmamk_f32 v3, v3, 0xbdd2d3e7, v225
	v_mul_f32_e32 v1, v1, v0
	v_mul_f32_e32 v3, v3, v2
	v_exp_f32_e32 v1, v1
	v_exp_f32_e32 v3, v3
	v_add_f32_e32 v1, 1.0, v1
	v_add_f32_e32 v3, 1.0, v3
	v_rcp_f32_e32 v1, v1
	v_rcp_f32_e32 v3, v3
	v_mul_f32_e32 v0, v1, v0
	v_add_f32_e32 v1, v10, v240
	v_mul_f32_e32 v2, v3, v2
	v_mul_f32_e32 v0, v0, v11
	v_mul_f32_e32 v1, v2, v1
	v_cvt_pk_bf16_f32 v10, v0, v1
	v_lshl_add_u64 v[0:1], v[186:187], 0, s[44:45]
	v_add_co_u32_e32 v2, vcc, s78, v0
	s_nop 1
	v_addc_co_u32_e32 v3, vcc, 0, v1, vcc
	global_store_short v[2:3], v10, off
	v_add_co_u32_e32 v2, vcc, s79, v0
	s_nop 1
	v_addc_co_u32_e32 v3, vcc, 0, v1, vcc
	global_store_short_d16_hi v[2:3], v10, off
	s_waitcnt vmcnt(15)
	v_lshlrev_b32_e32 v2, 16, v28
	v_mul_f32_e32 v3, v2, v2
	s_waitcnt vmcnt(14)
	v_lshlrev_b32_e32 v10, 16, v29
	v_fmamk_f32 v3, v3, 0xbdd2d3e7, v225
	v_mul_f32_e32 v11, v10, v10
	v_mul_f32_e32 v3, v3, v2
	v_fmamk_f32 v11, v11, 0xbdd2d3e7, v225
	v_exp_f32_e32 v3, v3
	v_mul_f32_e32 v11, v11, v10
	v_exp_f32_e32 v11, v11
	v_add_f32_e32 v3, 1.0, v3
	v_rcp_f32_e32 v3, v3
	v_add_f32_e32 v11, 1.0, v11
	v_rcp_f32_e32 v11, v11
	v_mul_f32_e32 v2, v3, v2
	v_mul_f32_e32 v2, v2, v7
	v_add_f32_e32 v3, v6, v242
	v_mul_f32_e32 v6, v11, v10
	v_mul_f32_e32 v3, v6, v3
	v_cvt_pk_bf16_f32 v6, v2, v3
	v_add_co_u32_e32 v2, vcc, 0x1c104000, v0
	s_nop 1
	v_addc_co_u32_e32 v3, vcc, 0, v1, vcc
	v_add_co_u32_e32 v0, vcc, 0x1c106000, v0
	global_store_short v[2:3], v6, off
	s_nop 0
	v_addc_co_u32_e32 v1, vcc, 0, v1, vcc
	s_and_b64 vcc, exec, s[2:3]
	global_store_short_d16_hi v[0:1], v6, off
	s_cbranch_vccnz .LBB0_439
	ds_write_b128 v230, v[160:163] offset:16
	s_branch .LBB0_439

.LBB0_682:
	v_lshl_add_u32 v146, s48, 8, v148
	v_lshl_or_b32 v144, s65, 7, v150
	v_ashrrev_i32_e32 v147, 31, v146
	v_ashrrev_i32_e32 v145, 31, v144
	v_lshlrev_b64 v[154:155], 12, v[146:147]
	v_lshl_add_u64 v[154:155], v[154:155], 0, v[144:145]
	v_lshlrev_b64 v[162:163], 1, v[154:155]
	v_lshl_add_u64 v[158:159], s[74:75], 0, v[162:163]
	v_lshl_add_u64 v[154:155], s[6:7], 0, v[162:163]
	global_load_dwordx4 v[154:157], v[154:155], off
	s_nop 0
	global_load_dwordx4 v[158:161], v[158:159], off
	v_mul_f32_e32 v124, 0xbfb8aa3b, v124
	v_mul_f32_e32 v120, 0xbfb8aa3b, v120
	v_mul_f32_e32 v112, 0xbfb8aa3b, v112
	v_mul_f32_e32 v113, 0xbfb8aa3b, v113
	v_exp_f32_e32 v124, v124
	v_exp_f32_e32 v120, v120
	v_mul_f32_e32 v114, 0xbfb8aa3b, v114
	v_exp_f32_e32 v112, v112
	v_exp_f32_e32 v113, v113
	v_mul_f32_e32 v125, 0xbfb8aa3b, v125
	v_mul_f32_e32 v117, 0xbfb8aa3b, v117
	v_mul_f32_e32 v122, 0xbfb8aa3b, v122
	v_mul_f32_e32 v127, 0xbfb8aa3b, v127
	v_exp_f32_e32 v114, v114
	v_mul_f32_e32 v123, 0xbfb8aa3b, v123
	v_exp_f32_e32 v125, v125
	v_exp_f32_e32 v117, v117
	v_exp_f32_e32 v122, v122
	v_exp_f32_e32 v127, v127
	v_mul_f32_e32 v126, 0xbfb8aa3b, v126
	v_mul_f32_e32 v118, 0xbfb8aa3b, v118
	v_exp_f32_e32 v147, v123
	v_add_f32_e32 v123, 1.0, v124
	v_add_f32_e32 v120, 1.0, v120
	v_exp_f32_e32 v126, v126
	v_exp_f32_e32 v118, v118
	v_add_f32_e32 v124, 1.0, v112
	v_add_f32_e32 v165, 1.0, v113
	v_rcp_f32_e32 v112, v123
	v_rcp_f32_e32 v113, v120
	v_mul_f32_e32 v116, 0xbfb8aa3b, v116
	v_mul_f32_e32 v121, 0xbfb8aa3b, v121
	v_add_f32_e32 v114, 1.0, v114
	v_exp_f32_e32 v116, v116
	v_exp_f32_e32 v121, v121
	v_add_f32_e32 v125, 1.0, v125
	v_add_f32_e32 v164, 1.0, v117
	v_add_f32_e32 v166, 1.0, v122
	v_add_f32_e32 v167, 1.0, v127
	v_rcp_f32_e32 v127, v114
	v_mul_f32_e32 v114, 0xbfb8aa3b, v119
	v_mul_f32_e32 v115, 0xbfb8aa3b, v115
	v_rcp_f32_e32 v120, v125
	v_rcp_f32_e32 v122, v164
	v_rcp_f32_e32 v125, v166
	v_rcp_f32_e32 v164, v167
	v_exp_f32_e32 v114, v114
	v_exp_f32_e32 v115, v115
	v_add_f32_e32 v126, 1.0, v126
	v_add_f32_e32 v118, 1.0, v118
	v_rcp_f32_e32 v117, v124
	v_rcp_f32_e32 v124, v126
	v_rcp_f32_e32 v126, v118
	v_add_f32_e32 v116, 1.0, v116
	v_add_f32_e32 v121, 1.0, v121
	v_rcp_f32_e32 v123, v165
	v_rcp_f32_e32 v116, v116
	v_rcp_f32_e32 v121, v121
	v_add_f32_e32 v114, 1.0, v114
	v_add_f32_e32 v115, 1.0, v115
	v_rcp_f32_e32 v114, v114
	v_rcp_f32_e32 v115, v115
	v_mul_f32_e32 v108, 0xbfb8aa3b, v108
	v_mul_f32_e32 v100, 0xbfb8aa3b, v100
	v_mul_f32_e32 v96, 0xbfb8aa3b, v96
	v_mul_f32_e32 v97, 0xbfb8aa3b, v97
	v_exp_f32_e32 v108, v108
	v_exp_f32_e32 v100, v100
	v_exp_f32_e32 v96, v96
	v_exp_f32_e32 v97, v97
	v_mul_f32_e32 v101, 0xbfb8aa3b, v101
	v_mul_f32_e32 v104, 0xbfb8aa3b, v104
	v_mul_f32_e32 v105, 0xbfb8aa3b, v105
	v_exp_f32_e32 v101, v101
	v_exp_f32_e32 v104, v104
	v_exp_f32_e32 v105, v105
	v_add_f32_e32 v108, 1.0, v108
	v_add_f32_e32 v100, 1.0, v100
	s_waitcnt vmcnt(0)
	v_lshlrev_b32_e32 v167, 16, v154
	v_lshlrev_b32_e32 v166, 16, v158
	v_pk_mul_f32 v[112:113], v[112:113], v[166:167]
	v_lshlrev_b32_e32 v169, 16, v156
	v_add_f32_e32 v118, v112, v113
	v_add_f32_e32 v112, 1.0, v147
	v_rcp_f32_e32 v165, v112
	v_and_b32_e32 v113, 0xffff0000, v155
	v_and_b32_e32 v112, 0xffff0000, v159
	v_lshlrev_b32_e32 v168, 16, v160
	v_and_b32_e32 v171, 0xffff0000, v154
	v_and_b32_e32 v170, 0xffff0000, v158
	v_pk_mul_f32 v[112:113], v[164:165], v[112:113]
	v_and_b32_e32 v173, 0xffff0000, v156
	v_and_b32_e32 v172, 0xffff0000, v160
	v_lshlrev_b32_e32 v175, 16, v155
	v_lshlrev_b32_e32 v174, 16, v159
	v_pk_mul_f32 v[116:117], v[116:117], v[168:169]
	v_pk_mul_f32 v[120:121], v[120:121], v[170:171]
	v_add_f32_e32 v119, v112, v113
	v_and_b32_e32 v113, 0xffff0000, v157
	v_and_b32_e32 v112, 0xffff0000, v161
	v_lshlrev_b32_e32 v177, 16, v157
	v_lshlrev_b32_e32 v176, 16, v161
	v_pk_mul_f32 v[122:123], v[122:123], v[172:173]
	v_pk_mul_f32 v[124:125], v[124:125], v[174:175]
	v_add_f32_e32 v116, v116, v117
	v_add_f32_e32 v117, v120, v121
	v_pk_mul_f32 v[112:113], v[114:115], v[112:113]
	v_pk_mul_f32 v[126:127], v[126:127], v[176:177]
	v_add_f32_e32 v120, v122, v123
	v_add_f32_e32 v121, v124, v125
	v_add_f32_e32 v115, v112, v113
	v_cvt_pk_bf16_f32 v112, v118, v117
	v_cvt_pk_bf16_f32 v113, v121, v119
	v_cvt_pk_bf16_f32 v114, v116, v120
	v_lshl_add_u64 v[116:117], s[8:9], 0, v[162:163]
	v_add_f32_e32 v122, v126, v127
	v_cvt_pk_bf16_f32 v115, v122, v115
	global_store_dwordx4 v[116:117], v[112:115], off
	v_mul_f32_e32 v110, 0xbfb8aa3b, v110
	v_mul_f32_e32 v102, 0xbfb8aa3b, v102
	v_or_b32_e32 v112, 16, v146
	v_ashrrev_i32_e32 v113, 31, v112
	v_lshlrev_b64 v[112:113], 12, v[112:113]
	v_lshl_add_u64 v[112:113], v[112:113], 0, v[144:145]
	v_lshlrev_b64 v[120:121], 1, v[112:113]
	v_lshl_add_u64 v[116:117], s[74:75], 0, v[120:121]
	v_lshl_add_u64 v[112:113], s[6:7], 0, v[120:121]
	global_load_dwordx4 v[112:115], v[112:113], off
	s_nop 0
	global_load_dwordx4 v[116:119], v[116:117], off
	v_add_f32_e32 v122, 1.0, v96
	v_add_f32_e32 v125, 1.0, v97
	v_rcp_f32_e32 v96, v108
	v_rcp_f32_e32 v97, v100
	v_mul_f32_e32 v109, 0xbfb8aa3b, v109
	v_exp_f32_e32 v110, v110
	v_exp_f32_e32 v102, v102
	v_exp_f32_e32 v109, v109
	v_add_f32_e32 v123, 1.0, v101
	v_add_f32_e32 v104, 1.0, v104
	v_add_f32_e32 v124, 1.0, v105
	v_rcp_f32_e32 v101, v122
	v_rcp_f32_e32 v105, v123
	v_rcp_f32_e32 v100, v104
	v_mul_f32_e32 v98, 0xbfb8aa3b, v98
	v_add_f32_e32 v109, 1.0, v109
	v_exp_f32_e32 v98, v98
	v_rcp_f32_e32 v104, v109
	v_rcp_f32_e32 v108, v124
	v_rcp_f32_e32 v109, v125
	v_add_f32_e32 v98, 1.0, v98
	v_mul_f32_e32 v99, 0xbfb8aa3b, v99
	v_exp_f32_e32 v99, v99
	v_mul_f32_e32 v92, 0xbfb8aa3b, v92
	v_mul_f32_e32 v84, 0xbfb8aa3b, v84
	v_mul_f32_e32 v80, 0xbfb8aa3b, v80
	v_add_f32_e32 v99, 1.0, v99
	v_rcp_f32_e32 v99, v99
	v_exp_f32_e32 v84, v84
	v_exp_f32_e32 v80, v80
	v_mul_f32_e32 v88, 0xbfb8aa3b, v88
	v_exp_f32_e32 v88, v88
	v_mul_f32_e32 v93, 0xbfb8aa3b, v93
	v_add_f32_e32 v80, 1.0, v80
	v_mul_f32_e32 v90, 0xbfb8aa3b, v90
	v_add_f32_e32 v88, 1.0, v88
	v_mul_f32_e32 v82, 0xbfb8aa3b, v82
	v_exp_f32_e32 v90, v90
	v_exp_f32_e32 v82, v82
	v_mul_f32_e32 v83, 0xbfb8aa3b, v83
	v_exp_f32_e32 v83, v83
	v_mul_f32_e32 v68, 0xbfb8aa3b, v68
	v_add_f32_e32 v82, 1.0, v82
	v_mul_f32_e32 v76, 0xbfb8aa3b, v76
	v_add_f32_e32 v83, 1.0, v83
	v_rcp_f32_e32 v83, v83
	v_exp_f32_e32 v68, v68
	v_exp_f32_e32 v76, v76
	v_mul_f32_e32 v64, 0xbfb8aa3b, v64
	v_exp_f32_e32 v64, v64
	v_add_f32_e32 v68, 1.0, v68
	v_add_f32_e32 v76, 1.0, v76
	v_mul_f32_e32 v74, 0xbfb8aa3b, v74
	v_add_f32_e32 v64, 1.0, v64
	v_mul_f32_e32 v66, 0xbfb8aa3b, v66
	v_exp_f32_e32 v74, v74
	v_exp_f32_e32 v66, v66
	v_mul_f32_e32 v67, 0xbfb8aa3b, v67
	v_exp_f32_e32 v67, v67
	v_mul_f32_e32 v52, 0xbfb8aa3b, v52
	v_add_f32_e32 v66, 1.0, v66
	v_mul_f32_e32 v60, 0xbfb8aa3b, v60
	v_add_f32_e32 v67, 1.0, v67
	v_rcp_f32_e32 v67, v67
	v_exp_f32_e32 v52, v52
	v_exp_f32_e32 v60, v60
	v_mul_f32_e32 v48, 0xbfb8aa3b, v48
	v_exp_f32_e32 v48, v48
	v_add_f32_e32 v52, 1.0, v52
	v_add_f32_e32 v60, 1.0, v60
	v_mul_f32_e32 v58, 0xbfb8aa3b, v58
	v_add_f32_e32 v48, 1.0, v48
	v_mul_f32_e32 v50, 0xbfb8aa3b, v50
	v_exp_f32_e32 v58, v58
	v_exp_f32_e32 v50, v50
	v_mul_f32_e32 v51, 0xbfb8aa3b, v51
	v_exp_f32_e32 v51, v51
	v_mul_f32_e32 v36, 0xbfb8aa3b, v36
	s_waitcnt vmcnt(1)
	v_lshlrev_b32_e32 v123, 16, v112
	s_waitcnt vmcnt(0)
	v_lshlrev_b32_e32 v122, 16, v116
	v_pk_mul_f32 v[96:97], v[96:97], v[122:123]
	v_and_b32_e32 v127, 0xffff0000, v112
	v_add_f32_e32 v112, v96, v97
	v_add_f32_e32 v96, 1.0, v110
	v_add_f32_e32 v97, 1.0, v102
	v_mul_f32_e32 v102, 0xbfb8aa3b, v106
	v_rcp_f32_e32 v96, v96
	v_rcp_f32_e32 v97, v97
	v_exp_f32_e32 v102, v102
	v_lshlrev_b32_e32 v125, 16, v114
	v_lshlrev_b32_e32 v124, 16, v118
	v_pk_mul_f32 v[100:101], v[100:101], v[124:125]
	v_and_b32_e32 v155, 0xffff0000, v114
	v_add_f32_e32 v114, v100, v101
	v_lshlrev_b32_e32 v101, 16, v113
	v_lshlrev_b32_e32 v100, 16, v117
	v_pk_mul_f32 v[96:97], v[96:97], v[100:101]
	v_add_f32_e32 v100, 1.0, v102
	v_rcp_f32_e32 v100, v100
	v_rcp_f32_e32 v101, v98
	v_mul_f32_e32 v98, 0xbfb8aa3b, v111
	v_exp_f32_e32 v98, v98
	v_add_f32_e32 v102, v96, v97
	v_lshlrev_b32_e32 v97, 16, v115
	v_lshlrev_b32_e32 v96, 16, v119
	v_pk_mul_f32 v[96:97], v[100:101], v[96:97]
	v_mul_f32_e32 v100, 0xbfb8aa3b, v103
	v_exp_f32_e32 v100, v100
	v_add_f32_e32 v103, v96, v97
	v_add_f32_e32 v96, 1.0, v98
	v_mul_f32_e32 v98, 0xbfb8aa3b, v107
	v_exp_f32_e32 v98, v98
	v_add_f32_e32 v97, 1.0, v100
	v_rcp_f32_e32 v96, v96
	v_rcp_f32_e32 v97, v97
	v_add_f32_e32 v98, 1.0, v98
	v_rcp_f32_e32 v98, v98
	v_and_b32_e32 v101, 0xffff0000, v113
	v_and_b32_e32 v100, 0xffff0000, v117
	v_pk_mul_f32 v[96:97], v[96:97], v[100:101]
	v_and_b32_e32 v126, 0xffff0000, v116
	v_add_f32_e32 v100, v96, v97
	v_and_b32_e32 v97, 0xffff0000, v115
	v_and_b32_e32 v96, 0xffff0000, v119
	v_and_b32_e32 v154, 0xffff0000, v118
	v_pk_mul_f32 v[104:105], v[104:105], v[126:127]
	v_pk_mul_f32 v[96:97], v[98:99], v[96:97]
	v_pk_mul_f32 v[108:109], v[108:109], v[154:155]
	v_add_f32_e32 v104, v104, v105
	v_add_f32_e32 v99, v96, v97
	v_cvt_pk_bf16_f32 v96, v112, v104
	v_cvt_pk_bf16_f32 v97, v102, v100
	v_lshl_add_u64 v[100:101], s[8:9], 0, v[120:121]
	v_add_f32_e32 v105, v108, v109
	v_cvt_pk_bf16_f32 v98, v114, v105
	v_cvt_pk_bf16_f32 v99, v103, v99
	global_store_dwordx4 v[100:101], v[96:99], off
	v_mul_f32_e32 v110, 0xbfb8aa3b, v85
	v_exp_f32_e32 v85, v92
	v_or_b32_e32 v96, 32, v146
	v_ashrrev_i32_e32 v97, 31, v96
	v_lshlrev_b64 v[96:97], 12, v[96:97]
	v_lshl_add_u64 v[96:97], v[96:97], 0, v[144:145]
	v_lshlrev_b64 v[104:105], 1, v[96:97]
	v_lshl_add_u64 v[100:101], s[74:75], 0, v[104:105]
	v_lshl_add_u64 v[96:97], s[6:7], 0, v[104:105]
	global_load_dwordx4 v[96:99], v[96:97], off
	s_nop 0
	global_load_dwordx4 v[100:103], v[100:101], off
	v_add_f32_e32 v85, 1.0, v85
	v_add_f32_e32 v92, 1.0, v84
	v_exp_f32_e32 v111, v93
	v_rcp_f32_e32 v84, v85
	v_rcp_f32_e32 v85, v92
	v_rcp_f32_e32 v93, v80
	v_exp_f32_e32 v80, v110
	v_rcp_f32_e32 v92, v88
	v_add_f32_e32 v50, 1.0, v50
	v_add_f32_e32 v51, 1.0, v51
	v_add_f32_e32 v80, 1.0, v80
	v_rcp_f32_e32 v51, v51
	v_mul_f32_e32 v44, 0xbfb8aa3b, v44
	v_exp_f32_e32 v36, v36
	v_exp_f32_e32 v44, v44
	v_mul_f32_e32 v32, 0xbfb8aa3b, v32
	v_exp_f32_e32 v32, v32
	v_add_f32_e32 v36, 1.0, v36
	v_add_f32_e32 v44, 1.0, v44
	v_mul_f32_e32 v42, 0xbfb8aa3b, v42
	v_add_f32_e32 v32, 1.0, v32
	v_mul_f32_e32 v34, 0xbfb8aa3b, v34
	v_exp_f32_e32 v42, v42
	v_exp_f32_e32 v34, v34
	v_mul_f32_e32 v35, 0xbfb8aa3b, v35
	v_exp_f32_e32 v35, v35
	v_mul_f32_e32 v20, 0xbfb8aa3b, v20
	v_add_f32_e32 v34, 1.0, v34
	v_mul_f32_e32 v28, 0xbfb8aa3b, v28
	v_add_f32_e32 v35, 1.0, v35
	v_rcp_f32_e32 v35, v35
	v_exp_f32_e32 v20, v20
	v_exp_f32_e32 v28, v28
	v_mul_f32_e32 v16, 0xbfb8aa3b, v16
	v_exp_f32_e32 v16, v16
	v_add_f32_e32 v20, 1.0, v20
	v_add_f32_e32 v28, 1.0, v28
	v_mul_f32_e32 v26, 0xbfb8aa3b, v26
	v_add_f32_e32 v16, 1.0, v16
	v_mul_f32_e32 v18, 0xbfb8aa3b, v18
	v_exp_f32_e32 v26, v26
	v_exp_f32_e32 v18, v18
	v_mul_f32_e32 v19, 0xbfb8aa3b, v19
	v_exp_f32_e32 v19, v19
	v_mul_f32_e32 v4, 0xbfb8aa3b, v4
	v_add_f32_e32 v18, 1.0, v18
	v_mul_f32_e32 v12, 0xbfb8aa3b, v12
	v_add_f32_e32 v19, 1.0, v19
	v_rcp_f32_e32 v19, v19
	v_exp_f32_e32 v4, v4
	v_exp_f32_e32 v12, v12
	v_mul_f32_e32 v0, 0xbfb8aa3b, v0
	v_exp_f32_e32 v0, v0
	v_add_f32_e32 v4, 1.0, v4
	v_add_f32_e32 v12, 1.0, v12
	v_mul_f32_e32 v10, 0xbfb8aa3b, v10
	v_add_f32_e32 v0, 1.0, v0
	v_mul_f32_e32 v2, 0xbfb8aa3b, v2
	v_exp_f32_e32 v10, v10
	v_exp_f32_e32 v2, v2
	v_mul_f32_e32 v3, 0xbfb8aa3b, v3
	v_exp_f32_e32 v3, v3
	s_andn2_b64 vcc, exec, s[0:1]
	v_add_f32_e32 v2, 1.0, v2
	s_mov_b64 s[0:1], -1
	v_add_f32_e32 v3, 1.0, v3
	v_rcp_f32_e32 v3, v3
	s_waitcnt vmcnt(1)
	v_lshlrev_b32_e32 v107, 16, v96
	s_waitcnt vmcnt(0)
	v_lshlrev_b32_e32 v106, 16, v100
	v_pk_mul_f32 v[84:85], v[84:85], v[106:107]
	v_lshlrev_b32_e32 v109, 16, v98
	v_lshlrev_b32_e32 v108, 16, v102
	v_add_f32_e32 v88, v84, v85
	v_rcp_f32_e32 v85, v80
	v_mul_f32_e32 v80, 0xbfb8aa3b, v89
	v_pk_mul_f32 v[92:93], v[92:93], v[108:109]
	v_add_f32_e32 v84, 1.0, v111
	v_exp_f32_e32 v89, v80
	v_mul_f32_e32 v80, 0xbfb8aa3b, v81
	v_add_f32_e32 v106, v92, v93
	v_rcp_f32_e32 v84, v84
	v_and_b32_e32 v93, 0xffff0000, v96
	v_exp_f32_e32 v96, v80
	v_and_b32_e32 v92, 0xffff0000, v100
	v_pk_mul_f32 v[80:81], v[84:85], v[92:93]
	v_add_f32_e32 v84, 1.0, v89
	v_add_f32_e32 v85, 1.0, v96
	v_rcp_f32_e32 v84, v84
	v_rcp_f32_e32 v85, v85
	v_add_f32_e32 v89, v80, v81
	v_and_b32_e32 v81, 0xffff0000, v98
	v_and_b32_e32 v80, 0xffff0000, v102
	v_pk_mul_f32 v[80:81], v[84:85], v[80:81]
	v_mul_f32_e32 v84, 0xbfb8aa3b, v94
	v_mul_f32_e32 v85, 0xbfb8aa3b, v86
	v_exp_f32_e32 v84, v84
	v_exp_f32_e32 v85, v85
	v_add_f32_e32 v86, v80, v81
	v_add_f32_e32 v80, 1.0, v84
	v_add_f32_e32 v81, 1.0, v85
	v_rcp_f32_e32 v80, v80
	v_rcp_f32_e32 v81, v81
	v_lshlrev_b32_e32 v85, 16, v97
	v_lshlrev_b32_e32 v84, 16, v101
	v_pk_mul_f32 v[80:81], v[80:81], v[84:85]
	v_add_f32_e32 v84, 1.0, v90
	v_rcp_f32_e32 v84, v84
	v_rcp_f32_e32 v85, v82
	v_mul_f32_e32 v82, 0xbfb8aa3b, v95
	v_exp_f32_e32 v82, v82
	v_add_f32_e32 v90, v80, v81
	v_lshlrev_b32_e32 v81, 16, v99
	v_lshlrev_b32_e32 v80, 16, v103
	v_pk_mul_f32 v[80:81], v[84:85], v[80:81]
	v_mul_f32_e32 v84, 0xbfb8aa3b, v87
	v_exp_f32_e32 v84, v84
	v_add_f32_e32 v87, v80, v81
	v_add_f32_e32 v80, 1.0, v82
	v_mul_f32_e32 v82, 0xbfb8aa3b, v91
	v_exp_f32_e32 v82, v82
	v_add_f32_e32 v81, 1.0, v84
	v_rcp_f32_e32 v80, v80
	v_rcp_f32_e32 v81, v81
	v_add_f32_e32 v82, 1.0, v82
	v_rcp_f32_e32 v82, v82
	v_and_b32_e32 v85, 0xffff0000, v97
	v_and_b32_e32 v84, 0xffff0000, v101
	v_pk_mul_f32 v[80:81], v[80:81], v[84:85]
	v_rcp_f32_e32 v91, v68
	v_add_f32_e32 v84, v80, v81
	v_and_b32_e32 v81, 0xffff0000, v99
	v_and_b32_e32 v80, 0xffff0000, v103
	v_pk_mul_f32 v[80:81], v[82:83], v[80:81]
	v_mul_f32_e32 v68, 0xbfb8aa3b, v72
	v_add_f32_e32 v83, v80, v81
	v_cvt_pk_bf16_f32 v80, v88, v89
	v_cvt_pk_bf16_f32 v81, v90, v84
	v_lshl_add_u64 v[84:85], s[8:9], 0, v[104:105]
	v_cvt_pk_bf16_f32 v82, v106, v86
	v_cvt_pk_bf16_f32 v83, v87, v83
	global_store_dwordx4 v[84:85], v[80:83], off
	v_rcp_f32_e32 v90, v76
	v_exp_f32_e32 v68, v68
	v_or_b32_e32 v80, 48, v146
	v_ashrrev_i32_e32 v81, 31, v80
	v_lshlrev_b64 v[80:81], 12, v[80:81]
	v_lshl_add_u64 v[80:81], v[80:81], 0, v[144:145]
	v_lshlrev_b64 v[88:89], 1, v[80:81]
	v_lshl_add_u64 v[84:85], s[74:75], 0, v[88:89]
	v_lshl_add_u64 v[80:81], s[6:7], 0, v[88:89]
	global_load_dwordx4 v[80:83], v[80:81], off
	s_nop 0
	global_load_dwordx4 v[84:87], v[84:85], off
	v_add_f32_e32 v68, 1.0, v68
	s_waitcnt vmcnt(1)
	v_lshlrev_b32_e32 v93, 16, v80
	s_waitcnt vmcnt(0)
	v_lshlrev_b32_e32 v92, 16, v84
	v_pk_mul_f32 v[90:91], v[90:91], v[92:93]
	v_rcp_f32_e32 v93, v64
	v_mul_f32_e32 v64, 0xbfb8aa3b, v77
	v_rcp_f32_e32 v92, v68
	v_exp_f32_e32 v64, v64
	v_mul_f32_e32 v68, 0xbfb8aa3b, v69
	v_exp_f32_e32 v69, v68
	v_and_b32_e32 v77, 0xffff0000, v80
	v_add_f32_e32 v64, 1.0, v64
	v_rcp_f32_e32 v68, v64
	v_add_f32_e32 v64, 1.0, v69
	v_rcp_f32_e32 v69, v64
	v_mul_f32_e32 v64, 0xbfb8aa3b, v73
	v_exp_f32_e32 v73, v64
	v_mul_f32_e32 v64, 0xbfb8aa3b, v65
	v_exp_f32_e32 v80, v64
	v_and_b32_e32 v76, 0xffff0000, v84
	v_pk_mul_f32 v[64:65], v[68:69], v[76:77]
	v_add_f32_e32 v68, 1.0, v73
	v_add_f32_e32 v69, 1.0, v80
	v_rcp_f32_e32 v68, v68
	v_rcp_f32_e32 v69, v69
	v_add_f32_e32 v73, v64, v65
	v_and_b32_e32 v65, 0xffff0000, v82
	v_and_b32_e32 v64, 0xffff0000, v86
	v_pk_mul_f32 v[64:65], v[68:69], v[64:65]
	v_mul_f32_e32 v68, 0xbfb8aa3b, v78
	v_mul_f32_e32 v69, 0xbfb8aa3b, v70
	v_exp_f32_e32 v68, v68
	v_exp_f32_e32 v69, v69
	v_add_f32_e32 v70, v64, v65
	v_add_f32_e32 v72, v90, v91
	v_add_f32_e32 v64, 1.0, v68
	v_add_f32_e32 v65, 1.0, v69
	v_rcp_f32_e32 v64, v64
	v_rcp_f32_e32 v65, v65
	v_lshlrev_b32_e32 v69, 16, v81
	v_lshlrev_b32_e32 v68, 16, v85
	v_lshlrev_b32_e32 v91, 16, v82
	v_pk_mul_f32 v[64:65], v[64:65], v[68:69]
	v_add_f32_e32 v68, 1.0, v74
	v_rcp_f32_e32 v68, v68
	v_rcp_f32_e32 v69, v66
	v_mul_f32_e32 v66, 0xbfb8aa3b, v79
	v_exp_f32_e32 v66, v66
	v_add_f32_e32 v74, v64, v65
	v_lshlrev_b32_e32 v65, 16, v83
	v_lshlrev_b32_e32 v64, 16, v87
	v_pk_mul_f32 v[64:65], v[68:69], v[64:65]
	v_mul_f32_e32 v68, 0xbfb8aa3b, v71
	v_exp_f32_e32 v68, v68
	v_add_f32_e32 v71, v64, v65
	v_add_f32_e32 v64, 1.0, v66
	v_mul_f32_e32 v66, 0xbfb8aa3b, v75
	v_exp_f32_e32 v66, v66
	v_add_f32_e32 v65, 1.0, v68
	v_rcp_f32_e32 v64, v64
	v_rcp_f32_e32 v65, v65
	v_add_f32_e32 v66, 1.0, v66
	v_rcp_f32_e32 v66, v66
	v_and_b32_e32 v69, 0xffff0000, v81
	v_and_b32_e32 v68, 0xffff0000, v85
	v_pk_mul_f32 v[64:65], v[64:65], v[68:69]
	v_lshlrev_b32_e32 v90, 16, v86
	v_add_f32_e32 v68, v64, v65
	v_and_b32_e32 v65, 0xffff0000, v83
	v_and_b32_e32 v64, 0xffff0000, v87
	v_pk_mul_f32 v[64:65], v[66:67], v[64:65]
	v_pk_mul_f32 v[90:91], v[92:93], v[90:91]
	v_add_f32_e32 v67, v64, v65
	v_cvt_pk_bf16_f32 v64, v72, v73
	v_cvt_pk_bf16_f32 v65, v74, v68
	v_lshl_add_u64 v[68:69], s[8:9], 0, v[88:89]
	v_add_f32_e32 v90, v90, v91
	v_cvt_pk_bf16_f32 v66, v90, v70
	v_cvt_pk_bf16_f32 v67, v71, v67
	global_store_dwordx4 v[68:69], v[64:67], off
	v_rcp_f32_e32 v75, v52
	v_mul_f32_e32 v52, 0xbfb8aa3b, v56
	v_add_u32_e32 v64, 0x80, v146
	v_ashrrev_i32_e32 v65, 31, v64
	v_lshlrev_b64 v[64:65], 12, v[64:65]
	v_lshl_add_u64 v[64:65], v[64:65], 0, v[144:145]
	v_lshlrev_b64 v[72:73], 1, v[64:65]
	v_lshl_add_u64 v[68:69], s[74:75], 0, v[72:73]
	v_lshl_add_u64 v[64:65], s[6:7], 0, v[72:73]
	global_load_dwordx4 v[64:67], v[64:65], off
	s_nop 0
	global_load_dwordx4 v[68:71], v[68:69], off
	v_rcp_f32_e32 v74, v60
	v_exp_f32_e32 v52, v52
	s_waitcnt vmcnt(1)
	v_lshlrev_b32_e32 v77, 16, v64
	s_waitcnt vmcnt(0)
	v_lshlrev_b32_e32 v76, 16, v68
	v_pk_mul_f32 v[74:75], v[74:75], v[76:77]
	v_add_f32_e32 v52, 1.0, v52
	v_rcp_f32_e32 v77, v48
	v_mul_f32_e32 v48, 0xbfb8aa3b, v61
	v_rcp_f32_e32 v76, v52
	v_exp_f32_e32 v48, v48
	v_mul_f32_e32 v52, 0xbfb8aa3b, v53
	v_exp_f32_e32 v53, v52
	v_and_b32_e32 v61, 0xffff0000, v64
	v_add_f32_e32 v48, 1.0, v48
	v_rcp_f32_e32 v52, v48
	v_add_f32_e32 v48, 1.0, v53
	v_rcp_f32_e32 v53, v48
	v_mul_f32_e32 v48, 0xbfb8aa3b, v57
	v_exp_f32_e32 v57, v48
	v_mul_f32_e32 v48, 0xbfb8aa3b, v49
	v_exp_f32_e32 v64, v48
	v_and_b32_e32 v60, 0xffff0000, v68
	v_pk_mul_f32 v[48:49], v[52:53], v[60:61]
	v_add_f32_e32 v52, 1.0, v57
	v_add_f32_e32 v53, 1.0, v64
	v_rcp_f32_e32 v52, v52
	v_rcp_f32_e32 v53, v53
	v_add_f32_e32 v57, v48, v49
	v_and_b32_e32 v49, 0xffff0000, v66
	v_and_b32_e32 v48, 0xffff0000, v70
	v_pk_mul_f32 v[48:49], v[52:53], v[48:49]
	v_mul_f32_e32 v52, 0xbfb8aa3b, v62
	v_mul_f32_e32 v53, 0xbfb8aa3b, v54
	v_exp_f32_e32 v52, v52
	v_exp_f32_e32 v53, v53
	v_add_f32_e32 v54, v48, v49
	v_add_f32_e32 v56, v74, v75
	v_add_f32_e32 v48, 1.0, v52
	v_add_f32_e32 v49, 1.0, v53
	v_rcp_f32_e32 v48, v48
	v_rcp_f32_e32 v49, v49
	v_lshlrev_b32_e32 v53, 16, v65
	v_lshlrev_b32_e32 v52, 16, v69
	v_lshlrev_b32_e32 v75, 16, v66
	v_pk_mul_f32 v[48:49], v[48:49], v[52:53]
	v_add_f32_e32 v52, 1.0, v58
	v_rcp_f32_e32 v52, v52
	v_rcp_f32_e32 v53, v50
	v_mul_f32_e32 v50, 0xbfb8aa3b, v63
	v_exp_f32_e32 v50, v50
	v_add_f32_e32 v58, v48, v49
	v_lshlrev_b32_e32 v49, 16, v67
	v_lshlrev_b32_e32 v48, 16, v71
	v_pk_mul_f32 v[48:49], v[52:53], v[48:49]
	v_mul_f32_e32 v52, 0xbfb8aa3b, v55
	v_exp_f32_e32 v52, v52
	v_add_f32_e32 v55, v48, v49
	v_add_f32_e32 v48, 1.0, v50
	v_mul_f32_e32 v50, 0xbfb8aa3b, v59
	v_exp_f32_e32 v50, v50
	v_add_f32_e32 v49, 1.0, v52
	v_rcp_f32_e32 v48, v48
	v_rcp_f32_e32 v49, v49
	v_add_f32_e32 v50, 1.0, v50
	v_rcp_f32_e32 v50, v50
	v_and_b32_e32 v53, 0xffff0000, v65
	v_and_b32_e32 v52, 0xffff0000, v69
	v_pk_mul_f32 v[48:49], v[48:49], v[52:53]
	v_lshlrev_b32_e32 v74, 16, v70
	v_add_f32_e32 v52, v48, v49
	v_and_b32_e32 v49, 0xffff0000, v67
	v_and_b32_e32 v48, 0xffff0000, v71
	v_pk_mul_f32 v[48:49], v[50:51], v[48:49]
	v_pk_mul_f32 v[74:75], v[76:77], v[74:75]
	v_add_f32_e32 v51, v48, v49
	v_cvt_pk_bf16_f32 v48, v56, v57
	v_cvt_pk_bf16_f32 v49, v58, v52
	v_lshl_add_u64 v[52:53], s[8:9], 0, v[72:73]
	v_add_f32_e32 v74, v74, v75
	v_cvt_pk_bf16_f32 v50, v74, v54
	v_cvt_pk_bf16_f32 v51, v55, v51
	global_store_dwordx4 v[52:53], v[48:51], off
	v_rcp_f32_e32 v59, v36
	v_mul_f32_e32 v36, 0xbfb8aa3b, v40
	v_add_u32_e32 v48, 0x90, v146
	v_ashrrev_i32_e32 v49, 31, v48
	v_lshlrev_b64 v[48:49], 12, v[48:49]
	v_lshl_add_u64 v[48:49], v[48:49], 0, v[144:145]
	v_lshlrev_b64 v[56:57], 1, v[48:49]
	v_lshl_add_u64 v[52:53], s[74:75], 0, v[56:57]
	v_lshl_add_u64 v[48:49], s[6:7], 0, v[56:57]
	global_load_dwordx4 v[48:51], v[48:49], off
	s_nop 0
	global_load_dwordx4 v[52:55], v[52:53], off
	v_rcp_f32_e32 v58, v44
	v_exp_f32_e32 v36, v36
	s_waitcnt vmcnt(1)
	v_lshlrev_b32_e32 v61, 16, v48
	s_waitcnt vmcnt(0)
	v_lshlrev_b32_e32 v60, 16, v52
	v_pk_mul_f32 v[58:59], v[58:59], v[60:61]
	v_add_f32_e32 v36, 1.0, v36
	v_rcp_f32_e32 v61, v32
	v_mul_f32_e32 v32, 0xbfb8aa3b, v45
	v_rcp_f32_e32 v60, v36
	v_exp_f32_e32 v32, v32
	v_mul_f32_e32 v36, 0xbfb8aa3b, v37
	v_exp_f32_e32 v37, v36
	v_and_b32_e32 v45, 0xffff0000, v48
	v_add_f32_e32 v32, 1.0, v32
	v_rcp_f32_e32 v36, v32
	v_add_f32_e32 v32, 1.0, v37
	v_rcp_f32_e32 v37, v32
	v_mul_f32_e32 v32, 0xbfb8aa3b, v41
	v_exp_f32_e32 v41, v32
	v_mul_f32_e32 v32, 0xbfb8aa3b, v33
	v_exp_f32_e32 v48, v32
	v_and_b32_e32 v44, 0xffff0000, v52
	v_pk_mul_f32 v[32:33], v[36:37], v[44:45]
	v_add_f32_e32 v36, 1.0, v41
	v_add_f32_e32 v37, 1.0, v48
	v_rcp_f32_e32 v36, v36
	v_rcp_f32_e32 v37, v37
	v_add_f32_e32 v41, v32, v33
	v_and_b32_e32 v33, 0xffff0000, v50
	v_and_b32_e32 v32, 0xffff0000, v54
	v_pk_mul_f32 v[32:33], v[36:37], v[32:33]
	v_mul_f32_e32 v36, 0xbfb8aa3b, v46
	v_mul_f32_e32 v37, 0xbfb8aa3b, v38
	v_exp_f32_e32 v36, v36
	v_exp_f32_e32 v37, v37
	v_add_f32_e32 v38, v32, v33
	v_add_f32_e32 v40, v58, v59
	v_add_f32_e32 v32, 1.0, v36
	v_add_f32_e32 v33, 1.0, v37
	v_rcp_f32_e32 v32, v32
	v_rcp_f32_e32 v33, v33
	v_lshlrev_b32_e32 v37, 16, v49
	v_lshlrev_b32_e32 v36, 16, v53
	v_lshlrev_b32_e32 v59, 16, v50
	v_pk_mul_f32 v[32:33], v[32:33], v[36:37]
	v_add_f32_e32 v36, 1.0, v42
	v_rcp_f32_e32 v36, v36
	v_rcp_f32_e32 v37, v34
	v_mul_f32_e32 v34, 0xbfb8aa3b, v47
	v_exp_f32_e32 v34, v34
	v_add_f32_e32 v42, v32, v33
	v_lshlrev_b32_e32 v33, 16, v51
	v_lshlrev_b32_e32 v32, 16, v55
	v_pk_mul_f32 v[32:33], v[36:37], v[32:33]
	v_mul_f32_e32 v36, 0xbfb8aa3b, v39
	v_exp_f32_e32 v36, v36
	v_add_f32_e32 v39, v32, v33
	v_add_f32_e32 v32, 1.0, v34
	v_mul_f32_e32 v34, 0xbfb8aa3b, v43
	v_exp_f32_e32 v34, v34
	v_add_f32_e32 v33, 1.0, v36
	v_rcp_f32_e32 v32, v32
	v_rcp_f32_e32 v33, v33
	v_add_f32_e32 v34, 1.0, v34
	v_rcp_f32_e32 v34, v34
	v_and_b32_e32 v37, 0xffff0000, v49
	v_and_b32_e32 v36, 0xffff0000, v53
	v_pk_mul_f32 v[32:33], v[32:33], v[36:37]
	v_lshlrev_b32_e32 v58, 16, v54
	v_add_f32_e32 v36, v32, v33
	v_and_b32_e32 v33, 0xffff0000, v51
	v_and_b32_e32 v32, 0xffff0000, v55
	v_pk_mul_f32 v[32:33], v[34:35], v[32:33]
	v_pk_mul_f32 v[58:59], v[60:61], v[58:59]
	v_add_f32_e32 v35, v32, v33
	v_cvt_pk_bf16_f32 v32, v40, v41
	v_cvt_pk_bf16_f32 v33, v42, v36
	v_lshl_add_u64 v[36:37], s[8:9], 0, v[56:57]
	v_add_f32_e32 v58, v58, v59
	v_cvt_pk_bf16_f32 v34, v58, v38
	v_cvt_pk_bf16_f32 v35, v39, v35
	global_store_dwordx4 v[36:37], v[32:35], off
	v_rcp_f32_e32 v43, v20
	v_mul_f32_e32 v20, 0xbfb8aa3b, v24
	v_add_u32_e32 v32, 0xa0, v146
	v_ashrrev_i32_e32 v33, 31, v32
	v_lshlrev_b64 v[32:33], 12, v[32:33]
	v_lshl_add_u64 v[32:33], v[32:33], 0, v[144:145]
	v_lshlrev_b64 v[40:41], 1, v[32:33]
	v_lshl_add_u64 v[36:37], s[74:75], 0, v[40:41]
	v_lshl_add_u64 v[32:33], s[6:7], 0, v[40:41]
	global_load_dwordx4 v[32:35], v[32:33], off
	s_nop 0
	global_load_dwordx4 v[36:39], v[36:37], off
	v_rcp_f32_e32 v42, v28
	v_exp_f32_e32 v20, v20
	s_waitcnt vmcnt(1)
	v_lshlrev_b32_e32 v45, 16, v32
	s_waitcnt vmcnt(0)
	v_lshlrev_b32_e32 v44, 16, v36
	v_pk_mul_f32 v[42:43], v[42:43], v[44:45]
	v_add_f32_e32 v20, 1.0, v20
	v_rcp_f32_e32 v45, v16
	v_mul_f32_e32 v16, 0xbfb8aa3b, v29
	v_rcp_f32_e32 v44, v20
	v_exp_f32_e32 v16, v16
	v_mul_f32_e32 v20, 0xbfb8aa3b, v21
	v_exp_f32_e32 v21, v20
	v_and_b32_e32 v29, 0xffff0000, v32
	v_add_f32_e32 v16, 1.0, v16
	v_rcp_f32_e32 v20, v16
	v_add_f32_e32 v16, 1.0, v21
	v_rcp_f32_e32 v21, v16
	v_mul_f32_e32 v16, 0xbfb8aa3b, v25
	v_exp_f32_e32 v25, v16
	v_mul_f32_e32 v16, 0xbfb8aa3b, v17
	v_exp_f32_e32 v32, v16
	v_and_b32_e32 v28, 0xffff0000, v36
	v_pk_mul_f32 v[16:17], v[20:21], v[28:29]
	v_add_f32_e32 v20, 1.0, v25
	v_add_f32_e32 v21, 1.0, v32
	v_rcp_f32_e32 v20, v20
	v_rcp_f32_e32 v21, v21
	v_add_f32_e32 v25, v16, v17
	v_and_b32_e32 v17, 0xffff0000, v34
	v_and_b32_e32 v16, 0xffff0000, v38
	v_pk_mul_f32 v[16:17], v[20:21], v[16:17]
	v_mul_f32_e32 v20, 0xbfb8aa3b, v30
	v_mul_f32_e32 v21, 0xbfb8aa3b, v22
	v_exp_f32_e32 v20, v20
	v_exp_f32_e32 v21, v21
	v_add_f32_e32 v22, v16, v17
	v_add_f32_e32 v24, v42, v43
	v_add_f32_e32 v16, 1.0, v20
	v_add_f32_e32 v17, 1.0, v21
	v_rcp_f32_e32 v16, v16
	v_rcp_f32_e32 v17, v17
	v_lshlrev_b32_e32 v21, 16, v33
	v_lshlrev_b32_e32 v20, 16, v37
	v_lshlrev_b32_e32 v43, 16, v34
	v_pk_mul_f32 v[16:17], v[16:17], v[20:21]
	v_add_f32_e32 v20, 1.0, v26
	v_rcp_f32_e32 v20, v20
	v_rcp_f32_e32 v21, v18
	v_mul_f32_e32 v18, 0xbfb8aa3b, v31
	v_exp_f32_e32 v18, v18
	v_add_f32_e32 v26, v16, v17
	v_lshlrev_b32_e32 v17, 16, v35
	v_lshlrev_b32_e32 v16, 16, v39
	v_pk_mul_f32 v[16:17], v[20:21], v[16:17]
	v_mul_f32_e32 v20, 0xbfb8aa3b, v23
	v_exp_f32_e32 v20, v20
	v_add_f32_e32 v23, v16, v17
	v_add_f32_e32 v16, 1.0, v18
	v_mul_f32_e32 v18, 0xbfb8aa3b, v27
	v_exp_f32_e32 v18, v18
	v_add_f32_e32 v17, 1.0, v20
	v_rcp_f32_e32 v16, v16
	v_rcp_f32_e32 v17, v17
	v_add_f32_e32 v18, 1.0, v18
	v_rcp_f32_e32 v18, v18
	v_and_b32_e32 v21, 0xffff0000, v33
	v_and_b32_e32 v20, 0xffff0000, v37
	v_pk_mul_f32 v[16:17], v[16:17], v[20:21]
	v_lshlrev_b32_e32 v42, 16, v38
	v_add_f32_e32 v20, v16, v17
	v_and_b32_e32 v17, 0xffff0000, v35
	v_and_b32_e32 v16, 0xffff0000, v39
	v_pk_mul_f32 v[16:17], v[18:19], v[16:17]
	v_pk_mul_f32 v[42:43], v[44:45], v[42:43]
	v_add_f32_e32 v19, v16, v17
	v_cvt_pk_bf16_f32 v16, v24, v25
	v_cvt_pk_bf16_f32 v17, v26, v20
	v_lshl_add_u64 v[20:21], s[8:9], 0, v[40:41]
	v_add_f32_e32 v42, v42, v43
	v_cvt_pk_bf16_f32 v18, v42, v22
	v_cvt_pk_bf16_f32 v19, v23, v19
	global_store_dwordx4 v[20:21], v[16:19], off
	v_rcp_f32_e32 v27, v4
	v_mul_f32_e32 v4, 0xbfb8aa3b, v8
	v_add_u32_e32 v16, 0xb0, v146
	v_ashrrev_i32_e32 v17, 31, v16
	v_lshlrev_b64 v[16:17], 12, v[16:17]
	v_lshl_add_u64 v[16:17], v[16:17], 0, v[144:145]
	v_lshlrev_b64 v[24:25], 1, v[16:17]
	v_lshl_add_u64 v[20:21], s[74:75], 0, v[24:25]
	v_lshl_add_u64 v[16:17], s[6:7], 0, v[24:25]
	global_load_dwordx4 v[16:19], v[16:17], off
	s_nop 0
	global_load_dwordx4 v[20:23], v[20:21], off
	v_rcp_f32_e32 v26, v12
	v_exp_f32_e32 v4, v4
	s_waitcnt vmcnt(1)
	v_lshlrev_b32_e32 v29, 16, v16
	s_waitcnt vmcnt(0)
	v_lshlrev_b32_e32 v28, 16, v20
	v_pk_mul_f32 v[26:27], v[26:27], v[28:29]
	v_add_f32_e32 v4, 1.0, v4
	v_rcp_f32_e32 v29, v0
	v_mul_f32_e32 v0, 0xbfb8aa3b, v13
	v_rcp_f32_e32 v28, v4
	v_exp_f32_e32 v0, v0
	v_mul_f32_e32 v4, 0xbfb8aa3b, v5
	v_exp_f32_e32 v5, v4
	v_and_b32_e32 v13, 0xffff0000, v16
	v_add_f32_e32 v0, 1.0, v0
	v_rcp_f32_e32 v4, v0
	v_add_f32_e32 v0, 1.0, v5
	v_rcp_f32_e32 v5, v0
	v_mul_f32_e32 v0, 0xbfb8aa3b, v9
	v_exp_f32_e32 v9, v0
	v_mul_f32_e32 v0, 0xbfb8aa3b, v1
	v_exp_f32_e32 v16, v0
	v_and_b32_e32 v12, 0xffff0000, v20
	v_pk_mul_f32 v[0:1], v[4:5], v[12:13]
	v_add_f32_e32 v4, 1.0, v9
	v_add_f32_e32 v5, 1.0, v16
	v_rcp_f32_e32 v4, v4
	v_rcp_f32_e32 v5, v5
	v_add_f32_e32 v9, v0, v1
	v_and_b32_e32 v1, 0xffff0000, v18
	v_and_b32_e32 v0, 0xffff0000, v22
	v_pk_mul_f32 v[0:1], v[4:5], v[0:1]
	v_mul_f32_e32 v4, 0xbfb8aa3b, v14
	v_mul_f32_e32 v5, 0xbfb8aa3b, v6
	v_exp_f32_e32 v4, v4
	v_exp_f32_e32 v5, v5
	v_add_f32_e32 v6, v0, v1
	v_add_f32_e32 v8, v26, v27
	v_add_f32_e32 v0, 1.0, v4
	v_add_f32_e32 v1, 1.0, v5
	v_rcp_f32_e32 v0, v0
	v_rcp_f32_e32 v1, v1
	v_lshlrev_b32_e32 v5, 16, v17
	v_lshlrev_b32_e32 v4, 16, v21
	v_lshlrev_b32_e32 v27, 16, v18
	v_pk_mul_f32 v[0:1], v[0:1], v[4:5]
	v_add_f32_e32 v4, 1.0, v10
	v_rcp_f32_e32 v4, v4
	v_rcp_f32_e32 v5, v2
	v_mul_f32_e32 v2, 0xbfb8aa3b, v15
	v_exp_f32_e32 v2, v2
	v_add_f32_e32 v10, v0, v1
	v_lshlrev_b32_e32 v1, 16, v19
	v_lshlrev_b32_e32 v0, 16, v23
	v_pk_mul_f32 v[0:1], v[4:5], v[0:1]
	v_mul_f32_e32 v4, 0xbfb8aa3b, v7
	v_exp_f32_e32 v4, v4
	v_add_f32_e32 v7, v0, v1
	v_add_f32_e32 v0, 1.0, v2
	v_mul_f32_e32 v2, 0xbfb8aa3b, v11
	v_exp_f32_e32 v2, v2
	v_add_f32_e32 v1, 1.0, v4
	v_rcp_f32_e32 v0, v0
	v_rcp_f32_e32 v1, v1
	v_add_f32_e32 v2, 1.0, v2
	v_rcp_f32_e32 v2, v2
	v_and_b32_e32 v5, 0xffff0000, v17
	v_and_b32_e32 v4, 0xffff0000, v21
	v_pk_mul_f32 v[0:1], v[0:1], v[4:5]
	v_lshlrev_b32_e32 v26, 16, v22
	v_add_f32_e32 v4, v0, v1
	v_and_b32_e32 v1, 0xffff0000, v19
	v_and_b32_e32 v0, 0xffff0000, v23
	v_pk_mul_f32 v[0:1], v[2:3], v[0:1]
	v_pk_mul_f32 v[26:27], v[28:29], v[26:27]
	v_add_f32_e32 v3, v0, v1
	v_cvt_pk_bf16_f32 v0, v8, v9
	v_cvt_pk_bf16_f32 v1, v10, v4
	v_lshl_add_u64 v[4:5], s[8:9], 0, v[24:25]
	v_add_f32_e32 v26, v26, v27
	v_cvt_pk_bf16_f32 v2, v26, v6
	v_cvt_pk_bf16_f32 v3, v7, v3
	global_store_dwordx4 v[4:5], v[0:3], off
	s_cbranch_vccnz .LBB0_671
	s_andn2_b64 vcc, exec, s[4:5]
	s_cbranch_vccnz .LBB0_670
	s_barrier
	s_branch .LBB0_670

.LBB0_761:
	v_lshl_add_u32 v148, s44, 8, v150
	v_lshl_or_b32 v146, s63, 8, v152
	s_cmp_lt_i32 s44, 64
	v_readlane_b32 s36, v254, 7
	v_ashrrev_i32_e32 v149, 31, v148
	v_readlane_b32 s37, v254, 8
	v_readlane_b32 s38, v254, 9
	v_readlane_b32 s39, v254, 10
	v_ashrrev_i32_e32 v147, 31, v146
	v_lshlrev_b64 v[144:145], 12, v[148:149]
	s_cselect_b32 s39, s37, s60
	s_cselect_b32 s38, s36, s59
	v_lshl_add_u64 v[144:145], v[144:145], 0, v[146:147]
	v_lshl_add_u64 v[164:165], v[144:145], 2, s[38:39]
	global_load_dwordx4 v[156:159], v[164:165], off
	global_load_dwordx4 v[160:163], v[164:165], off offset:16
	v_lshl_add_u64 v[166:167], v[144:145], 1, s[74:75]
	s_mov_b64 s[34:35], 0x80000
	s_andn2_b64 vcc, exec, s[0:1]
	s_mov_b64 s[0:1], -1
	v_readlane_b32 s40, v254, 11
	v_readlane_b32 s41, v254, 12
	v_readlane_b32 s42, v254, 13
	v_readlane_b32 s43, v254, 14
	v_readlane_b32 s44, v254, 15
	v_readlane_b32 s45, v254, 16
	v_readlane_b32 s46, v254, 17
	v_readlane_b32 s47, v254, 18
	v_readlane_b32 s48, v254, 19
	v_readlane_b32 s49, v254, 20
	v_readlane_b32 s50, v254, 21
	v_readlane_b32 s51, v254, 22
	s_waitcnt vmcnt(0)
	v_pk_add_f32 v[124:125], v[124:125], v[156:157]
	v_pk_add_f32 v[156:157], v[122:123], v[162:163]
	v_pk_add_f32 v[122:123], v[120:121], v[160:161]
	v_pk_add_f32 v[126:127], v[126:127], v[158:159]
	v_cvt_pk_bf16_f32 v120, v124, v125
	s_nop 0
	v_cvt_pk_bf16_f32 v121, v126, v127
	v_cvt_pk_bf16_f32 v122, v122, v123
	v_cvt_pk_bf16_f32 v123, v156, v157
	global_store_dwordx4 v[166:167], v[120:123], off
	global_load_dwordx4 v[120:123], v[164:165], off offset:512
	s_nop 0
	global_load_dwordx4 v[124:127], v[164:165], off offset:528
	v_or_b32_e32 v156, 16, v148
	v_ashrrev_i32_e32 v157, 31, v156
	v_lshlrev_b64 v[156:157], 12, v[156:157]
	v_lshl_add_u64 v[156:157], v[156:157], 0, v[146:147]
	v_lshl_add_u64 v[158:159], v[156:157], 2, s[38:39]
	s_waitcnt vmcnt(1)
	v_pk_add_f32 v[116:117], v[116:117], v[120:121]
	s_waitcnt vmcnt(0)
	v_pk_add_f32 v[120:121], v[114:115], v[126:127]
	v_pk_add_f32 v[114:115], v[112:113], v[124:125]
	v_pk_add_f32 v[118:119], v[118:119], v[122:123]
	v_cvt_pk_bf16_f32 v112, v116, v117
	s_nop 0
	v_cvt_pk_bf16_f32 v113, v118, v119
	v_cvt_pk_bf16_f32 v114, v114, v115
	v_cvt_pk_bf16_f32 v115, v120, v121
	global_store_dwordx4 v[166:167], v[112:115], off offset:256
	global_load_dwordx4 v[112:115], v[158:159], off
	s_nop 0
	global_load_dwordx4 v[116:119], v[158:159], off offset:16
	v_lshl_add_u64 v[120:121], v[156:157], 1, s[74:75]
	s_waitcnt vmcnt(1)
	v_pk_add_f32 v[108:109], v[108:109], v[112:113]
	s_waitcnt vmcnt(0)
	v_pk_add_f32 v[112:113], v[106:107], v[118:119]
	v_pk_add_f32 v[106:107], v[104:105], v[116:117]
	v_pk_add_f32 v[110:111], v[110:111], v[114:115]
	v_cvt_pk_bf16_f32 v104, v108, v109
	s_nop 0
	v_cvt_pk_bf16_f32 v105, v110, v111
	v_cvt_pk_bf16_f32 v106, v106, v107
	v_cvt_pk_bf16_f32 v107, v112, v113
	global_store_dwordx4 v[120:121], v[104:107], off
	global_load_dwordx4 v[104:107], v[158:159], off offset:512
	s_nop 0
	global_load_dwordx4 v[108:111], v[158:159], off offset:528
	v_or_b32_e32 v112, 32, v148
	v_ashrrev_i32_e32 v113, 31, v112
	v_lshlrev_b64 v[112:113], 12, v[112:113]
	v_lshl_add_u64 v[112:113], v[112:113], 0, v[146:147]
	v_lshl_add_u64 v[114:115], v[112:113], 2, s[38:39]
	s_waitcnt vmcnt(1)
	v_pk_add_f32 v[100:101], v[100:101], v[104:105]
	s_waitcnt vmcnt(0)
	v_pk_add_f32 v[104:105], v[98:99], v[110:111]
	v_pk_add_f32 v[98:99], v[96:97], v[108:109]
	v_pk_add_f32 v[102:103], v[102:103], v[106:107]
	v_cvt_pk_bf16_f32 v96, v100, v101
	s_nop 0
	v_cvt_pk_bf16_f32 v97, v102, v103
	v_cvt_pk_bf16_f32 v98, v98, v99
	v_cvt_pk_bf16_f32 v99, v104, v105
	global_store_dwordx4 v[120:121], v[96:99], off offset:256
	global_load_dwordx4 v[96:99], v[114:115], off
	s_nop 0
	global_load_dwordx4 v[100:103], v[114:115], off offset:16
	v_lshl_add_u64 v[104:105], v[112:113], 1, s[74:75]
	s_waitcnt vmcnt(1)
	v_pk_add_f32 v[92:93], v[92:93], v[96:97]
	s_waitcnt vmcnt(0)
	v_pk_add_f32 v[96:97], v[90:91], v[102:103]
	v_pk_add_f32 v[90:91], v[88:89], v[100:101]
	v_pk_add_f32 v[94:95], v[94:95], v[98:99]
	v_cvt_pk_bf16_f32 v88, v92, v93
	s_nop 0
	v_cvt_pk_bf16_f32 v89, v94, v95
	v_cvt_pk_bf16_f32 v90, v90, v91
	v_cvt_pk_bf16_f32 v91, v96, v97
	global_store_dwordx4 v[104:105], v[88:91], off
	global_load_dwordx4 v[88:91], v[114:115], off offset:512
	s_nop 0
	global_load_dwordx4 v[92:95], v[114:115], off offset:528
	v_or_b32_e32 v96, 48, v148
	v_ashrrev_i32_e32 v97, 31, v96
	v_lshlrev_b64 v[96:97], 12, v[96:97]
	v_lshl_add_u64 v[96:97], v[96:97], 0, v[146:147]
	v_lshl_add_u64 v[98:99], v[96:97], 2, s[38:39]
	s_waitcnt vmcnt(1)
	v_pk_add_f32 v[84:85], v[84:85], v[88:89]
	s_waitcnt vmcnt(0)
	v_pk_add_f32 v[88:89], v[82:83], v[94:95]
	v_pk_add_f32 v[82:83], v[80:81], v[92:93]
	v_pk_add_f32 v[86:87], v[86:87], v[90:91]
	v_cvt_pk_bf16_f32 v80, v84, v85
	s_nop 0
	v_cvt_pk_bf16_f32 v81, v86, v87
	v_cvt_pk_bf16_f32 v82, v82, v83
	v_cvt_pk_bf16_f32 v83, v88, v89
	global_store_dwordx4 v[104:105], v[80:83], off offset:256
	global_load_dwordx4 v[80:83], v[98:99], off
	s_nop 0
	global_load_dwordx4 v[84:87], v[98:99], off offset:16
	v_lshl_add_u64 v[88:89], v[96:97], 1, s[74:75]
	s_waitcnt vmcnt(1)
	v_pk_add_f32 v[76:77], v[76:77], v[80:81]
	s_waitcnt vmcnt(0)
	v_pk_add_f32 v[80:81], v[74:75], v[86:87]
	v_pk_add_f32 v[74:75], v[72:73], v[84:85]
	v_pk_add_f32 v[78:79], v[78:79], v[82:83]
	v_cvt_pk_bf16_f32 v72, v76, v77
	s_nop 0
	v_cvt_pk_bf16_f32 v73, v78, v79
	v_cvt_pk_bf16_f32 v74, v74, v75
	v_cvt_pk_bf16_f32 v75, v80, v81
	global_store_dwordx4 v[88:89], v[72:75], off
	global_load_dwordx4 v[72:75], v[98:99], off offset:512
	s_nop 0
	global_load_dwordx4 v[76:79], v[98:99], off offset:528
	v_lshl_add_u64 v[80:81], v[144:145], 0, s[34:35]
	v_lshl_add_u64 v[82:83], v[80:81], 2, s[38:39]
	s_mov_b64 s[34:35], 0x90000
	s_waitcnt vmcnt(1)
	v_pk_add_f32 v[68:69], v[68:69], v[72:73]
	s_waitcnt vmcnt(0)
	v_pk_add_f32 v[72:73], v[66:67], v[78:79]
	v_pk_add_f32 v[66:67], v[64:65], v[76:77]
	v_pk_add_f32 v[70:71], v[70:71], v[74:75]
	v_cvt_pk_bf16_f32 v64, v68, v69
	s_nop 0
	v_cvt_pk_bf16_f32 v65, v70, v71
	v_cvt_pk_bf16_f32 v66, v66, v67
	v_cvt_pk_bf16_f32 v67, v72, v73
	global_store_dwordx4 v[88:89], v[64:67], off offset:256
	global_load_dwordx4 v[64:67], v[82:83], off
	s_nop 0
	global_load_dwordx4 v[68:71], v[82:83], off offset:16
	v_lshl_add_u64 v[72:73], v[80:81], 1, s[74:75]
	s_waitcnt vmcnt(1)
	v_pk_add_f32 v[60:61], v[60:61], v[64:65]
	s_waitcnt vmcnt(0)
	v_pk_add_f32 v[64:65], v[58:59], v[70:71]
	v_pk_add_f32 v[58:59], v[56:57], v[68:69]
	v_pk_add_f32 v[62:63], v[62:63], v[66:67]
	v_cvt_pk_bf16_f32 v56, v60, v61
	s_nop 0
	v_cvt_pk_bf16_f32 v57, v62, v63
	v_cvt_pk_bf16_f32 v58, v58, v59
	v_cvt_pk_bf16_f32 v59, v64, v65
	global_store_dwordx4 v[72:73], v[56:59], off
	global_load_dwordx4 v[56:59], v[82:83], off offset:512
	s_nop 0
	global_load_dwordx4 v[60:63], v[82:83], off offset:528
	v_lshl_add_u64 v[64:65], v[144:145], 0, s[34:35]
	v_lshl_add_u64 v[66:67], v[64:65], 2, s[38:39]
	s_mov_b64 s[34:35], 0xa0000
	s_waitcnt vmcnt(1)
	v_pk_add_f32 v[52:53], v[52:53], v[56:57]
	s_waitcnt vmcnt(0)
	v_pk_add_f32 v[56:57], v[50:51], v[62:63]
	v_pk_add_f32 v[50:51], v[48:49], v[60:61]
	v_pk_add_f32 v[54:55], v[54:55], v[58:59]
	v_cvt_pk_bf16_f32 v48, v52, v53
	s_nop 0
	v_cvt_pk_bf16_f32 v49, v54, v55
	v_cvt_pk_bf16_f32 v50, v50, v51
	v_cvt_pk_bf16_f32 v51, v56, v57
	global_store_dwordx4 v[72:73], v[48:51], off offset:256
	global_load_dwordx4 v[48:51], v[66:67], off
	s_nop 0
	global_load_dwordx4 v[52:55], v[66:67], off offset:16
	v_lshl_add_u64 v[56:57], v[64:65], 1, s[74:75]
	s_waitcnt vmcnt(1)
	v_pk_add_f32 v[44:45], v[44:45], v[48:49]
	s_waitcnt vmcnt(0)
	v_pk_add_f32 v[48:49], v[42:43], v[54:55]
	v_pk_add_f32 v[42:43], v[40:41], v[52:53]
	v_pk_add_f32 v[46:47], v[46:47], v[50:51]
	v_cvt_pk_bf16_f32 v40, v44, v45
	s_nop 0
	v_cvt_pk_bf16_f32 v41, v46, v47
	v_cvt_pk_bf16_f32 v42, v42, v43
	v_cvt_pk_bf16_f32 v43, v48, v49
	global_store_dwordx4 v[56:57], v[40:43], off
	global_load_dwordx4 v[40:43], v[66:67], off offset:512
	s_nop 0
	global_load_dwordx4 v[44:47], v[66:67], off offset:528
	v_lshl_add_u64 v[48:49], v[144:145], 0, s[34:35]
	v_lshl_add_u64 v[50:51], v[48:49], 2, s[38:39]
	s_mov_b64 s[34:35], 0xb0000
	s_waitcnt vmcnt(1)
	v_pk_add_f32 v[36:37], v[36:37], v[40:41]
	s_waitcnt vmcnt(0)
	v_pk_add_f32 v[40:41], v[34:35], v[46:47]
	v_pk_add_f32 v[34:35], v[32:33], v[44:45]
	v_pk_add_f32 v[38:39], v[38:39], v[42:43]
	v_cvt_pk_bf16_f32 v32, v36, v37
	s_nop 0
	v_cvt_pk_bf16_f32 v33, v38, v39
	v_cvt_pk_bf16_f32 v34, v34, v35
	v_cvt_pk_bf16_f32 v35, v40, v41
	global_store_dwordx4 v[56:57], v[32:35], off offset:256
	global_load_dwordx4 v[32:35], v[50:51], off
	s_nop 0
	global_load_dwordx4 v[36:39], v[50:51], off offset:16
	v_lshl_add_u64 v[40:41], v[48:49], 1, s[74:75]
	s_waitcnt vmcnt(1)
	v_pk_add_f32 v[28:29], v[28:29], v[32:33]
	s_waitcnt vmcnt(0)
	v_pk_add_f32 v[32:33], v[26:27], v[38:39]
	v_pk_add_f32 v[26:27], v[24:25], v[36:37]
	v_pk_add_f32 v[30:31], v[30:31], v[34:35]
	v_cvt_pk_bf16_f32 v24, v28, v29
	s_nop 0
	v_cvt_pk_bf16_f32 v25, v30, v31
	v_cvt_pk_bf16_f32 v26, v26, v27
	v_cvt_pk_bf16_f32 v27, v32, v33
	global_store_dwordx4 v[40:41], v[24:27], off
	global_load_dwordx4 v[24:27], v[50:51], off offset:512
	s_nop 0
	global_load_dwordx4 v[28:31], v[50:51], off offset:528
	v_lshl_add_u64 v[32:33], v[144:145], 0, s[34:35]
	v_lshl_add_u64 v[34:35], v[32:33], 2, s[38:39]
	s_waitcnt vmcnt(1)
	v_pk_add_f32 v[20:21], v[20:21], v[24:25]
	s_waitcnt vmcnt(0)
	v_pk_add_f32 v[24:25], v[18:19], v[30:31]
	v_pk_add_f32 v[18:19], v[16:17], v[28:29]
	v_pk_add_f32 v[22:23], v[22:23], v[26:27]
	v_cvt_pk_bf16_f32 v16, v20, v21
	s_nop 0
	v_cvt_pk_bf16_f32 v17, v22, v23
	v_cvt_pk_bf16_f32 v18, v18, v19
	v_cvt_pk_bf16_f32 v19, v24, v25
	global_store_dwordx4 v[40:41], v[16:19], off offset:256
	global_load_dwordx4 v[16:19], v[34:35], off
	s_nop 0
	global_load_dwordx4 v[20:23], v[34:35], off offset:16
	v_lshl_add_u64 v[24:25], v[32:33], 1, s[74:75]
	s_waitcnt vmcnt(1)
	v_pk_add_f32 v[12:13], v[12:13], v[16:17]
	s_waitcnt vmcnt(0)
	v_pk_add_f32 v[16:17], v[10:11], v[22:23]
	v_pk_add_f32 v[10:11], v[8:9], v[20:21]
	v_pk_add_f32 v[14:15], v[14:15], v[18:19]
	v_cvt_pk_bf16_f32 v8, v12, v13
	s_nop 0
	v_cvt_pk_bf16_f32 v9, v14, v15
	v_cvt_pk_bf16_f32 v10, v10, v11
	v_cvt_pk_bf16_f32 v11, v16, v17
	global_store_dwordx4 v[24:25], v[8:11], off
	global_load_dwordx4 v[8:11], v[34:35], off offset:512
	s_nop 0
	global_load_dwordx4 v[12:15], v[34:35], off offset:528
	s_waitcnt vmcnt(1)
	v_pk_add_f32 v[4:5], v[4:5], v[8:9]
	s_waitcnt vmcnt(0)
	v_pk_add_f32 v[8:9], v[2:3], v[14:15]
	v_pk_add_f32 v[2:3], v[0:1], v[12:13]
	v_pk_add_f32 v[6:7], v[6:7], v[10:11]
	v_cvt_pk_bf16_f32 v0, v4, v5
	s_nop 0
	v_cvt_pk_bf16_f32 v1, v6, v7
	v_cvt_pk_bf16_f32 v2, v2, v3
	v_cvt_pk_bf16_f32 v3, v8, v9
	global_store_dwordx4 v[24:25], v[0:3], off offset:256
	s_cbranch_vccnz .LBB0_750
	s_andn2_b64 vcc, exec, s[4:5]
	s_cbranch_vccnz .LBB0_749
	s_barrier
	s_branch .LBB0_749

.LBB0_923:
	s_or_b64 exec, exec, s[48:49]
	v_readlane_b32 s16, v254, 23
	v_lshlrev_b64 v[144:145], 2, v[178:179]
	v_readlane_b32 s24, v254, 31
	v_readlane_b32 s25, v254, 32
	v_readlane_b32 s26, v254, 33
	v_readlane_b32 s27, v254, 34
	v_lshl_add_u64 v[180:181], s[24:25], 0, v[144:145]
	v_lshl_add_u64 v[136:137], s[88:89], 0, v[144:145]
	global_load_dwordx4 v[128:131], v[180:181], off
	global_load_dwordx4 v[150:153], v[136:137], off
	v_lshl_add_u64 v[182:183], s[26:27], 0, v[144:145]
	v_lshl_add_u64 v[136:137], s[36:37], 0, v[144:145]
	global_load_dwordx4 v[132:135], v[182:183], off
	v_lshl_add_u64 v[140:141], s[58:59], 0, v[144:145]
	global_load_dwordx4 v[136:139], v[136:137], off
	v_lshl_add_u64 v[146:147], s[94:95], 0, v[144:145]
	global_load_dwordx4 v[140:143], v[140:141], off
	s_nop 0
	global_load_dwordx4 v[154:157], v[146:147], off
	v_lshl_add_u64 v[146:147], s[60:61], 0, v[144:145]
	v_lshl_add_u64 v[148:149], s[62:63], 0, v[144:145]
	global_load_dwordx4 v[144:147], v[146:147], off
	s_nop 0
	global_load_dwordx4 v[158:161], v[148:149], off
	v_mov_b32_dpp v194, v97 row_ror:1 row_mask:0xf bank_mask:0xf bound_ctrl:1
	v_mov_b32_dpp v193, v96 row_ror:1 row_mask:0xf bank_mask:0xf bound_ctrl:1
	v_mov_b32_dpp v148, v104 row_ror:1 row_mask:0xf bank_mask:0xf bound_ctrl:1
	v_mov_b32_dpp v197, v124 row_ror:15 row_mask:0xf bank_mask:0xf bound_ctrl:1
	v_mov_b32_dpp v201, v120 row_ror:15 row_mask:0xf bank_mask:0xf bound_ctrl:1
	v_mov_b32_dpp v149, v105 row_ror:1 row_mask:0xf bank_mask:0xf bound_ctrl:1
	v_mov_b32_dpp v202, v121 row_ror:15 row_mask:0xf bank_mask:0xf bound_ctrl:1
	v_mov_b32_dpp v195, v98 row_ror:1 row_mask:0xf bank_mask:0xf bound_ctrl:1
	v_mov_b32_dpp v196, v99 row_ror:1 row_mask:0xf bank_mask:0xf bound_ctrl:1
	v_mov_b32_dpp v203, v122 row_ror:15 row_mask:0xf bank_mask:0xf bound_ctrl:1
	v_mov_b32_dpp v198, v125 row_ror:15 row_mask:0xf bank_mask:0xf bound_ctrl:1
	v_mov_b32_dpp v204, v123 row_ror:15 row_mask:0xf bank_mask:0xf bound_ctrl:1
	v_mov_b32_dpp v191, v106 row_ror:1 row_mask:0xf bank_mask:0xf bound_ctrl:1
	v_mov_b32_dpp v199, v126 row_ror:15 row_mask:0xf bank_mask:0xf bound_ctrl:1
	v_mov_b32_dpp v192, v107 row_ror:1 row_mask:0xf bank_mask:0xf bound_ctrl:1
	v_mov_b32_dpp v200, v127 row_ror:15 row_mask:0xf bank_mask:0xf bound_ctrl:1
	v_readlane_b32 s17, v254, 24
	v_readlane_b32 s18, v254, 25
	v_readlane_b32 s19, v254, 26
	v_readlane_b32 s20, v254, 27
	v_readlane_b32 s21, v254, 28
	v_readlane_b32 s22, v254, 29
	v_readlane_b32 s23, v254, 30
	v_readlane_b32 s28, v254, 35
	v_readlane_b32 s29, v254, 36
	v_readlane_b32 s30, v254, 37
	v_readlane_b32 s31, v254, 38
	s_waitcnt vmcnt(0)
	v_fma_f32 v148, v128, v148, v132
	v_fma_f32 v205, v124, v128, v132
	v_fma_f32 v194, v151, v194, v137
	v_fma_f32 v193, v150, v193, v136
	v_fmac_f32_e32 v194, v121, v155
	v_fmac_f32_e32 v193, v120, v154
	v_fmac_f32_e32 v148, v124, v140
	v_fmac_f32_e32 v194, v113, v159
	v_fmac_f32_e32 v193, v112, v158
	v_mul_f32_e32 v124, v194, v194
	v_fma_f32 v206, v120, v150, v136
	v_mul_f32_e32 v120, v193, v193
	v_fmamk_f32 v124, v124, 0xbdd2d3e7, v190
	v_fmamk_f32 v120, v120, 0xbdd2d3e7, v190
	v_mul_f32_e32 v124, v194, v124
	v_mul_f32_e32 v120, v193, v120
	v_exp_f32_e32 v124, v124
	v_exp_f32_e32 v120, v120
	v_fma_f32 v149, v129, v149, v133
	v_fmac_f32_e32 v149, v125, v141
	v_add_f32_e32 v124, 1.0, v124
	v_add_f32_e32 v120, 1.0, v120
	v_rcp_f32_e32 v124, v124
	v_rcp_f32_e32 v120, v120
	v_fma_f32 v121, v121, v151, v137
	v_fmac_f32_e32 v149, v117, v145
	v_mul_f32_e32 v124, v194, v124
	v_fmac_f32_e32 v121, v113, v155
	v_fmac_f32_e32 v148, v116, v144
	v_mul_f32_e32 v120, v193, v120
	v_mul_f32_e32 v124, v149, v124
	v_fmac_f32_e32 v121, v101, v159
	v_mul_f32_e32 v120, v148, v120
	v_cvt_pk_bf16_f32 v148, v120, v124
	v_mul_f32_e32 v124, v121, v121
	v_fmamk_f32 v124, v124, 0xbdd2d3e7, v190
	v_mul_f32_e32 v124, v121, v124
	v_exp_f32_e32 v124, v124
	v_fma_f32 v195, v152, v195, v138
	v_fmac_f32_e32 v195, v122, v156
	v_fma_f32 v122, v122, v152, v138
	v_add_f32_e32 v124, 1.0, v124
	v_rcp_f32_e32 v124, v124
	v_fma_f32 v196, v153, v196, v139
	v_fmac_f32_e32 v206, v112, v154
	v_fmac_f32_e32 v122, v114, v156
	v_fmac_f32_e32 v196, v123, v157
	v_fmac_f32_e32 v195, v114, v160
	v_fmac_f32_e32 v206, v100, v158
	v_fmac_f32_e32 v122, v102, v160
	v_fmac_f32_e32 v196, v115, v161
	v_mul_f32_e32 v207, v195, v195
	v_mul_f32_e32 v209, v206, v206
	v_mul_f32_e32 v121, v121, v124
	v_mul_f32_e32 v124, v122, v122
	v_mul_f32_e32 v208, v196, v196
	v_fmamk_f32 v207, v207, 0xbdd2d3e7, v190
	v_fmamk_f32 v209, v209, 0xbdd2d3e7, v190
	v_fmamk_f32 v124, v124, 0xbdd2d3e7, v190
	v_fmamk_f32 v208, v208, 0xbdd2d3e7, v190
	v_mul_f32_e32 v207, v195, v207
	v_mul_f32_e32 v209, v206, v209
	v_fma_f32 v125, v125, v129, v133
	v_mul_f32_e32 v124, v122, v124
	v_fma_f32 v123, v123, v153, v139
	v_mul_f32_e32 v208, v196, v208
	v_exp_f32_e32 v207, v207
	v_exp_f32_e32 v209, v209
	v_fmac_f32_e32 v125, v117, v141
	v_exp_f32_e32 v124, v124
	v_fmac_f32_e32 v123, v115, v157
	v_fma_f32 v191, v130, v191, v134
	v_exp_f32_e32 v208, v208
	v_fmac_f32_e32 v125, v109, v145
	v_fmac_f32_e32 v123, v103, v161
	v_fmac_f32_e32 v191, v126, v142
	v_mul_f32_e32 v121, v125, v121
	v_fma_f32 v125, v126, v130, v134
	v_mul_f32_e32 v126, v123, v123
	v_fmamk_f32 v126, v126, 0xbdd2d3e7, v190
	v_add_f32_e32 v207, 1.0, v207
	v_add_f32_e32 v120, 1.0, v209
	v_add_f32_e32 v124, 1.0, v124
	v_mul_f32_e32 v126, v123, v126
	v_add_f32_e32 v208, 1.0, v208
	v_rcp_f32_e32 v207, v207
	v_rcp_f32_e32 v120, v120
	v_rcp_f32_e32 v124, v124
	v_exp_f32_e32 v126, v126
	v_rcp_f32_e32 v208, v208
	v_fma_f32 v113, v113, v151, v137
	v_fma_f32 v192, v131, v192, v135
	v_fmac_f32_e32 v205, v116, v140
	v_fma_f32 v112, v112, v150, v136
	v_fmac_f32_e32 v113, v101, v155
	v_fma_f32 v101, v101, v151, v137
	v_fmac_f32_e32 v192, v127, v143
	v_fmac_f32_e32 v191, v118, v146
	v_mul_f32_e32 v193, v195, v207
	v_fmac_f32_e32 v205, v108, v144
	v_mul_f32_e32 v120, v206, v120
	v_mul_f32_e32 v122, v122, v124
	v_add_f32_e32 v124, 1.0, v126
	v_fmac_f32_e32 v112, v100, v154
	v_fmac_f32_e32 v101, v97, v155
	v_fmac_f32_e32 v192, v119, v147
	v_mul_f32_e32 v194, v196, v208
	v_mul_f32_e32 v149, v191, v193
	v_mul_f32_e32 v120, v205, v120
	v_rcp_f32_e32 v124, v124
	v_fmac_f32_e32 v112, v96, v158
	v_fmac_f32_e32 v101, v159, v202
	v_mul_f32_e32 v191, v192, v194
	v_cvt_pk_bf16_f32 v149, v149, v191
	v_fmac_f32_e32 v125, v118, v142
	v_cvt_pk_bf16_f32 v120, v120, v121
	v_mul_f32_e32 v121, v112, v112
	v_fmac_f32_e32 v113, v97, v159
	v_mul_f32_e32 v97, v101, v101
	v_fmac_f32_e32 v125, v110, v146
	v_fmamk_f32 v121, v121, 0xbdd2d3e7, v190
	v_fmamk_f32 v97, v97, 0xbdd2d3e7, v190
	v_mul_f32_e32 v122, v125, v122
	v_fma_f32 v125, v127, v131, v135
	v_mul_f32_e32 v121, v112, v121
	v_mul_f32_e32 v97, v101, v97
	v_fmac_f32_e32 v125, v119, v143
	v_mul_f32_e32 v123, v123, v124
	v_exp_f32_e32 v124, v121
	v_exp_f32_e32 v97, v97
	v_fmac_f32_e32 v125, v111, v147
	v_mul_f32_e32 v123, v125, v123
	v_cvt_pk_bf16_f32 v121, v122, v123
	v_mul_f32_e32 v123, v113, v113
	v_add_f32_e32 v122, 1.0, v124
	v_fmamk_f32 v123, v123, 0xbdd2d3e7, v190
	v_fma_f32 v100, v100, v150, v136
	v_add_f32_e32 v97, 1.0, v97
	v_rcp_f32_e32 v122, v122
	v_mul_f32_e32 v123, v113, v123
	v_fmac_f32_e32 v100, v96, v154
	v_rcp_f32_e32 v97, v97
	v_exp_f32_e32 v123, v123
	v_fmac_f32_e32 v100, v158, v201
	v_fma_f32 v116, v116, v128, v132
	v_mul_f32_e32 v96, v100, v100
	v_fmac_f32_e32 v116, v108, v140
	v_fmamk_f32 v96, v96, 0xbdd2d3e7, v190
	v_fmac_f32_e32 v116, v104, v144
	v_mul_f32_e32 v112, v112, v122
	v_mul_f32_e32 v96, v100, v96
	v_mul_f32_e32 v97, v101, v97
	v_fma_f32 v101, v102, v152, v138
	v_mul_f32_e32 v112, v116, v112
	v_add_f32_e32 v116, 1.0, v123
	v_fma_f32 v114, v114, v152, v138
	v_exp_f32_e32 v96, v96
	v_fmac_f32_e32 v101, v98, v156
	v_rcp_f32_e32 v116, v116
	v_fmac_f32_e32 v114, v102, v156
	v_fmac_f32_e32 v101, v160, v203
	v_fmac_f32_e32 v114, v98, v160
	v_mul_f32_e32 v98, v101, v101
	v_fmamk_f32 v98, v98, 0xbdd2d3e7, v190
	v_add_f32_e32 v96, 1.0, v96
	v_mul_f32_e32 v98, v101, v98
	v_mul_f32_e32 v113, v113, v116
	v_mul_f32_e32 v116, v114, v114
	v_rcp_f32_e32 v96, v96
	v_exp_f32_e32 v98, v98
	v_fma_f32 v102, v103, v153, v139
	v_fmamk_f32 v116, v116, 0xbdd2d3e7, v190
	v_fma_f32 v115, v115, v153, v139
	v_fmac_f32_e32 v102, v99, v157
	v_fma_f32 v117, v117, v129, v133
	v_mul_f32_e32 v116, v114, v116
	v_fmac_f32_e32 v115, v103, v157
	v_fmac_f32_e32 v102, v161, v204
	v_fmac_f32_e32 v117, v109, v141
	v_exp_f32_e32 v116, v116
	v_fmac_f32_e32 v115, v99, v161
	v_mul_f32_e32 v99, v102, v102
	v_fmac_f32_e32 v117, v105, v145
	v_mul_f32_e32 v96, v100, v96
	v_fma_f32 v100, v109, v129, v133
	v_add_f32_e32 v98, 1.0, v98
	v_fmamk_f32 v99, v99, 0xbdd2d3e7, v190
	v_mul_f32_e32 v113, v117, v113
	v_fma_f32 v117, v118, v130, v134
	v_mul_f32_e32 v118, v115, v115
	v_fmac_f32_e32 v100, v105, v141
	v_rcp_f32_e32 v98, v98
	v_mul_f32_e32 v99, v102, v99
	v_fmamk_f32 v118, v118, 0xbdd2d3e7, v190
	v_fmac_f32_e32 v100, v145, v198
	v_exp_f32_e32 v99, v99
	v_add_f32_e32 v116, 1.0, v116
	v_mul_f32_e32 v118, v115, v118
	v_mul_f32_e32 v97, v100, v97
	v_fma_f32 v100, v110, v130, v134
	v_rcp_f32_e32 v116, v116
	v_exp_f32_e32 v118, v118
	v_fmac_f32_e32 v100, v106, v142
	v_fmac_f32_e32 v100, v146, v199
	v_mul_f32_e32 v98, v101, v98
	v_mul_f32_e32 v100, v100, v98
	v_add_f32_e32 v98, 1.0, v99
	v_rcp_f32_e32 v98, v98
	v_mul_f32_e32 v114, v114, v116
	v_add_f32_e32 v116, 1.0, v118
	v_fmac_f32_e32 v117, v110, v142
	v_rcp_f32_e32 v116, v116
	v_fmac_f32_e32 v117, v106, v146
	v_mul_f32_e32 v114, v117, v114
	v_fma_f32 v117, v119, v131, v135
	v_mul_f32_e32 v98, v102, v98
	v_mov_b32_dpp v102, v64 row_ror:1 row_mask:0xf bank_mask:0xf bound_ctrl:1
	v_fmac_f32_e32 v117, v111, v143
	v_fma_f32 v102, v150, v102, v136
	v_fmac_f32_e32 v117, v107, v147
	v_mul_f32_e32 v115, v115, v116
	v_fmac_f32_e32 v102, v88, v154
	v_mul_f32_e32 v115, v117, v115
	v_fmac_f32_e32 v102, v80, v158
	v_cvt_pk_bf16_f32 v112, v112, v113
	v_cvt_pk_bf16_f32 v113, v114, v115
	v_mul_f32_e32 v115, v102, v102
	v_fmamk_f32 v115, v115, 0xbdd2d3e7, v190
	v_mov_b32_dpp v103, v65 row_ror:1 row_mask:0xf bank_mask:0xf bound_ctrl:1
	v_mul_f32_e32 v115, v102, v115
	v_exp_f32_e32 v115, v115
	v_fma_f32 v103, v151, v103, v137
	v_fmac_f32_e32 v103, v89, v155
	v_fma_f32 v108, v108, v128, v132
	v_fmac_f32_e32 v103, v81, v159
	v_fmac_f32_e32 v108, v104, v140
	v_fma_f32 v99, v111, v131, v135
	v_mul_f32_e32 v117, v103, v103
	v_fmac_f32_e32 v108, v144, v197
	v_fmac_f32_e32 v99, v107, v143
	v_add_f32_e32 v115, 1.0, v115
	v_fmamk_f32 v117, v117, 0xbdd2d3e7, v190
	v_mul_f32_e32 v96, v108, v96
	v_fmac_f32_e32 v99, v147, v200
	v_rcp_f32_e32 v115, v115
	v_mul_f32_e32 v117, v103, v117
	v_mul_f32_e32 v99, v99, v98
	v_cvt_pk_bf16_f32 v98, v96, v97
	v_mov_b32_dpp v96, v72 row_ror:1 row_mask:0xf bank_mask:0xf bound_ctrl:1
	v_exp_f32_e32 v117, v117
	v_fma_f32 v96, v128, v96, v132
	v_fmac_f32_e32 v96, v92, v140
	v_fmac_f32_e32 v96, v84, v144
	v_mul_f32_e32 v102, v102, v115
	v_mul_f32_e32 v96, v96, v102
	v_add_f32_e32 v102, 1.0, v117
	v_rcp_f32_e32 v102, v102
	v_mov_b32_dpp v104, v66 row_ror:1 row_mask:0xf bank_mask:0xf bound_ctrl:1
	v_mov_b32_dpp v97, v73 row_ror:1 row_mask:0xf bank_mask:0xf bound_ctrl:1
	v_fma_f32 v97, v129, v97, v133
	v_mul_f32_e32 v102, v103, v102
	v_fma_f32 v103, v152, v104, v138
	v_fmac_f32_e32 v103, v90, v156
	v_fmac_f32_e32 v103, v82, v160
	v_mul_f32_e32 v104, v103, v103
	v_fmamk_f32 v104, v104, 0xbdd2d3e7, v190
	v_mul_f32_e32 v104, v103, v104
	v_exp_f32_e32 v104, v104
	v_fmac_f32_e32 v97, v93, v141
	v_mov_b32_dpp v105, v67 row_ror:1 row_mask:0xf bank_mask:0xf bound_ctrl:1
	v_fmac_f32_e32 v97, v85, v145
	v_mul_f32_e32 v97, v97, v102
	v_add_f32_e32 v102, 1.0, v104
	v_fma_f32 v104, v153, v105, v139
	v_fmac_f32_e32 v104, v91, v157
	v_fmac_f32_e32 v104, v83, v161
	v_mul_f32_e32 v105, v104, v104
	v_fmamk_f32 v105, v105, 0xbdd2d3e7, v190
	v_rcp_f32_e32 v102, v102
	v_mul_f32_e32 v105, v104, v105
	v_cvt_pk_bf16_f32 v99, v100, v99
	v_mov_b32_dpp v100, v74 row_ror:1 row_mask:0xf bank_mask:0xf bound_ctrl:1
	v_exp_f32_e32 v105, v105
	v_fma_f32 v100, v130, v100, v134
	v_fmac_f32_e32 v100, v94, v142
	v_fmac_f32_e32 v100, v86, v146
	v_mul_f32_e32 v102, v103, v102
	v_mov_b32_dpp v110, v88 row_ror:15 row_mask:0xf bank_mask:0xf bound_ctrl:1
	v_mul_f32_e32 v100, v100, v102
	v_add_f32_e32 v102, 1.0, v105
	v_fma_f32 v88, v88, v150, v136
	v_rcp_f32_e32 v102, v102
	v_fmac_f32_e32 v88, v80, v154
	v_mov_b32_dpp v101, v75 row_ror:1 row_mask:0xf bank_mask:0xf bound_ctrl:1
	v_fmac_f32_e32 v88, v68, v158
	v_fma_f32 v101, v131, v101, v135
	v_cvt_pk_bf16_f32 v96, v96, v97
	v_mul_f32_e32 v97, v88, v88
	v_fmac_f32_e32 v101, v95, v143
	v_fmamk_f32 v97, v97, 0xbdd2d3e7, v190
	v_fmac_f32_e32 v101, v87, v147
	v_mul_f32_e32 v102, v104, v102
	v_mul_f32_e32 v97, v88, v97
	v_mov_b32_dpp v111, v89 row_ror:15 row_mask:0xf bank_mask:0xf bound_ctrl:1
	v_mul_f32_e32 v101, v101, v102
	v_exp_f32_e32 v102, v97
	v_fma_f32 v89, v89, v151, v137
	v_fmac_f32_e32 v89, v81, v155
	v_fmac_f32_e32 v89, v69, v159
	v_cvt_pk_bf16_f32 v97, v100, v101
	v_mul_f32_e32 v101, v89, v89
	v_add_f32_e32 v100, 1.0, v102
	v_fmamk_f32 v101, v101, 0xbdd2d3e7, v190
	v_rcp_f32_e32 v100, v100
	v_mul_f32_e32 v101, v89, v101
	v_exp_f32_e32 v101, v101
	v_mov_b32_dpp v106, v92 row_ror:15 row_mask:0xf bank_mask:0xf bound_ctrl:1
	v_fma_f32 v92, v92, v128, v132
	v_fmac_f32_e32 v92, v84, v140
	v_fmac_f32_e32 v92, v76, v144
	v_mul_f32_e32 v88, v88, v100
	v_mul_f32_e32 v88, v92, v88
	v_add_f32_e32 v92, 1.0, v101
	v_rcp_f32_e32 v92, v92
	v_mov_b32_dpp v114, v90 row_ror:15 row_mask:0xf bank_mask:0xf bound_ctrl:1
	v_fma_f32 v90, v90, v152, v138
	v_fmac_f32_e32 v90, v82, v156
	v_fmac_f32_e32 v90, v70, v160
	v_mul_f32_e32 v89, v89, v92
	v_mul_f32_e32 v92, v90, v90
	v_fmamk_f32 v92, v92, 0xbdd2d3e7, v190
	v_mov_b32_dpp v107, v93 row_ror:15 row_mask:0xf bank_mask:0xf bound_ctrl:1
	v_mov_b32_dpp v116, v91 row_ror:15 row_mask:0xf bank_mask:0xf bound_ctrl:1
	v_fma_f32 v93, v93, v129, v133
	v_mul_f32_e32 v92, v90, v92
	v_fma_f32 v91, v91, v153, v139
	v_fmac_f32_e32 v93, v85, v141
	v_exp_f32_e32 v92, v92
	v_fmac_f32_e32 v91, v83, v157
	v_fmac_f32_e32 v93, v77, v145
	v_fmac_f32_e32 v91, v71, v161
	v_mov_b32_dpp v108, v94 row_ror:15 row_mask:0xf bank_mask:0xf bound_ctrl:1
	v_mul_f32_e32 v89, v93, v89
	v_fma_f32 v93, v94, v130, v134
	v_mul_f32_e32 v94, v91, v91
	v_fmamk_f32 v94, v94, 0xbdd2d3e7, v190
	v_add_f32_e32 v92, 1.0, v92
	v_mul_f32_e32 v94, v91, v94
	v_rcp_f32_e32 v92, v92
	v_exp_f32_e32 v94, v94
	v_fma_f32 v80, v80, v150, v136
	v_fmac_f32_e32 v80, v68, v154
	v_mul_f32_e32 v90, v90, v92
	v_add_f32_e32 v92, 1.0, v94
	v_rcp_f32_e32 v92, v92
	v_fmac_f32_e32 v80, v64, v158
	v_fmac_f32_e32 v93, v86, v142
	v_cvt_pk_bf16_f32 v88, v88, v89
	v_mul_f32_e32 v89, v80, v80
	v_fmac_f32_e32 v93, v78, v146
	v_fmamk_f32 v89, v89, 0xbdd2d3e7, v190
	v_mul_f32_e32 v90, v93, v90
	v_fma_f32 v93, v95, v131, v135
	v_mul_f32_e32 v89, v80, v89
	v_fmac_f32_e32 v93, v87, v143
	v_mul_f32_e32 v91, v91, v92
	v_exp_f32_e32 v92, v89
	v_fma_f32 v81, v81, v151, v137
	v_fmac_f32_e32 v93, v79, v147
	v_fmac_f32_e32 v81, v69, v155
	v_fma_f32 v69, v69, v151, v137
	v_mul_f32_e32 v91, v93, v91
	v_fmac_f32_e32 v81, v65, v159
	v_fmac_f32_e32 v69, v65, v155
	v_cvt_pk_bf16_f32 v89, v90, v91
	v_mul_f32_e32 v91, v81, v81
	v_fmac_f32_e32 v69, v159, v111
	v_add_f32_e32 v90, 1.0, v92
	v_fmamk_f32 v91, v91, 0xbdd2d3e7, v190
	v_mul_f32_e32 v65, v69, v69
	v_rcp_f32_e32 v90, v90
	v_mul_f32_e32 v91, v81, v91
	v_fmamk_f32 v65, v65, 0xbdd2d3e7, v190
	v_exp_f32_e32 v91, v91
	v_mul_f32_e32 v65, v69, v65
	v_fma_f32 v84, v84, v128, v132
	v_exp_f32_e32 v65, v65
	v_fmac_f32_e32 v84, v76, v140
	v_fmac_f32_e32 v84, v72, v144
	v_mul_f32_e32 v80, v80, v90
	v_mul_f32_e32 v80, v84, v80
	v_add_f32_e32 v84, 1.0, v91
	v_rcp_f32_e32 v84, v84
	v_fma_f32 v68, v68, v150, v136
	v_add_f32_e32 v65, 1.0, v65
	v_fma_f32 v82, v82, v152, v138
	v_fmac_f32_e32 v68, v64, v154
	v_rcp_f32_e32 v65, v65
	v_fmac_f32_e32 v82, v70, v156
	v_fmac_f32_e32 v68, v158, v110
	v_fmac_f32_e32 v82, v66, v160
	v_mul_f32_e32 v64, v68, v68
	v_mul_f32_e32 v81, v81, v84
	v_mul_f32_e32 v84, v82, v82
	v_fmamk_f32 v64, v64, 0xbdd2d3e7, v190
	v_fmamk_f32 v84, v84, 0xbdd2d3e7, v190
	v_mul_f32_e32 v64, v68, v64
	v_mul_f32_e32 v65, v69, v65
	v_fma_f32 v69, v70, v152, v138
	v_fma_f32 v85, v85, v129, v133
	v_mul_f32_e32 v84, v82, v84
	v_fma_f32 v83, v83, v153, v139
	v_exp_f32_e32 v64, v64
	v_fmac_f32_e32 v69, v66, v156
	v_fmac_f32_e32 v139, v71, v153
	v_fmac_f32_e32 v85, v77, v141
	v_exp_f32_e32 v84, v84
	v_fmac_f32_e32 v83, v71, v157
	v_fmac_f32_e32 v69, v160, v114
	v_fmac_f32_e32 v139, v67, v157
	v_fmac_f32_e32 v85, v73, v145
	v_fmac_f32_e32 v83, v67, v161
	v_mul_f32_e32 v66, v69, v69
	v_fmac_f32_e32 v139, v161, v116
	v_mul_f32_e32 v81, v85, v81
	v_fma_f32 v85, v86, v130, v134
	v_mul_f32_e32 v86, v83, v83
	v_fmamk_f32 v66, v66, 0xbdd2d3e7, v190
	v_mul_f32_e32 v67, v139, v139
	v_fmamk_f32 v86, v86, 0xbdd2d3e7, v190
	v_add_f32_e32 v64, 1.0, v64
	v_mul_f32_e32 v66, v69, v66
	v_fmamk_f32 v67, v67, 0xbdd2d3e7, v190
	v_add_f32_e32 v84, 1.0, v84
	v_mul_f32_e32 v86, v83, v86
	v_rcp_f32_e32 v64, v64
	v_exp_f32_e32 v66, v66
	v_mul_f32_e32 v67, v139, v67
	v_rcp_f32_e32 v84, v84
	v_exp_f32_e32 v86, v86
	v_exp_f32_e32 v67, v67
	v_mul_f32_e32 v64, v68, v64
	v_fma_f32 v68, v77, v129, v133
	v_add_f32_e32 v66, 1.0, v66
	v_mul_f32_e32 v82, v82, v84
	v_add_f32_e32 v84, 1.0, v86
	v_fmac_f32_e32 v68, v73, v141
	v_rcp_f32_e32 v66, v66
	v_add_f32_e32 v67, 1.0, v67
	v_fmac_f32_e32 v85, v78, v142
	v_rcp_f32_e32 v84, v84
	v_fmac_f32_e32 v68, v145, v107
	v_rcp_f32_e32 v67, v67
	v_fmac_f32_e32 v85, v74, v146
	v_fma_f32 v76, v76, v128, v132
	v_mul_f32_e32 v65, v68, v65
	v_fma_f32 v68, v78, v130, v134
	v_mul_f32_e32 v82, v85, v82
	v_fma_f32 v85, v87, v131, v135
	v_fmac_f32_e32 v76, v72, v140
	v_fmac_f32_e32 v68, v74, v142
	v_fmac_f32_e32 v135, v79, v131
	v_mov_b32_dpp v109, v95 row_ror:15 row_mask:0xf bank_mask:0xf bound_ctrl:1
	v_fmac_f32_e32 v85, v79, v143
	v_fmac_f32_e32 v76, v144, v106
	v_fmac_f32_e32 v68, v146, v108
	v_mul_f32_e32 v66, v69, v66
	v_fmac_f32_e32 v135, v75, v143
	v_fmac_f32_e32 v85, v75, v147
	v_mul_f32_e32 v83, v83, v84
	v_mul_f32_e32 v64, v76, v64
	v_mul_f32_e32 v66, v68, v66
	v_fmac_f32_e32 v135, v147, v109
	v_mul_f32_e32 v67, v139, v67
	v_mul_f32_e32 v83, v85, v83
	v_cvt_pk_bf16_f32 v80, v80, v81
	v_cvt_pk_bf16_f32 v81, v82, v83
	v_mul_f32_e32 v67, v135, v67
	v_cvt_pk_bf16_f32 v64, v64, v65
	v_cvt_pk_bf16_f32 v65, v66, v67
	v_or_b32_e32 v66, 4, v178
	v_ashrrev_i32_e32 v67, 31, v66
	v_lshlrev_b64 v[78:79], 2, v[66:67]
	v_lshl_add_u64 v[66:67], s[88:89], 0, v[78:79]
	v_lshl_add_u64 v[68:69], s[94:95], 0, v[78:79]
	global_load_dwordx4 v[106:109], v[66:67], off
	global_load_dwordx4 v[102:105], v[68:69], off
	v_lshl_add_u64 v[66:67], s[36:37], 0, v[78:79]
	global_load_dwordx4 v[66:69], v[66:67], off
	v_lshl_add_u64 v[70:71], s[62:63], 0, v[78:79]
	global_load_dwordx4 v[116:119], v[70:71], off
	global_load_dwordx4 v[74:77], v[180:181], off offset:16
	v_lshl_add_u64 v[82:83], s[58:59], 0, v[78:79]
	global_load_dwordx4 v[70:73], v[182:183], off offset:16
	global_load_dwordx4 v[84:87], v[82:83], off
	v_lshl_add_u64 v[78:79], s[60:61], 0, v[78:79]
	global_load_dwordx4 v[92:95], v[78:79], off
	v_mov_b32_dpp v100, v32 row_ror:1 row_mask:0xf bank_mask:0xf bound_ctrl:1
	v_mov_b32_dpp v110, v33 row_ror:1 row_mask:0xf bank_mask:0xf bound_ctrl:1
	v_mov_b32_dpp v78, v40 row_ror:1 row_mask:0xf bank_mask:0xf bound_ctrl:1
	v_mov_b32_dpp v111, v34 row_ror:1 row_mask:0xf bank_mask:0xf bound_ctrl:1
	v_mov_b32_dpp v79, v41 row_ror:1 row_mask:0xf bank_mask:0xf bound_ctrl:1
	v_mov_b32_dpp v114, v35 row_ror:1 row_mask:0xf bank_mask:0xf bound_ctrl:1
	v_mov_b32_dpp v82, v42 row_ror:1 row_mask:0xf bank_mask:0xf bound_ctrl:1
	v_mov_b32_dpp v83, v43 row_ror:1 row_mask:0xf bank_mask:0xf bound_ctrl:1
	v_lshl_add_u32 v140, s46, 8, v185
	v_mov_b32_dpp v142, v60 row_ror:15 row_mask:0xf bank_mask:0xf bound_ctrl:1
	v_mov_b32_dpp v141, v61 row_ror:15 row_mask:0xf bank_mask:0xf bound_ctrl:1
	v_mov_b32_dpp v91, v62 row_ror:15 row_mask:0xf bank_mask:0xf bound_ctrl:1
	v_mov_b32_dpp v90, v63 row_ror:15 row_mask:0xf bank_mask:0xf bound_ctrl:1
	v_mov_b32_dpp v144, v52 row_ror:15 row_mask:0xf bank_mask:0xf bound_ctrl:1
	v_mov_b32_dpp v143, v53 row_ror:15 row_mask:0xf bank_mask:0xf bound_ctrl:1
	v_mov_b32_dpp v101, v54 row_ror:15 row_mask:0xf bank_mask:0xf bound_ctrl:1
	s_waitcnt vmcnt(5)
	v_fma_f32 v115, v106, v100, v66
	v_fmac_f32_e32 v115, v52, v102
	s_waitcnt vmcnt(4)
	v_fmac_f32_e32 v115, v48, v116
	v_mul_f32_e32 v100, v115, v115
	v_fmamk_f32 v100, v100, 0xbdd2d3e7, v190
	v_mul_f32_e32 v100, v115, v100
	v_exp_f32_e32 v122, v100
	v_fma_f32 v110, v107, v110, v67
	v_fmac_f32_e32 v110, v53, v103
	v_fmac_f32_e32 v110, v49, v117
	v_mul_f32_e32 v123, v110, v110
	v_add_f32_e32 v122, 1.0, v122
	v_fmamk_f32 v123, v123, 0xbdd2d3e7, v190
	v_rcp_f32_e32 v122, v122
	v_mul_f32_e32 v123, v110, v123
	v_exp_f32_e32 v123, v123
	s_waitcnt vmcnt(2)
	v_fma_f32 v78, v74, v78, v70
	s_waitcnt vmcnt(1)
	v_fmac_f32_e32 v78, v60, v84
	s_waitcnt vmcnt(0)
	v_fmac_f32_e32 v78, v56, v92
	v_mul_f32_e32 v115, v115, v122
	v_mul_f32_e32 v78, v78, v115
	v_add_f32_e32 v115, 1.0, v123
	v_rcp_f32_e32 v115, v115
	v_fma_f32 v111, v108, v111, v68
	v_fmac_f32_e32 v111, v54, v104
	v_fmac_f32_e32 v111, v50, v118
	v_mul_f32_e32 v110, v110, v115
	v_mul_f32_e32 v115, v111, v111
	v_fmamk_f32 v115, v115, 0xbdd2d3e7, v190
	v_mul_f32_e32 v115, v111, v115
	v_exp_f32_e32 v115, v115
	v_fma_f32 v79, v75, v79, v71
	v_fma_f32 v114, v109, v114, v69
	v_fmac_f32_e32 v79, v61, v85
	v_fmac_f32_e32 v114, v55, v105
	v_fmac_f32_e32 v79, v57, v93
	v_fmac_f32_e32 v114, v51, v119
	v_mul_f32_e32 v79, v79, v110
	v_add_f32_e32 v110, 1.0, v115
	v_mul_f32_e32 v115, v114, v114
	v_fmamk_f32 v115, v115, 0xbdd2d3e7, v190
	v_rcp_f32_e32 v110, v110
	v_mul_f32_e32 v115, v114, v115
	v_exp_f32_e32 v115, v115
	v_fma_f32 v82, v76, v82, v72
	v_fmac_f32_e32 v82, v62, v86
	v_fmac_f32_e32 v82, v58, v94
	v_mul_f32_e32 v110, v111, v110
	v_mul_f32_e32 v82, v82, v110
	v_add_f32_e32 v110, 1.0, v115
	v_rcp_f32_e32 v110, v110
	v_fma_f32 v83, v77, v83, v73
	v_fmac_f32_e32 v83, v63, v87
	v_mov_b32_dpp v100, v55 row_ror:15 row_mask:0xf bank_mask:0xf bound_ctrl:1
	v_fmac_f32_e32 v83, v59, v95
	v_mul_f32_e32 v110, v114, v110
	v_mul_f32_e32 v83, v83, v110
	v_cvt_pk_bf16_f32 v150, v78, v79
	v_cvt_pk_bf16_f32 v151, v82, v83
	s_and_saveexec_b64 s[46:47], s[2:3]
	s_cbranch_execz .LBB0_925
	v_mov_b64_e32 v[78:79], s[12:13]
	v_mad_i64_i32 v[78:79], s[34:35], v140, s78, v[78:79]
	v_lshl_add_u64 v[78:79], v[178:179], 1, v[78:79]
	global_store_dwordx4 v[78:79], v[148:151], off
.LBB0_925:
	s_or_b64 exec, exec, s[46:47]
	v_mov_b32_e32 v114, v60
	v_mov_b32_e32 v115, v52
	v_mov_b32_e32 v78, v74
	v_mov_b32_e32 v79, v106
	v_mov_b32_e32 v110, v70
	v_mov_b32_e32 v111, v66
	v_mov_b32_e32 v138, v56
	v_mov_b32_e32 v139, v48
	v_mov_b32_e32 v82, v84
	v_mov_b32_e32 v83, v102
	v_pk_fma_f32 v[114:115], v[114:115], v[78:79], v[110:111]
	v_mov_b32_e32 v146, v44
	v_pk_fma_f32 v[114:115], v[138:139], v[82:83], v[114:115]
	v_mov_b32_e32 v147, v36
	v_mov_b32_e32 v124, v92
	v_mov_b32_e32 v125, v116
	v_pk_fma_f32 v[114:115], v[146:147], v[124:125], v[114:115]
	v_mov_b32_e32 v52, v61
	v_mul_f32_e32 v48, v115, v115
	v_fmamk_f32 v48, v48, 0xbdd2d3e7, v190
	v_mul_f32_e32 v48, v115, v48
	v_exp_f32_e32 v48, v48
	v_mov_b32_e32 v60, v75
	v_mov_b32_e32 v61, v107
	v_mov_b32_e32 v126, v71
	v_add_f32_e32 v48, 1.0, v48
	v_mov_b32_e32 v127, v67
	v_rcp_f32_e32 v128, v48
	v_mov_b32_e32 v48, v57
	v_mov_b32_e32 v56, v85
	v_mov_b32_e32 v57, v103
	v_pk_fma_f32 v[52:53], v[52:53], v[60:61], v[126:127]
	v_mov_b32_e32 v148, v45
	v_pk_fma_f32 v[122:123], v[48:49], v[56:57], v[52:53]
	v_mov_b32_e32 v149, v37
	v_mov_b32_e32 v52, v93
	v_mov_b32_e32 v53, v117
	v_pk_fma_f32 v[122:123], v[148:149], v[52:53], v[122:123]
	v_mul_f32_e32 v115, v115, v128
	v_mul_f32_e32 v129, v123, v123
	v_fmamk_f32 v129, v129, 0xbdd2d3e7, v190
	v_mul_f32_e32 v129, v123, v129
	v_exp_f32_e32 v129, v129
	v_mul_f32_e32 v145, v114, v115
	v_mov_b32_e32 v115, v54
	v_mov_b32_e32 v128, v76
	v_add_f32_e32 v114, 1.0, v129
	v_rcp_f32_e32 v158, v114
	v_mov_b32_e32 v114, v62
	v_mov_b32_e32 v129, v108
	v_mov_b32_e32 v132, v72
	v_mov_b32_e32 v133, v68
	v_mov_b32_e32 v150, v58
	v_mov_b32_e32 v151, v50
	v_mov_b32_e32 v130, v86
	v_mov_b32_e32 v131, v104
	v_pk_fma_f32 v[114:115], v[114:115], v[128:129], v[132:133]
	v_mov_b32_e32 v152, v46
	v_pk_fma_f32 v[114:115], v[150:151], v[130:131], v[114:115]
	v_mov_b32_e32 v153, v38
	v_mov_b32_e32 v134, v94
	v_mov_b32_e32 v135, v118
	v_pk_fma_f32 v[114:115], v[152:153], v[134:135], v[114:115]
	v_mov_b32_e32 v54, v63
	v_mul_f32_e32 v50, v115, v115
	v_fmamk_f32 v50, v50, 0xbdd2d3e7, v190
	v_mul_f32_e32 v50, v115, v50
	v_mov_b32_e32 v62, v77
	v_mov_b32_e32 v63, v109
	v_mov_b32_e32 v136, v73
	v_mov_b32_e32 v137, v69
	v_exp_f32_e32 v159, v50
	v_mov_b32_e32 v50, v59
	v_mov_b32_e32 v58, v87
	v_mov_b32_e32 v59, v105
	v_pk_fma_f32 v[54:55], v[54:55], v[62:63], v[136:137]
	v_mov_b32_e32 v156, v47
	v_pk_fma_f32 v[154:155], v[50:51], v[58:59], v[54:55]
	v_mov_b32_e32 v157, v39
	v_mov_b32_e32 v54, v95
	v_mov_b32_e32 v55, v119
	v_pk_fma_f32 v[154:155], v[156:157], v[54:55], v[154:155]
	v_mul_f32_e32 v123, v123, v158
	v_mul_f32_e32 v160, v155, v155
	v_fmamk_f32 v160, v160, 0xbdd2d3e7, v190
	v_mul_f32_e32 v160, v155, v160
	v_exp_f32_e32 v160, v160
	v_add_f32_e32 v158, 1.0, v159
	v_rcp_f32_e32 v158, v158
	v_mul_f32_e32 v122, v122, v123
	v_add_f32_e32 v159, 1.0, v160
	v_rcp_f32_e32 v159, v159
	v_mul_f32_e32 v115, v115, v158
	v_mul_f32_e32 v114, v114, v115
	v_cvt_pk_bf16_f32 v122, v145, v122
	v_mul_f32_e32 v115, v155, v159
	v_mul_f32_e32 v115, v154, v115
	v_cvt_pk_bf16_f32 v123, v114, v115
	v_pk_fma_f32 v[114:115], v[138:139], v[78:79], v[110:111]
	v_mov_b32_e32 v138, v40
	v_pk_fma_f32 v[114:115], v[146:147], v[82:83], v[114:115]
	v_mov_b32_e32 v139, v32
	v_pk_fma_f32 v[114:115], v[138:139], v[124:125], v[114:115]
	v_pk_fma_f32 v[48:49], v[48:49], v[60:61], v[126:127]
	v_mul_f32_e32 v138, v115, v115
	v_fmamk_f32 v138, v138, 0xbdd2d3e7, v190
	v_mul_f32_e32 v138, v115, v138
	v_exp_f32_e32 v158, v138
	v_fma_f32 v37, v37, v107, v67
	v_pk_fma_f32 v[48:49], v[148:149], v[56:57], v[48:49]
	v_mov_b32_e32 v148, v41
	v_mov_b32_e32 v149, v33
	v_fmac_f32_e32 v37, v33, v103
	v_pk_fma_f32 v[48:49], v[148:149], v[52:53], v[48:49]
	v_fmac_f32_e32 v37, v117, v143
	v_or_b32_e32 v145, 1, v140
	v_mov_b64_e32 v[154:155], s[12:13]
	v_mul_f32_e32 v148, v49, v49
	v_mul_f32_e32 v33, v37, v37
	v_mad_i64_i32 v[146:147], s[34:35], v145, s78, v[154:155]
	v_add_f32_e32 v145, 1.0, v158
	v_fmamk_f32 v148, v148, 0xbdd2d3e7, v190
	v_fmamk_f32 v33, v33, 0xbdd2d3e7, v190
	v_rcp_f32_e32 v145, v145
	v_mul_f32_e32 v148, v49, v148
	v_mul_f32_e32 v33, v37, v33
	v_exp_f32_e32 v148, v148
	v_exp_f32_e32 v33, v33
	v_lshlrev_b64 v[138:139], 1, v[178:179]
	v_lshl_add_u64 v[146:147], v[146:147], 0, v[138:139]
	v_mul_f32_e32 v115, v115, v145
	global_store_dwordx4 v[146:147], v[120:123], off
	v_fma_f32 v36, v36, v106, v66
	v_add_f32_e32 v33, 1.0, v33
	v_mul_f32_e32 v122, v114, v115
	v_add_f32_e32 v114, 1.0, v148
	v_rcp_f32_e32 v123, v114
	v_pk_fma_f32 v[114:115], v[150:151], v[128:129], v[132:133]
	v_fmac_f32_e32 v36, v32, v102
	v_rcp_f32_e32 v33, v33
	v_pk_fma_f32 v[114:115], v[152:153], v[130:131], v[114:115]
	v_mov_b32_e32 v120, v42
	v_mov_b32_e32 v121, v34
	v_fmac_f32_e32 v36, v116, v144
	v_pk_fma_f32 v[114:115], v[120:121], v[134:135], v[114:115]
	v_mul_f32_e32 v32, v36, v36
	v_mul_f32_e32 v120, v115, v115
	v_fmamk_f32 v32, v32, 0xbdd2d3e7, v190
	v_fmamk_f32 v120, v120, 0xbdd2d3e7, v190
	v_mul_f32_e32 v32, v36, v32
	v_mul_f32_e32 v33, v37, v33
	v_fma_f32 v37, v38, v108, v68
	v_mul_f32_e32 v120, v115, v120
	v_pk_fma_f32 v[50:51], v[50:51], v[62:63], v[136:137]
	v_exp_f32_e32 v32, v32
	v_fmac_f32_e32 v37, v34, v104
	v_exp_f32_e32 v145, v120
	v_pk_fma_f32 v[50:51], v[156:157], v[58:59], v[50:51]
	v_mov_b32_e32 v120, v43
	v_mov_b32_e32 v121, v35
	v_fmac_f32_e32 v37, v118, v101
	v_pk_fma_f32 v[50:51], v[120:121], v[54:55], v[50:51]
	v_mul_f32_e32 v34, v37, v37
	v_fma_f32 v38, v39, v109, v69
	v_mul_f32_e32 v120, v51, v51
	v_fmamk_f32 v34, v34, 0xbdd2d3e7, v190
	v_fmac_f32_e32 v38, v35, v105
	v_fmamk_f32 v120, v120, 0xbdd2d3e7, v190
	v_add_f32_e32 v32, 1.0, v32
	v_mul_f32_e32 v34, v37, v34
	v_fmac_f32_e32 v38, v119, v100
	v_mul_f32_e32 v120, v51, v120
	v_rcp_f32_e32 v32, v32
	v_exp_f32_e32 v34, v34
	v_mul_f32_e32 v35, v38, v38
	v_exp_f32_e32 v120, v120
	v_fmamk_f32 v35, v35, 0xbdd2d3e7, v190
	v_mul_f32_e32 v35, v38, v35
	v_exp_f32_e32 v35, v35
	v_add_f32_e32 v121, 1.0, v145
	v_mul_f32_e32 v32, v36, v32
	v_fma_f32 v36, v45, v75, v71
	v_add_f32_e32 v34, 1.0, v34
	v_rcp_f32_e32 v121, v121
	v_add_f32_e32 v120, 1.0, v120
	v_fmac_f32_e32 v36, v41, v85
	v_rcp_f32_e32 v34, v34
	v_rcp_f32_e32 v120, v120
	v_fmac_f32_e32 v36, v93, v141
	v_mul_f32_e32 v33, v36, v33
	v_fma_f32 v36, v46, v76, v72
	v_add_f32_e32 v35, 1.0, v35
	v_mul_f32_e32 v49, v49, v123
	v_fmac_f32_e32 v36, v42, v86
	v_rcp_f32_e32 v35, v35
	v_mul_f32_e32 v48, v48, v49
	v_mul_f32_e32 v49, v115, v121
	v_fmac_f32_e32 v36, v94, v91
	v_mul_f32_e32 v34, v37, v34
	v_mul_f32_e32 v49, v114, v49
	v_mul_f32_e32 v51, v51, v120
	v_cvt_pk_bf16_f32 v114, v122, v48
	v_or_b32_e32 v48, 2, v140
	v_fma_f32 v44, v44, v74, v70
	v_mul_f32_e32 v34, v36, v34
	v_fma_f32 v36, v47, v77, v73
	v_mul_f32_e32 v50, v50, v51
	v_cvt_pk_bf16_f32 v115, v49, v50
	v_mad_i64_i32 v[48:49], s[34:35], v48, s78, v[154:155]
	v_fmac_f32_e32 v44, v40, v84
	v_fmac_f32_e32 v36, v43, v87
	v_lshl_add_u64 v[48:49], v[48:49], 0, v[138:139]
	v_fmac_f32_e32 v44, v92, v142
	v_fmac_f32_e32 v36, v95, v90
	v_mul_f32_e32 v35, v38, v35
	global_store_dwordx4 v[48:49], v[112:115], off
	v_mul_f32_e32 v32, v44, v32
	v_mul_f32_e32 v35, v36, v35
	v_cvt_pk_bf16_f32 v100, v32, v33
	v_cvt_pk_bf16_f32 v101, v34, v35
	s_and_saveexec_b64 s[46:47], s[6:7]
	s_cbranch_execz .LBB0_927
	v_or_b32_e32 v34, 3, v140
	v_mov_b64_e32 v[32:33], s[12:13]
	v_mad_i64_i32 v[32:33], s[34:35], v34, s78, v[32:33]
	v_lshl_add_u64 v[32:33], v[178:179], 1, v[32:33]
	global_store_dwordx4 v[32:33], v[98:101], off
.LBB0_927:
	s_or_b64 exec, exec, s[46:47]
	v_mov_b32_dpp v34, v0 row_ror:1 row_mask:0xf bank_mask:0xf bound_ctrl:1
	v_fma_f32 v47, v106, v34, v66
	v_fmac_f32_e32 v47, v20, v102
	v_fmac_f32_e32 v47, v16, v116
	v_mul_f32_e32 v34, v47, v47
	v_fmamk_f32 v34, v34, 0xbdd2d3e7, v190
	v_mov_b32_dpp v44, v1 row_ror:1 row_mask:0xf bank_mask:0xf bound_ctrl:1
	v_mul_f32_e32 v34, v47, v34
	v_exp_f32_e32 v48, v34
	v_fma_f32 v44, v107, v44, v67
	v_fmac_f32_e32 v44, v21, v103
	v_fmac_f32_e32 v44, v17, v117
	v_mul_f32_e32 v49, v44, v44
	v_add_f32_e32 v48, 1.0, v48
	v_fmamk_f32 v49, v49, 0xbdd2d3e7, v190
	v_rcp_f32_e32 v48, v48
	v_mul_f32_e32 v49, v44, v49
	v_mov_b32_dpp v40, v8 row_ror:1 row_mask:0xf bank_mask:0xf bound_ctrl:1
	v_exp_f32_e32 v49, v49
	v_fma_f32 v40, v74, v40, v70
	v_fmac_f32_e32 v40, v28, v84
	v_fmac_f32_e32 v40, v24, v92
	v_mul_f32_e32 v47, v47, v48
	v_mul_f32_e32 v40, v40, v47
	v_add_f32_e32 v47, 1.0, v49
	v_mov_b32_dpp v45, v2 row_ror:1 row_mask:0xf bank_mask:0xf bound_ctrl:1
	v_rcp_f32_e32 v47, v47
	v_fma_f32 v45, v108, v45, v68
	v_fmac_f32_e32 v45, v22, v104
	v_fmac_f32_e32 v45, v18, v118
	v_mul_f32_e32 v44, v44, v47
	v_mul_f32_e32 v47, v45, v45
	v_fmamk_f32 v47, v47, 0xbdd2d3e7, v190
	v_mul_f32_e32 v47, v45, v47
	v_mov_b32_dpp v41, v9 row_ror:1 row_mask:0xf bank_mask:0xf bound_ctrl:1
	v_mov_b32_dpp v46, v3 row_ror:1 row_mask:0xf bank_mask:0xf bound_ctrl:1
	v_exp_f32_e32 v47, v47
	v_fma_f32 v41, v75, v41, v71
	v_fma_f32 v46, v109, v46, v69
	v_fmac_f32_e32 v41, v29, v85
	v_fmac_f32_e32 v46, v23, v105
	v_fmac_f32_e32 v41, v25, v93
	v_fmac_f32_e32 v46, v19, v119
	v_mul_f32_e32 v41, v41, v44
	v_add_f32_e32 v44, 1.0, v47
	v_mul_f32_e32 v47, v46, v46
	v_fmamk_f32 v47, v47, 0xbdd2d3e7, v190
	v_rcp_f32_e32 v44, v44
	v_mul_f32_e32 v47, v46, v47
	v_mov_b32_dpp v42, v10 row_ror:1 row_mask:0xf bank_mask:0xf bound_ctrl:1
	v_exp_f32_e32 v47, v47
	v_fma_f32 v42, v76, v42, v72
	v_fmac_f32_e32 v42, v30, v86
	v_fmac_f32_e32 v42, v26, v94
	v_mul_f32_e32 v44, v45, v44
	v_mul_f32_e32 v42, v42, v44
	v_add_f32_e32 v44, 1.0, v47
	v_rcp_f32_e32 v44, v44
	v_mov_b32_dpp v43, v11 row_ror:1 row_mask:0xf bank_mask:0xf bound_ctrl:1
	v_fma_f32 v43, v77, v43, v73
	v_fmac_f32_e32 v43, v31, v87
	v_mov_b32_dpp v37, v28 row_ror:15 row_mask:0xf bank_mask:0xf bound_ctrl:1
	v_mov_b32_dpp v36, v29 row_ror:15 row_mask:0xf bank_mask:0xf bound_ctrl:1
	v_mov_b32_dpp v33, v30 row_ror:15 row_mask:0xf bank_mask:0xf bound_ctrl:1
	v_mov_b32_dpp v32, v31 row_ror:15 row_mask:0xf bank_mask:0xf bound_ctrl:1
	v_mov_b32_dpp v39, v20 row_ror:15 row_mask:0xf bank_mask:0xf bound_ctrl:1
	v_mov_b32_dpp v38, v21 row_ror:15 row_mask:0xf bank_mask:0xf bound_ctrl:1
	v_mov_b32_dpp v35, v22 row_ror:15 row_mask:0xf bank_mask:0xf bound_ctrl:1
	v_mov_b32_dpp v34, v23 row_ror:15 row_mask:0xf bank_mask:0xf bound_ctrl:1
	v_fmac_f32_e32 v43, v27, v95
	v_mul_f32_e32 v44, v46, v44
	v_mul_f32_e32 v43, v43, v44
	v_cvt_pk_bf16_f32 v98, v40, v41
	v_cvt_pk_bf16_f32 v99, v42, v43
	s_and_saveexec_b64 s[46:47], s[2:3]
	s_cbranch_execz .LBB0_929
	v_add_u32_e32 v42, 0x80, v140
	v_mov_b64_e32 v[40:41], s[12:13]
	v_mad_i64_i32 v[40:41], s[34:35], v42, s78, v[40:41]
	v_lshl_add_u64 v[40:41], v[178:179], 1, v[40:41]
	global_store_dwordx4 v[40:41], v[96:99], off
.LBB0_929:
	s_or_b64 exec, exec, s[46:47]
	v_mov_b32_e32 v40, v28
	v_mov_b32_e32 v41, v20
	v_mov_b32_e32 v42, v24
	v_mov_b32_e32 v43, v16
	v_pk_fma_f32 v[40:41], v[40:41], v[78:79], v[110:111]
	v_mov_b32_e32 v44, v12
	v_pk_fma_f32 v[40:41], v[42:43], v[82:83], v[40:41]
	v_mov_b32_e32 v45, v4
	v_pk_fma_f32 v[40:41], v[44:45], v[124:125], v[40:41]
	v_mov_b32_e32 v20, v29
	v_mul_f32_e32 v16, v41, v41
	v_fmamk_f32 v16, v16, 0xbdd2d3e7, v190
	v_mul_f32_e32 v16, v41, v16
	v_exp_f32_e32 v16, v16
	v_pk_fma_f32 v[20:21], v[20:21], v[60:61], v[126:127]
	v_mov_b32_e32 v24, v13
	v_mov_b32_e32 v46, v14
	v_add_f32_e32 v16, 1.0, v16
	v_rcp_f32_e32 v28, v16
	v_mov_b32_e32 v16, v25
	v_pk_fma_f32 v[20:21], v[16:17], v[56:57], v[20:21]
	v_mov_b32_e32 v25, v5
	v_pk_fma_f32 v[20:21], v[24:25], v[52:53], v[20:21]
	v_mul_f32_e32 v28, v41, v28
	v_mul_f32_e32 v29, v21, v21
	v_fmamk_f32 v29, v29, 0xbdd2d3e7, v190
	v_mul_f32_e32 v29, v21, v29
	v_exp_f32_e32 v29, v29
	v_mul_f32_e32 v48, v40, v28
	v_mov_b32_e32 v40, v26
	v_mov_b32_e32 v41, v18
	v_add_f32_e32 v28, 1.0, v29
	v_rcp_f32_e32 v49, v28
	v_mov_b32_e32 v28, v30
	v_mov_b32_e32 v29, v22
	v_pk_fma_f32 v[28:29], v[28:29], v[128:129], v[132:133]
	v_mov_b32_e32 v47, v6
	v_pk_fma_f32 v[28:29], v[40:41], v[130:131], v[28:29]
	v_mov_b32_e32 v22, v31
	v_pk_fma_f32 v[28:29], v[46:47], v[134:135], v[28:29]
	v_pk_fma_f32 v[22:23], v[22:23], v[62:63], v[136:137]
	v_mul_f32_e32 v18, v29, v29
	v_fmamk_f32 v18, v18, 0xbdd2d3e7, v190
	v_mul_f32_e32 v18, v29, v18
	v_exp_f32_e32 v30, v18
	v_mov_b32_e32 v18, v27
	v_pk_fma_f32 v[22:23], v[18:19], v[58:59], v[22:23]
	v_mov_b32_e32 v26, v15
	v_mov_b32_e32 v27, v7
	v_pk_fma_f32 v[22:23], v[26:27], v[54:55], v[22:23]
	v_add_f32_e32 v30, 1.0, v30
	v_mul_f32_e32 v31, v23, v23
	v_fmamk_f32 v31, v31, 0xbdd2d3e7, v190
	v_mul_f32_e32 v31, v23, v31
	v_exp_f32_e32 v31, v31
	v_rcp_f32_e32 v30, v30
	v_mul_f32_e32 v21, v21, v49
	v_mul_f32_e32 v20, v20, v21
	v_add_f32_e32 v31, 1.0, v31
	v_rcp_f32_e32 v31, v31
	v_mul_f32_e32 v21, v29, v30
	v_mul_f32_e32 v21, v28, v21
	v_cvt_pk_bf16_f32 v90, v48, v20
	v_mul_f32_e32 v23, v23, v31
	v_mul_f32_e32 v22, v22, v23
	v_cvt_pk_bf16_f32 v91, v21, v22
	v_pk_fma_f32 v[22:23], v[42:43], v[78:79], v[110:111]
	v_mov_b32_e32 v28, v8
	v_pk_fma_f32 v[22:23], v[44:45], v[82:83], v[22:23]
	v_mov_b32_e32 v29, v0
	v_pk_fma_f32 v[22:23], v[28:29], v[124:125], v[22:23]
	v_pk_fma_f32 v[16:17], v[16:17], v[60:61], v[126:127]
	v_mul_f32_e32 v28, v23, v23
	v_fmamk_f32 v28, v28, 0xbdd2d3e7, v190
	v_mul_f32_e32 v28, v23, v28
	v_exp_f32_e32 v31, v28
	v_pk_fma_f32 v[16:17], v[24:25], v[56:57], v[16:17]
	v_mov_b32_e32 v24, v9
	v_mov_b32_e32 v25, v1
	v_pk_fma_f32 v[16:17], v[24:25], v[52:53], v[16:17]
	v_add_u32_e32 v30, 0x81, v140
	v_mov_b64_e32 v[20:21], s[12:13]
	v_mul_f32_e32 v24, v17, v17
	v_fma_f32 v5, v5, v107, v67
	v_mad_i64_i32 v[28:29], s[34:35], v30, s78, v[20:21]
	v_add_f32_e32 v30, 1.0, v31
	v_fmamk_f32 v24, v24, 0xbdd2d3e7, v190
	v_fmac_f32_e32 v5, v1, v103
	v_rcp_f32_e32 v30, v30
	v_mul_f32_e32 v24, v17, v24
	v_fmac_f32_e32 v5, v117, v38
	v_exp_f32_e32 v24, v24
	v_mul_f32_e32 v1, v5, v5
	v_fmamk_f32 v1, v1, 0xbdd2d3e7, v190
	v_mul_f32_e32 v1, v5, v1
	v_lshl_add_u64 v[28:29], v[28:29], 0, v[138:139]
	v_mul_f32_e32 v23, v23, v30
	v_exp_f32_e32 v1, v1
	global_store_dwordx4 v[28:29], v[88:91], off
	v_mul_f32_e32 v28, v22, v23
	v_add_f32_e32 v22, 1.0, v24
	v_rcp_f32_e32 v29, v22
	v_pk_fma_f32 v[22:23], v[40:41], v[128:129], v[132:133]
	v_mov_b32_e32 v24, v10
	v_pk_fma_f32 v[22:23], v[46:47], v[130:131], v[22:23]
	v_mov_b32_e32 v25, v2
	v_pk_fma_f32 v[22:23], v[24:25], v[134:135], v[22:23]
	v_fma_f32 v4, v4, v106, v66
	v_add_f32_e32 v1, 1.0, v1
	v_mul_f32_e32 v24, v23, v23
	v_fmac_f32_e32 v4, v0, v102
	v_rcp_f32_e32 v1, v1
	v_fmamk_f32 v24, v24, 0xbdd2d3e7, v190
	v_fmac_f32_e32 v4, v116, v39
	v_mul_f32_e32 v24, v23, v24
	v_pk_fma_f32 v[18:19], v[18:19], v[62:63], v[136:137]
	v_mul_f32_e32 v0, v4, v4
	v_exp_f32_e32 v30, v24
	v_pk_fma_f32 v[18:19], v[26:27], v[58:59], v[18:19]
	v_mov_b32_e32 v24, v11
	v_mov_b32_e32 v25, v3
	v_fmamk_f32 v0, v0, 0xbdd2d3e7, v190
	v_pk_fma_f32 v[18:19], v[24:25], v[54:55], v[18:19]
	v_mul_f32_e32 v0, v4, v0
	v_mul_f32_e32 v1, v5, v1
	v_fma_f32 v5, v6, v108, v68
	v_fmac_f32_e32 v69, v7, v109
	v_mul_f32_e32 v24, v19, v19
	v_exp_f32_e32 v0, v0
	v_fmac_f32_e32 v5, v2, v104
	v_fmac_f32_e32 v69, v3, v105
	v_fmamk_f32 v24, v24, 0xbdd2d3e7, v190
	v_fmac_f32_e32 v5, v118, v35
	v_fmac_f32_e32 v69, v119, v34
	v_mul_f32_e32 v24, v19, v24
	v_mul_f32_e32 v2, v5, v5
	v_mul_f32_e32 v3, v69, v69
	v_exp_f32_e32 v24, v24
	v_fmamk_f32 v2, v2, 0xbdd2d3e7, v190
	v_fmamk_f32 v3, v3, 0xbdd2d3e7, v190
	v_add_f32_e32 v0, 1.0, v0
	v_mul_f32_e32 v2, v5, v2
	v_mul_f32_e32 v3, v69, v3
	v_rcp_f32_e32 v0, v0
	v_exp_f32_e32 v2, v2
	v_exp_f32_e32 v3, v3
	v_add_f32_e32 v25, 1.0, v30
	v_rcp_f32_e32 v25, v25
	v_add_f32_e32 v24, 1.0, v24
	v_rcp_f32_e32 v24, v24
	v_mul_f32_e32 v0, v4, v0
	v_fma_f32 v4, v13, v75, v71
	v_add_f32_e32 v2, 1.0, v2
	v_add_f32_e32 v3, 1.0, v3
	v_mul_f32_e32 v17, v17, v29
	v_fmac_f32_e32 v4, v9, v85
	v_rcp_f32_e32 v2, v2
	v_rcp_f32_e32 v3, v3
	v_mul_f32_e32 v16, v16, v17
	v_mul_f32_e32 v17, v23, v25
	v_fmac_f32_e32 v4, v93, v36
	v_mul_f32_e32 v17, v22, v17
	v_mul_f32_e32 v19, v19, v24
	v_cvt_pk_bf16_f32 v82, v28, v16
	v_add_u32_e32 v16, 0x82, v140
	v_fma_f32 v12, v12, v74, v70
	v_mul_f32_e32 v1, v4, v1
	v_fma_f32 v4, v14, v76, v72
	v_fmac_f32_e32 v73, v15, v77
	v_mul_f32_e32 v18, v18, v19
	v_cvt_pk_bf16_f32 v83, v17, v18
	v_mad_i64_i32 v[16:17], s[34:35], v16, s78, v[20:21]
	v_fmac_f32_e32 v12, v8, v84
	v_fmac_f32_e32 v4, v10, v86
	v_fmac_f32_e32 v73, v11, v87
	v_lshl_add_u64 v[16:17], v[16:17], 0, v[138:139]
	v_fmac_f32_e32 v12, v92, v37
	v_fmac_f32_e32 v4, v94, v33
	v_mul_f32_e32 v2, v5, v2
	v_fmac_f32_e32 v73, v95, v32
	v_mul_f32_e32 v3, v69, v3
	global_store_dwordx4 v[16:17], v[80:83], off
	v_mul_f32_e32 v0, v12, v0
	v_mul_f32_e32 v2, v4, v2
	v_mul_f32_e32 v3, v73, v3
	v_cvt_pk_bf16_f32 v66, v0, v1
	v_cvt_pk_bf16_f32 v67, v2, v3
	s_and_saveexec_b64 s[46:47], s[6:7]
	s_cbranch_execz .LBB0_910
	v_add_u32_e32 v2, 0x83, v140
	v_mov_b64_e32 v[0:1], s[12:13]
	v_mad_i64_i32 v[0:1], s[34:35], v2, s78, v[0:1]
	v_lshl_add_u64 v[0:1], v[178:179], 1, v[0:1]
	global_store_dwordx4 v[0:1], v[64:67], off
	s_branch .LBB0_910

.LBB0_1080:
	v_lshl_add_u32 v148, s51, 8, v150
	v_lshl_or_b32 v146, s52, 8, v152
	v_ashrrev_i32_e32 v149, 31, v148
	v_ashrrev_i32_e32 v147, 31, v146
	v_lshlrev_b64 v[144:145], 12, v[148:149]
	v_lshl_add_u64 v[144:145], v[144:145], 0, v[146:147]
	v_lshlrev_b64 v[144:145], 1, v[144:145]
	v_lshl_add_u64 v[160:161], s[74:75], 0, v[144:145]
	global_load_dwordx4 v[156:159], v[160:161], off
	v_lshl_add_u64 v[162:163], s[86:87], 0, v[144:145]
	s_and_b64 vcc, exec, s[0:1]
	s_mov_b64 s[0:1], -1
	s_waitcnt vmcnt(0)
	v_lshlrev_b32_e32 v164, 16, v156
	v_and_b32_e32 v165, 0xffff0000, v156
	v_lshlrev_b32_e32 v156, 16, v157
	v_and_b32_e32 v157, 0xffff0000, v157
	v_lshlrev_b32_e32 v166, 16, v158
	v_and_b32_e32 v167, 0xffff0000, v158
	v_lshlrev_b32_e32 v158, 16, v159
	v_and_b32_e32 v159, 0xffff0000, v159
	v_pk_add_f32 v[126:127], v[126:127], v[156:157]
	v_pk_add_f32 v[156:157], v[122:123], v[158:159]
	v_pk_add_f32 v[122:123], v[120:121], v[166:167]
	v_pk_add_f32 v[124:125], v[124:125], v[164:165]
	s_nop 0
	v_cvt_pk_bf16_f32 v120, v124, v125
	v_cvt_pk_bf16_f32 v121, v126, v127
	v_cvt_pk_bf16_f32 v122, v122, v123
	v_cvt_pk_bf16_f32 v123, v156, v157
	global_store_dwordx4 v[162:163], v[120:123], off
	global_load_dwordx4 v[120:123], v[160:161], off offset:256
	v_or_b32_e32 v124, 16, v148
	v_ashrrev_i32_e32 v125, 31, v124
	v_lshlrev_b64 v[124:125], 12, v[124:125]
	v_lshl_add_u64 v[124:125], v[124:125], 0, v[146:147]
	v_lshlrev_b64 v[124:125], 1, v[124:125]
	v_lshl_add_u64 v[126:127], s[74:75], 0, v[124:125]
	s_waitcnt vmcnt(0)
	v_lshlrev_b32_e32 v156, 16, v120
	v_and_b32_e32 v157, 0xffff0000, v120
	v_lshlrev_b32_e32 v120, 16, v121
	v_and_b32_e32 v121, 0xffff0000, v121
	v_lshlrev_b32_e32 v158, 16, v122
	v_and_b32_e32 v159, 0xffff0000, v122
	v_lshlrev_b32_e32 v122, 16, v123
	v_and_b32_e32 v123, 0xffff0000, v123
	v_pk_add_f32 v[118:119], v[118:119], v[120:121]
	v_pk_add_f32 v[120:121], v[114:115], v[122:123]
	v_pk_add_f32 v[114:115], v[112:113], v[158:159]
	v_pk_add_f32 v[116:117], v[116:117], v[156:157]
	s_nop 0
	v_cvt_pk_bf16_f32 v112, v116, v117
	v_cvt_pk_bf16_f32 v113, v118, v119
	v_cvt_pk_bf16_f32 v114, v114, v115
	v_cvt_pk_bf16_f32 v115, v120, v121
	global_store_dwordx4 v[162:163], v[112:115], off offset:256
	global_load_dwordx4 v[112:115], v[126:127], off
	v_lshl_add_u64 v[116:117], s[86:87], 0, v[124:125]
	s_waitcnt vmcnt(0)
	v_lshlrev_b32_e32 v118, 16, v112
	v_and_b32_e32 v119, 0xffff0000, v112
	v_lshlrev_b32_e32 v112, 16, v113
	v_and_b32_e32 v113, 0xffff0000, v113
	v_lshlrev_b32_e32 v120, 16, v114
	v_and_b32_e32 v121, 0xffff0000, v114
	v_lshlrev_b32_e32 v114, 16, v115
	v_and_b32_e32 v115, 0xffff0000, v115
	v_pk_add_f32 v[110:111], v[110:111], v[112:113]
	v_pk_add_f32 v[112:113], v[106:107], v[114:115]
	v_pk_add_f32 v[106:107], v[104:105], v[120:121]
	v_pk_add_f32 v[108:109], v[108:109], v[118:119]
	s_nop 0
	v_cvt_pk_bf16_f32 v104, v108, v109
	v_cvt_pk_bf16_f32 v105, v110, v111
	v_cvt_pk_bf16_f32 v106, v106, v107
	v_cvt_pk_bf16_f32 v107, v112, v113
	global_store_dwordx4 v[116:117], v[104:107], off
	global_load_dwordx4 v[104:107], v[126:127], off offset:256
	v_or_b32_e32 v108, 32, v148
	v_ashrrev_i32_e32 v109, 31, v108
	v_lshlrev_b64 v[108:109], 12, v[108:109]
	v_lshl_add_u64 v[108:109], v[108:109], 0, v[146:147]
	v_lshlrev_b64 v[108:109], 1, v[108:109]
	v_lshl_add_u64 v[110:111], s[74:75], 0, v[108:109]
	s_waitcnt vmcnt(0)
	v_lshlrev_b32_e32 v112, 16, v104
	v_and_b32_e32 v113, 0xffff0000, v104
	v_lshlrev_b32_e32 v104, 16, v105
	v_and_b32_e32 v105, 0xffff0000, v105
	v_lshlrev_b32_e32 v114, 16, v106
	v_and_b32_e32 v115, 0xffff0000, v106
	v_lshlrev_b32_e32 v106, 16, v107
	v_and_b32_e32 v107, 0xffff0000, v107
	v_pk_add_f32 v[102:103], v[102:103], v[104:105]
	v_pk_add_f32 v[104:105], v[98:99], v[106:107]
	v_pk_add_f32 v[98:99], v[96:97], v[114:115]
	v_pk_add_f32 v[100:101], v[100:101], v[112:113]
	s_nop 0
	v_cvt_pk_bf16_f32 v96, v100, v101
	v_cvt_pk_bf16_f32 v97, v102, v103
	v_cvt_pk_bf16_f32 v98, v98, v99
	v_cvt_pk_bf16_f32 v99, v104, v105
	global_store_dwordx4 v[116:117], v[96:99], off offset:256
	global_load_dwordx4 v[96:99], v[110:111], off
	v_lshl_add_u64 v[100:101], s[86:87], 0, v[108:109]
	s_waitcnt vmcnt(0)
	v_lshlrev_b32_e32 v102, 16, v96
	v_and_b32_e32 v103, 0xffff0000, v96
	v_lshlrev_b32_e32 v96, 16, v97
	v_and_b32_e32 v97, 0xffff0000, v97
	v_lshlrev_b32_e32 v104, 16, v98
	v_and_b32_e32 v105, 0xffff0000, v98
	v_lshlrev_b32_e32 v98, 16, v99
	v_and_b32_e32 v99, 0xffff0000, v99
	v_pk_add_f32 v[94:95], v[94:95], v[96:97]
	v_pk_add_f32 v[96:97], v[90:91], v[98:99]
	v_pk_add_f32 v[90:91], v[88:89], v[104:105]
	v_pk_add_f32 v[92:93], v[92:93], v[102:103]
	s_nop 0
	v_cvt_pk_bf16_f32 v88, v92, v93
	v_cvt_pk_bf16_f32 v89, v94, v95
	v_cvt_pk_bf16_f32 v90, v90, v91
	v_cvt_pk_bf16_f32 v91, v96, v97
	global_store_dwordx4 v[100:101], v[88:91], off
	global_load_dwordx4 v[88:91], v[110:111], off offset:256
	v_or_b32_e32 v92, 48, v148
	v_ashrrev_i32_e32 v93, 31, v92
	v_lshlrev_b64 v[92:93], 12, v[92:93]
	v_lshl_add_u64 v[92:93], v[92:93], 0, v[146:147]
	v_lshlrev_b64 v[92:93], 1, v[92:93]
	v_lshl_add_u64 v[94:95], s[74:75], 0, v[92:93]
	s_waitcnt vmcnt(0)
	v_lshlrev_b32_e32 v96, 16, v88
	v_and_b32_e32 v97, 0xffff0000, v88
	v_lshlrev_b32_e32 v88, 16, v89
	v_and_b32_e32 v89, 0xffff0000, v89
	v_lshlrev_b32_e32 v98, 16, v90
	v_and_b32_e32 v99, 0xffff0000, v90
	v_lshlrev_b32_e32 v90, 16, v91
	v_and_b32_e32 v91, 0xffff0000, v91
	v_pk_add_f32 v[86:87], v[86:87], v[88:89]
	v_pk_add_f32 v[88:89], v[82:83], v[90:91]
	v_pk_add_f32 v[82:83], v[80:81], v[98:99]
	v_pk_add_f32 v[84:85], v[84:85], v[96:97]
	s_nop 0
	v_cvt_pk_bf16_f32 v80, v84, v85
	v_cvt_pk_bf16_f32 v81, v86, v87
	v_cvt_pk_bf16_f32 v82, v82, v83
	v_cvt_pk_bf16_f32 v83, v88, v89
	global_store_dwordx4 v[100:101], v[80:83], off offset:256
	global_load_dwordx4 v[80:83], v[94:95], off
	v_lshl_add_u64 v[84:85], s[86:87], 0, v[92:93]
	s_waitcnt vmcnt(0)
	v_lshlrev_b32_e32 v86, 16, v80
	v_and_b32_e32 v87, 0xffff0000, v80
	v_lshlrev_b32_e32 v80, 16, v81
	v_and_b32_e32 v81, 0xffff0000, v81
	v_lshlrev_b32_e32 v88, 16, v82
	v_and_b32_e32 v89, 0xffff0000, v82
	v_lshlrev_b32_e32 v82, 16, v83
	v_and_b32_e32 v83, 0xffff0000, v83
	v_pk_add_f32 v[78:79], v[78:79], v[80:81]
	v_pk_add_f32 v[80:81], v[74:75], v[82:83]
	v_pk_add_f32 v[74:75], v[72:73], v[88:89]
	v_pk_add_f32 v[76:77], v[76:77], v[86:87]
	s_nop 0
	v_cvt_pk_bf16_f32 v72, v76, v77
	v_cvt_pk_bf16_f32 v73, v78, v79
	v_cvt_pk_bf16_f32 v74, v74, v75
	v_cvt_pk_bf16_f32 v75, v80, v81
	global_store_dwordx4 v[84:85], v[72:75], off
	global_load_dwordx4 v[72:75], v[94:95], off offset:256
	v_lshl_add_u64 v[76:77], v[144:145], 0, s[16:17]
	v_lshl_add_u64 v[78:79], s[74:75], 0, v[76:77]
	s_waitcnt vmcnt(0)
	v_lshlrev_b32_e32 v80, 16, v72
	v_and_b32_e32 v81, 0xffff0000, v72
	v_lshlrev_b32_e32 v72, 16, v73
	v_and_b32_e32 v73, 0xffff0000, v73
	v_lshlrev_b32_e32 v82, 16, v74
	v_and_b32_e32 v83, 0xffff0000, v74
	v_lshlrev_b32_e32 v74, 16, v75
	v_and_b32_e32 v75, 0xffff0000, v75
	v_pk_add_f32 v[70:71], v[70:71], v[72:73]
	v_pk_add_f32 v[72:73], v[66:67], v[74:75]
	v_pk_add_f32 v[66:67], v[64:65], v[82:83]
	v_pk_add_f32 v[68:69], v[68:69], v[80:81]
	s_nop 0
	v_cvt_pk_bf16_f32 v64, v68, v69
	v_cvt_pk_bf16_f32 v65, v70, v71
	v_cvt_pk_bf16_f32 v66, v66, v67
	v_cvt_pk_bf16_f32 v67, v72, v73
	global_store_dwordx4 v[84:85], v[64:67], off offset:256
	global_load_dwordx4 v[64:67], v[78:79], off
	v_lshl_add_u64 v[68:69], s[86:87], 0, v[76:77]
	s_waitcnt vmcnt(0)
	v_lshlrev_b32_e32 v70, 16, v64
	v_and_b32_e32 v71, 0xffff0000, v64
	v_lshlrev_b32_e32 v64, 16, v65
	v_and_b32_e32 v65, 0xffff0000, v65
	v_lshlrev_b32_e32 v72, 16, v66
	v_and_b32_e32 v73, 0xffff0000, v66
	v_lshlrev_b32_e32 v66, 16, v67
	v_and_b32_e32 v67, 0xffff0000, v67
	v_pk_add_f32 v[62:63], v[62:63], v[64:65]
	v_pk_add_f32 v[64:65], v[58:59], v[66:67]
	v_pk_add_f32 v[58:59], v[56:57], v[72:73]
	v_pk_add_f32 v[60:61], v[60:61], v[70:71]
	s_nop 0
	v_cvt_pk_bf16_f32 v56, v60, v61
	v_cvt_pk_bf16_f32 v57, v62, v63
	v_cvt_pk_bf16_f32 v58, v58, v59
	v_cvt_pk_bf16_f32 v59, v64, v65
	global_store_dwordx4 v[68:69], v[56:59], off
	global_load_dwordx4 v[56:59], v[78:79], off offset:256
	v_lshl_add_u64 v[60:61], v[144:145], 0, s[18:19]
	v_lshl_add_u64 v[62:63], s[74:75], 0, v[60:61]
	s_waitcnt vmcnt(0)
	v_lshlrev_b32_e32 v64, 16, v56
	v_and_b32_e32 v65, 0xffff0000, v56
	v_lshlrev_b32_e32 v56, 16, v57
	v_and_b32_e32 v57, 0xffff0000, v57
	v_lshlrev_b32_e32 v66, 16, v58
	v_and_b32_e32 v67, 0xffff0000, v58
	v_lshlrev_b32_e32 v58, 16, v59
	v_and_b32_e32 v59, 0xffff0000, v59
	v_pk_add_f32 v[54:55], v[54:55], v[56:57]
	v_pk_add_f32 v[56:57], v[50:51], v[58:59]
	v_pk_add_f32 v[50:51], v[48:49], v[66:67]
	v_pk_add_f32 v[52:53], v[52:53], v[64:65]
	s_nop 0
	v_cvt_pk_bf16_f32 v48, v52, v53
	v_cvt_pk_bf16_f32 v49, v54, v55
	v_cvt_pk_bf16_f32 v50, v50, v51
	v_cvt_pk_bf16_f32 v51, v56, v57
	global_store_dwordx4 v[68:69], v[48:51], off offset:256
	global_load_dwordx4 v[48:51], v[62:63], off
	v_lshl_add_u64 v[52:53], s[86:87], 0, v[60:61]
	s_waitcnt vmcnt(0)
	v_lshlrev_b32_e32 v54, 16, v48
	v_and_b32_e32 v55, 0xffff0000, v48
	v_lshlrev_b32_e32 v48, 16, v49
	v_and_b32_e32 v49, 0xffff0000, v49
	v_lshlrev_b32_e32 v56, 16, v50
	v_and_b32_e32 v57, 0xffff0000, v50
	v_lshlrev_b32_e32 v50, 16, v51
	v_and_b32_e32 v51, 0xffff0000, v51
	v_pk_add_f32 v[46:47], v[46:47], v[48:49]
	v_pk_add_f32 v[48:49], v[42:43], v[50:51]
	v_pk_add_f32 v[42:43], v[40:41], v[56:57]
	v_pk_add_f32 v[44:45], v[44:45], v[54:55]
	s_nop 0
	v_cvt_pk_bf16_f32 v40, v44, v45
	v_cvt_pk_bf16_f32 v41, v46, v47
	v_cvt_pk_bf16_f32 v42, v42, v43
	v_cvt_pk_bf16_f32 v43, v48, v49
	global_store_dwordx4 v[52:53], v[40:43], off
	global_load_dwordx4 v[40:43], v[62:63], off offset:256
	v_lshl_add_u64 v[44:45], v[144:145], 0, s[20:21]
	v_lshl_add_u64 v[46:47], s[74:75], 0, v[44:45]
	s_waitcnt vmcnt(0)
	v_lshlrev_b32_e32 v48, 16, v40
	v_and_b32_e32 v49, 0xffff0000, v40
	v_lshlrev_b32_e32 v40, 16, v41
	v_and_b32_e32 v41, 0xffff0000, v41
	v_lshlrev_b32_e32 v50, 16, v42
	v_and_b32_e32 v51, 0xffff0000, v42
	v_lshlrev_b32_e32 v42, 16, v43
	v_and_b32_e32 v43, 0xffff0000, v43
	v_pk_add_f32 v[38:39], v[38:39], v[40:41]
	v_pk_add_f32 v[40:41], v[34:35], v[42:43]
	v_pk_add_f32 v[34:35], v[32:33], v[50:51]
	v_pk_add_f32 v[36:37], v[36:37], v[48:49]
	s_nop 0
	v_cvt_pk_bf16_f32 v32, v36, v37
	v_cvt_pk_bf16_f32 v33, v38, v39
	v_cvt_pk_bf16_f32 v34, v34, v35
	v_cvt_pk_bf16_f32 v35, v40, v41
	global_store_dwordx4 v[52:53], v[32:35], off offset:256
	global_load_dwordx4 v[32:35], v[46:47], off
	v_lshl_add_u64 v[36:37], s[86:87], 0, v[44:45]
	s_waitcnt vmcnt(0)
	v_lshlrev_b32_e32 v38, 16, v32
	v_and_b32_e32 v39, 0xffff0000, v32
	v_lshlrev_b32_e32 v32, 16, v33
	v_and_b32_e32 v33, 0xffff0000, v33
	v_lshlrev_b32_e32 v40, 16, v34
	v_and_b32_e32 v41, 0xffff0000, v34
	v_lshlrev_b32_e32 v34, 16, v35
	v_and_b32_e32 v35, 0xffff0000, v35
	v_pk_add_f32 v[30:31], v[30:31], v[32:33]
	v_pk_add_f32 v[32:33], v[26:27], v[34:35]
	v_pk_add_f32 v[26:27], v[24:25], v[40:41]
	v_pk_add_f32 v[28:29], v[28:29], v[38:39]
	s_nop 0
	v_cvt_pk_bf16_f32 v24, v28, v29
	v_cvt_pk_bf16_f32 v25, v30, v31
	v_cvt_pk_bf16_f32 v26, v26, v27
	v_cvt_pk_bf16_f32 v27, v32, v33
	global_store_dwordx4 v[36:37], v[24:27], off
	global_load_dwordx4 v[24:27], v[46:47], off offset:256
	v_lshl_add_u64 v[28:29], v[144:145], 0, s[22:23]
	v_lshl_add_u64 v[30:31], s[74:75], 0, v[28:29]
	s_waitcnt vmcnt(0)
	v_lshlrev_b32_e32 v32, 16, v24
	v_and_b32_e32 v33, 0xffff0000, v24
	v_lshlrev_b32_e32 v24, 16, v25
	v_and_b32_e32 v25, 0xffff0000, v25
	v_lshlrev_b32_e32 v34, 16, v26
	v_and_b32_e32 v35, 0xffff0000, v26
	v_lshlrev_b32_e32 v26, 16, v27
	v_and_b32_e32 v27, 0xffff0000, v27
	v_pk_add_f32 v[22:23], v[22:23], v[24:25]
	v_pk_add_f32 v[24:25], v[18:19], v[26:27]
	v_pk_add_f32 v[18:19], v[16:17], v[34:35]
	v_pk_add_f32 v[20:21], v[20:21], v[32:33]
	s_nop 0
	v_cvt_pk_bf16_f32 v16, v20, v21
	v_cvt_pk_bf16_f32 v17, v22, v23
	v_cvt_pk_bf16_f32 v18, v18, v19
	v_cvt_pk_bf16_f32 v19, v24, v25
	global_store_dwordx4 v[36:37], v[16:19], off offset:256
	global_load_dwordx4 v[16:19], v[30:31], off
	v_lshl_add_u64 v[20:21], s[86:87], 0, v[28:29]
	s_waitcnt vmcnt(0)
	v_lshlrev_b32_e32 v22, 16, v16
	v_and_b32_e32 v23, 0xffff0000, v16
	v_lshlrev_b32_e32 v16, 16, v17
	v_and_b32_e32 v17, 0xffff0000, v17
	v_lshlrev_b32_e32 v24, 16, v18
	v_and_b32_e32 v25, 0xffff0000, v18
	v_lshlrev_b32_e32 v18, 16, v19
	v_and_b32_e32 v19, 0xffff0000, v19
	v_pk_add_f32 v[14:15], v[14:15], v[16:17]
	v_pk_add_f32 v[16:17], v[10:11], v[18:19]
	v_pk_add_f32 v[10:11], v[8:9], v[24:25]
	v_pk_add_f32 v[12:13], v[12:13], v[22:23]
	s_nop 0
	v_cvt_pk_bf16_f32 v8, v12, v13
	v_cvt_pk_bf16_f32 v9, v14, v15
	v_cvt_pk_bf16_f32 v10, v10, v11
	v_cvt_pk_bf16_f32 v11, v16, v17
	global_store_dwordx4 v[20:21], v[8:11], off
	global_load_dwordx4 v[8:11], v[30:31], off offset:256
	s_waitcnt vmcnt(0)
	v_lshlrev_b32_e32 v12, 16, v8
	v_and_b32_e32 v13, 0xffff0000, v8
	v_lshlrev_b32_e32 v8, 16, v9
	v_and_b32_e32 v9, 0xffff0000, v9
	v_lshlrev_b32_e32 v14, 16, v10
	v_and_b32_e32 v15, 0xffff0000, v10
	v_lshlrev_b32_e32 v10, 16, v11
	v_and_b32_e32 v11, 0xffff0000, v11
	v_pk_add_f32 v[6:7], v[6:7], v[8:9]
	v_pk_add_f32 v[8:9], v[2:3], v[10:11]
	v_pk_add_f32 v[2:3], v[0:1], v[14:15]
	v_pk_add_f32 v[4:5], v[4:5], v[12:13]
	s_nop 0
	v_cvt_pk_bf16_f32 v0, v4, v5
	v_cvt_pk_bf16_f32 v1, v6, v7
	v_cvt_pk_bf16_f32 v2, v2, v3
	v_cvt_pk_bf16_f32 v3, v8, v9
	global_store_dwordx4 v[20:21], v[0:3], off offset:256
	s_cbranch_vccnz .LBB0_1065
	s_andn2_b64 vcc, exec, s[8:9]
	s_cbranch_vccnz .LBB0_1064
	s_barrier
	s_branch .LBB0_1064

.LBB0_1316:
	v_lshl_add_u32 v154, s38, 8, v160
	v_lshl_or_b32 v152, s8, 8, v162
	v_ashrrev_i32_e32 v155, 31, v154
	v_ashrrev_i32_e32 v153, 31, v152
	v_lshlrev_b64 v[48:49], 12, v[154:155]
	v_lshl_add_u64 v[48:49], v[48:49], 0, v[152:153]
	v_lshlrev_b64 v[158:159], 1, v[48:49]
	v_lshl_add_u64 v[176:177], s[16:17], 0, v[158:159]
	global_load_dwordx4 v[168:171], v[176:177], off
	v_lshl_add_u64 v[178:179], s[86:87], 0, v[158:159]
	v_lshl_add_u64 v[156:157], v[154:155], 2, s[18:19]
	global_load_dwordx4 v[172:175], v[178:179], off
	global_load_dword v167, v[156:157], off
	v_lshl_add_u64 v[180:181], v[152:153], 2, s[70:71]
	global_load_dwordx4 v[52:55], v[180:181], off
	global_load_dwordx4 v[48:51], v[180:181], off offset:16
	v_mul_f32_e32 v44, 0xbfb8aa3b, v44
	v_mul_f32_e32 v40, 0xbfb8aa3b, v40
	v_mul_f32_e32 v45, 0xbfb8aa3b, v45
	v_mul_f32_e32 v41, 0xbfb8aa3b, v41
	v_mul_f32_e32 v46, 0xbfb8aa3b, v46
	v_mul_f32_e32 v42, 0xbfb8aa3b, v42
	v_mul_f32_e32 v47, 0xbfb8aa3b, v47
	v_mul_f32_e32 v43, 0xbfb8aa3b, v43
	v_exp_f32_e32 v182, v44
	v_exp_f32_e32 v183, v40
	v_exp_f32_e32 v184, v45
	v_exp_f32_e32 v185, v41
	v_exp_f32_e32 v186, v46
	v_exp_f32_e32 v187, v42
	v_exp_f32_e32 v188, v47
	v_exp_f32_e32 v189, v43
	global_load_dwordx4 v[40:43], v[180:181], off offset:528
	global_load_dwordx4 v[44:47], v[180:181], off offset:512
	v_add_f32_e32 v180, 1.0, v182
	v_add_f32_e32 v181, 1.0, v183
	v_add_f32_e32 v182, 1.0, v184
	v_add_f32_e32 v183, 1.0, v185
	v_add_f32_e32 v184, 1.0, v186
	v_add_f32_e32 v185, 1.0, v187
	v_add_f32_e32 v186, 1.0, v188
	v_add_f32_e32 v187, 1.0, v189
	v_rcp_f32_e32 v180, v180
	v_rcp_f32_e32 v181, v181
	v_rcp_f32_e32 v182, v182
	v_rcp_f32_e32 v183, v183
	v_rcp_f32_e32 v184, v184
	v_rcp_f32_e32 v185, v185
	v_rcp_f32_e32 v186, v186
	v_rcp_f32_e32 v187, v187
	v_mul_f32_e32 v128, 0xbfb8aa3b, v128
	v_exp_f32_e32 v128, v128
	v_mul_f32_e32 v129, 0xbfb8aa3b, v129
	v_mul_f32_e32 v133, 0xbfb8aa3b, v133
	v_mul_f32_e32 v135, 0xbfb8aa3b, v135
	v_exp_f32_e32 v129, v129
	v_mul_f32_e32 v132, 0xbfb8aa3b, v132
	v_mul_f32_e32 v134, 0xbfb8aa3b, v134
	v_mul_f32_e32 v131, 0xbfb8aa3b, v131
	v_exp_f32_e32 v133, v133
	v_exp_f32_e32 v135, v135
	v_add_f32_e32 v128, 1.0, v128
	v_exp_f32_e32 v132, v132
	v_exp_f32_e32 v134, v134
	v_exp_f32_e32 v131, v131
	v_rcp_f32_e32 v128, v128
	v_add_f32_e32 v129, 1.0, v129
	v_mul_f32_e32 v130, 0xbfb8aa3b, v130
	v_add_f32_e32 v133, 1.0, v133
	v_add_f32_e32 v135, 1.0, v135
	v_rcp_f32_e32 v129, v129
	v_exp_f32_e32 v130, v130
	v_add_f32_e32 v132, 1.0, v132
	v_add_f32_e32 v134, 1.0, v134
	v_rcp_f32_e32 v133, v133
	v_rcp_f32_e32 v135, v135
	v_rcp_f32_e32 v132, v132
	v_rcp_f32_e32 v134, v134
	v_add_f32_e32 v130, 1.0, v130
	v_rcp_f32_e32 v130, v130
	s_lshl_b32 s38, s8, 2
	s_ashr_i32 s39, s38, 31
	s_waitcnt vmcnt(0)
	v_lshlrev_b32_e32 v188, 16, v168
	v_and_b32_e32 v168, 0xffff0000, v168
	v_lshlrev_b32_e32 v189, 16, v169
	v_and_b32_e32 v169, 0xffff0000, v169
	v_lshlrev_b32_e32 v190, 16, v170
	v_and_b32_e32 v170, 0xffff0000, v170
	v_lshlrev_b32_e32 v191, 16, v171
	v_and_b32_e32 v171, 0xffff0000, v171
	v_lshlrev_b32_e32 v192, 16, v172
	v_and_b32_e32 v193, 0xffff0000, v172
	v_lshlrev_b32_e32 v194, 16, v173
	v_and_b32_e32 v195, 0xffff0000, v173
	v_lshlrev_b32_e32 v196, 16, v174
	v_and_b32_e32 v197, 0xffff0000, v174
	v_lshlrev_b32_e32 v198, 16, v175
	v_and_b32_e32 v199, 0xffff0000, v175
	v_mul_f32_e32 v172, v167, v188
	v_mul_f32_e32 v173, v167, v190
	v_mul_f32_e32 v168, v167, v168
	v_mul_f32_e32 v170, v167, v170
	v_mul_f32_e32 v174, v167, v189
	v_mul_f32_e32 v175, v167, v191
	v_mul_f32_e32 v169, v167, v169
	v_mul_f32_e32 v171, v167, v171
	v_mul_f32_e32 v172, v52, v172
	v_mul_f32_e32 v173, v48, v173
	v_mul_f32_e32 v168, v53, v168
	v_mul_f32_e32 v170, v49, v170
	v_mul_f32_e32 v174, v54, v174
	v_mul_f32_e32 v175, v50, v175
	v_mul_f32_e32 v169, v55, v169
	v_mul_f32_e32 v171, v51, v171
	v_fmac_f32_e32 v192, v180, v172
	v_fmac_f32_e32 v196, v181, v173
	v_fmac_f32_e32 v193, v182, v168
	v_fmac_f32_e32 v197, v183, v170
	v_fmac_f32_e32 v194, v184, v174
	v_fmac_f32_e32 v198, v185, v175
	v_fmac_f32_e32 v195, v186, v169
	v_fmac_f32_e32 v199, v187, v171
	v_cvt_pk_bf16_f32 v168, v192, v193
	v_cvt_pk_bf16_f32 v169, v194, v195
	v_cvt_pk_bf16_f32 v170, v196, v197
	v_cvt_pk_bf16_f32 v171, v198, v199
	global_load_dwordx4 v[172:175], v[176:177], off offset:256
	s_nop 0
	global_load_dwordx4 v[176:179], v[178:179], off offset:256
	v_mul_f32_e32 v180, v193, v193
	v_mul_f32_e32 v181, v195, v195
	v_mul_f32_e32 v182, v197, v197
	v_fmac_f32_e32 v180, v192, v192
	v_fmac_f32_e32 v181, v194, v194
	v_mul_f32_e32 v183, v199, v199
	v_fmac_f32_e32 v182, v196, v196
	v_add_f32_e32 v180, v180, v181
	v_fmac_f32_e32 v183, v198, v198
	v_add_f32_e32 v180, v182, v180
	v_add_f32_e32 v180, v183, v180
	s_waitcnt vmcnt(1)
	v_lshlrev_b32_e32 v183, 16, v174
	v_mul_f32_e32 v183, v167, v183
	s_waitcnt vmcnt(0)
	v_lshlrev_b32_e32 v187, 16, v178
	v_mul_f32_e32 v183, v40, v183
	v_and_b32_e32 v174, 0xffff0000, v174
	v_fmac_f32_e32 v187, v128, v183
	v_add_f32_e32 v128, 1.0, v131
	v_lshlrev_b32_e32 v181, 16, v172
	v_and_b32_e32 v172, 0xffff0000, v172
	v_lshlrev_b32_e32 v182, 16, v173
	v_and_b32_e32 v173, 0xffff0000, v173
	v_mul_f32_e32 v174, v167, v174
	v_rcp_f32_e32 v128, v128
	v_lshlrev_b32_e32 v184, 16, v175
	v_and_b32_e32 v175, 0xffff0000, v175
	v_and_b32_e32 v178, 0xffff0000, v178
	v_mul_f32_e32 v172, v167, v172
	v_mul_f32_e32 v173, v167, v173
	v_mul_f32_e32 v174, v41, v174
	v_lshlrev_b32_e32 v185, 16, v176
	v_and_b32_e32 v176, 0xffff0000, v176
	v_lshlrev_b32_e32 v186, 16, v177
	v_and_b32_e32 v177, 0xffff0000, v177
	v_mul_f32_e32 v181, v167, v181
	v_mul_f32_e32 v182, v167, v182
	v_mul_f32_e32 v172, v45, v172
	v_mul_f32_e32 v173, v47, v173
	v_fmac_f32_e32 v178, v129, v174
	v_mul_f32_e32 v129, v167, v175
	v_lshlrev_b32_e32 v188, 16, v179
	v_and_b32_e32 v179, 0xffff0000, v179
	v_mul_f32_e32 v181, v44, v181
	v_mul_f32_e32 v182, v46, v182
	v_fmac_f32_e32 v176, v133, v172
	v_fmac_f32_e32 v177, v135, v173
	v_mul_f32_e32 v129, v43, v129
	v_fmac_f32_e32 v185, v132, v181
	v_fmac_f32_e32 v186, v134, v182
	v_fmac_f32_e32 v179, v128, v129
	v_mul_f32_e32 v128, v176, v176
	v_mul_f32_e32 v129, v177, v177
	v_fmac_f32_e32 v128, v185, v185
	v_fmac_f32_e32 v129, v186, v186
	v_mul_f32_e32 v184, v167, v184
	v_add_f32_e32 v128, v128, v129
	v_mul_f32_e32 v129, v178, v178
	v_mul_f32_e32 v184, v42, v184
	v_fmac_f32_e32 v129, v187, v187
	v_fmac_f32_e32 v188, v130, v184
	v_add_f32_e32 v128, v129, v128
	v_mul_f32_e32 v129, v179, v179
	v_fmac_f32_e32 v129, v188, v188
	v_and_b32_e32 v130, 64, v166
	v_add_f32_e32 v128, v129, v128
	v_xor_b32_e32 v129, 16, v166
	v_add_u32_e32 v133, 64, v130
	v_cmp_lt_i32_e32 vcc, v129, v133
	v_add_f32_e32 v128, v180, v128
	v_lshl_add_u64 v[130:131], s[12:13], 0, v[158:159]
	v_cndmask_b32_e32 v129, v166, v129, vcc
	v_lshlrev_b32_e32 v132, 2, v129
	ds_bpermute_b32 v129, v132, v128
	global_store_dwordx4 v[130:131], v[168:171], off
	s_waitcnt lgkmcnt(0)
	v_add_f32_e32 v128, v128, v129
	v_xor_b32_e32 v129, 32, v166
	v_cmp_lt_i32_e32 vcc, v129, v133
	v_cvt_pk_bf16_f32 v168, v185, v176
	v_cvt_pk_bf16_f32 v169, v186, v177
	v_cvt_pk_bf16_f32 v170, v187, v178
	v_cvt_pk_bf16_f32 v171, v188, v179
	global_store_dwordx4 v[130:131], v[168:171], off offset:256
	s_nop 0
	v_cndmask_b32_e32 v129, v166, v129, vcc
	v_lshlrev_b32_e32 v133, 2, v129
	ds_bpermute_b32 v129, v133, v128
	s_and_saveexec_b64 s[40:41], s[2:3]
	s_cbranch_execz .LBB0_1318
	v_lshlrev_b64 v[130:131], 8, v[154:155]
	v_lshl_add_u64 v[130:131], s[20:21], 0, v[130:131]
	v_lshl_add_u64 v[130:131], s[38:39], 2, v[130:131]
	s_lshl_b32 s8, s51, 2
	v_lshl_add_u64 v[130:131], v[130:131], 0, s[8:9]
	s_waitcnt lgkmcnt(0)
	v_add_f32_e32 v128, v128, v129
	global_store_dword v[130:131], v128, off
.LBB0_1318:
	s_or_b64 exec, exec, s[40:41]
	v_or_b32_e32 v128, 16, v154
	s_waitcnt lgkmcnt(0)
	v_ashrrev_i32_e32 v129, 31, v128
	v_lshlrev_b64 v[130:131], 12, v[128:129]
	v_lshl_add_u64 v[130:131], v[130:131], 0, v[152:153]
	v_lshlrev_b64 v[130:131], 1, v[130:131]
	v_lshl_add_u64 v[134:135], s[16:17], 0, v[130:131]
	global_load_dwordx4 v[168:171], v[134:135], off
	v_lshl_add_u64 v[176:177], v[128:129], 2, s[18:19]
	v_lshl_add_u64 v[158:159], s[86:87], 0, v[130:131]
	global_load_dword v155, v[176:177], off
	global_load_dwordx4 v[172:175], v[158:159], off
	v_mul_f32_e32 v124, 0xbfb8aa3b, v124
	v_mul_f32_e32 v120, 0xbfb8aa3b, v120
	v_mul_f32_e32 v125, 0xbfb8aa3b, v125
	v_mul_f32_e32 v121, 0xbfb8aa3b, v121
	v_mul_f32_e32 v126, 0xbfb8aa3b, v126
	v_mul_f32_e32 v122, 0xbfb8aa3b, v122
	v_mul_f32_e32 v127, 0xbfb8aa3b, v127
	v_mul_f32_e32 v123, 0xbfb8aa3b, v123
	v_exp_f32_e32 v124, v124
	v_exp_f32_e32 v120, v120
	v_exp_f32_e32 v125, v125
	v_exp_f32_e32 v121, v121
	v_exp_f32_e32 v126, v126
	v_exp_f32_e32 v122, v122
	v_exp_f32_e32 v127, v127
	v_exp_f32_e32 v123, v123
	v_add_f32_e32 v124, 1.0, v124
	v_add_f32_e32 v120, 1.0, v120
	v_add_f32_e32 v125, 1.0, v125
	v_add_f32_e32 v121, 1.0, v121
	v_add_f32_e32 v126, 1.0, v126
	v_add_f32_e32 v122, 1.0, v122
	v_add_f32_e32 v127, 1.0, v127
	v_add_f32_e32 v123, 1.0, v123
	v_rcp_f32_e32 v124, v124
	v_rcp_f32_e32 v120, v120
	v_rcp_f32_e32 v125, v125
	v_rcp_f32_e32 v121, v121
	v_rcp_f32_e32 v126, v126
	v_rcp_f32_e32 v122, v122
	v_rcp_f32_e32 v127, v127
	v_rcp_f32_e32 v123, v123
	v_mul_f32_e32 v117, 0xbfb8aa3b, v117
	v_mul_f32_e32 v119, 0xbfb8aa3b, v119
	v_mul_f32_e32 v116, 0xbfb8aa3b, v116
	v_mul_f32_e32 v112, 0xbfb8aa3b, v112
	v_mul_f32_e32 v113, 0xbfb8aa3b, v113
	v_mul_f32_e32 v118, 0xbfb8aa3b, v118
	v_exp_f32_e32 v117, v117
	v_exp_f32_e32 v119, v119
	v_exp_f32_e32 v116, v116
	v_exp_f32_e32 v112, v112
	v_exp_f32_e32 v113, v113
	v_exp_f32_e32 v118, v118
	v_mul_f32_e32 v115, 0xbfb8aa3b, v115
	v_mul_f32_e32 v114, 0xbfb8aa3b, v114
	v_exp_f32_e32 v115, v115
	v_add_f32_e32 v117, 1.0, v117
	v_add_f32_e32 v119, 1.0, v119
	v_exp_f32_e32 v114, v114
	v_add_f32_e32 v116, 1.0, v116
	v_add_f32_e32 v112, 1.0, v112
	v_add_f32_e32 v113, 1.0, v113
	v_add_f32_e32 v118, 1.0, v118
	v_rcp_f32_e32 v117, v117
	v_rcp_f32_e32 v119, v119
	v_rcp_f32_e32 v116, v116
	v_rcp_f32_e32 v112, v112
	v_rcp_f32_e32 v113, v113
	v_rcp_f32_e32 v118, v118
	v_add_f32_e32 v115, 1.0, v115
	v_add_f32_e32 v114, 1.0, v114
	v_rcp_f32_e32 v115, v115
	v_rcp_f32_e32 v114, v114
	s_waitcnt vmcnt(2)
	v_lshlrev_b32_e32 v167, 16, v168
	v_and_b32_e32 v168, 0xffff0000, v168
	v_lshlrev_b32_e32 v176, 16, v169
	v_and_b32_e32 v169, 0xffff0000, v169
	v_lshlrev_b32_e32 v177, 16, v170
	v_and_b32_e32 v170, 0xffff0000, v170
	v_lshlrev_b32_e32 v178, 16, v171
	v_and_b32_e32 v171, 0xffff0000, v171
	s_waitcnt vmcnt(1)
	v_mul_f32_e32 v167, v155, v167
	v_mul_f32_e32 v177, v155, v177
	v_mul_f32_e32 v168, v155, v168
	v_mul_f32_e32 v170, v155, v170
	v_mul_f32_e32 v176, v155, v176
	v_mul_f32_e32 v178, v155, v178
	v_mul_f32_e32 v169, v155, v169
	v_mul_f32_e32 v171, v155, v171
	s_waitcnt vmcnt(0)
	v_lshlrev_b32_e32 v179, 16, v172
	v_and_b32_e32 v172, 0xffff0000, v172
	v_lshlrev_b32_e32 v180, 16, v173
	v_and_b32_e32 v173, 0xffff0000, v173
	v_lshlrev_b32_e32 v181, 16, v174
	v_and_b32_e32 v174, 0xffff0000, v174
	v_lshlrev_b32_e32 v182, 16, v175
	v_and_b32_e32 v175, 0xffff0000, v175
	v_mul_f32_e32 v167, v52, v167
	v_mul_f32_e32 v177, v48, v177
	v_mul_f32_e32 v168, v53, v168
	v_mul_f32_e32 v170, v49, v170
	v_mul_f32_e32 v176, v54, v176
	v_mul_f32_e32 v178, v50, v178
	v_mul_f32_e32 v169, v55, v169
	v_mul_f32_e32 v171, v51, v171
	v_fmac_f32_e32 v179, v124, v167
	v_fmac_f32_e32 v181, v120, v177
	v_fmac_f32_e32 v172, v125, v168
	v_fmac_f32_e32 v174, v121, v170
	v_fmac_f32_e32 v180, v126, v176
	v_fmac_f32_e32 v182, v122, v178
	v_fmac_f32_e32 v173, v127, v169
	v_fmac_f32_e32 v175, v123, v171
	v_cvt_pk_bf16_f32 v120, v179, v172
	v_cvt_pk_bf16_f32 v121, v180, v173
	v_cvt_pk_bf16_f32 v122, v181, v174
	v_cvt_pk_bf16_f32 v123, v182, v175
	global_load_dwordx4 v[124:127], v[134:135], off offset:256
	global_load_dwordx4 v[168:171], v[158:159], off offset:256
	v_mul_f32_e32 v134, v172, v172
	v_mul_f32_e32 v135, v173, v173
	v_mul_f32_e32 v158, v174, v174
	v_fmac_f32_e32 v134, v179, v179
	v_fmac_f32_e32 v135, v180, v180
	v_mul_f32_e32 v159, v175, v175
	v_fmac_f32_e32 v158, v181, v181
	v_add_f32_e32 v134, v134, v135
	v_fmac_f32_e32 v159, v182, v182
	v_add_f32_e32 v134, v158, v134
	v_add_f32_e32 v134, v159, v134
	s_waitcnt vmcnt(1)
	v_lshlrev_b32_e32 v135, 16, v124
	v_and_b32_e32 v124, 0xffff0000, v124
	v_lshlrev_b32_e32 v158, 16, v125
	v_and_b32_e32 v125, 0xffff0000, v125
	v_lshlrev_b32_e32 v159, 16, v126
	v_and_b32_e32 v126, 0xffff0000, v126
	v_mul_f32_e32 v124, v155, v124
	v_mul_f32_e32 v125, v155, v125
	v_lshlrev_b32_e32 v167, 16, v127
	v_and_b32_e32 v127, 0xffff0000, v127
	s_waitcnt vmcnt(0)
	v_lshlrev_b32_e32 v172, 16, v168
	v_and_b32_e32 v168, 0xffff0000, v168
	v_lshlrev_b32_e32 v173, 16, v169
	v_and_b32_e32 v169, 0xffff0000, v169
	v_mul_f32_e32 v135, v155, v135
	v_mul_f32_e32 v159, v155, v159
	v_mul_f32_e32 v126, v155, v126
	v_mul_f32_e32 v158, v155, v158
	v_mul_f32_e32 v124, v45, v124
	v_mul_f32_e32 v125, v47, v125
	v_lshlrev_b32_e32 v174, 16, v170
	v_and_b32_e32 v170, 0xffff0000, v170
	v_mul_f32_e32 v167, v155, v167
	v_mul_f32_e32 v127, v155, v127
	v_mul_f32_e32 v135, v44, v135
	v_mul_f32_e32 v155, v40, v159
	v_mul_f32_e32 v126, v41, v126
	v_mul_f32_e32 v158, v46, v158
	v_fmac_f32_e32 v168, v117, v124
	v_fmac_f32_e32 v169, v119, v125
	v_fmac_f32_e32 v172, v116, v135
	v_fmac_f32_e32 v174, v112, v155
	v_fmac_f32_e32 v170, v113, v126
	v_fmac_f32_e32 v173, v118, v158
	v_mul_f32_e32 v112, v168, v168
	v_mul_f32_e32 v113, v169, v169
	v_fmac_f32_e32 v112, v172, v172
	v_fmac_f32_e32 v113, v173, v173
	v_lshlrev_b32_e32 v175, 16, v171
	v_and_b32_e32 v171, 0xffff0000, v171
	v_mul_f32_e32 v127, v43, v127
	v_add_f32_e32 v112, v112, v113
	v_mul_f32_e32 v113, v170, v170
	v_mul_f32_e32 v159, v42, v167
	v_fmac_f32_e32 v171, v115, v127
	v_fmac_f32_e32 v113, v174, v174
	v_fmac_f32_e32 v175, v114, v159
	v_add_f32_e32 v112, v113, v112
	v_mul_f32_e32 v113, v171, v171
	v_fmac_f32_e32 v113, v175, v175
	v_add_f32_e32 v112, v113, v112
	v_add_f32_e32 v112, v134, v112
	ds_bpermute_b32 v113, v132, v112
	v_lshl_add_u64 v[118:119], s[12:13], 0, v[130:131]
	global_store_dwordx4 v[118:119], v[120:123], off
	v_cvt_pk_bf16_f32 v114, v172, v168
	v_cvt_pk_bf16_f32 v115, v173, v169
	s_waitcnt lgkmcnt(0)
	v_add_f32_e32 v112, v112, v113
	ds_bpermute_b32 v113, v133, v112
	v_cvt_pk_bf16_f32 v116, v174, v170
	v_cvt_pk_bf16_f32 v117, v175, v171
	global_store_dwordx4 v[118:119], v[114:117], off offset:256
	s_and_saveexec_b64 s[40:41], s[2:3]
	s_cbranch_execz .LBB0_1320
	v_lshlrev_b64 v[114:115], 8, v[128:129]
	v_lshl_add_u64 v[114:115], s[20:21], 0, v[114:115]
	v_lshl_add_u64 v[114:115], s[38:39], 2, v[114:115]
	s_lshl_b32 s8, s51, 2
	v_lshl_add_u64 v[114:115], v[114:115], 0, s[8:9]
	s_waitcnt lgkmcnt(0)
	v_add_f32_e32 v112, v112, v113
	global_store_dword v[114:115], v112, off
.LBB0_1320:
	s_or_b64 exec, exec, s[40:41]
	v_or_b32_e32 v112, 32, v154
	s_waitcnt lgkmcnt(0)
	v_ashrrev_i32_e32 v113, 31, v112
	v_lshlrev_b64 v[114:115], 12, v[112:113]
	v_lshl_add_u64 v[114:115], v[114:115], 0, v[152:153]
	v_lshlrev_b64 v[114:115], 1, v[114:115]
	v_lshl_add_u64 v[124:125], s[16:17], 0, v[114:115]
	global_load_dwordx4 v[116:119], v[124:125], off
	v_lshl_add_u64 v[128:129], v[112:113], 2, s[18:19]
	v_lshl_add_u64 v[126:127], s[86:87], 0, v[114:115]
	global_load_dword v128, v[128:129], off
	v_mul_f32_e32 v108, 0xbfb8aa3b, v108
	global_load_dwordx4 v[120:123], v[126:127], off
	v_mul_f32_e32 v104, 0xbfb8aa3b, v104
	v_mul_f32_e32 v109, 0xbfb8aa3b, v109
	v_mul_f32_e32 v105, 0xbfb8aa3b, v105
	v_mul_f32_e32 v110, 0xbfb8aa3b, v110
	v_mul_f32_e32 v106, 0xbfb8aa3b, v106
	v_mul_f32_e32 v111, 0xbfb8aa3b, v111
	v_mul_f32_e32 v107, 0xbfb8aa3b, v107
	v_exp_f32_e32 v108, v108
	v_exp_f32_e32 v104, v104
	v_exp_f32_e32 v109, v109
	v_exp_f32_e32 v105, v105
	v_exp_f32_e32 v110, v110
	v_exp_f32_e32 v106, v106
	v_exp_f32_e32 v111, v111
	v_exp_f32_e32 v107, v107
	v_add_f32_e32 v108, 1.0, v108
	v_add_f32_e32 v104, 1.0, v104
	v_add_f32_e32 v109, 1.0, v109
	v_add_f32_e32 v105, 1.0, v105
	v_add_f32_e32 v110, 1.0, v110
	v_add_f32_e32 v106, 1.0, v106
	v_add_f32_e32 v111, 1.0, v111
	v_add_f32_e32 v107, 1.0, v107
	v_rcp_f32_e32 v108, v108
	v_rcp_f32_e32 v104, v104
	v_rcp_f32_e32 v109, v109
	v_rcp_f32_e32 v105, v105
	v_rcp_f32_e32 v110, v110
	v_rcp_f32_e32 v106, v106
	v_rcp_f32_e32 v111, v111
	v_rcp_f32_e32 v107, v107
	v_mul_f32_e32 v101, 0xbfb8aa3b, v101
	v_mul_f32_e32 v103, 0xbfb8aa3b, v103
	v_mul_f32_e32 v100, 0xbfb8aa3b, v100
	v_mul_f32_e32 v96, 0xbfb8aa3b, v96
	v_mul_f32_e32 v97, 0xbfb8aa3b, v97
	v_mul_f32_e32 v102, 0xbfb8aa3b, v102
	v_exp_f32_e32 v101, v101
	v_exp_f32_e32 v103, v103
	v_exp_f32_e32 v100, v100
	v_exp_f32_e32 v96, v96
	v_exp_f32_e32 v97, v97
	v_exp_f32_e32 v102, v102
	v_mul_f32_e32 v99, 0xbfb8aa3b, v99
	v_mul_f32_e32 v98, 0xbfb8aa3b, v98
	v_exp_f32_e32 v99, v99
	v_add_f32_e32 v101, 1.0, v101
	v_add_f32_e32 v103, 1.0, v103
	v_exp_f32_e32 v98, v98
	v_add_f32_e32 v100, 1.0, v100
	v_add_f32_e32 v96, 1.0, v96
	v_add_f32_e32 v97, 1.0, v97
	v_add_f32_e32 v102, 1.0, v102
	v_rcp_f32_e32 v101, v101
	v_rcp_f32_e32 v103, v103
	v_rcp_f32_e32 v100, v100
	v_rcp_f32_e32 v96, v96
	v_rcp_f32_e32 v97, v97
	v_rcp_f32_e32 v102, v102
	v_add_f32_e32 v99, 1.0, v99
	v_add_f32_e32 v98, 1.0, v98
	v_rcp_f32_e32 v99, v99
	v_rcp_f32_e32 v98, v98
	s_waitcnt vmcnt(2)
	v_lshlrev_b32_e32 v129, 16, v116
	v_and_b32_e32 v116, 0xffff0000, v116
	v_lshlrev_b32_e32 v130, 16, v117
	v_and_b32_e32 v117, 0xffff0000, v117
	v_lshlrev_b32_e32 v131, 16, v118
	v_and_b32_e32 v118, 0xffff0000, v118
	v_lshlrev_b32_e32 v134, 16, v119
	v_and_b32_e32 v119, 0xffff0000, v119
	s_waitcnt vmcnt(1)
	v_mul_f32_e32 v129, v128, v129
	v_mul_f32_e32 v131, v128, v131
	v_mul_f32_e32 v116, v128, v116
	v_mul_f32_e32 v118, v128, v118
	v_mul_f32_e32 v130, v128, v130
	v_mul_f32_e32 v134, v128, v134
	v_mul_f32_e32 v117, v128, v117
	v_mul_f32_e32 v119, v128, v119
	s_waitcnt vmcnt(0)
	v_lshlrev_b32_e32 v135, 16, v120
	v_and_b32_e32 v120, 0xffff0000, v120
	v_lshlrev_b32_e32 v155, 16, v121
	v_and_b32_e32 v121, 0xffff0000, v121
	v_lshlrev_b32_e32 v158, 16, v122
	v_and_b32_e32 v122, 0xffff0000, v122
	v_lshlrev_b32_e32 v159, 16, v123
	v_and_b32_e32 v123, 0xffff0000, v123
	v_mul_f32_e32 v129, v52, v129
	v_mul_f32_e32 v131, v48, v131
	v_mul_f32_e32 v116, v53, v116
	v_mul_f32_e32 v118, v49, v118
	v_mul_f32_e32 v130, v54, v130
	v_mul_f32_e32 v134, v50, v134
	v_mul_f32_e32 v117, v55, v117
	v_mul_f32_e32 v119, v51, v119
	v_fmac_f32_e32 v135, v108, v129
	v_fmac_f32_e32 v158, v104, v131
	v_fmac_f32_e32 v120, v109, v116
	v_fmac_f32_e32 v122, v105, v118
	v_fmac_f32_e32 v155, v110, v130
	v_fmac_f32_e32 v159, v106, v134
	v_fmac_f32_e32 v121, v111, v117
	v_fmac_f32_e32 v123, v107, v119
	v_cvt_pk_bf16_f32 v104, v135, v120
	v_cvt_pk_bf16_f32 v105, v155, v121
	v_cvt_pk_bf16_f32 v106, v158, v122
	v_cvt_pk_bf16_f32 v107, v159, v123
	global_load_dwordx4 v[108:111], v[124:125], off offset:256
	global_load_dwordx4 v[116:119], v[126:127], off offset:256
	v_mul_f32_e32 v120, v120, v120
	v_mul_f32_e32 v121, v121, v121
	v_mul_f32_e32 v122, v122, v122
	v_fmac_f32_e32 v120, v135, v135
	v_fmac_f32_e32 v121, v155, v155
	v_mul_f32_e32 v123, v123, v123
	v_fmac_f32_e32 v122, v158, v158
	v_add_f32_e32 v120, v120, v121
	v_fmac_f32_e32 v123, v159, v159
	v_add_f32_e32 v120, v122, v120
	v_add_f32_e32 v120, v123, v120
	s_waitcnt vmcnt(1)
	v_lshlrev_b32_e32 v121, 16, v108
	v_and_b32_e32 v108, 0xffff0000, v108
	v_lshlrev_b32_e32 v122, 16, v109
	v_and_b32_e32 v109, 0xffff0000, v109
	v_lshlrev_b32_e32 v123, 16, v110
	v_and_b32_e32 v110, 0xffff0000, v110
	v_mul_f32_e32 v108, v128, v108
	v_mul_f32_e32 v109, v128, v109
	s_waitcnt vmcnt(0)
	v_lshlrev_b32_e32 v125, 16, v116
	v_and_b32_e32 v116, 0xffff0000, v116
	v_lshlrev_b32_e32 v126, 16, v117
	v_and_b32_e32 v117, 0xffff0000, v117
	v_mul_f32_e32 v121, v128, v121
	v_mul_f32_e32 v123, v128, v123
	v_mul_f32_e32 v110, v128, v110
	v_mul_f32_e32 v122, v128, v122
	v_mul_f32_e32 v108, v45, v108
	v_mul_f32_e32 v109, v47, v109
	v_lshlrev_b32_e32 v127, 16, v118
	v_and_b32_e32 v118, 0xffff0000, v118
	v_mul_f32_e32 v121, v44, v121
	v_mul_f32_e32 v123, v40, v123
	v_mul_f32_e32 v110, v41, v110
	v_mul_f32_e32 v122, v46, v122
	v_fmac_f32_e32 v116, v101, v108
	v_fmac_f32_e32 v117, v103, v109
	v_lshlrev_b32_e32 v124, 16, v111
	v_and_b32_e32 v111, 0xffff0000, v111
	v_fmac_f32_e32 v125, v100, v121
	v_fmac_f32_e32 v127, v96, v123
	v_fmac_f32_e32 v118, v97, v110
	v_fmac_f32_e32 v126, v102, v122
	v_mul_f32_e32 v96, v116, v116
	v_mul_f32_e32 v97, v117, v117
	v_mul_f32_e32 v111, v128, v111
	v_fmac_f32_e32 v96, v125, v125
	v_fmac_f32_e32 v97, v126, v126
	v_lshlrev_b32_e32 v129, 16, v119
	v_and_b32_e32 v119, 0xffff0000, v119
	v_mul_f32_e32 v124, v128, v124
	v_mul_f32_e32 v111, v43, v111
	v_add_f32_e32 v96, v96, v97
	v_mul_f32_e32 v97, v118, v118
	v_mul_f32_e32 v124, v42, v124
	v_fmac_f32_e32 v119, v99, v111
	v_fmac_f32_e32 v97, v127, v127
	v_fmac_f32_e32 v129, v98, v124
	v_add_f32_e32 v96, v97, v96
	v_mul_f32_e32 v97, v119, v119
	v_fmac_f32_e32 v97, v129, v129
	v_add_f32_e32 v96, v97, v96
	v_add_f32_e32 v96, v120, v96
	ds_bpermute_b32 v97, v132, v96
	v_lshl_add_u64 v[102:103], s[12:13], 0, v[114:115]
	global_store_dwordx4 v[102:103], v[104:107], off
	v_cvt_pk_bf16_f32 v98, v125, v116
	v_cvt_pk_bf16_f32 v99, v126, v117
	s_waitcnt lgkmcnt(0)
	v_add_f32_e32 v96, v96, v97
	ds_bpermute_b32 v97, v133, v96
	v_cvt_pk_bf16_f32 v100, v127, v118
	v_cvt_pk_bf16_f32 v101, v129, v119
	global_store_dwordx4 v[102:103], v[98:101], off offset:256
	s_and_saveexec_b64 s[40:41], s[2:3]
	s_cbranch_execz .LBB0_1322
	v_lshlrev_b64 v[98:99], 8, v[112:113]
	v_lshl_add_u64 v[98:99], s[20:21], 0, v[98:99]
	v_lshl_add_u64 v[98:99], s[38:39], 2, v[98:99]
	s_lshl_b32 s8, s51, 2
	v_lshl_add_u64 v[98:99], v[98:99], 0, s[8:9]
	s_waitcnt lgkmcnt(0)
	v_add_f32_e32 v96, v96, v97
	global_store_dword v[98:99], v96, off
.LBB0_1322:
	s_or_b64 exec, exec, s[40:41]
	v_or_b32_e32 v96, 48, v154
	s_waitcnt lgkmcnt(0)
	v_ashrrev_i32_e32 v97, 31, v96
	v_lshlrev_b64 v[98:99], 12, v[96:97]
	v_lshl_add_u64 v[98:99], v[98:99], 0, v[152:153]
	v_lshlrev_b64 v[98:99], 1, v[98:99]
	v_lshl_add_u64 v[108:109], s[16:17], 0, v[98:99]
	global_load_dwordx4 v[100:103], v[108:109], off
	v_lshl_add_u64 v[112:113], v[96:97], 2, s[18:19]
	v_lshl_add_u64 v[110:111], s[86:87], 0, v[98:99]
	global_load_dword v112, v[112:113], off
	v_mul_f32_e32 v92, 0xbfb8aa3b, v92
	global_load_dwordx4 v[104:107], v[110:111], off
	v_mul_f32_e32 v88, 0xbfb8aa3b, v88
	v_mul_f32_e32 v93, 0xbfb8aa3b, v93
	v_mul_f32_e32 v89, 0xbfb8aa3b, v89
	v_mul_f32_e32 v94, 0xbfb8aa3b, v94
	v_mul_f32_e32 v90, 0xbfb8aa3b, v90
	v_mul_f32_e32 v95, 0xbfb8aa3b, v95
	v_mul_f32_e32 v91, 0xbfb8aa3b, v91
	v_exp_f32_e32 v92, v92
	v_exp_f32_e32 v88, v88
	v_exp_f32_e32 v93, v93
	v_exp_f32_e32 v89, v89
	v_exp_f32_e32 v94, v94
	v_exp_f32_e32 v90, v90
	v_exp_f32_e32 v95, v95
	v_exp_f32_e32 v91, v91
	v_add_f32_e32 v92, 1.0, v92
	v_add_f32_e32 v88, 1.0, v88
	v_add_f32_e32 v93, 1.0, v93
	v_add_f32_e32 v89, 1.0, v89
	v_add_f32_e32 v94, 1.0, v94
	v_add_f32_e32 v90, 1.0, v90
	v_add_f32_e32 v95, 1.0, v95
	v_add_f32_e32 v91, 1.0, v91
	v_rcp_f32_e32 v92, v92
	v_rcp_f32_e32 v88, v88
	v_rcp_f32_e32 v93, v93
	v_rcp_f32_e32 v89, v89
	v_rcp_f32_e32 v94, v94
	v_rcp_f32_e32 v90, v90
	v_rcp_f32_e32 v95, v95
	v_rcp_f32_e32 v91, v91
	v_mul_f32_e32 v85, 0xbfb8aa3b, v85
	v_mul_f32_e32 v87, 0xbfb8aa3b, v87
	v_mul_f32_e32 v84, 0xbfb8aa3b, v84
	v_mul_f32_e32 v80, 0xbfb8aa3b, v80
	v_mul_f32_e32 v81, 0xbfb8aa3b, v81
	v_mul_f32_e32 v86, 0xbfb8aa3b, v86
	v_exp_f32_e32 v85, v85
	v_exp_f32_e32 v87, v87
	v_exp_f32_e32 v84, v84
	v_exp_f32_e32 v80, v80
	v_exp_f32_e32 v81, v81
	v_exp_f32_e32 v86, v86
	v_mul_f32_e32 v83, 0xbfb8aa3b, v83
	v_mul_f32_e32 v82, 0xbfb8aa3b, v82
	v_exp_f32_e32 v83, v83
	v_add_f32_e32 v85, 1.0, v85
	v_add_f32_e32 v87, 1.0, v87
	v_exp_f32_e32 v82, v82
	v_add_f32_e32 v84, 1.0, v84
	v_add_f32_e32 v80, 1.0, v80
	v_add_f32_e32 v81, 1.0, v81
	v_add_f32_e32 v86, 1.0, v86
	v_rcp_f32_e32 v85, v85
	v_rcp_f32_e32 v87, v87
	v_rcp_f32_e32 v84, v84
	v_rcp_f32_e32 v80, v80
	v_rcp_f32_e32 v81, v81
	v_rcp_f32_e32 v86, v86
	v_add_f32_e32 v83, 1.0, v83
	v_add_f32_e32 v82, 1.0, v82
	v_rcp_f32_e32 v83, v83
	v_rcp_f32_e32 v82, v82
	s_waitcnt vmcnt(2)
	v_lshlrev_b32_e32 v113, 16, v100
	v_and_b32_e32 v100, 0xffff0000, v100
	v_lshlrev_b32_e32 v114, 16, v101
	v_and_b32_e32 v101, 0xffff0000, v101
	v_lshlrev_b32_e32 v115, 16, v102
	v_and_b32_e32 v102, 0xffff0000, v102
	v_lshlrev_b32_e32 v116, 16, v103
	v_and_b32_e32 v103, 0xffff0000, v103
	s_waitcnt vmcnt(1)
	v_mul_f32_e32 v113, v112, v113
	v_mul_f32_e32 v115, v112, v115
	v_mul_f32_e32 v100, v112, v100
	v_mul_f32_e32 v102, v112, v102
	v_mul_f32_e32 v114, v112, v114
	v_mul_f32_e32 v116, v112, v116
	v_mul_f32_e32 v101, v112, v101
	v_mul_f32_e32 v103, v112, v103
	s_waitcnt vmcnt(0)
	v_lshlrev_b32_e32 v117, 16, v104
	v_and_b32_e32 v104, 0xffff0000, v104
	v_lshlrev_b32_e32 v118, 16, v105
	v_and_b32_e32 v105, 0xffff0000, v105
	v_lshlrev_b32_e32 v119, 16, v106
	v_and_b32_e32 v106, 0xffff0000, v106
	v_lshlrev_b32_e32 v120, 16, v107
	v_and_b32_e32 v107, 0xffff0000, v107
	v_mul_f32_e32 v113, v52, v113
	v_mul_f32_e32 v115, v48, v115
	v_mul_f32_e32 v100, v53, v100
	v_mul_f32_e32 v102, v49, v102
	v_mul_f32_e32 v114, v54, v114
	v_mul_f32_e32 v116, v50, v116
	v_mul_f32_e32 v101, v55, v101
	v_mul_f32_e32 v103, v51, v103
	v_fmac_f32_e32 v117, v92, v113
	v_fmac_f32_e32 v119, v88, v115
	v_fmac_f32_e32 v104, v93, v100
	v_fmac_f32_e32 v106, v89, v102
	v_fmac_f32_e32 v118, v94, v114
	v_fmac_f32_e32 v120, v90, v116
	v_fmac_f32_e32 v105, v95, v101
	v_fmac_f32_e32 v107, v91, v103
	v_cvt_pk_bf16_f32 v88, v117, v104
	v_cvt_pk_bf16_f32 v89, v118, v105
	v_cvt_pk_bf16_f32 v90, v119, v106
	v_cvt_pk_bf16_f32 v91, v120, v107
	global_load_dwordx4 v[92:95], v[108:109], off offset:256
	global_load_dwordx4 v[100:103], v[110:111], off offset:256
	v_mul_f32_e32 v104, v104, v104
	v_mul_f32_e32 v105, v105, v105
	v_mul_f32_e32 v106, v106, v106
	v_fmac_f32_e32 v104, v117, v117
	v_fmac_f32_e32 v105, v118, v118
	v_mul_f32_e32 v107, v107, v107
	v_fmac_f32_e32 v106, v119, v119
	v_add_f32_e32 v104, v104, v105
	v_fmac_f32_e32 v107, v120, v120
	v_add_f32_e32 v104, v106, v104
	v_add_f32_e32 v104, v107, v104
	s_waitcnt vmcnt(1)
	v_lshlrev_b32_e32 v105, 16, v92
	v_and_b32_e32 v92, 0xffff0000, v92
	v_lshlrev_b32_e32 v106, 16, v93
	v_and_b32_e32 v93, 0xffff0000, v93
	v_lshlrev_b32_e32 v107, 16, v94
	v_and_b32_e32 v94, 0xffff0000, v94
	v_mul_f32_e32 v92, v112, v92
	v_mul_f32_e32 v93, v112, v93
	s_waitcnt vmcnt(0)
	v_lshlrev_b32_e32 v109, 16, v100
	v_and_b32_e32 v100, 0xffff0000, v100
	v_lshlrev_b32_e32 v110, 16, v101
	v_and_b32_e32 v101, 0xffff0000, v101
	v_mul_f32_e32 v105, v112, v105
	v_mul_f32_e32 v107, v112, v107
	v_mul_f32_e32 v94, v112, v94
	v_mul_f32_e32 v106, v112, v106
	v_mul_f32_e32 v92, v45, v92
	v_mul_f32_e32 v93, v47, v93
	v_lshlrev_b32_e32 v111, 16, v102
	v_and_b32_e32 v102, 0xffff0000, v102
	v_mul_f32_e32 v105, v44, v105
	v_mul_f32_e32 v107, v40, v107
	v_mul_f32_e32 v94, v41, v94
	v_mul_f32_e32 v106, v46, v106
	v_fmac_f32_e32 v100, v85, v92
	v_fmac_f32_e32 v101, v87, v93
	v_lshlrev_b32_e32 v108, 16, v95
	v_and_b32_e32 v95, 0xffff0000, v95
	v_fmac_f32_e32 v109, v84, v105
	v_fmac_f32_e32 v111, v80, v107
	v_fmac_f32_e32 v102, v81, v94
	v_fmac_f32_e32 v110, v86, v106
	v_mul_f32_e32 v80, v100, v100
	v_mul_f32_e32 v81, v101, v101
	v_mul_f32_e32 v95, v112, v95
	v_fmac_f32_e32 v80, v109, v109
	v_fmac_f32_e32 v81, v110, v110
	v_lshlrev_b32_e32 v113, 16, v103
	v_and_b32_e32 v103, 0xffff0000, v103
	v_mul_f32_e32 v108, v112, v108
	v_mul_f32_e32 v95, v43, v95
	v_add_f32_e32 v80, v80, v81
	v_mul_f32_e32 v81, v102, v102
	v_mul_f32_e32 v108, v42, v108
	v_fmac_f32_e32 v103, v83, v95
	v_fmac_f32_e32 v81, v111, v111
	v_fmac_f32_e32 v113, v82, v108
	v_add_f32_e32 v80, v81, v80
	v_mul_f32_e32 v81, v103, v103
	v_fmac_f32_e32 v81, v113, v113
	v_add_f32_e32 v80, v81, v80
	v_add_f32_e32 v80, v104, v80
	ds_bpermute_b32 v81, v132, v80
	v_lshl_add_u64 v[86:87], s[12:13], 0, v[98:99]
	global_store_dwordx4 v[86:87], v[88:91], off
	v_cvt_pk_bf16_f32 v82, v109, v100
	v_cvt_pk_bf16_f32 v83, v110, v101
	s_waitcnt lgkmcnt(0)
	v_add_f32_e32 v80, v80, v81
	ds_bpermute_b32 v81, v133, v80
	v_cvt_pk_bf16_f32 v84, v111, v102
	v_cvt_pk_bf16_f32 v85, v113, v103
	global_store_dwordx4 v[86:87], v[82:85], off offset:256
	s_and_saveexec_b64 s[40:41], s[2:3]
	s_cbranch_execz .LBB0_1324
	v_lshlrev_b64 v[82:83], 8, v[96:97]
	v_lshl_add_u64 v[82:83], s[20:21], 0, v[82:83]
	v_lshl_add_u64 v[82:83], s[38:39], 2, v[82:83]
	s_lshl_b32 s8, s51, 2
	v_lshl_add_u64 v[82:83], v[82:83], 0, s[8:9]
	s_waitcnt lgkmcnt(0)
	v_add_f32_e32 v80, v80, v81
	global_store_dword v[82:83], v80, off
.LBB0_1324:
	s_or_b64 exec, exec, s[40:41]
	v_add_u32_e32 v80, 0x80, v154
	s_waitcnt lgkmcnt(0)
	v_ashrrev_i32_e32 v81, 31, v80
	v_lshlrev_b64 v[82:83], 12, v[80:81]
	v_lshl_add_u64 v[82:83], v[82:83], 0, v[152:153]
	v_lshlrev_b64 v[82:83], 1, v[82:83]
	v_lshl_add_u64 v[92:93], s[16:17], 0, v[82:83]
	global_load_dwordx4 v[84:87], v[92:93], off
	v_lshl_add_u64 v[94:95], s[86:87], 0, v[82:83]
	global_load_dwordx4 v[88:91], v[94:95], off
	global_load_dword v96, v[156:157], off offset:512
	v_mul_f32_e32 v76, 0xbfb8aa3b, v76
	v_mul_f32_e32 v72, 0xbfb8aa3b, v72
	v_mul_f32_e32 v77, 0xbfb8aa3b, v77
	v_mul_f32_e32 v73, 0xbfb8aa3b, v73
	v_mul_f32_e32 v78, 0xbfb8aa3b, v78
	v_mul_f32_e32 v74, 0xbfb8aa3b, v74
	v_mul_f32_e32 v79, 0xbfb8aa3b, v79
	v_mul_f32_e32 v75, 0xbfb8aa3b, v75
	v_exp_f32_e32 v76, v76
	v_exp_f32_e32 v72, v72
	v_exp_f32_e32 v77, v77
	v_exp_f32_e32 v73, v73
	v_exp_f32_e32 v78, v78
	v_exp_f32_e32 v74, v74
	v_exp_f32_e32 v79, v79
	v_exp_f32_e32 v75, v75
	v_add_f32_e32 v76, 1.0, v76
	v_add_f32_e32 v72, 1.0, v72
	v_add_f32_e32 v77, 1.0, v77
	v_add_f32_e32 v73, 1.0, v73
	v_add_f32_e32 v78, 1.0, v78
	v_add_f32_e32 v74, 1.0, v74
	v_add_f32_e32 v79, 1.0, v79
	v_add_f32_e32 v75, 1.0, v75
	v_rcp_f32_e32 v76, v76
	v_rcp_f32_e32 v72, v72
	v_rcp_f32_e32 v77, v77
	v_rcp_f32_e32 v73, v73
	v_rcp_f32_e32 v78, v78
	v_rcp_f32_e32 v74, v74
	v_rcp_f32_e32 v79, v79
	v_rcp_f32_e32 v75, v75
	v_mul_f32_e32 v69, 0xbfb8aa3b, v69
	v_mul_f32_e32 v71, 0xbfb8aa3b, v71
	v_mul_f32_e32 v68, 0xbfb8aa3b, v68
	v_mul_f32_e32 v64, 0xbfb8aa3b, v64
	v_mul_f32_e32 v65, 0xbfb8aa3b, v65
	v_mul_f32_e32 v70, 0xbfb8aa3b, v70
	v_exp_f32_e32 v69, v69
	v_exp_f32_e32 v71, v71
	v_mul_f32_e32 v66, 0xbfb8aa3b, v66
	v_mul_f32_e32 v67, 0xbfb8aa3b, v67
	v_exp_f32_e32 v68, v68
	v_exp_f32_e32 v64, v64
	v_exp_f32_e32 v65, v65
	v_exp_f32_e32 v70, v70
	v_exp_f32_e32 v66, v66
	v_exp_f32_e32 v67, v67
	v_add_f32_e32 v69, 1.0, v69
	v_add_f32_e32 v71, 1.0, v71
	v_add_f32_e32 v68, 1.0, v68
	v_add_f32_e32 v64, 1.0, v64
	v_add_f32_e32 v65, 1.0, v65
	v_add_f32_e32 v70, 1.0, v70
	v_rcp_f32_e32 v69, v69
	v_rcp_f32_e32 v71, v71
	v_add_f32_e32 v66, 1.0, v66
	v_add_f32_e32 v67, 1.0, v67
	v_rcp_f32_e32 v68, v68
	v_rcp_f32_e32 v64, v64
	v_rcp_f32_e32 v65, v65
	v_rcp_f32_e32 v70, v70
	v_rcp_f32_e32 v66, v66
	v_rcp_f32_e32 v67, v67
	s_waitcnt vmcnt(2)
	v_lshlrev_b32_e32 v97, 16, v84
	v_and_b32_e32 v84, 0xffff0000, v84
	v_lshlrev_b32_e32 v98, 16, v85
	v_and_b32_e32 v85, 0xffff0000, v85
	v_lshlrev_b32_e32 v99, 16, v86
	v_and_b32_e32 v86, 0xffff0000, v86
	v_lshlrev_b32_e32 v100, 16, v87
	v_and_b32_e32 v87, 0xffff0000, v87
	s_waitcnt vmcnt(0)
	v_mul_f32_e32 v97, v96, v97
	v_mul_f32_e32 v99, v96, v99
	v_mul_f32_e32 v84, v96, v84
	v_mul_f32_e32 v86, v96, v86
	v_mul_f32_e32 v98, v96, v98
	v_mul_f32_e32 v100, v96, v100
	v_mul_f32_e32 v85, v96, v85
	v_mul_f32_e32 v87, v96, v87
	v_lshlrev_b32_e32 v101, 16, v88
	v_and_b32_e32 v88, 0xffff0000, v88
	v_lshlrev_b32_e32 v102, 16, v89
	v_and_b32_e32 v89, 0xffff0000, v89
	v_lshlrev_b32_e32 v103, 16, v90
	v_and_b32_e32 v90, 0xffff0000, v90
	v_lshlrev_b32_e32 v104, 16, v91
	v_and_b32_e32 v91, 0xffff0000, v91
	v_mul_f32_e32 v97, v52, v97
	v_mul_f32_e32 v99, v48, v99
	v_mul_f32_e32 v84, v53, v84
	v_mul_f32_e32 v86, v49, v86
	v_mul_f32_e32 v98, v54, v98
	v_mul_f32_e32 v100, v50, v100
	v_mul_f32_e32 v85, v55, v85
	v_mul_f32_e32 v87, v51, v87
	v_fmac_f32_e32 v101, v76, v97
	v_fmac_f32_e32 v103, v72, v99
	v_fmac_f32_e32 v88, v77, v84
	v_fmac_f32_e32 v90, v73, v86
	v_fmac_f32_e32 v102, v78, v98
	v_fmac_f32_e32 v104, v74, v100
	v_fmac_f32_e32 v89, v79, v85
	v_fmac_f32_e32 v91, v75, v87
	v_cvt_pk_bf16_f32 v72, v101, v88
	v_cvt_pk_bf16_f32 v73, v102, v89
	v_cvt_pk_bf16_f32 v74, v103, v90
	v_cvt_pk_bf16_f32 v75, v104, v91
	global_load_dwordx4 v[76:79], v[92:93], off offset:256
	global_load_dwordx4 v[84:87], v[94:95], off offset:256
	v_mul_f32_e32 v88, v88, v88
	v_mul_f32_e32 v89, v89, v89
	v_mul_f32_e32 v90, v90, v90
	v_fmac_f32_e32 v88, v101, v101
	v_fmac_f32_e32 v89, v102, v102
	v_mul_f32_e32 v91, v91, v91
	v_fmac_f32_e32 v90, v103, v103
	v_add_f32_e32 v88, v88, v89
	v_fmac_f32_e32 v91, v104, v104
	v_add_f32_e32 v88, v90, v88
	v_add_f32_e32 v88, v91, v88
	s_waitcnt vmcnt(1)
	v_lshlrev_b32_e32 v89, 16, v76
	v_and_b32_e32 v76, 0xffff0000, v76
	v_lshlrev_b32_e32 v90, 16, v77
	v_and_b32_e32 v77, 0xffff0000, v77
	v_lshlrev_b32_e32 v91, 16, v78
	v_and_b32_e32 v78, 0xffff0000, v78
	v_mul_f32_e32 v76, v96, v76
	v_mul_f32_e32 v77, v96, v77
	v_lshlrev_b32_e32 v92, 16, v79
	v_and_b32_e32 v79, 0xffff0000, v79
	s_waitcnt vmcnt(0)
	v_lshlrev_b32_e32 v93, 16, v84
	v_and_b32_e32 v84, 0xffff0000, v84
	v_lshlrev_b32_e32 v94, 16, v85
	v_and_b32_e32 v85, 0xffff0000, v85
	v_mul_f32_e32 v89, v96, v89
	v_mul_f32_e32 v91, v96, v91
	v_mul_f32_e32 v78, v96, v78
	v_mul_f32_e32 v90, v96, v90
	v_mul_f32_e32 v76, v45, v76
	v_mul_f32_e32 v77, v47, v77
	v_lshlrev_b32_e32 v95, 16, v86
	v_and_b32_e32 v86, 0xffff0000, v86
	v_mul_f32_e32 v92, v96, v92
	v_mul_f32_e32 v79, v96, v79
	v_mul_f32_e32 v89, v44, v89
	v_mul_f32_e32 v91, v40, v91
	v_mul_f32_e32 v78, v41, v78
	v_mul_f32_e32 v90, v46, v90
	v_fmac_f32_e32 v84, v69, v76
	v_fmac_f32_e32 v85, v71, v77
	v_lshlrev_b32_e32 v97, 16, v87
	v_and_b32_e32 v87, 0xffff0000, v87
	v_mul_f32_e32 v92, v42, v92
	v_mul_f32_e32 v79, v43, v79
	v_fmac_f32_e32 v93, v68, v89
	v_fmac_f32_e32 v95, v64, v91
	v_fmac_f32_e32 v86, v65, v78
	v_fmac_f32_e32 v94, v70, v90
	v_mul_f32_e32 v64, v84, v84
	v_mul_f32_e32 v65, v85, v85
	v_fmac_f32_e32 v97, v66, v92
	v_fmac_f32_e32 v87, v67, v79
	v_mul_f32_e32 v66, v86, v86
	v_fmac_f32_e32 v64, v93, v93
	v_fmac_f32_e32 v65, v94, v94
	v_add_f32_e32 v64, v64, v65
	v_fmac_f32_e32 v66, v95, v95
	v_mul_f32_e32 v65, v87, v87
	v_add_f32_e32 v64, v66, v64
	v_fmac_f32_e32 v65, v97, v97
	v_add_f32_e32 v64, v65, v64
	v_add_f32_e32 v64, v88, v64
	ds_bpermute_b32 v65, v132, v64
	v_lshl_add_u64 v[70:71], s[12:13], 0, v[82:83]
	global_store_dwordx4 v[70:71], v[72:75], off
	v_cvt_pk_bf16_f32 v66, v93, v84
	v_cvt_pk_bf16_f32 v67, v94, v85
	s_waitcnt lgkmcnt(0)
	v_add_f32_e32 v64, v64, v65
	ds_bpermute_b32 v65, v133, v64
	v_cvt_pk_bf16_f32 v68, v95, v86
	v_cvt_pk_bf16_f32 v69, v97, v87
	global_store_dwordx4 v[70:71], v[66:69], off offset:256
	s_and_saveexec_b64 s[40:41], s[2:3]
	s_cbranch_execz .LBB0_1326
	v_lshlrev_b64 v[66:67], 8, v[80:81]
	v_lshl_add_u64 v[66:67], s[20:21], 0, v[66:67]
	v_lshl_add_u64 v[66:67], s[38:39], 2, v[66:67]
	s_lshl_b32 s8, s51, 2
	v_lshl_add_u64 v[66:67], v[66:67], 0, s[8:9]
	s_waitcnt lgkmcnt(0)
	v_add_f32_e32 v64, v64, v65
	global_store_dword v[66:67], v64, off
.LBB0_1326:
	s_or_b64 exec, exec, s[40:41]
	v_add_u32_e32 v64, 0x90, v154
	s_waitcnt lgkmcnt(0)
	v_ashrrev_i32_e32 v65, 31, v64
	v_lshlrev_b64 v[66:67], 12, v[64:65]
	v_lshl_add_u64 v[66:67], v[66:67], 0, v[152:153]
	v_lshlrev_b64 v[66:67], 1, v[66:67]
	v_lshl_add_u64 v[76:77], s[16:17], 0, v[66:67]
	global_load_dwordx4 v[68:71], v[76:77], off
	v_lshl_add_u64 v[78:79], s[86:87], 0, v[66:67]
	global_load_dwordx4 v[72:75], v[78:79], off
	global_load_dword v80, v[156:157], off offset:576
	v_mul_f32_e32 v60, 0xbfb8aa3b, v60
	v_mul_f32_e32 v56, 0xbfb8aa3b, v56
	v_mul_f32_e32 v61, 0xbfb8aa3b, v61
	v_mul_f32_e32 v57, 0xbfb8aa3b, v57
	v_mul_f32_e32 v62, 0xbfb8aa3b, v62
	v_mul_f32_e32 v58, 0xbfb8aa3b, v58
	v_mul_f32_e32 v63, 0xbfb8aa3b, v63
	v_mul_f32_e32 v59, 0xbfb8aa3b, v59
	v_exp_f32_e32 v60, v60
	v_exp_f32_e32 v56, v56
	v_exp_f32_e32 v61, v61
	v_exp_f32_e32 v57, v57
	v_exp_f32_e32 v62, v62
	v_exp_f32_e32 v58, v58
	v_exp_f32_e32 v63, v63
	v_exp_f32_e32 v59, v59
	v_add_f32_e32 v60, 1.0, v60
	v_add_f32_e32 v56, 1.0, v56
	v_add_f32_e32 v61, 1.0, v61
	v_add_f32_e32 v57, 1.0, v57
	v_add_f32_e32 v62, 1.0, v62
	v_add_f32_e32 v58, 1.0, v58
	v_add_f32_e32 v63, 1.0, v63
	v_add_f32_e32 v59, 1.0, v59
	v_rcp_f32_e32 v60, v60
	v_rcp_f32_e32 v56, v56
	v_rcp_f32_e32 v61, v61
	v_rcp_f32_e32 v57, v57
	v_rcp_f32_e32 v62, v62
	v_rcp_f32_e32 v58, v58
	v_rcp_f32_e32 v63, v63
	v_rcp_f32_e32 v59, v59
	v_mul_f32_e32 v37, 0xbfb8aa3b, v37
	v_mul_f32_e32 v39, 0xbfb8aa3b, v39
	v_mul_f32_e32 v36, 0xbfb8aa3b, v36
	v_mul_f32_e32 v32, 0xbfb8aa3b, v32
	v_mul_f32_e32 v33, 0xbfb8aa3b, v33
	v_mul_f32_e32 v38, 0xbfb8aa3b, v38
	v_exp_f32_e32 v37, v37
	v_exp_f32_e32 v39, v39
	v_mul_f32_e32 v34, 0xbfb8aa3b, v34
	v_mul_f32_e32 v35, 0xbfb8aa3b, v35
	v_exp_f32_e32 v36, v36
	v_exp_f32_e32 v32, v32
	v_exp_f32_e32 v33, v33
	v_exp_f32_e32 v38, v38
	v_exp_f32_e32 v34, v34
	v_exp_f32_e32 v35, v35
	v_add_f32_e32 v37, 1.0, v37
	v_add_f32_e32 v39, 1.0, v39
	v_add_f32_e32 v36, 1.0, v36
	v_add_f32_e32 v32, 1.0, v32
	v_add_f32_e32 v33, 1.0, v33
	v_add_f32_e32 v38, 1.0, v38
	v_rcp_f32_e32 v37, v37
	v_rcp_f32_e32 v39, v39
	v_add_f32_e32 v34, 1.0, v34
	v_add_f32_e32 v35, 1.0, v35
	v_rcp_f32_e32 v36, v36
	v_rcp_f32_e32 v32, v32
	v_rcp_f32_e32 v33, v33
	v_rcp_f32_e32 v38, v38
	v_rcp_f32_e32 v34, v34
	v_rcp_f32_e32 v35, v35
	s_waitcnt vmcnt(2)
	v_lshlrev_b32_e32 v81, 16, v68
	v_and_b32_e32 v68, 0xffff0000, v68
	v_lshlrev_b32_e32 v82, 16, v69
	v_and_b32_e32 v69, 0xffff0000, v69
	v_lshlrev_b32_e32 v83, 16, v70
	v_and_b32_e32 v70, 0xffff0000, v70
	v_lshlrev_b32_e32 v84, 16, v71
	v_and_b32_e32 v71, 0xffff0000, v71
	s_waitcnt vmcnt(0)
	v_mul_f32_e32 v81, v80, v81
	v_mul_f32_e32 v83, v80, v83
	v_mul_f32_e32 v68, v80, v68
	v_mul_f32_e32 v70, v80, v70
	v_mul_f32_e32 v82, v80, v82
	v_mul_f32_e32 v84, v80, v84
	v_mul_f32_e32 v69, v80, v69
	v_mul_f32_e32 v71, v80, v71
	v_lshlrev_b32_e32 v85, 16, v72
	v_and_b32_e32 v72, 0xffff0000, v72
	v_lshlrev_b32_e32 v86, 16, v73
	v_and_b32_e32 v73, 0xffff0000, v73
	v_lshlrev_b32_e32 v87, 16, v74
	v_and_b32_e32 v74, 0xffff0000, v74
	v_lshlrev_b32_e32 v88, 16, v75
	v_and_b32_e32 v75, 0xffff0000, v75
	v_mul_f32_e32 v81, v52, v81
	v_mul_f32_e32 v83, v48, v83
	v_mul_f32_e32 v68, v53, v68
	v_mul_f32_e32 v70, v49, v70
	v_mul_f32_e32 v82, v54, v82
	v_mul_f32_e32 v84, v50, v84
	v_mul_f32_e32 v69, v55, v69
	v_mul_f32_e32 v71, v51, v71
	v_fmac_f32_e32 v85, v60, v81
	v_fmac_f32_e32 v87, v56, v83
	v_fmac_f32_e32 v72, v61, v68
	v_fmac_f32_e32 v74, v57, v70
	v_fmac_f32_e32 v86, v62, v82
	v_fmac_f32_e32 v88, v58, v84
	v_fmac_f32_e32 v73, v63, v69
	v_fmac_f32_e32 v75, v59, v71
	v_cvt_pk_bf16_f32 v56, v85, v72
	v_cvt_pk_bf16_f32 v57, v86, v73
	v_cvt_pk_bf16_f32 v58, v87, v74
	v_cvt_pk_bf16_f32 v59, v88, v75
	global_load_dwordx4 v[60:63], v[76:77], off offset:256
	global_load_dwordx4 v[68:71], v[78:79], off offset:256
	v_mul_f32_e32 v72, v72, v72
	v_mul_f32_e32 v73, v73, v73
	v_mul_f32_e32 v74, v74, v74
	v_fmac_f32_e32 v72, v85, v85
	v_fmac_f32_e32 v73, v86, v86
	v_mul_f32_e32 v75, v75, v75
	v_fmac_f32_e32 v74, v87, v87
	v_add_f32_e32 v72, v72, v73
	v_fmac_f32_e32 v75, v88, v88
	v_add_f32_e32 v72, v74, v72
	v_add_f32_e32 v72, v75, v72
	s_waitcnt vmcnt(1)
	v_lshlrev_b32_e32 v73, 16, v60
	v_and_b32_e32 v60, 0xffff0000, v60
	v_lshlrev_b32_e32 v74, 16, v61
	v_and_b32_e32 v61, 0xffff0000, v61
	v_lshlrev_b32_e32 v75, 16, v62
	v_and_b32_e32 v62, 0xffff0000, v62
	v_mul_f32_e32 v60, v80, v60
	v_mul_f32_e32 v61, v80, v61
	v_lshlrev_b32_e32 v76, 16, v63
	v_and_b32_e32 v63, 0xffff0000, v63
	s_waitcnt vmcnt(0)
	v_lshlrev_b32_e32 v77, 16, v68
	v_and_b32_e32 v68, 0xffff0000, v68
	v_lshlrev_b32_e32 v78, 16, v69
	v_and_b32_e32 v69, 0xffff0000, v69
	v_mul_f32_e32 v73, v80, v73
	v_mul_f32_e32 v75, v80, v75
	v_mul_f32_e32 v62, v80, v62
	v_mul_f32_e32 v74, v80, v74
	v_mul_f32_e32 v60, v45, v60
	v_mul_f32_e32 v61, v47, v61
	v_lshlrev_b32_e32 v79, 16, v70
	v_and_b32_e32 v70, 0xffff0000, v70
	v_mul_f32_e32 v76, v80, v76
	v_mul_f32_e32 v63, v80, v63
	v_mul_f32_e32 v73, v44, v73
	v_mul_f32_e32 v75, v40, v75
	v_mul_f32_e32 v62, v41, v62
	v_mul_f32_e32 v74, v46, v74
	v_fmac_f32_e32 v68, v37, v60
	v_fmac_f32_e32 v69, v39, v61
	v_lshlrev_b32_e32 v81, 16, v71
	v_and_b32_e32 v71, 0xffff0000, v71
	v_mul_f32_e32 v76, v42, v76
	v_mul_f32_e32 v63, v43, v63
	v_fmac_f32_e32 v77, v36, v73
	v_fmac_f32_e32 v79, v32, v75
	v_fmac_f32_e32 v70, v33, v62
	v_fmac_f32_e32 v78, v38, v74
	v_mul_f32_e32 v32, v68, v68
	v_mul_f32_e32 v33, v69, v69
	v_fmac_f32_e32 v81, v34, v76
	v_fmac_f32_e32 v71, v35, v63
	v_mul_f32_e32 v34, v70, v70
	v_fmac_f32_e32 v32, v77, v77
	v_fmac_f32_e32 v33, v78, v78
	v_add_f32_e32 v32, v32, v33
	v_fmac_f32_e32 v34, v79, v79
	v_mul_f32_e32 v33, v71, v71
	v_add_f32_e32 v32, v34, v32
	v_fmac_f32_e32 v33, v81, v81
	v_add_f32_e32 v32, v33, v32
	v_add_f32_e32 v32, v72, v32
	ds_bpermute_b32 v33, v132, v32
	v_lshl_add_u64 v[38:39], s[12:13], 0, v[66:67]
	global_store_dwordx4 v[38:39], v[56:59], off
	v_cvt_pk_bf16_f32 v34, v77, v68
	v_cvt_pk_bf16_f32 v35, v78, v69
	s_waitcnt lgkmcnt(0)
	v_add_f32_e32 v32, v32, v33
	ds_bpermute_b32 v33, v133, v32
	v_cvt_pk_bf16_f32 v36, v79, v70
	v_cvt_pk_bf16_f32 v37, v81, v71
	global_store_dwordx4 v[38:39], v[34:37], off offset:256
	s_and_saveexec_b64 s[40:41], s[2:3]
	s_cbranch_execz .LBB0_1328
	v_lshlrev_b64 v[34:35], 8, v[64:65]
	v_lshl_add_u64 v[34:35], s[20:21], 0, v[34:35]
	v_lshl_add_u64 v[34:35], s[38:39], 2, v[34:35]
	s_lshl_b32 s8, s51, 2
	v_lshl_add_u64 v[34:35], v[34:35], 0, s[8:9]
	s_waitcnt lgkmcnt(0)
	v_add_f32_e32 v32, v32, v33
	global_store_dword v[34:35], v32, off
.LBB0_1328:
	s_or_b64 exec, exec, s[40:41]
	v_add_u32_e32 v32, 0xa0, v154
	s_waitcnt lgkmcnt(0)
	v_ashrrev_i32_e32 v33, 31, v32
	v_lshlrev_b64 v[34:35], 12, v[32:33]
	v_lshl_add_u64 v[34:35], v[34:35], 0, v[152:153]
	v_lshlrev_b64 v[34:35], 1, v[34:35]
	v_lshl_add_u64 v[60:61], s[16:17], 0, v[34:35]
	global_load_dwordx4 v[36:39], v[60:61], off
	v_lshl_add_u64 v[62:63], s[86:87], 0, v[34:35]
	global_load_dwordx4 v[56:59], v[62:63], off
	global_load_dword v64, v[156:157], off offset:640
	v_mul_f32_e32 v28, 0xbfb8aa3b, v28
	v_mul_f32_e32 v24, 0xbfb8aa3b, v24
	v_mul_f32_e32 v29, 0xbfb8aa3b, v29
	v_mul_f32_e32 v25, 0xbfb8aa3b, v25
	v_mul_f32_e32 v30, 0xbfb8aa3b, v30
	v_mul_f32_e32 v26, 0xbfb8aa3b, v26
	v_mul_f32_e32 v31, 0xbfb8aa3b, v31
	v_mul_f32_e32 v27, 0xbfb8aa3b, v27
	v_exp_f32_e32 v28, v28
	v_exp_f32_e32 v24, v24
	v_exp_f32_e32 v29, v29
	v_exp_f32_e32 v25, v25
	v_exp_f32_e32 v30, v30
	v_exp_f32_e32 v26, v26
	v_exp_f32_e32 v31, v31
	v_exp_f32_e32 v27, v27
	v_add_f32_e32 v28, 1.0, v28
	v_add_f32_e32 v24, 1.0, v24
	v_add_f32_e32 v29, 1.0, v29
	v_add_f32_e32 v25, 1.0, v25
	v_add_f32_e32 v30, 1.0, v30
	v_add_f32_e32 v26, 1.0, v26
	v_add_f32_e32 v31, 1.0, v31
	v_add_f32_e32 v27, 1.0, v27
	v_rcp_f32_e32 v28, v28
	v_rcp_f32_e32 v24, v24
	v_rcp_f32_e32 v29, v29
	v_rcp_f32_e32 v25, v25
	v_rcp_f32_e32 v30, v30
	v_rcp_f32_e32 v26, v26
	v_rcp_f32_e32 v31, v31
	v_rcp_f32_e32 v27, v27
	v_mul_f32_e32 v21, 0xbfb8aa3b, v21
	v_mul_f32_e32 v23, 0xbfb8aa3b, v23
	v_mul_f32_e32 v20, 0xbfb8aa3b, v20
	v_mul_f32_e32 v16, 0xbfb8aa3b, v16
	v_mul_f32_e32 v17, 0xbfb8aa3b, v17
	v_mul_f32_e32 v22, 0xbfb8aa3b, v22
	v_exp_f32_e32 v21, v21
	v_exp_f32_e32 v23, v23
	v_mul_f32_e32 v18, 0xbfb8aa3b, v18
	v_mul_f32_e32 v19, 0xbfb8aa3b, v19
	v_exp_f32_e32 v20, v20
	v_exp_f32_e32 v16, v16
	v_exp_f32_e32 v17, v17
	v_exp_f32_e32 v22, v22
	v_exp_f32_e32 v18, v18
	v_exp_f32_e32 v19, v19
	v_add_f32_e32 v21, 1.0, v21
	v_add_f32_e32 v23, 1.0, v23
	v_add_f32_e32 v20, 1.0, v20
	v_add_f32_e32 v16, 1.0, v16
	v_add_f32_e32 v17, 1.0, v17
	v_add_f32_e32 v22, 1.0, v22
	v_rcp_f32_e32 v21, v21
	v_rcp_f32_e32 v23, v23
	v_add_f32_e32 v18, 1.0, v18
	v_add_f32_e32 v19, 1.0, v19
	v_rcp_f32_e32 v20, v20
	v_rcp_f32_e32 v16, v16
	v_rcp_f32_e32 v17, v17
	v_rcp_f32_e32 v22, v22
	v_rcp_f32_e32 v18, v18
	v_rcp_f32_e32 v19, v19
	s_waitcnt vmcnt(2)
	v_lshlrev_b32_e32 v65, 16, v36
	v_and_b32_e32 v36, 0xffff0000, v36
	v_lshlrev_b32_e32 v66, 16, v37
	v_and_b32_e32 v37, 0xffff0000, v37
	v_lshlrev_b32_e32 v67, 16, v38
	v_and_b32_e32 v38, 0xffff0000, v38
	v_lshlrev_b32_e32 v68, 16, v39
	v_and_b32_e32 v39, 0xffff0000, v39
	s_waitcnt vmcnt(0)
	v_mul_f32_e32 v65, v64, v65
	v_mul_f32_e32 v67, v64, v67
	v_mul_f32_e32 v36, v64, v36
	v_mul_f32_e32 v38, v64, v38
	v_mul_f32_e32 v66, v64, v66
	v_mul_f32_e32 v68, v64, v68
	v_mul_f32_e32 v37, v64, v37
	v_mul_f32_e32 v39, v64, v39
	v_lshlrev_b32_e32 v69, 16, v56
	v_and_b32_e32 v56, 0xffff0000, v56
	v_lshlrev_b32_e32 v70, 16, v57
	v_and_b32_e32 v57, 0xffff0000, v57
	v_lshlrev_b32_e32 v71, 16, v58
	v_and_b32_e32 v58, 0xffff0000, v58
	v_lshlrev_b32_e32 v72, 16, v59
	v_and_b32_e32 v59, 0xffff0000, v59
	v_mul_f32_e32 v65, v52, v65
	v_mul_f32_e32 v67, v48, v67
	v_mul_f32_e32 v36, v53, v36
	v_mul_f32_e32 v38, v49, v38
	v_mul_f32_e32 v66, v54, v66
	v_mul_f32_e32 v68, v50, v68
	v_mul_f32_e32 v37, v55, v37
	v_mul_f32_e32 v39, v51, v39
	v_fmac_f32_e32 v69, v28, v65
	v_fmac_f32_e32 v71, v24, v67
	v_fmac_f32_e32 v56, v29, v36
	v_fmac_f32_e32 v58, v25, v38
	v_fmac_f32_e32 v70, v30, v66
	v_fmac_f32_e32 v72, v26, v68
	v_fmac_f32_e32 v57, v31, v37
	v_fmac_f32_e32 v59, v27, v39
	v_cvt_pk_bf16_f32 v24, v69, v56
	v_cvt_pk_bf16_f32 v25, v70, v57
	v_cvt_pk_bf16_f32 v26, v71, v58
	v_cvt_pk_bf16_f32 v27, v72, v59
	global_load_dwordx4 v[28:31], v[60:61], off offset:256
	global_load_dwordx4 v[36:39], v[62:63], off offset:256
	v_mul_f32_e32 v56, v56, v56
	v_mul_f32_e32 v57, v57, v57
	v_mul_f32_e32 v58, v58, v58
	v_fmac_f32_e32 v56, v69, v69
	v_fmac_f32_e32 v57, v70, v70
	v_mul_f32_e32 v59, v59, v59
	v_fmac_f32_e32 v58, v71, v71
	v_add_f32_e32 v56, v56, v57
	v_fmac_f32_e32 v59, v72, v72
	v_add_f32_e32 v56, v58, v56
	v_add_f32_e32 v56, v59, v56
	s_waitcnt vmcnt(1)
	v_lshlrev_b32_e32 v57, 16, v28
	v_and_b32_e32 v28, 0xffff0000, v28
	v_lshlrev_b32_e32 v58, 16, v29
	v_and_b32_e32 v29, 0xffff0000, v29
	v_lshlrev_b32_e32 v59, 16, v30
	v_and_b32_e32 v30, 0xffff0000, v30
	v_mul_f32_e32 v28, v64, v28
	v_mul_f32_e32 v29, v64, v29
	v_lshlrev_b32_e32 v60, 16, v31
	v_and_b32_e32 v31, 0xffff0000, v31
	s_waitcnt vmcnt(0)
	v_lshlrev_b32_e32 v61, 16, v36
	v_and_b32_e32 v36, 0xffff0000, v36
	v_lshlrev_b32_e32 v62, 16, v37
	v_and_b32_e32 v37, 0xffff0000, v37
	v_mul_f32_e32 v57, v64, v57
	v_mul_f32_e32 v59, v64, v59
	v_mul_f32_e32 v30, v64, v30
	v_mul_f32_e32 v58, v64, v58
	v_mul_f32_e32 v28, v45, v28
	v_mul_f32_e32 v29, v47, v29
	v_lshlrev_b32_e32 v63, 16, v38
	v_and_b32_e32 v38, 0xffff0000, v38
	v_mul_f32_e32 v60, v64, v60
	v_mul_f32_e32 v31, v64, v31
	v_mul_f32_e32 v57, v44, v57
	v_mul_f32_e32 v59, v40, v59
	v_mul_f32_e32 v30, v41, v30
	v_mul_f32_e32 v58, v46, v58
	v_fmac_f32_e32 v36, v21, v28
	v_fmac_f32_e32 v37, v23, v29
	v_lshlrev_b32_e32 v65, 16, v39
	v_and_b32_e32 v39, 0xffff0000, v39
	v_mul_f32_e32 v60, v42, v60
	v_mul_f32_e32 v31, v43, v31
	v_fmac_f32_e32 v61, v20, v57
	v_fmac_f32_e32 v63, v16, v59
	v_fmac_f32_e32 v38, v17, v30
	v_fmac_f32_e32 v62, v22, v58
	v_mul_f32_e32 v16, v36, v36
	v_mul_f32_e32 v17, v37, v37
	v_fmac_f32_e32 v65, v18, v60
	v_fmac_f32_e32 v39, v19, v31
	v_mul_f32_e32 v18, v38, v38
	v_fmac_f32_e32 v16, v61, v61
	v_fmac_f32_e32 v17, v62, v62
	v_add_f32_e32 v16, v16, v17
	v_fmac_f32_e32 v18, v63, v63
	v_mul_f32_e32 v17, v39, v39
	v_add_f32_e32 v16, v18, v16
	v_fmac_f32_e32 v17, v65, v65
	v_add_f32_e32 v16, v17, v16
	v_add_f32_e32 v16, v56, v16
	ds_bpermute_b32 v17, v132, v16
	v_lshl_add_u64 v[22:23], s[12:13], 0, v[34:35]
	global_store_dwordx4 v[22:23], v[24:27], off
	v_cvt_pk_bf16_f32 v18, v61, v36
	v_cvt_pk_bf16_f32 v19, v62, v37
	s_waitcnt lgkmcnt(0)
	v_add_f32_e32 v16, v16, v17
	ds_bpermute_b32 v17, v133, v16
	v_cvt_pk_bf16_f32 v20, v63, v38
	v_cvt_pk_bf16_f32 v21, v65, v39
	global_store_dwordx4 v[22:23], v[18:21], off offset:256
	s_and_saveexec_b64 s[40:41], s[2:3]
	s_cbranch_execz .LBB0_1330
	v_lshlrev_b64 v[18:19], 8, v[32:33]
	v_lshl_add_u64 v[18:19], s[20:21], 0, v[18:19]
	v_lshl_add_u64 v[18:19], s[38:39], 2, v[18:19]
	s_lshl_b32 s8, s51, 2
	v_lshl_add_u64 v[18:19], v[18:19], 0, s[8:9]
	s_waitcnt lgkmcnt(0)
	v_add_f32_e32 v16, v16, v17
	global_store_dword v[18:19], v16, off
.LBB0_1330:
	s_or_b64 exec, exec, s[40:41]
	v_add_u32_e32 v16, 0xb0, v154
	s_waitcnt lgkmcnt(0)
	v_ashrrev_i32_e32 v17, 31, v16
	v_lshlrev_b64 v[18:19], 12, v[16:17]
	v_lshl_add_u64 v[18:19], v[18:19], 0, v[152:153]
	v_lshlrev_b64 v[18:19], 1, v[18:19]
	v_lshl_add_u64 v[28:29], s[16:17], 0, v[18:19]
	global_load_dwordx4 v[20:23], v[28:29], off
	v_lshl_add_u64 v[30:31], s[86:87], 0, v[18:19]
	global_load_dwordx4 v[24:27], v[30:31], off
	global_load_dword v32, v[156:157], off offset:704
	v_mul_f32_e32 v12, 0xbfb8aa3b, v12
	v_mul_f32_e32 v8, 0xbfb8aa3b, v8
	v_mul_f32_e32 v13, 0xbfb8aa3b, v13
	v_mul_f32_e32 v9, 0xbfb8aa3b, v9
	v_mul_f32_e32 v14, 0xbfb8aa3b, v14
	v_mul_f32_e32 v10, 0xbfb8aa3b, v10
	v_mul_f32_e32 v15, 0xbfb8aa3b, v15
	v_mul_f32_e32 v11, 0xbfb8aa3b, v11
	v_exp_f32_e32 v12, v12
	v_exp_f32_e32 v8, v8
	v_exp_f32_e32 v13, v13
	v_exp_f32_e32 v9, v9
	v_exp_f32_e32 v14, v14
	v_exp_f32_e32 v10, v10
	v_exp_f32_e32 v15, v15
	v_exp_f32_e32 v11, v11
	v_add_f32_e32 v12, 1.0, v12
	v_add_f32_e32 v8, 1.0, v8
	v_add_f32_e32 v13, 1.0, v13
	v_add_f32_e32 v9, 1.0, v9
	v_add_f32_e32 v14, 1.0, v14
	v_add_f32_e32 v10, 1.0, v10
	v_add_f32_e32 v15, 1.0, v15
	v_add_f32_e32 v11, 1.0, v11
	v_rcp_f32_e32 v12, v12
	v_rcp_f32_e32 v8, v8
	v_rcp_f32_e32 v13, v13
	v_rcp_f32_e32 v9, v9
	v_rcp_f32_e32 v14, v14
	v_rcp_f32_e32 v10, v10
	v_rcp_f32_e32 v15, v15
	v_rcp_f32_e32 v11, v11
	v_mul_f32_e32 v5, 0xbfb8aa3b, v5
	v_mul_f32_e32 v7, 0xbfb8aa3b, v7
	v_mul_f32_e32 v4, 0xbfb8aa3b, v4
	v_mul_f32_e32 v0, 0xbfb8aa3b, v0
	v_mul_f32_e32 v1, 0xbfb8aa3b, v1
	v_mul_f32_e32 v6, 0xbfb8aa3b, v6
	v_exp_f32_e32 v5, v5
	v_exp_f32_e32 v7, v7
	v_mul_f32_e32 v2, 0xbfb8aa3b, v2
	v_mul_f32_e32 v3, 0xbfb8aa3b, v3
	v_exp_f32_e32 v4, v4
	v_exp_f32_e32 v0, v0
	v_exp_f32_e32 v1, v1
	v_exp_f32_e32 v6, v6
	v_exp_f32_e32 v2, v2
	v_exp_f32_e32 v3, v3
	v_add_f32_e32 v5, 1.0, v5
	v_add_f32_e32 v7, 1.0, v7
	v_add_f32_e32 v4, 1.0, v4
	v_add_f32_e32 v0, 1.0, v0
	v_add_f32_e32 v1, 1.0, v1
	v_add_f32_e32 v6, 1.0, v6
	v_rcp_f32_e32 v5, v5
	v_rcp_f32_e32 v7, v7
	v_add_f32_e32 v2, 1.0, v2
	v_add_f32_e32 v3, 1.0, v3
	v_rcp_f32_e32 v4, v4
	v_rcp_f32_e32 v0, v0
	v_rcp_f32_e32 v1, v1
	v_rcp_f32_e32 v6, v6
	v_rcp_f32_e32 v2, v2
	v_rcp_f32_e32 v3, v3
	s_waitcnt vmcnt(2)
	v_lshlrev_b32_e32 v33, 16, v20
	v_and_b32_e32 v20, 0xffff0000, v20
	v_lshlrev_b32_e32 v34, 16, v21
	v_and_b32_e32 v21, 0xffff0000, v21
	v_lshlrev_b32_e32 v35, 16, v22
	v_and_b32_e32 v22, 0xffff0000, v22
	v_lshlrev_b32_e32 v36, 16, v23
	v_and_b32_e32 v23, 0xffff0000, v23
	s_waitcnt vmcnt(0)
	v_mul_f32_e32 v33, v32, v33
	v_mul_f32_e32 v35, v32, v35
	v_mul_f32_e32 v20, v32, v20
	v_mul_f32_e32 v22, v32, v22
	v_mul_f32_e32 v34, v32, v34
	v_mul_f32_e32 v36, v32, v36
	v_mul_f32_e32 v21, v32, v21
	v_mul_f32_e32 v23, v32, v23
	v_lshlrev_b32_e32 v37, 16, v24
	v_and_b32_e32 v24, 0xffff0000, v24
	v_lshlrev_b32_e32 v38, 16, v25
	v_and_b32_e32 v25, 0xffff0000, v25
	v_lshlrev_b32_e32 v39, 16, v26
	v_and_b32_e32 v26, 0xffff0000, v26
	v_lshlrev_b32_e32 v56, 16, v27
	v_and_b32_e32 v27, 0xffff0000, v27
	v_mul_f32_e32 v33, v52, v33
	v_mul_f32_e32 v35, v48, v35
	v_mul_f32_e32 v20, v53, v20
	v_mul_f32_e32 v22, v49, v22
	v_mul_f32_e32 v34, v54, v34
	v_mul_f32_e32 v36, v50, v36
	v_mul_f32_e32 v21, v55, v21
	v_mul_f32_e32 v23, v51, v23
	v_fmac_f32_e32 v37, v12, v33
	v_fmac_f32_e32 v39, v8, v35
	v_fmac_f32_e32 v24, v13, v20
	v_fmac_f32_e32 v26, v9, v22
	v_fmac_f32_e32 v38, v14, v34
	v_fmac_f32_e32 v56, v10, v36
	v_fmac_f32_e32 v25, v15, v21
	v_fmac_f32_e32 v27, v11, v23
	v_cvt_pk_bf16_f32 v8, v37, v24
	v_cvt_pk_bf16_f32 v9, v38, v25
	v_cvt_pk_bf16_f32 v10, v39, v26
	v_cvt_pk_bf16_f32 v11, v56, v27
	global_load_dwordx4 v[12:15], v[28:29], off offset:256
	global_load_dwordx4 v[20:23], v[30:31], off offset:256
	v_mul_f32_e32 v24, v24, v24
	v_mul_f32_e32 v25, v25, v25
	v_mul_f32_e32 v26, v26, v26
	v_fmac_f32_e32 v24, v37, v37
	v_fmac_f32_e32 v25, v38, v38
	v_mul_f32_e32 v27, v27, v27
	v_fmac_f32_e32 v26, v39, v39
	v_add_f32_e32 v24, v24, v25
	v_fmac_f32_e32 v27, v56, v56
	v_add_f32_e32 v24, v26, v24
	v_add_f32_e32 v24, v27, v24
	s_waitcnt vmcnt(1)
	v_lshlrev_b32_e32 v25, 16, v12
	v_and_b32_e32 v12, 0xffff0000, v12
	v_lshlrev_b32_e32 v26, 16, v13
	v_and_b32_e32 v13, 0xffff0000, v13
	v_lshlrev_b32_e32 v27, 16, v14
	v_and_b32_e32 v14, 0xffff0000, v14
	v_mul_f32_e32 v12, v32, v12
	v_mul_f32_e32 v13, v32, v13
	v_lshlrev_b32_e32 v28, 16, v15
	v_and_b32_e32 v15, 0xffff0000, v15
	s_waitcnt vmcnt(0)
	v_lshlrev_b32_e32 v29, 16, v20
	v_and_b32_e32 v20, 0xffff0000, v20
	v_lshlrev_b32_e32 v30, 16, v21
	v_and_b32_e32 v21, 0xffff0000, v21
	v_mul_f32_e32 v25, v32, v25
	v_mul_f32_e32 v27, v32, v27
	v_mul_f32_e32 v14, v32, v14
	v_mul_f32_e32 v26, v32, v26
	v_mul_f32_e32 v12, v45, v12
	v_mul_f32_e32 v13, v47, v13
	v_lshlrev_b32_e32 v31, 16, v22
	v_and_b32_e32 v22, 0xffff0000, v22
	v_mul_f32_e32 v28, v32, v28
	v_mul_f32_e32 v15, v32, v15
	v_mul_f32_e32 v25, v44, v25
	v_mul_f32_e32 v27, v40, v27
	v_mul_f32_e32 v14, v41, v14
	v_mul_f32_e32 v26, v46, v26
	v_fmac_f32_e32 v20, v5, v12
	v_fmac_f32_e32 v21, v7, v13
	v_lshlrev_b32_e32 v33, 16, v23
	v_and_b32_e32 v23, 0xffff0000, v23
	v_mul_f32_e32 v28, v42, v28
	v_mul_f32_e32 v15, v43, v15
	v_fmac_f32_e32 v29, v4, v25
	v_fmac_f32_e32 v31, v0, v27
	v_fmac_f32_e32 v22, v1, v14
	v_fmac_f32_e32 v30, v6, v26
	v_mul_f32_e32 v0, v20, v20
	v_mul_f32_e32 v1, v21, v21
	v_fmac_f32_e32 v33, v2, v28
	v_fmac_f32_e32 v23, v3, v15
	v_mul_f32_e32 v2, v22, v22
	v_fmac_f32_e32 v0, v29, v29
	v_fmac_f32_e32 v1, v30, v30
	v_add_f32_e32 v0, v0, v1
	v_fmac_f32_e32 v2, v31, v31
	v_mul_f32_e32 v1, v23, v23
	v_add_f32_e32 v0, v2, v0
	v_fmac_f32_e32 v1, v33, v33
	v_add_f32_e32 v0, v1, v0
	v_add_f32_e32 v0, v24, v0
	ds_bpermute_b32 v1, v132, v0
	v_lshl_add_u64 v[6:7], s[12:13], 0, v[18:19]
	global_store_dwordx4 v[6:7], v[8:11], off
	v_cvt_pk_bf16_f32 v2, v29, v20
	v_cvt_pk_bf16_f32 v3, v30, v21
	s_waitcnt lgkmcnt(0)
	v_add_f32_e32 v0, v0, v1
	ds_bpermute_b32 v1, v133, v0
	v_cvt_pk_bf16_f32 v4, v31, v22
	v_cvt_pk_bf16_f32 v5, v33, v23
	global_store_dwordx4 v[6:7], v[2:5], off offset:256
	s_and_saveexec_b64 s[40:41], s[2:3]
	s_cbranch_execz .LBB0_1332
	v_lshlrev_b64 v[2:3], 8, v[16:17]
	v_lshl_add_u64 v[2:3], s[20:21], 0, v[2:3]
	v_lshl_add_u64 v[2:3], s[38:39], 2, v[2:3]
	s_lshl_b32 s8, s51, 2
	v_lshl_add_u64 v[2:3], v[2:3], 0, s[8:9]
	s_waitcnt lgkmcnt(0)
	v_add_f32_e32 v0, v0, v1
	global_store_dword v[2:3], v0, off
